# K-loop: phase-2 SA(0,0) DMAs moved to phase 3, saddr-form DMAs, peeled first iteration (C=0, relaxed waits), re-stagger barrier after tile index math; P0 x->bf16 loop software-pipelined
# speedup vs baseline: 1.0060x; 1.0060x over previous
_Z8yoco_fwd4Args:
	s_mov_b32 s98, 0
	s_load_dwordx2 s[38:39], s[0:1], 0xd0
	s_load_dword s14, s[0:1], 0xd8
	s_add_u32 s4, s0, 0xd0
	s_addc_u32 s5, s1, 0
	v_and_b32_e32 v168, 0x3ff, v0
	v_writelane_b32 v244, s4, 0
	v_cmp_gt_u32_e32 vcc, 2, v168
	s_nop 0
	v_writelane_b32 v244, s5, 1
	s_and_saveexec_b64 s[6:7], vcc
	v_lshl_add_u32 v1, v168, 2, 0
	v_add_u32_e32 v1, 0x20040, v1
	v_mov_b32_e32 v2, 0
	ds_write_b32 v1, v2
	s_or_b64 exec, exec, s[6:7]
	s_cmp_lg_u32 s2, 0
	s_mov_b32 s16, 0
	s_cbranch_scc1 .LBB0_10
	s_mov_b64 s[4:5], s[0:1]
	s_load_dwordx2 s[4:5], s[4:5], 0xc8
	v_sub_u32_e32 v1, 0xd7f, v168
	v_lshrrev_b32_e32 v2, 9, v1
	v_add_u32_e32 v1, 2, v2
	v_add_u32_e32 v169, 0x200, v168
	s_waitcnt lgkmcnt(0)
	s_add_u32 s6, s4, 0x4000
	v_and_b32_e32 v3, 14, v1
	s_addc_u32 s7, s5, 0
	v_mov_b32_e32 v1, v2
	s_mov_b64 s[8:9], 0
	s_mov_b32 s17, 1
	v_mov_b32_e32 v5, 0
	s_mov_b32 s10, s16
	v_mov_b64_e32 v[6:7], v[168:169]
	s_branch .LBB0_5

.LBB0_124:
	v_mbcnt_lo_u32_b32 v169, -1, 0
	s_cmp_gt_i32 s2, 0xffff
	s_cbranch_scc1 .LBB0_135
	s_waitcnt lgkmcnt(0)
	s_load_dwordx2 s[6:7], s[48:49], 0x0
	v_lshlrev_b32_e32 v64, 4, v1
	v_lshlrev_b32_e32 v2, 3, v1
	v_mov_b32_e32 v3, 0
	v_mov_b32_e32 v65, 0x358637bd
	v_mov_b32_e32 v67, 0x260
	s_mov_b32 s30, 0xf800000
	s_add_u32 s0, s54, 0x100000
	s_addc_u32 s1, s55, 0
	s_add_u32 s8, s54, 0x8000000
	s_addc_u32 s9, s55, 0
	s_lshl_b32 s4, s33, 2
	s_waitcnt lgkmcnt(0)
	s_mov_b32 s10, s2
	s_mov_b32 s31, s10
	s_lshr_b32 s5, s31, 20
	s_lshl_b32 s31, s31, 12
	s_add_u32 s34, s6, s31
	s_addc_u32 s5, s7, s5
	s_mov_b32 s12, s34
	s_mov_b32 s13, s5
	global_load_dwordx4 v[170:173], v64, s[12:13]
	global_load_dwordx4 v[174:177], v64, s[12:13] offset:1024
	global_load_dwordx4 v[178:181], v64, s[12:13] offset:2048
	global_load_dwordx4 v[182:185], v64, s[12:13] offset:3072
	s_add_i32 s10, s10, s33
	s_mov_b32 s31, s10
	s_lshr_b32 s5, s31, 20
	s_lshl_b32 s31, s31, 12
	s_add_u32 s34, s6, s31
	s_addc_u32 s5, s7, s5
	s_mov_b32 s12, s34
	s_mov_b32 s13, s5
	global_load_dwordx4 v[186:189], v64, s[12:13]
	global_load_dwordx4 v[190:193], v64, s[12:13] offset:1024
	global_load_dwordx4 v[194:197], v64, s[12:13] offset:2048
	global_load_dwordx4 v[198:201], v64, s[12:13] offset:3072
	s_add_i32 s10, s10, s33
	s_mov_b32 s31, s10
	s_lshr_b32 s5, s31, 20
	s_lshl_b32 s31, s31, 12
	s_add_u32 s34, s6, s31
	s_addc_u32 s5, s7, s5
	s_mov_b32 s12, s34
	s_mov_b32 s13, s5
	global_load_dwordx4 v[202:205], v64, s[12:13]
	global_load_dwordx4 v[206:209], v64, s[12:13] offset:1024
	global_load_dwordx4 v[210:213], v64, s[12:13] offset:2048
	global_load_dwordx4 v[214:217], v64, s[12:13] offset:3072
	s_add_i32 s10, s10, s33
	s_mov_b32 s31, s10
	s_lshr_b32 s5, s31, 20
	s_lshl_b32 s31, s31, 12
	s_add_u32 s34, s6, s31
	s_addc_u32 s5, s7, s5
	s_mov_b32 s12, s34
	s_mov_b32 s13, s5
	global_load_dwordx4 v[218:221], v64, s[12:13]
	global_load_dwordx4 v[222:225], v64, s[12:13] offset:1024
	global_load_dwordx4 v[226:229], v64, s[12:13] offset:2048
	global_load_dwordx4 v[230:233], v64, s[12:13] offset:3072
	s_mov_b32 s3, s2
	s_add_i32 s2, s2, s4
.Lxc_loop:
	s_cmp_lt_i32 s2, 0x10000
	s_cbranch_scc0 .Lxc_a_nonext
	s_mov_b32 s10, s2
	s_mov_b32 s31, s10
	s_lshr_b32 s5, s31, 20
	s_lshl_b32 s31, s31, 12
	s_add_u32 s34, s6, s31
	s_addc_u32 s5, s7, s5
	s_mov_b32 s12, s34
	s_mov_b32 s13, s5
	global_load_dwordx4 v[4:7], v64, s[12:13]
	global_load_dwordx4 v[8:11], v64, s[12:13] offset:1024
	global_load_dwordx4 v[12:15], v64, s[12:13] offset:2048
	global_load_dwordx4 v[16:19], v64, s[12:13] offset:3072
	s_add_i32 s10, s10, s33
	s_mov_b32 s31, s10
	s_lshr_b32 s5, s31, 20
	s_lshl_b32 s31, s31, 12
	s_add_u32 s34, s6, s31
	s_addc_u32 s5, s7, s5
	s_mov_b32 s12, s34
	s_mov_b32 s13, s5
	global_load_dwordx4 v[20:23], v64, s[12:13]
	global_load_dwordx4 v[24:27], v64, s[12:13] offset:1024
	global_load_dwordx4 v[28:31], v64, s[12:13] offset:2048
	global_load_dwordx4 v[32:35], v64, s[12:13] offset:3072
	s_add_i32 s10, s10, s33
	s_mov_b32 s31, s10
	s_lshr_b32 s5, s31, 20
	s_lshl_b32 s31, s31, 12
	s_add_u32 s34, s6, s31
	s_addc_u32 s5, s7, s5
	s_mov_b32 s12, s34
	s_mov_b32 s13, s5
	global_load_dwordx4 v[36:39], v64, s[12:13]
	global_load_dwordx4 v[40:43], v64, s[12:13] offset:1024
	global_load_dwordx4 v[44:47], v64, s[12:13] offset:2048
	global_load_dwordx4 v[48:51], v64, s[12:13] offset:3072
	s_add_i32 s10, s10, s33
	s_mov_b32 s31, s10
	s_lshr_b32 s5, s31, 20
	s_lshl_b32 s31, s31, 12
	s_add_u32 s34, s6, s31
	s_addc_u32 s5, s7, s5
	s_mov_b32 s12, s34
	s_mov_b32 s13, s5
	global_load_dwordx4 v[52:55], v64, s[12:13]
	global_load_dwordx4 v[56:59], v64, s[12:13] offset:1024
	global_load_dwordx4 v[60:63], v64, s[12:13] offset:2048
	global_load_dwordx4 v[72:75], v64, s[12:13] offset:3072
	s_waitcnt vmcnt(16)
	s_branch .Lxc_a_proc

.Lxc_a_proc:
	v_mul_f32_e32 v118, v170, v170
	v_fmac_f32_e32 v118, v171, v171
	v_fmac_f32_e32 v118, v172, v172
	v_fmac_f32_e32 v118, v173, v173
	v_mul_f32_e32 v119, v174, v174
	v_fmac_f32_e32 v119, v175, v175
	v_fmac_f32_e32 v119, v176, v176
	v_fmac_f32_e32 v119, v177, v177
	v_mul_f32_e32 v120, v178, v178
	v_fmac_f32_e32 v120, v179, v179
	v_fmac_f32_e32 v120, v180, v180
	v_fmac_f32_e32 v120, v181, v181
	v_mul_f32_e32 v121, v182, v182
	v_fmac_f32_e32 v121, v183, v183
	v_fmac_f32_e32 v121, v184, v184
	v_fmac_f32_e32 v121, v185, v185
	v_mul_f32_e32 v122, v186, v186
	v_fmac_f32_e32 v122, v187, v187
	v_fmac_f32_e32 v122, v188, v188
	v_fmac_f32_e32 v122, v189, v189
	v_mul_f32_e32 v123, v190, v190
	v_fmac_f32_e32 v123, v191, v191
	v_fmac_f32_e32 v123, v192, v192
	v_fmac_f32_e32 v123, v193, v193
	v_mul_f32_e32 v124, v194, v194
	v_fmac_f32_e32 v124, v195, v195
	v_fmac_f32_e32 v124, v196, v196
	v_fmac_f32_e32 v124, v197, v197
	v_mul_f32_e32 v125, v198, v198
	v_fmac_f32_e32 v125, v199, v199
	v_fmac_f32_e32 v125, v200, v200
	v_fmac_f32_e32 v125, v201, v201
	v_mul_f32_e32 v126, v202, v202
	v_fmac_f32_e32 v126, v203, v203
	v_fmac_f32_e32 v126, v204, v204
	v_fmac_f32_e32 v126, v205, v205
	v_mul_f32_e32 v127, v206, v206
	v_fmac_f32_e32 v127, v207, v207
	v_fmac_f32_e32 v127, v208, v208
	v_fmac_f32_e32 v127, v209, v209
	v_mul_f32_e32 v128, v210, v210
	v_fmac_f32_e32 v128, v211, v211
	v_fmac_f32_e32 v128, v212, v212
	v_fmac_f32_e32 v128, v213, v213
	v_mul_f32_e32 v129, v214, v214
	v_fmac_f32_e32 v129, v215, v215
	v_fmac_f32_e32 v129, v216, v216
	v_fmac_f32_e32 v129, v217, v217
	v_mul_f32_e32 v130, v218, v218
	v_fmac_f32_e32 v130, v219, v219
	v_fmac_f32_e32 v130, v220, v220
	v_fmac_f32_e32 v130, v221, v221
	v_mul_f32_e32 v131, v222, v222
	v_fmac_f32_e32 v131, v223, v223
	v_fmac_f32_e32 v131, v224, v224
	v_fmac_f32_e32 v131, v225, v225
	v_mul_f32_e32 v132, v226, v226
	v_fmac_f32_e32 v132, v227, v227
	v_fmac_f32_e32 v132, v228, v228
	v_fmac_f32_e32 v132, v229, v229
	v_mul_f32_e32 v133, v230, v230
	v_fmac_f32_e32 v133, v231, v231
	v_fmac_f32_e32 v133, v232, v232
	v_fmac_f32_e32 v133, v233, v233
	v_add_f32_e32 v118, v118, v119
	v_add_f32_e32 v120, v120, v121
	v_add_f32_e32 v122, v122, v123
	v_add_f32_e32 v124, v124, v125
	v_add_f32_e32 v126, v126, v127
	v_add_f32_e32 v128, v128, v129
	v_add_f32_e32 v130, v130, v131
	v_add_f32_e32 v132, v132, v133
	v_add_f32_e32 v134, v118, v120
	v_add_f32_e32 v135, v122, v124
	v_add_f32_e32 v136, v126, v128
	v_add_f32_e32 v137, v130, v132
	s_nop 1
	v_add_f32_dpp v134, v134, v134 quad_perm:[1,0,3,2] row_mask:0xf bank_mask:0xf
	v_add_f32_dpp v135, v135, v135 quad_perm:[1,0,3,2] row_mask:0xf bank_mask:0xf
	v_add_f32_dpp v136, v136, v136 quad_perm:[1,0,3,2] row_mask:0xf bank_mask:0xf
	v_add_f32_dpp v137, v137, v137 quad_perm:[1,0,3,2] row_mask:0xf bank_mask:0xf
	v_add_f32_dpp v134, v134, v134 quad_perm:[2,3,0,1] row_mask:0xf bank_mask:0xf
	v_add_f32_dpp v135, v135, v135 quad_perm:[2,3,0,1] row_mask:0xf bank_mask:0xf
	v_add_f32_dpp v136, v136, v136 quad_perm:[2,3,0,1] row_mask:0xf bank_mask:0xf
	v_add_f32_dpp v137, v137, v137 quad_perm:[2,3,0,1] row_mask:0xf bank_mask:0xf
	v_add_f32_dpp v134, v134, v134 row_half_mirror row_mask:0xf bank_mask:0xf
	v_add_f32_dpp v135, v135, v135 row_half_mirror row_mask:0xf bank_mask:0xf
	v_add_f32_dpp v136, v136, v136 row_half_mirror row_mask:0xf bank_mask:0xf
	v_add_f32_dpp v137, v137, v137 row_half_mirror row_mask:0xf bank_mask:0xf
	v_add_f32_dpp v134, v134, v134 row_mirror row_mask:0xf bank_mask:0xf
	v_add_f32_dpp v135, v135, v135 row_mirror row_mask:0xf bank_mask:0xf
	v_add_f32_dpp v136, v136, v136 row_mirror row_mask:0xf bank_mask:0xf
	v_add_f32_dpp v137, v137, v137 row_mirror row_mask:0xf bank_mask:0xf
	s_nop 1
	v_readlane_b32 s12, v134, 0
	v_readlane_b32 s13, v134, 16
	v_readlane_b32 s14, v134, 32
	v_readlane_b32 s15, v134, 48
	v_readlane_b32 s16, v135, 0
	v_readlane_b32 s17, v135, 16
	v_readlane_b32 s18, v135, 32
	v_readlane_b32 s19, v135, 48
	v_readlane_b32 s20, v136, 0
	v_readlane_b32 s21, v136, 16
	v_readlane_b32 s22, v136, 32
	v_readlane_b32 s23, v136, 48
	v_readlane_b32 s24, v137, 0
	v_readlane_b32 s25, v137, 16
	v_readlane_b32 s26, v137, 32
	v_readlane_b32 s27, v137, 48
	s_nop 1
	v_mov_b32_e32 v138, s12
	v_mov_b32_e32 v139, s16
	v_mov_b32_e32 v140, s20
	v_mov_b32_e32 v141, s24
	v_add_f32_e32 v138, s13, v138
	v_add_f32_e32 v139, s17, v139
	v_add_f32_e32 v140, s21, v140
	v_add_f32_e32 v141, s25, v141
	v_add_f32_e32 v138, s14, v138
	v_add_f32_e32 v139, s18, v139
	v_add_f32_e32 v140, s22, v140
	v_add_f32_e32 v141, s26, v141
	v_add_f32_e32 v138, s15, v138
	v_add_f32_e32 v139, s19, v139
	v_add_f32_e32 v140, s23, v140
	v_add_f32_e32 v141, s27, v141
	v_fmamk_f32 v138, v138, 0x3a800000, v65
	v_mul_f32_e32 v142, 0x4f800000, v138
	v_cmp_gt_f32_e32 vcc, s30, v138
	s_nop 1
	v_cndmask_b32_e32 v138, v138, v142, vcc
	v_sqrt_f32_e32 v142, v138
	s_nop 0
	v_add_u32_e32 v143, -1, v142
	v_fma_f32 v145, -v143, v142, v138
	v_add_u32_e32 v144, 1, v142
	v_cmp_ge_f32_e64 s[28:29], 0, v145
	s_nop 1
	v_cndmask_b32_e64 v143, v142, v143, s[28:29]
	v_fma_f32 v142, -v144, v142, v138
	v_cmp_lt_f32_e64 s[28:29], 0, v142
	s_nop 1
	v_cndmask_b32_e64 v142, v143, v144, s[28:29]
	v_mul_f32_e32 v143, 0x37800000, v142
	v_cndmask_b32_e32 v142, v142, v143, vcc
	v_cmp_class_f32_e32 vcc, v138, v67
	s_nop 1
	v_cndmask_b32_e32 v138, v142, v138, vcc
	v_div_scale_f32 v142, s[28:29], v138, v138, 1.0
	v_rcp_f32_e32 v143, v142
	s_nop 0
	v_fma_f32 v144, -v142, v143, 1.0
	v_fmac_f32_e32 v143, v144, v143
	v_div_scale_f32 v144, vcc, 1.0, v138, 1.0
	v_mul_f32_e32 v145, v144, v143
	v_fma_f32 v146, -v142, v145, v144
	v_fmac_f32_e32 v145, v146, v143
	v_fma_f32 v142, -v142, v145, v144
	v_div_fmas_f32 v142, v142, v143, v145
	v_div_fixup_f32 v138, v142, v138, 1.0
	v_fmamk_f32 v139, v139, 0x3a800000, v65
	v_mul_f32_e32 v142, 0x4f800000, v139
	v_cmp_gt_f32_e32 vcc, s30, v139
	s_nop 1
	v_cndmask_b32_e32 v139, v139, v142, vcc
	v_sqrt_f32_e32 v142, v139
	s_nop 0
	v_add_u32_e32 v143, -1, v142
	v_fma_f32 v145, -v143, v142, v139
	v_add_u32_e32 v144, 1, v142
	v_cmp_ge_f32_e64 s[28:29], 0, v145
	s_nop 1
	v_cndmask_b32_e64 v143, v142, v143, s[28:29]
	v_fma_f32 v142, -v144, v142, v139
	v_cmp_lt_f32_e64 s[28:29], 0, v142
	s_nop 1
	v_cndmask_b32_e64 v142, v143, v144, s[28:29]
	v_mul_f32_e32 v143, 0x37800000, v142
	v_cndmask_b32_e32 v142, v142, v143, vcc
	v_cmp_class_f32_e32 vcc, v139, v67
	s_nop 1
	v_cndmask_b32_e32 v139, v142, v139, vcc
	v_div_scale_f32 v142, s[28:29], v139, v139, 1.0
	v_rcp_f32_e32 v143, v142
	s_nop 0
	v_fma_f32 v144, -v142, v143, 1.0
	v_fmac_f32_e32 v143, v144, v143
	v_div_scale_f32 v144, vcc, 1.0, v139, 1.0
	v_mul_f32_e32 v145, v144, v143
	v_fma_f32 v146, -v142, v145, v144
	v_fmac_f32_e32 v145, v146, v143
	v_fma_f32 v142, -v142, v145, v144
	v_div_fmas_f32 v142, v142, v143, v145
	v_div_fixup_f32 v139, v142, v139, 1.0
	v_fmamk_f32 v140, v140, 0x3a800000, v65
	v_mul_f32_e32 v142, 0x4f800000, v140
	v_cmp_gt_f32_e32 vcc, s30, v140
	s_nop 1
	v_cndmask_b32_e32 v140, v140, v142, vcc
	v_sqrt_f32_e32 v142, v140
	s_nop 0
	v_add_u32_e32 v143, -1, v142
	v_fma_f32 v145, -v143, v142, v140
	v_add_u32_e32 v144, 1, v142
	v_cmp_ge_f32_e64 s[28:29], 0, v145
	s_nop 1
	v_cndmask_b32_e64 v143, v142, v143, s[28:29]
	v_fma_f32 v142, -v144, v142, v140
	v_cmp_lt_f32_e64 s[28:29], 0, v142
	s_nop 1
	v_cndmask_b32_e64 v142, v143, v144, s[28:29]
	v_mul_f32_e32 v143, 0x37800000, v142
	v_cndmask_b32_e32 v142, v142, v143, vcc
	v_cmp_class_f32_e32 vcc, v140, v67
	s_nop 1
	v_cndmask_b32_e32 v140, v142, v140, vcc
	v_div_scale_f32 v142, s[28:29], v140, v140, 1.0
	v_rcp_f32_e32 v143, v142
	s_nop 0
	v_fma_f32 v144, -v142, v143, 1.0
	v_fmac_f32_e32 v143, v144, v143
	v_div_scale_f32 v144, vcc, 1.0, v140, 1.0
	v_mul_f32_e32 v145, v144, v143
	v_fma_f32 v146, -v142, v145, v144
	v_fmac_f32_e32 v145, v146, v143
	v_fma_f32 v142, -v142, v145, v144
	v_div_fmas_f32 v142, v142, v143, v145
	v_div_fixup_f32 v140, v142, v140, 1.0
	v_fmamk_f32 v141, v141, 0x3a800000, v65
	v_mul_f32_e32 v142, 0x4f800000, v141
	v_cmp_gt_f32_e32 vcc, s30, v141
	s_nop 1
	v_cndmask_b32_e32 v141, v141, v142, vcc
	v_sqrt_f32_e32 v142, v141
	s_nop 0
	v_add_u32_e32 v143, -1, v142
	v_fma_f32 v145, -v143, v142, v141
	v_add_u32_e32 v144, 1, v142
	v_cmp_ge_f32_e64 s[28:29], 0, v145
	s_nop 1
	v_cndmask_b32_e64 v143, v142, v143, s[28:29]
	v_fma_f32 v142, -v144, v142, v141
	v_cmp_lt_f32_e64 s[28:29], 0, v142
	s_nop 1
	v_cndmask_b32_e64 v142, v143, v144, s[28:29]
	v_mul_f32_e32 v143, 0x37800000, v142
	v_cndmask_b32_e32 v142, v142, v143, vcc
	v_cmp_class_f32_e32 vcc, v141, v67
	s_nop 1
	v_cndmask_b32_e32 v141, v142, v141, vcc
	v_div_scale_f32 v142, s[28:29], v141, v141, 1.0
	v_rcp_f32_e32 v143, v142
	s_nop 0
	v_fma_f32 v144, -v142, v143, 1.0
	v_fmac_f32_e32 v143, v144, v143
	v_div_scale_f32 v144, vcc, 1.0, v141, 1.0
	v_mul_f32_e32 v145, v144, v143
	v_fma_f32 v146, -v142, v145, v144
	v_fmac_f32_e32 v145, v146, v143
	v_fma_f32 v142, -v142, v145, v144
	v_div_fmas_f32 v142, v142, v143, v145
	v_div_fixup_f32 v141, v142, v141, 1.0
	s_mov_b64 s[28:29], exec
	s_mov_b64 exec, 1
	s_mov_b32 s10, s3
	s_lshl_b32 s31, s10, 2
	s_add_u32 s12, s0, s31
	s_addc_u32 s13, s1, 0
	global_store_dword v3, v138, s[12:13]
	s_add_i32 s10, s10, s33
	s_lshl_b32 s31, s10, 2
	s_add_u32 s12, s0, s31
	s_addc_u32 s13, s1, 0
	global_store_dword v3, v139, s[12:13]
	s_add_i32 s10, s10, s33
	s_lshl_b32 s31, s10, 2
	s_add_u32 s12, s0, s31
	s_addc_u32 s13, s1, 0
	global_store_dword v3, v140, s[12:13]
	s_add_i32 s10, s10, s33
	s_lshl_b32 s31, s10, 2
	s_add_u32 s12, s0, s31
	s_addc_u32 s13, s1, 0
	global_store_dword v3, v141, s[12:13]
	s_mov_b64 exec, s[28:29]
	s_mov_b32 s10, s3
	s_lshr_b32 s5, s10, 21
	s_lshl_b32 s31, s10, 11
	s_add_u32 s12, s8, s31
	s_addc_u32 s13, s9, s5
	v_cvt_pk_bf16_f32 v170, v170, v171
	v_cvt_pk_bf16_f32 v171, v172, v173
	v_cvt_pk_bf16_f32 v174, v174, v175
	v_cvt_pk_bf16_f32 v175, v176, v177
	v_cvt_pk_bf16_f32 v178, v178, v179
	v_cvt_pk_bf16_f32 v179, v180, v181
	v_cvt_pk_bf16_f32 v182, v182, v183
	v_cvt_pk_bf16_f32 v183, v184, v185
	global_store_dwordx2 v2, v[170:171], s[12:13]
	global_store_dwordx2 v2, v[174:175], s[12:13] offset:512
	global_store_dwordx2 v2, v[178:179], s[12:13] offset:1024
	global_store_dwordx2 v2, v[182:183], s[12:13] offset:1536
	s_add_i32 s10, s10, s33
	s_lshr_b32 s5, s10, 21
	s_lshl_b32 s31, s10, 11
	s_add_u32 s12, s8, s31
	s_addc_u32 s13, s9, s5
	v_cvt_pk_bf16_f32 v186, v186, v187
	v_cvt_pk_bf16_f32 v187, v188, v189
	v_cvt_pk_bf16_f32 v190, v190, v191
	v_cvt_pk_bf16_f32 v191, v192, v193
	v_cvt_pk_bf16_f32 v194, v194, v195
	v_cvt_pk_bf16_f32 v195, v196, v197
	v_cvt_pk_bf16_f32 v198, v198, v199
	v_cvt_pk_bf16_f32 v199, v200, v201
	global_store_dwordx2 v2, v[186:187], s[12:13]
	global_store_dwordx2 v2, v[190:191], s[12:13] offset:512
	global_store_dwordx2 v2, v[194:195], s[12:13] offset:1024
	global_store_dwordx2 v2, v[198:199], s[12:13] offset:1536
	s_add_i32 s10, s10, s33
	s_lshr_b32 s5, s10, 21
	s_lshl_b32 s31, s10, 11
	s_add_u32 s12, s8, s31
	s_addc_u32 s13, s9, s5
	v_cvt_pk_bf16_f32 v202, v202, v203
	v_cvt_pk_bf16_f32 v203, v204, v205
	v_cvt_pk_bf16_f32 v206, v206, v207
	v_cvt_pk_bf16_f32 v207, v208, v209
	v_cvt_pk_bf16_f32 v210, v210, v211
	v_cvt_pk_bf16_f32 v211, v212, v213
	v_cvt_pk_bf16_f32 v214, v214, v215
	v_cvt_pk_bf16_f32 v215, v216, v217
	global_store_dwordx2 v2, v[202:203], s[12:13]
	global_store_dwordx2 v2, v[206:207], s[12:13] offset:512
	global_store_dwordx2 v2, v[210:211], s[12:13] offset:1024
	global_store_dwordx2 v2, v[214:215], s[12:13] offset:1536
	s_add_i32 s10, s10, s33
	s_lshr_b32 s5, s10, 21
	s_lshl_b32 s31, s10, 11
	s_add_u32 s12, s8, s31
	s_addc_u32 s13, s9, s5
	v_cvt_pk_bf16_f32 v218, v218, v219
	v_cvt_pk_bf16_f32 v219, v220, v221
	v_cvt_pk_bf16_f32 v222, v222, v223
	v_cvt_pk_bf16_f32 v223, v224, v225
	v_cvt_pk_bf16_f32 v226, v226, v227
	v_cvt_pk_bf16_f32 v227, v228, v229
	v_cvt_pk_bf16_f32 v230, v230, v231
	v_cvt_pk_bf16_f32 v231, v232, v233
	global_store_dwordx2 v2, v[218:219], s[12:13]
	global_store_dwordx2 v2, v[222:223], s[12:13] offset:512
	global_store_dwordx2 v2, v[226:227], s[12:13] offset:1024
	global_store_dwordx2 v2, v[230:231], s[12:13] offset:1536
	s_cmp_lt_i32 s2, 0x10000
	s_cbranch_scc0 .LBB0_135
	s_mov_b32 s3, s2
	s_add_i32 s2, s2, s4
	s_cmp_lt_i32 s2, 0x10000
	s_cbranch_scc0 .Lxc_b_nonext
	s_mov_b32 s10, s2
	s_mov_b32 s31, s10
	s_lshr_b32 s5, s31, 20
	s_lshl_b32 s31, s31, 12
	s_add_u32 s34, s6, s31
	s_addc_u32 s5, s7, s5
	s_mov_b32 s12, s34
	s_mov_b32 s13, s5
	global_load_dwordx4 v[170:173], v64, s[12:13]
	global_load_dwordx4 v[174:177], v64, s[12:13] offset:1024
	global_load_dwordx4 v[178:181], v64, s[12:13] offset:2048
	global_load_dwordx4 v[182:185], v64, s[12:13] offset:3072
	s_add_i32 s10, s10, s33
	s_mov_b32 s31, s10
	s_lshr_b32 s5, s31, 20
	s_lshl_b32 s31, s31, 12
	s_add_u32 s34, s6, s31
	s_addc_u32 s5, s7, s5
	s_mov_b32 s12, s34
	s_mov_b32 s13, s5
	global_load_dwordx4 v[186:189], v64, s[12:13]
	global_load_dwordx4 v[190:193], v64, s[12:13] offset:1024
	global_load_dwordx4 v[194:197], v64, s[12:13] offset:2048
	global_load_dwordx4 v[198:201], v64, s[12:13] offset:3072
	s_add_i32 s10, s10, s33
	s_mov_b32 s31, s10
	s_lshr_b32 s5, s31, 20
	s_lshl_b32 s31, s31, 12
	s_add_u32 s34, s6, s31
	s_addc_u32 s5, s7, s5
	s_mov_b32 s12, s34
	s_mov_b32 s13, s5
	global_load_dwordx4 v[202:205], v64, s[12:13]
	global_load_dwordx4 v[206:209], v64, s[12:13] offset:1024
	global_load_dwordx4 v[210:213], v64, s[12:13] offset:2048
	global_load_dwordx4 v[214:217], v64, s[12:13] offset:3072
	s_add_i32 s10, s10, s33
	s_mov_b32 s31, s10
	s_lshr_b32 s5, s31, 20
	s_lshl_b32 s31, s31, 12
	s_add_u32 s34, s6, s31
	s_addc_u32 s5, s7, s5
	s_mov_b32 s12, s34
	s_mov_b32 s13, s5
	global_load_dwordx4 v[218:221], v64, s[12:13]
	global_load_dwordx4 v[222:225], v64, s[12:13] offset:1024
	global_load_dwordx4 v[226:229], v64, s[12:13] offset:2048
	global_load_dwordx4 v[230:233], v64, s[12:13] offset:3072
	s_waitcnt vmcnt(16)
	s_branch .Lxc_b_proc

.Lxc_b_proc:
	v_mul_f32_e32 v118, v4, v4
	v_fmac_f32_e32 v118, v5, v5
	v_fmac_f32_e32 v118, v6, v6
	v_fmac_f32_e32 v118, v7, v7
	v_mul_f32_e32 v119, v8, v8
	v_fmac_f32_e32 v119, v9, v9
	v_fmac_f32_e32 v119, v10, v10
	v_fmac_f32_e32 v119, v11, v11
	v_mul_f32_e32 v120, v12, v12
	v_fmac_f32_e32 v120, v13, v13
	v_fmac_f32_e32 v120, v14, v14
	v_fmac_f32_e32 v120, v15, v15
	v_mul_f32_e32 v121, v16, v16
	v_fmac_f32_e32 v121, v17, v17
	v_fmac_f32_e32 v121, v18, v18
	v_fmac_f32_e32 v121, v19, v19
	v_mul_f32_e32 v122, v20, v20
	v_fmac_f32_e32 v122, v21, v21
	v_fmac_f32_e32 v122, v22, v22
	v_fmac_f32_e32 v122, v23, v23
	v_mul_f32_e32 v123, v24, v24
	v_fmac_f32_e32 v123, v25, v25
	v_fmac_f32_e32 v123, v26, v26
	v_fmac_f32_e32 v123, v27, v27
	v_mul_f32_e32 v124, v28, v28
	v_fmac_f32_e32 v124, v29, v29
	v_fmac_f32_e32 v124, v30, v30
	v_fmac_f32_e32 v124, v31, v31
	v_mul_f32_e32 v125, v32, v32
	v_fmac_f32_e32 v125, v33, v33
	v_fmac_f32_e32 v125, v34, v34
	v_fmac_f32_e32 v125, v35, v35
	v_mul_f32_e32 v126, v36, v36
	v_fmac_f32_e32 v126, v37, v37
	v_fmac_f32_e32 v126, v38, v38
	v_fmac_f32_e32 v126, v39, v39
	v_mul_f32_e32 v127, v40, v40
	v_fmac_f32_e32 v127, v41, v41
	v_fmac_f32_e32 v127, v42, v42
	v_fmac_f32_e32 v127, v43, v43
	v_mul_f32_e32 v128, v44, v44
	v_fmac_f32_e32 v128, v45, v45
	v_fmac_f32_e32 v128, v46, v46
	v_fmac_f32_e32 v128, v47, v47
	v_mul_f32_e32 v129, v48, v48
	v_fmac_f32_e32 v129, v49, v49
	v_fmac_f32_e32 v129, v50, v50
	v_fmac_f32_e32 v129, v51, v51
	v_mul_f32_e32 v130, v52, v52
	v_fmac_f32_e32 v130, v53, v53
	v_fmac_f32_e32 v130, v54, v54
	v_fmac_f32_e32 v130, v55, v55
	v_mul_f32_e32 v131, v56, v56
	v_fmac_f32_e32 v131, v57, v57
	v_fmac_f32_e32 v131, v58, v58
	v_fmac_f32_e32 v131, v59, v59
	v_mul_f32_e32 v132, v60, v60
	v_fmac_f32_e32 v132, v61, v61
	v_fmac_f32_e32 v132, v62, v62
	v_fmac_f32_e32 v132, v63, v63
	v_mul_f32_e32 v133, v72, v72
	v_fmac_f32_e32 v133, v73, v73
	v_fmac_f32_e32 v133, v74, v74
	v_fmac_f32_e32 v133, v75, v75
	v_add_f32_e32 v118, v118, v119
	v_add_f32_e32 v120, v120, v121
	v_add_f32_e32 v122, v122, v123
	v_add_f32_e32 v124, v124, v125
	v_add_f32_e32 v126, v126, v127
	v_add_f32_e32 v128, v128, v129
	v_add_f32_e32 v130, v130, v131
	v_add_f32_e32 v132, v132, v133
	v_add_f32_e32 v134, v118, v120
	v_add_f32_e32 v135, v122, v124
	v_add_f32_e32 v136, v126, v128
	v_add_f32_e32 v137, v130, v132
	s_nop 1
	v_add_f32_dpp v134, v134, v134 quad_perm:[1,0,3,2] row_mask:0xf bank_mask:0xf
	v_add_f32_dpp v135, v135, v135 quad_perm:[1,0,3,2] row_mask:0xf bank_mask:0xf
	v_add_f32_dpp v136, v136, v136 quad_perm:[1,0,3,2] row_mask:0xf bank_mask:0xf
	v_add_f32_dpp v137, v137, v137 quad_perm:[1,0,3,2] row_mask:0xf bank_mask:0xf
	v_add_f32_dpp v134, v134, v134 quad_perm:[2,3,0,1] row_mask:0xf bank_mask:0xf
	v_add_f32_dpp v135, v135, v135 quad_perm:[2,3,0,1] row_mask:0xf bank_mask:0xf
	v_add_f32_dpp v136, v136, v136 quad_perm:[2,3,0,1] row_mask:0xf bank_mask:0xf
	v_add_f32_dpp v137, v137, v137 quad_perm:[2,3,0,1] row_mask:0xf bank_mask:0xf
	v_add_f32_dpp v134, v134, v134 row_half_mirror row_mask:0xf bank_mask:0xf
	v_add_f32_dpp v135, v135, v135 row_half_mirror row_mask:0xf bank_mask:0xf
	v_add_f32_dpp v136, v136, v136 row_half_mirror row_mask:0xf bank_mask:0xf
	v_add_f32_dpp v137, v137, v137 row_half_mirror row_mask:0xf bank_mask:0xf
	v_add_f32_dpp v134, v134, v134 row_mirror row_mask:0xf bank_mask:0xf
	v_add_f32_dpp v135, v135, v135 row_mirror row_mask:0xf bank_mask:0xf
	v_add_f32_dpp v136, v136, v136 row_mirror row_mask:0xf bank_mask:0xf
	v_add_f32_dpp v137, v137, v137 row_mirror row_mask:0xf bank_mask:0xf
	s_nop 1
	v_readlane_b32 s12, v134, 0
	v_readlane_b32 s13, v134, 16
	v_readlane_b32 s14, v134, 32
	v_readlane_b32 s15, v134, 48
	v_readlane_b32 s16, v135, 0
	v_readlane_b32 s17, v135, 16
	v_readlane_b32 s18, v135, 32
	v_readlane_b32 s19, v135, 48
	v_readlane_b32 s20, v136, 0
	v_readlane_b32 s21, v136, 16
	v_readlane_b32 s22, v136, 32
	v_readlane_b32 s23, v136, 48
	v_readlane_b32 s24, v137, 0
	v_readlane_b32 s25, v137, 16
	v_readlane_b32 s26, v137, 32
	v_readlane_b32 s27, v137, 48
	s_nop 1
	v_mov_b32_e32 v138, s12
	v_mov_b32_e32 v139, s16
	v_mov_b32_e32 v140, s20
	v_mov_b32_e32 v141, s24
	v_add_f32_e32 v138, s13, v138
	v_add_f32_e32 v139, s17, v139
	v_add_f32_e32 v140, s21, v140
	v_add_f32_e32 v141, s25, v141
	v_add_f32_e32 v138, s14, v138
	v_add_f32_e32 v139, s18, v139
	v_add_f32_e32 v140, s22, v140
	v_add_f32_e32 v141, s26, v141
	v_add_f32_e32 v138, s15, v138
	v_add_f32_e32 v139, s19, v139
	v_add_f32_e32 v140, s23, v140
	v_add_f32_e32 v141, s27, v141
	v_fmamk_f32 v138, v138, 0x3a800000, v65
	v_mul_f32_e32 v142, 0x4f800000, v138
	v_cmp_gt_f32_e32 vcc, s30, v138
	s_nop 1
	v_cndmask_b32_e32 v138, v138, v142, vcc
	v_sqrt_f32_e32 v142, v138
	s_nop 0
	v_add_u32_e32 v143, -1, v142
	v_fma_f32 v145, -v143, v142, v138
	v_add_u32_e32 v144, 1, v142
	v_cmp_ge_f32_e64 s[28:29], 0, v145
	s_nop 1
	v_cndmask_b32_e64 v143, v142, v143, s[28:29]
	v_fma_f32 v142, -v144, v142, v138
	v_cmp_lt_f32_e64 s[28:29], 0, v142
	s_nop 1
	v_cndmask_b32_e64 v142, v143, v144, s[28:29]
	v_mul_f32_e32 v143, 0x37800000, v142
	v_cndmask_b32_e32 v142, v142, v143, vcc
	v_cmp_class_f32_e32 vcc, v138, v67
	s_nop 1
	v_cndmask_b32_e32 v138, v142, v138, vcc
	v_div_scale_f32 v142, s[28:29], v138, v138, 1.0
	v_rcp_f32_e32 v143, v142
	s_nop 0
	v_fma_f32 v144, -v142, v143, 1.0
	v_fmac_f32_e32 v143, v144, v143
	v_div_scale_f32 v144, vcc, 1.0, v138, 1.0
	v_mul_f32_e32 v145, v144, v143
	v_fma_f32 v146, -v142, v145, v144
	v_fmac_f32_e32 v145, v146, v143
	v_fma_f32 v142, -v142, v145, v144
	v_div_fmas_f32 v142, v142, v143, v145
	v_div_fixup_f32 v138, v142, v138, 1.0
	v_fmamk_f32 v139, v139, 0x3a800000, v65
	v_mul_f32_e32 v142, 0x4f800000, v139
	v_cmp_gt_f32_e32 vcc, s30, v139
	s_nop 1
	v_cndmask_b32_e32 v139, v139, v142, vcc
	v_sqrt_f32_e32 v142, v139
	s_nop 0
	v_add_u32_e32 v143, -1, v142
	v_fma_f32 v145, -v143, v142, v139
	v_add_u32_e32 v144, 1, v142
	v_cmp_ge_f32_e64 s[28:29], 0, v145
	s_nop 1
	v_cndmask_b32_e64 v143, v142, v143, s[28:29]
	v_fma_f32 v142, -v144, v142, v139
	v_cmp_lt_f32_e64 s[28:29], 0, v142
	s_nop 1
	v_cndmask_b32_e64 v142, v143, v144, s[28:29]
	v_mul_f32_e32 v143, 0x37800000, v142
	v_cndmask_b32_e32 v142, v142, v143, vcc
	v_cmp_class_f32_e32 vcc, v139, v67
	s_nop 1
	v_cndmask_b32_e32 v139, v142, v139, vcc
	v_div_scale_f32 v142, s[28:29], v139, v139, 1.0
	v_rcp_f32_e32 v143, v142
	s_nop 0
	v_fma_f32 v144, -v142, v143, 1.0
	v_fmac_f32_e32 v143, v144, v143
	v_div_scale_f32 v144, vcc, 1.0, v139, 1.0
	v_mul_f32_e32 v145, v144, v143
	v_fma_f32 v146, -v142, v145, v144
	v_fmac_f32_e32 v145, v146, v143
	v_fma_f32 v142, -v142, v145, v144
	v_div_fmas_f32 v142, v142, v143, v145
	v_div_fixup_f32 v139, v142, v139, 1.0
	v_fmamk_f32 v140, v140, 0x3a800000, v65
	v_mul_f32_e32 v142, 0x4f800000, v140
	v_cmp_gt_f32_e32 vcc, s30, v140
	s_nop 1
	v_cndmask_b32_e32 v140, v140, v142, vcc
	v_sqrt_f32_e32 v142, v140
	s_nop 0
	v_add_u32_e32 v143, -1, v142
	v_fma_f32 v145, -v143, v142, v140
	v_add_u32_e32 v144, 1, v142
	v_cmp_ge_f32_e64 s[28:29], 0, v145
	s_nop 1
	v_cndmask_b32_e64 v143, v142, v143, s[28:29]
	v_fma_f32 v142, -v144, v142, v140
	v_cmp_lt_f32_e64 s[28:29], 0, v142
	s_nop 1
	v_cndmask_b32_e64 v142, v143, v144, s[28:29]
	v_mul_f32_e32 v143, 0x37800000, v142
	v_cndmask_b32_e32 v142, v142, v143, vcc
	v_cmp_class_f32_e32 vcc, v140, v67
	s_nop 1
	v_cndmask_b32_e32 v140, v142, v140, vcc
	v_div_scale_f32 v142, s[28:29], v140, v140, 1.0
	v_rcp_f32_e32 v143, v142
	s_nop 0
	v_fma_f32 v144, -v142, v143, 1.0
	v_fmac_f32_e32 v143, v144, v143
	v_div_scale_f32 v144, vcc, 1.0, v140, 1.0
	v_mul_f32_e32 v145, v144, v143
	v_fma_f32 v146, -v142, v145, v144
	v_fmac_f32_e32 v145, v146, v143
	v_fma_f32 v142, -v142, v145, v144
	v_div_fmas_f32 v142, v142, v143, v145
	v_div_fixup_f32 v140, v142, v140, 1.0
	v_fmamk_f32 v141, v141, 0x3a800000, v65
	v_mul_f32_e32 v142, 0x4f800000, v141
	v_cmp_gt_f32_e32 vcc, s30, v141
	s_nop 1
	v_cndmask_b32_e32 v141, v141, v142, vcc
	v_sqrt_f32_e32 v142, v141
	s_nop 0
	v_add_u32_e32 v143, -1, v142
	v_fma_f32 v145, -v143, v142, v141
	v_add_u32_e32 v144, 1, v142
	v_cmp_ge_f32_e64 s[28:29], 0, v145
	s_nop 1
	v_cndmask_b32_e64 v143, v142, v143, s[28:29]
	v_fma_f32 v142, -v144, v142, v141
	v_cmp_lt_f32_e64 s[28:29], 0, v142
	s_nop 1
	v_cndmask_b32_e64 v142, v143, v144, s[28:29]
	v_mul_f32_e32 v143, 0x37800000, v142
	v_cndmask_b32_e32 v142, v142, v143, vcc
	v_cmp_class_f32_e32 vcc, v141, v67
	s_nop 1
	v_cndmask_b32_e32 v141, v142, v141, vcc
	v_div_scale_f32 v142, s[28:29], v141, v141, 1.0
	v_rcp_f32_e32 v143, v142
	s_nop 0
	v_fma_f32 v144, -v142, v143, 1.0
	v_fmac_f32_e32 v143, v144, v143
	v_div_scale_f32 v144, vcc, 1.0, v141, 1.0
	v_mul_f32_e32 v145, v144, v143
	v_fma_f32 v146, -v142, v145, v144
	v_fmac_f32_e32 v145, v146, v143
	v_fma_f32 v142, -v142, v145, v144
	v_div_fmas_f32 v142, v142, v143, v145
	v_div_fixup_f32 v141, v142, v141, 1.0
	s_mov_b64 s[28:29], exec
	s_mov_b64 exec, 1
	s_mov_b32 s10, s3
	s_lshl_b32 s31, s10, 2
	s_add_u32 s12, s0, s31
	s_addc_u32 s13, s1, 0
	global_store_dword v3, v138, s[12:13]
	s_add_i32 s10, s10, s33
	s_lshl_b32 s31, s10, 2
	s_add_u32 s12, s0, s31
	s_addc_u32 s13, s1, 0
	global_store_dword v3, v139, s[12:13]
	s_add_i32 s10, s10, s33
	s_lshl_b32 s31, s10, 2
	s_add_u32 s12, s0, s31
	s_addc_u32 s13, s1, 0
	global_store_dword v3, v140, s[12:13]
	s_add_i32 s10, s10, s33
	s_lshl_b32 s31, s10, 2
	s_add_u32 s12, s0, s31
	s_addc_u32 s13, s1, 0
	global_store_dword v3, v141, s[12:13]
	s_mov_b64 exec, s[28:29]
	s_mov_b32 s10, s3
	s_lshr_b32 s5, s10, 21
	s_lshl_b32 s31, s10, 11
	s_add_u32 s12, s8, s31
	s_addc_u32 s13, s9, s5
	v_cvt_pk_bf16_f32 v4, v4, v5
	v_cvt_pk_bf16_f32 v5, v6, v7
	v_cvt_pk_bf16_f32 v8, v8, v9
	v_cvt_pk_bf16_f32 v9, v10, v11
	v_cvt_pk_bf16_f32 v12, v12, v13
	v_cvt_pk_bf16_f32 v13, v14, v15
	v_cvt_pk_bf16_f32 v16, v16, v17
	v_cvt_pk_bf16_f32 v17, v18, v19
	global_store_dwordx2 v2, v[4:5], s[12:13]
	global_store_dwordx2 v2, v[8:9], s[12:13] offset:512
	global_store_dwordx2 v2, v[12:13], s[12:13] offset:1024
	global_store_dwordx2 v2, v[16:17], s[12:13] offset:1536
	s_add_i32 s10, s10, s33
	s_lshr_b32 s5, s10, 21
	s_lshl_b32 s31, s10, 11
	s_add_u32 s12, s8, s31
	s_addc_u32 s13, s9, s5
	v_cvt_pk_bf16_f32 v20, v20, v21
	v_cvt_pk_bf16_f32 v21, v22, v23
	v_cvt_pk_bf16_f32 v24, v24, v25
	v_cvt_pk_bf16_f32 v25, v26, v27
	v_cvt_pk_bf16_f32 v28, v28, v29
	v_cvt_pk_bf16_f32 v29, v30, v31
	v_cvt_pk_bf16_f32 v32, v32, v33
	v_cvt_pk_bf16_f32 v33, v34, v35
	global_store_dwordx2 v2, v[20:21], s[12:13]
	global_store_dwordx2 v2, v[24:25], s[12:13] offset:512
	global_store_dwordx2 v2, v[28:29], s[12:13] offset:1024
	global_store_dwordx2 v2, v[32:33], s[12:13] offset:1536
	s_add_i32 s10, s10, s33
	s_lshr_b32 s5, s10, 21
	s_lshl_b32 s31, s10, 11
	s_add_u32 s12, s8, s31
	s_addc_u32 s13, s9, s5
	v_cvt_pk_bf16_f32 v36, v36, v37
	v_cvt_pk_bf16_f32 v37, v38, v39
	v_cvt_pk_bf16_f32 v40, v40, v41
	v_cvt_pk_bf16_f32 v41, v42, v43
	v_cvt_pk_bf16_f32 v44, v44, v45
	v_cvt_pk_bf16_f32 v45, v46, v47
	v_cvt_pk_bf16_f32 v48, v48, v49
	v_cvt_pk_bf16_f32 v49, v50, v51
	global_store_dwordx2 v2, v[36:37], s[12:13]
	global_store_dwordx2 v2, v[40:41], s[12:13] offset:512
	global_store_dwordx2 v2, v[44:45], s[12:13] offset:1024
	global_store_dwordx2 v2, v[48:49], s[12:13] offset:1536
	s_add_i32 s10, s10, s33
	s_lshr_b32 s5, s10, 21
	s_lshl_b32 s31, s10, 11
	s_add_u32 s12, s8, s31
	s_addc_u32 s13, s9, s5
	v_cvt_pk_bf16_f32 v52, v52, v53
	v_cvt_pk_bf16_f32 v53, v54, v55
	v_cvt_pk_bf16_f32 v56, v56, v57
	v_cvt_pk_bf16_f32 v57, v58, v59
	v_cvt_pk_bf16_f32 v60, v60, v61
	v_cvt_pk_bf16_f32 v61, v62, v63
	v_cvt_pk_bf16_f32 v72, v72, v73
	v_cvt_pk_bf16_f32 v73, v74, v75
	global_store_dwordx2 v2, v[52:53], s[12:13]
	global_store_dwordx2 v2, v[56:57], s[12:13] offset:512
	global_store_dwordx2 v2, v[60:61], s[12:13] offset:1024
	global_store_dwordx2 v2, v[72:73], s[12:13] offset:1536
	s_cmp_lt_i32 s2, 0x10000
	s_cbranch_scc0 .LBB0_135
	s_mov_b32 s3, s2
	s_add_i32 s2, s2, s4
	s_branch .Lxc_loop

.LBB0_186:
	s_ashr_i32 s17, s16, 31
	s_lshl_b64 s[0:1], s[16:17], 19
	s_add_u32 s18, s35, s0
	s_addc_u32 s19, s36, s1
	s_and_b64 s[0:1], s[4:5], exec
	s_cselect_b32 s17, s19, s25
	s_cselect_b32 s55, s18, s24
	s_ashr_i32 s15, s14, 31
	s_lshl_b64 s[0:1], s[14:15], 19
	s_add_u32 s20, s37, s0
	s_addc_u32 s21, s40, s1
	s_and_b64 s[0:1], s[4:5], exec
	s_cselect_b32 s15, s21, s27
	s_cselect_b32 s56, s20, s26
	s_add_u32 s57, s26, 0x100
	s_addc_u32 s58, s27, 0
	s_mov_b32 s59, -2
	s_cmp_eq_u32 s98, 1
	s_cbranch_scc0 .Lrestag_187
	s_barrier
	s_mov_b32 s98, 0
.Lrestag_187:
	ds_read_b128 v[162:165], v157
	ds_read_b128 v[170:173], v157 offset:1024
	ds_read_b128 v[174:177], v157 offset:2048
	ds_read_b128 v[178:181], v157 offset:3072
	ds_read_b128 v[182:185], v158
	ds_read_b128 v[186:189], v158 offset:1024
	ds_read_b128 v[190:193], v158 offset:2048
	ds_read_b128 v[194:197], v158 offset:3072
	s_add_u32 s26, s24, 0x100
	s_addc_u32 s27, s25, 0
	s_cmp_eq_u32 s59, 12
	s_cselect_b32 s31, s17, s27
	s_cselect_b32 s30, s55, s26
	s_cselect_b32 s29, s15, s58
	s_cselect_b32 s28, s56, s57
	s_add_i32 m0, s23, 0xc000
	ds_read_b128 v[198:201], v159
	ds_read_b128 v[202:205], v159 offset:1024
	ds_read_b128 v[206:209], v159 offset:2048
	ds_read_b128 v[210:213], v159 offset:3072
	ds_read_b128 v[214:217], v159 offset:4096
	ds_read_b128 v[218:221], v159 offset:5120
	ds_read_b128 v[222:225], v159 offset:6144
	ds_read_b128 v[226:229], v159 offset:7168
	global_load_lds_dwordx4 v142, s[24:25]
	s_add_i32 m0, s23, 0xe000
	s_nop 0
	global_load_lds_dwordx4 v144, s[24:25]
	s_nop 0
	s_waitcnt lgkmcnt(0)
	s_barrier
	s_setprio 1
	s_waitcnt lgkmcnt(0)
	v_mfma_f32_16x16x32_bf16 v[124:127], v[162:165], v[198:201], 0
	v_mfma_f32_16x16x32_bf16 v[120:123], v[174:177], v[198:201], 0
	v_mfma_f32_16x16x32_bf16 v[112:115], v[162:165], v[206:209], 0
	v_mfma_f32_16x16x32_bf16 v[104:107], v[174:177], v[206:209], 0
	v_mfma_f32_16x16x32_bf16 v[96:99], v[162:165], v[214:217], 0
	v_mfma_f32_16x16x32_bf16 v[88:91], v[174:177], v[214:217], 0
	v_mfma_f32_16x16x32_bf16 v[80:83], v[162:165], v[222:225], 0
	v_mfma_f32_16x16x32_bf16 v[72:75], v[174:177], v[222:225], 0
	v_mfma_f32_16x16x32_bf16 v[124:127], v[170:173], v[202:205], v[124:127]
	v_mfma_f32_16x16x32_bf16 v[120:123], v[178:181], v[202:205], v[120:123]
	v_mfma_f32_16x16x32_bf16 v[112:115], v[170:173], v[210:213], v[112:115]
	v_mfma_f32_16x16x32_bf16 v[104:107], v[178:181], v[210:213], v[104:107]
	v_mfma_f32_16x16x32_bf16 v[96:99], v[170:173], v[218:221], v[96:99]
	v_mfma_f32_16x16x32_bf16 v[88:91], v[178:181], v[218:221], v[88:91]
	v_mfma_f32_16x16x32_bf16 v[80:83], v[170:173], v[226:229], v[80:83]
	v_mfma_f32_16x16x32_bf16 v[72:75], v[178:181], v[226:229], v[72:75]
	s_setprio 0
	s_setprio 1
	v_mfma_f32_16x16x32_bf16 v[116:119], v[182:185], v[198:201], 0
	v_mfma_f32_16x16x32_bf16 v[108:111], v[190:193], v[198:201], 0
	v_mfma_f32_16x16x32_bf16 v[100:103], v[182:185], v[206:209], 0
	v_mfma_f32_16x16x32_bf16 v[92:95], v[190:193], v[206:209], 0
	v_mfma_f32_16x16x32_bf16 v[84:87], v[182:185], v[214:217], 0
	v_mfma_f32_16x16x32_bf16 v[76:79], v[190:193], v[214:217], 0
	v_mfma_f32_16x16x32_bf16 v[68:71], v[182:185], v[222:225], 0
	v_mfma_f32_16x16x32_bf16 v[64:67], v[190:193], v[222:225], 0
	v_mfma_f32_16x16x32_bf16 v[116:119], v[186:189], v[202:205], v[116:119]
	v_mfma_f32_16x16x32_bf16 v[108:111], v[194:197], v[202:205], v[108:111]
	v_mfma_f32_16x16x32_bf16 v[100:103], v[186:189], v[210:213], v[100:103]
	v_mfma_f32_16x16x32_bf16 v[92:95], v[194:197], v[210:213], v[92:95]
	v_mfma_f32_16x16x32_bf16 v[84:87], v[186:189], v[218:221], v[84:87]
	v_mfma_f32_16x16x32_bf16 v[76:79], v[194:197], v[218:221], v[76:79]
	v_mfma_f32_16x16x32_bf16 v[68:71], v[186:189], v[226:229], v[68:71]
	v_mfma_f32_16x16x32_bf16 v[64:67], v[194:197], v[226:229], v[64:67]
	s_setprio 0
	s_barrier
	s_add_i32 s0, s51, s41
	v_lshl_add_u64 v[166:167], s[28:29], 0, v[130:131]
	s_mov_b32 m0, s0
	ds_read_b128 v[198:201], v159 offset:16384
	ds_read_b128 v[202:205], v159 offset:17408
	ds_read_b128 v[206:209], v159 offset:18432
	ds_read_b128 v[210:213], v159 offset:19456
	ds_read_b128 v[214:217], v159 offset:20480
	ds_read_b128 v[218:221], v159 offset:21504
	ds_read_b128 v[222:225], v159 offset:22528
	ds_read_b128 v[226:229], v159 offset:23552
	global_load_lds_dwordx4 v[166:167], off
	s_add_i32 m0, s0, 0x2000
	s_add_u32 s0, s28, 0x40000
	v_lshl_add_u64 v[230:231], s[28:29], 0, v[134:135]
	s_addc_u32 s1, s29, 0
	s_add_i32 s24, s52, s41
	global_load_lds_dwordx4 v[230:231], off
	s_mov_b32 m0, s24
	v_lshl_add_u64 v[234:235], s[30:31], 0, v[132:133]
	global_load_lds_dwordx4 v130, s[0:1]
	s_add_i32 m0, s24, 0x2000
	s_nop 0
	global_load_lds_dwordx4 v134, s[0:1]
	v_lshl_add_u64 v[232:233], s[30:31], 0, v[128:129]
	s_nop 0
	s_waitcnt lgkmcnt(0)
	s_barrier
	s_setprio 1
	s_waitcnt lgkmcnt(0)
	v_mfma_f32_16x16x32_bf16 v[60:63], v[162:165], v[198:201], 0
	v_mfma_f32_16x16x32_bf16 v[56:59], v[174:177], v[198:201], 0
	v_mfma_f32_16x16x32_bf16 v[48:51], v[162:165], v[206:209], 0
	v_mfma_f32_16x16x32_bf16 v[40:43], v[174:177], v[206:209], 0
	v_mfma_f32_16x16x32_bf16 v[32:35], v[162:165], v[214:217], 0
	v_mfma_f32_16x16x32_bf16 v[24:27], v[174:177], v[214:217], 0
	v_mfma_f32_16x16x32_bf16 v[16:19], v[162:165], v[222:225], 0
	v_mfma_f32_16x16x32_bf16 v[8:11], v[174:177], v[222:225], 0
	v_mfma_f32_16x16x32_bf16 v[60:63], v[170:173], v[202:205], v[60:63]
	v_mfma_f32_16x16x32_bf16 v[56:59], v[178:181], v[202:205], v[56:59]
	v_mfma_f32_16x16x32_bf16 v[48:51], v[170:173], v[210:213], v[48:51]
	v_mfma_f32_16x16x32_bf16 v[40:43], v[178:181], v[210:213], v[40:43]
	v_mfma_f32_16x16x32_bf16 v[32:35], v[170:173], v[218:221], v[32:35]
	v_mfma_f32_16x16x32_bf16 v[24:27], v[178:181], v[218:221], v[24:27]
	v_mfma_f32_16x16x32_bf16 v[16:19], v[170:173], v[226:229], v[16:19]
	v_mfma_f32_16x16x32_bf16 v[8:11], v[178:181], v[226:229], v[8:11]
	s_setprio 0
	s_setprio 1
	v_mfma_f32_16x16x32_bf16 v[52:55], v[182:185], v[198:201], 0
	v_mfma_f32_16x16x32_bf16 v[44:47], v[190:193], v[198:201], 0
	v_mfma_f32_16x16x32_bf16 v[36:39], v[182:185], v[206:209], 0
	v_mfma_f32_16x16x32_bf16 v[28:31], v[190:193], v[206:209], 0
	v_mfma_f32_16x16x32_bf16 v[20:23], v[182:185], v[214:217], 0
	v_mfma_f32_16x16x32_bf16 v[12:15], v[190:193], v[214:217], 0
	v_mfma_f32_16x16x32_bf16 v[4:7], v[182:185], v[222:225], 0
	v_mfma_f32_16x16x32_bf16 v[0:3], v[190:193], v[222:225], 0
	v_mfma_f32_16x16x32_bf16 v[52:55], v[186:189], v[202:205], v[52:55]
	v_mfma_f32_16x16x32_bf16 v[44:47], v[194:197], v[202:205], v[44:47]
	v_mfma_f32_16x16x32_bf16 v[36:39], v[186:189], v[210:213], v[36:39]
	v_mfma_f32_16x16x32_bf16 v[28:31], v[194:197], v[210:213], v[28:31]
	v_mfma_f32_16x16x32_bf16 v[20:23], v[186:189], v[218:221], v[20:23]
	v_mfma_f32_16x16x32_bf16 v[12:15], v[194:197], v[218:221], v[12:15]
	v_mfma_f32_16x16x32_bf16 v[4:7], v[186:189], v[226:229], v[4:7]
	v_mfma_f32_16x16x32_bf16 v[0:3], v[194:197], v[226:229], v[0:3]
	s_setprio 0
	s_barrier
	s_add_i32 s24, 0, 0x18000
	v_add_u32_e32 v150, s24, v153
	s_add_i32 s25, 0, 0x1c000
	ds_read_b128 v[162:165], v150
	ds_read_b128 v[170:173], v150 offset:1024
	ds_read_b128 v[174:177], v150 offset:2048
	ds_read_b128 v[178:181], v150 offset:3072
	v_add_u32_e32 v150, s25, v153
	ds_read_b128 v[182:185], v150
	ds_read_b128 v[186:189], v150 offset:1024
	ds_read_b128 v[190:193], v150 offset:2048
	ds_read_b128 v[194:197], v150 offset:3072
	s_add_u32 s0, s30, 0x40000
	s_addc_u32 s1, s31, 0
	s_mov_b32 m0, s43
	ds_read_b128 v[198:201], v159 offset:32768
	ds_read_b128 v[202:205], v159 offset:33792
	ds_read_b128 v[206:209], v159 offset:34816
	ds_read_b128 v[210:213], v159 offset:35840
	ds_read_b128 v[214:217], v159 offset:36864
	ds_read_b128 v[218:221], v159 offset:37888
	ds_read_b128 v[222:225], v159 offset:38912
	ds_read_b128 v[226:229], v159 offset:39936
	global_load_lds_dwordx4 v128, s[0:1]
	s_mov_b32 m0, s44
	s_nop 0
	global_load_lds_dwordx4 v132, s[0:1]
	s_mov_b32 m0, s23
	s_nop 0
	global_load_lds_dwordx4 v[232:233], off
	s_mov_b32 m0, s42
	s_nop 0
	global_load_lds_dwordx4 v[234:235], off
	s_waitcnt vmcnt(8)
	s_waitcnt lgkmcnt(0)
	s_barrier
	s_setprio 1
	s_waitcnt lgkmcnt(0)
	v_mfma_f32_16x16x32_bf16 v[124:127], v[162:165], v[198:201], v[124:127]
	v_mfma_f32_16x16x32_bf16 v[120:123], v[174:177], v[198:201], v[120:123]
	v_mfma_f32_16x16x32_bf16 v[112:115], v[162:165], v[206:209], v[112:115]
	v_mfma_f32_16x16x32_bf16 v[104:107], v[174:177], v[206:209], v[104:107]
	v_mfma_f32_16x16x32_bf16 v[96:99], v[162:165], v[214:217], v[96:99]
	v_mfma_f32_16x16x32_bf16 v[88:91], v[174:177], v[214:217], v[88:91]
	v_mfma_f32_16x16x32_bf16 v[80:83], v[162:165], v[222:225], v[80:83]
	v_mfma_f32_16x16x32_bf16 v[72:75], v[174:177], v[222:225], v[72:75]
	v_mfma_f32_16x16x32_bf16 v[124:127], v[170:173], v[202:205], v[124:127]
	v_mfma_f32_16x16x32_bf16 v[120:123], v[178:181], v[202:205], v[120:123]
	v_mfma_f32_16x16x32_bf16 v[112:115], v[170:173], v[210:213], v[112:115]
	v_mfma_f32_16x16x32_bf16 v[104:107], v[178:181], v[210:213], v[104:107]
	v_mfma_f32_16x16x32_bf16 v[96:99], v[170:173], v[218:221], v[96:99]
	v_mfma_f32_16x16x32_bf16 v[88:91], v[178:181], v[218:221], v[88:91]
	v_mfma_f32_16x16x32_bf16 v[80:83], v[170:173], v[226:229], v[80:83]
	v_mfma_f32_16x16x32_bf16 v[72:75], v[178:181], v[226:229], v[72:75]
	s_setprio 0
	s_setprio 1
	v_mfma_f32_16x16x32_bf16 v[116:119], v[182:185], v[198:201], v[116:119]
	v_mfma_f32_16x16x32_bf16 v[108:111], v[190:193], v[198:201], v[108:111]
	v_mfma_f32_16x16x32_bf16 v[100:103], v[182:185], v[206:209], v[100:103]
	v_mfma_f32_16x16x32_bf16 v[92:95], v[190:193], v[206:209], v[92:95]
	v_mfma_f32_16x16x32_bf16 v[84:87], v[182:185], v[214:217], v[84:87]
	v_mfma_f32_16x16x32_bf16 v[76:79], v[190:193], v[214:217], v[76:79]
	v_mfma_f32_16x16x32_bf16 v[68:71], v[182:185], v[222:225], v[68:71]
	v_mfma_f32_16x16x32_bf16 v[64:67], v[190:193], v[222:225], v[64:67]
	v_mfma_f32_16x16x32_bf16 v[116:119], v[186:189], v[202:205], v[116:119]
	v_mfma_f32_16x16x32_bf16 v[108:111], v[194:197], v[202:205], v[108:111]
	v_mfma_f32_16x16x32_bf16 v[100:103], v[186:189], v[210:213], v[100:103]
	v_mfma_f32_16x16x32_bf16 v[92:95], v[194:197], v[210:213], v[92:95]
	v_mfma_f32_16x16x32_bf16 v[84:87], v[186:189], v[218:221], v[84:87]
	v_mfma_f32_16x16x32_bf16 v[76:79], v[194:197], v[218:221], v[76:79]
	v_mfma_f32_16x16x32_bf16 v[68:71], v[186:189], v[226:229], v[68:71]
	v_mfma_f32_16x16x32_bf16 v[64:67], v[194:197], v[226:229], v[64:67]
	s_setprio 0
	s_barrier
	s_add_i32 s0, s24, s41
	v_lshl_add_u64 v[166:167], v[166:167], 0, s[8:9]
	s_mov_b32 m0, s0
	ds_read_b128 v[198:201], v159 offset:49152
	ds_read_b128 v[202:205], v159 offset:50176
	ds_read_b128 v[206:209], v159 offset:51200
	ds_read_b128 v[210:213], v159 offset:52224
	ds_read_b128 v[214:217], v159 offset:53248
	ds_read_b128 v[218:221], v159 offset:54272
	ds_read_b128 v[222:225], v159 offset:55296
	ds_read_b128 v[226:229], v159 offset:56320
	global_load_lds_dwordx4 v[166:167], off
	s_add_i32 m0, s0, 0x2000
	s_add_u32 s0, s28, 0x40080
	v_lshl_add_u64 v[166:167], v[230:231], 0, s[8:9]
	s_addc_u32 s1, s29, 0
	s_add_i32 s24, s25, s41
	global_load_lds_dwordx4 v[166:167], off
	s_mov_b32 m0, s24
	s_nop 0
	global_load_lds_dwordx4 v130, s[0:1]
	s_add_i32 m0, s24, 0x2000
	s_nop 0
	global_load_lds_dwordx4 v134, s[0:1]
	v_lshl_add_u64 v[166:167], v[232:233], 0, s[8:9]
	s_mov_b32 m0, s47
	s_nop 0
	global_load_lds_dwordx4 v[166:167], off
	v_lshl_add_u64 v[166:167], v[234:235], 0, s[8:9]
	s_mov_b32 m0, s48
	s_nop 0
	global_load_lds_dwordx4 v[166:167], off
	s_waitcnt vmcnt(6)
	s_waitcnt lgkmcnt(0)
	s_barrier
	s_setprio 1
	s_waitcnt lgkmcnt(0)
	v_mfma_f32_16x16x32_bf16 v[60:63], v[162:165], v[198:201], v[60:63]
	v_mfma_f32_16x16x32_bf16 v[56:59], v[174:177], v[198:201], v[56:59]
	v_mfma_f32_16x16x32_bf16 v[48:51], v[162:165], v[206:209], v[48:51]
	v_mfma_f32_16x16x32_bf16 v[40:43], v[174:177], v[206:209], v[40:43]
	v_mfma_f32_16x16x32_bf16 v[32:35], v[162:165], v[214:217], v[32:35]
	v_mfma_f32_16x16x32_bf16 v[24:27], v[174:177], v[214:217], v[24:27]
	v_mfma_f32_16x16x32_bf16 v[16:19], v[162:165], v[222:225], v[16:19]
	v_mfma_f32_16x16x32_bf16 v[8:11], v[174:177], v[222:225], v[8:11]
	v_mfma_f32_16x16x32_bf16 v[60:63], v[170:173], v[202:205], v[60:63]
	v_mfma_f32_16x16x32_bf16 v[56:59], v[178:181], v[202:205], v[56:59]
	v_mfma_f32_16x16x32_bf16 v[48:51], v[170:173], v[210:213], v[48:51]
	v_mfma_f32_16x16x32_bf16 v[40:43], v[178:181], v[210:213], v[40:43]
	v_mfma_f32_16x16x32_bf16 v[32:35], v[170:173], v[218:221], v[32:35]
	v_mfma_f32_16x16x32_bf16 v[24:27], v[178:181], v[218:221], v[24:27]
	v_mfma_f32_16x16x32_bf16 v[16:19], v[170:173], v[226:229], v[16:19]
	v_mfma_f32_16x16x32_bf16 v[8:11], v[178:181], v[226:229], v[8:11]
	s_setprio 0
	s_setprio 1
	v_mfma_f32_16x16x32_bf16 v[52:55], v[182:185], v[198:201], v[52:55]
	v_mfma_f32_16x16x32_bf16 v[44:47], v[190:193], v[198:201], v[44:47]
	v_mfma_f32_16x16x32_bf16 v[36:39], v[182:185], v[206:209], v[36:39]
	v_mfma_f32_16x16x32_bf16 v[28:31], v[190:193], v[206:209], v[28:31]
	v_mfma_f32_16x16x32_bf16 v[20:23], v[182:185], v[214:217], v[20:23]
	v_mfma_f32_16x16x32_bf16 v[12:15], v[190:193], v[214:217], v[12:15]
	v_mfma_f32_16x16x32_bf16 v[4:7], v[182:185], v[222:225], v[4:7]
	v_mfma_f32_16x16x32_bf16 v[0:3], v[190:193], v[222:225], v[0:3]
	v_mfma_f32_16x16x32_bf16 v[52:55], v[186:189], v[202:205], v[52:55]
	v_mfma_f32_16x16x32_bf16 v[44:47], v[194:197], v[202:205], v[44:47]
	v_mfma_f32_16x16x32_bf16 v[36:39], v[186:189], v[210:213], v[36:39]
	v_mfma_f32_16x16x32_bf16 v[28:31], v[194:197], v[210:213], v[28:31]
	v_mfma_f32_16x16x32_bf16 v[20:23], v[186:189], v[218:221], v[20:23]
	v_mfma_f32_16x16x32_bf16 v[12:15], v[194:197], v[218:221], v[12:15]
	v_mfma_f32_16x16x32_bf16 v[4:7], v[186:189], v[226:229], v[4:7]
	v_mfma_f32_16x16x32_bf16 v[0:3], v[194:197], v[226:229], v[0:3]
	s_setprio 0
	s_barrier
	s_add_i32 s59, s59, 2
	s_add_u32 s57, s57, 0x100
	s_addc_u32 s58, s58, 0
	s_cmp_gt_u32 s59, 13
	s_mov_b64 s[24:25], s[26:27]
.LBB0_187:
	ds_read_b128 v[162:165], v157
	ds_read_b128 v[170:173], v157 offset:1024
	ds_read_b128 v[174:177], v157 offset:2048
	ds_read_b128 v[178:181], v157 offset:3072
	ds_read_b128 v[182:185], v158
	ds_read_b128 v[186:189], v158 offset:1024
	ds_read_b128 v[190:193], v158 offset:2048
	ds_read_b128 v[194:197], v158 offset:3072
	s_add_u32 s26, s24, 0x100
	s_addc_u32 s27, s25, 0
	s_cmp_eq_u32 s59, 12
	s_cselect_b32 s31, s17, s27
	s_cselect_b32 s30, s55, s26
	s_cselect_b32 s29, s15, s58
	s_cselect_b32 s28, s56, s57
	s_add_i32 m0, s23, 0xc000
	ds_read_b128 v[198:201], v159
	ds_read_b128 v[202:205], v159 offset:1024
	ds_read_b128 v[206:209], v159 offset:2048
	ds_read_b128 v[210:213], v159 offset:3072
	ds_read_b128 v[214:217], v159 offset:4096
	ds_read_b128 v[218:221], v159 offset:5120
	ds_read_b128 v[222:225], v159 offset:6144
	ds_read_b128 v[226:229], v159 offset:7168
	global_load_lds_dwordx4 v142, s[24:25]
	s_add_i32 m0, s23, 0xe000
	s_nop 0
	global_load_lds_dwordx4 v144, s[24:25]
	s_waitcnt vmcnt(8)
	s_waitcnt lgkmcnt(0)
	s_barrier
	s_setprio 1
	s_waitcnt lgkmcnt(0)
	v_mfma_f32_16x16x32_bf16 v[124:127], v[162:165], v[198:201], v[124:127]
	v_mfma_f32_16x16x32_bf16 v[120:123], v[174:177], v[198:201], v[120:123]
	v_mfma_f32_16x16x32_bf16 v[112:115], v[162:165], v[206:209], v[112:115]
	v_mfma_f32_16x16x32_bf16 v[104:107], v[174:177], v[206:209], v[104:107]
	v_mfma_f32_16x16x32_bf16 v[96:99], v[162:165], v[214:217], v[96:99]
	v_mfma_f32_16x16x32_bf16 v[88:91], v[174:177], v[214:217], v[88:91]
	v_mfma_f32_16x16x32_bf16 v[80:83], v[162:165], v[222:225], v[80:83]
	v_mfma_f32_16x16x32_bf16 v[72:75], v[174:177], v[222:225], v[72:75]
	v_mfma_f32_16x16x32_bf16 v[124:127], v[170:173], v[202:205], v[124:127]
	v_mfma_f32_16x16x32_bf16 v[120:123], v[178:181], v[202:205], v[120:123]
	v_mfma_f32_16x16x32_bf16 v[112:115], v[170:173], v[210:213], v[112:115]
	v_mfma_f32_16x16x32_bf16 v[104:107], v[178:181], v[210:213], v[104:107]
	v_mfma_f32_16x16x32_bf16 v[96:99], v[170:173], v[218:221], v[96:99]
	v_mfma_f32_16x16x32_bf16 v[88:91], v[178:181], v[218:221], v[88:91]
	v_mfma_f32_16x16x32_bf16 v[80:83], v[170:173], v[226:229], v[80:83]
	v_mfma_f32_16x16x32_bf16 v[72:75], v[178:181], v[226:229], v[72:75]
	s_setprio 0
	s_setprio 1
	v_mfma_f32_16x16x32_bf16 v[116:119], v[182:185], v[198:201], v[116:119]
	v_mfma_f32_16x16x32_bf16 v[108:111], v[190:193], v[198:201], v[108:111]
	v_mfma_f32_16x16x32_bf16 v[100:103], v[182:185], v[206:209], v[100:103]
	v_mfma_f32_16x16x32_bf16 v[92:95], v[190:193], v[206:209], v[92:95]
	v_mfma_f32_16x16x32_bf16 v[84:87], v[182:185], v[214:217], v[84:87]
	v_mfma_f32_16x16x32_bf16 v[76:79], v[190:193], v[214:217], v[76:79]
	v_mfma_f32_16x16x32_bf16 v[68:71], v[182:185], v[222:225], v[68:71]
	v_mfma_f32_16x16x32_bf16 v[64:67], v[190:193], v[222:225], v[64:67]
	v_mfma_f32_16x16x32_bf16 v[116:119], v[186:189], v[202:205], v[116:119]
	v_mfma_f32_16x16x32_bf16 v[108:111], v[194:197], v[202:205], v[108:111]
	v_mfma_f32_16x16x32_bf16 v[100:103], v[186:189], v[210:213], v[100:103]
	v_mfma_f32_16x16x32_bf16 v[92:95], v[194:197], v[210:213], v[92:95]
	v_mfma_f32_16x16x32_bf16 v[84:87], v[186:189], v[218:221], v[84:87]
	v_mfma_f32_16x16x32_bf16 v[76:79], v[194:197], v[218:221], v[76:79]
	v_mfma_f32_16x16x32_bf16 v[68:71], v[186:189], v[226:229], v[68:71]
	v_mfma_f32_16x16x32_bf16 v[64:67], v[194:197], v[226:229], v[64:67]
	s_setprio 0
	s_barrier
	s_add_i32 s0, s51, s41
	v_lshl_add_u64 v[166:167], s[28:29], 0, v[130:131]
	s_mov_b32 m0, s0
	ds_read_b128 v[198:201], v159 offset:16384
	ds_read_b128 v[202:205], v159 offset:17408
	ds_read_b128 v[206:209], v159 offset:18432
	ds_read_b128 v[210:213], v159 offset:19456
	ds_read_b128 v[214:217], v159 offset:20480
	ds_read_b128 v[218:221], v159 offset:21504
	ds_read_b128 v[222:225], v159 offset:22528
	ds_read_b128 v[226:229], v159 offset:23552
	global_load_lds_dwordx4 v[166:167], off
	s_add_i32 m0, s0, 0x2000
	s_add_u32 s0, s28, 0x40000
	v_lshl_add_u64 v[230:231], s[28:29], 0, v[134:135]
	s_addc_u32 s1, s29, 0
	s_add_i32 s24, s52, s41
	global_load_lds_dwordx4 v[230:231], off
	s_mov_b32 m0, s24
	v_lshl_add_u64 v[234:235], s[30:31], 0, v[132:133]
	global_load_lds_dwordx4 v130, s[0:1]
	s_add_i32 m0, s24, 0x2000
	s_nop 0
	global_load_lds_dwordx4 v134, s[0:1]
	v_lshl_add_u64 v[232:233], s[30:31], 0, v[128:129]
	s_waitcnt vmcnt(6)
	s_waitcnt lgkmcnt(0)
	s_barrier
	s_setprio 1
	s_waitcnt lgkmcnt(0)
	v_mfma_f32_16x16x32_bf16 v[60:63], v[162:165], v[198:201], v[60:63]
	v_mfma_f32_16x16x32_bf16 v[56:59], v[174:177], v[198:201], v[56:59]
	v_mfma_f32_16x16x32_bf16 v[48:51], v[162:165], v[206:209], v[48:51]
	v_mfma_f32_16x16x32_bf16 v[40:43], v[174:177], v[206:209], v[40:43]
	v_mfma_f32_16x16x32_bf16 v[32:35], v[162:165], v[214:217], v[32:35]
	v_mfma_f32_16x16x32_bf16 v[24:27], v[174:177], v[214:217], v[24:27]
	v_mfma_f32_16x16x32_bf16 v[16:19], v[162:165], v[222:225], v[16:19]
	v_mfma_f32_16x16x32_bf16 v[8:11], v[174:177], v[222:225], v[8:11]
	v_mfma_f32_16x16x32_bf16 v[60:63], v[170:173], v[202:205], v[60:63]
	v_mfma_f32_16x16x32_bf16 v[56:59], v[178:181], v[202:205], v[56:59]
	v_mfma_f32_16x16x32_bf16 v[48:51], v[170:173], v[210:213], v[48:51]
	v_mfma_f32_16x16x32_bf16 v[40:43], v[178:181], v[210:213], v[40:43]
	v_mfma_f32_16x16x32_bf16 v[32:35], v[170:173], v[218:221], v[32:35]
	v_mfma_f32_16x16x32_bf16 v[24:27], v[178:181], v[218:221], v[24:27]
	v_mfma_f32_16x16x32_bf16 v[16:19], v[170:173], v[226:229], v[16:19]
	v_mfma_f32_16x16x32_bf16 v[8:11], v[178:181], v[226:229], v[8:11]
	s_setprio 0
	s_setprio 1
	v_mfma_f32_16x16x32_bf16 v[52:55], v[182:185], v[198:201], v[52:55]
	v_mfma_f32_16x16x32_bf16 v[44:47], v[190:193], v[198:201], v[44:47]
	v_mfma_f32_16x16x32_bf16 v[36:39], v[182:185], v[206:209], v[36:39]
	v_mfma_f32_16x16x32_bf16 v[28:31], v[190:193], v[206:209], v[28:31]
	v_mfma_f32_16x16x32_bf16 v[20:23], v[182:185], v[214:217], v[20:23]
	v_mfma_f32_16x16x32_bf16 v[12:15], v[190:193], v[214:217], v[12:15]
	v_mfma_f32_16x16x32_bf16 v[4:7], v[182:185], v[222:225], v[4:7]
	v_mfma_f32_16x16x32_bf16 v[0:3], v[190:193], v[222:225], v[0:3]
	v_mfma_f32_16x16x32_bf16 v[52:55], v[186:189], v[202:205], v[52:55]
	v_mfma_f32_16x16x32_bf16 v[44:47], v[194:197], v[202:205], v[44:47]
	v_mfma_f32_16x16x32_bf16 v[36:39], v[186:189], v[210:213], v[36:39]
	v_mfma_f32_16x16x32_bf16 v[28:31], v[194:197], v[210:213], v[28:31]
	v_mfma_f32_16x16x32_bf16 v[20:23], v[186:189], v[218:221], v[20:23]
	v_mfma_f32_16x16x32_bf16 v[12:15], v[194:197], v[218:221], v[12:15]
	v_mfma_f32_16x16x32_bf16 v[4:7], v[186:189], v[226:229], v[4:7]
	v_mfma_f32_16x16x32_bf16 v[0:3], v[194:197], v[226:229], v[0:3]
	s_setprio 0
	s_barrier
	s_add_i32 s24, 0, 0x18000
	v_add_u32_e32 v150, s24, v153
	s_add_i32 s25, 0, 0x1c000
	ds_read_b128 v[162:165], v150
	ds_read_b128 v[170:173], v150 offset:1024
	ds_read_b128 v[174:177], v150 offset:2048
	ds_read_b128 v[178:181], v150 offset:3072
	v_add_u32_e32 v150, s25, v153
	ds_read_b128 v[182:185], v150
	ds_read_b128 v[186:189], v150 offset:1024
	ds_read_b128 v[190:193], v150 offset:2048
	ds_read_b128 v[194:197], v150 offset:3072
	s_add_u32 s0, s30, 0x40000
	s_addc_u32 s1, s31, 0
	s_mov_b32 m0, s43
	ds_read_b128 v[198:201], v159 offset:32768
	ds_read_b128 v[202:205], v159 offset:33792
	ds_read_b128 v[206:209], v159 offset:34816
	ds_read_b128 v[210:213], v159 offset:35840
	ds_read_b128 v[214:217], v159 offset:36864
	ds_read_b128 v[218:221], v159 offset:37888
	ds_read_b128 v[222:225], v159 offset:38912
	ds_read_b128 v[226:229], v159 offset:39936
	global_load_lds_dwordx4 v128, s[0:1]
	s_mov_b32 m0, s44
	s_nop 0
	global_load_lds_dwordx4 v132, s[0:1]
	s_mov_b32 m0, s23
	s_nop 0
	global_load_lds_dwordx4 v[232:233], off
	s_mov_b32 m0, s42
	s_nop 0
	global_load_lds_dwordx4 v[234:235], off
	s_waitcnt vmcnt(8)
	s_waitcnt lgkmcnt(0)
	s_barrier
	s_setprio 1
	s_waitcnt lgkmcnt(0)
	v_mfma_f32_16x16x32_bf16 v[124:127], v[162:165], v[198:201], v[124:127]
	v_mfma_f32_16x16x32_bf16 v[120:123], v[174:177], v[198:201], v[120:123]
	v_mfma_f32_16x16x32_bf16 v[112:115], v[162:165], v[206:209], v[112:115]
	v_mfma_f32_16x16x32_bf16 v[104:107], v[174:177], v[206:209], v[104:107]
	v_mfma_f32_16x16x32_bf16 v[96:99], v[162:165], v[214:217], v[96:99]
	v_mfma_f32_16x16x32_bf16 v[88:91], v[174:177], v[214:217], v[88:91]
	v_mfma_f32_16x16x32_bf16 v[80:83], v[162:165], v[222:225], v[80:83]
	v_mfma_f32_16x16x32_bf16 v[72:75], v[174:177], v[222:225], v[72:75]
	v_mfma_f32_16x16x32_bf16 v[124:127], v[170:173], v[202:205], v[124:127]
	v_mfma_f32_16x16x32_bf16 v[120:123], v[178:181], v[202:205], v[120:123]
	v_mfma_f32_16x16x32_bf16 v[112:115], v[170:173], v[210:213], v[112:115]
	v_mfma_f32_16x16x32_bf16 v[104:107], v[178:181], v[210:213], v[104:107]
	v_mfma_f32_16x16x32_bf16 v[96:99], v[170:173], v[218:221], v[96:99]
	v_mfma_f32_16x16x32_bf16 v[88:91], v[178:181], v[218:221], v[88:91]
	v_mfma_f32_16x16x32_bf16 v[80:83], v[170:173], v[226:229], v[80:83]
	v_mfma_f32_16x16x32_bf16 v[72:75], v[178:181], v[226:229], v[72:75]
	s_setprio 0
	s_setprio 1
	v_mfma_f32_16x16x32_bf16 v[116:119], v[182:185], v[198:201], v[116:119]
	v_mfma_f32_16x16x32_bf16 v[108:111], v[190:193], v[198:201], v[108:111]
	v_mfma_f32_16x16x32_bf16 v[100:103], v[182:185], v[206:209], v[100:103]
	v_mfma_f32_16x16x32_bf16 v[92:95], v[190:193], v[206:209], v[92:95]
	v_mfma_f32_16x16x32_bf16 v[84:87], v[182:185], v[214:217], v[84:87]
	v_mfma_f32_16x16x32_bf16 v[76:79], v[190:193], v[214:217], v[76:79]
	v_mfma_f32_16x16x32_bf16 v[68:71], v[182:185], v[222:225], v[68:71]
	v_mfma_f32_16x16x32_bf16 v[64:67], v[190:193], v[222:225], v[64:67]
	v_mfma_f32_16x16x32_bf16 v[116:119], v[186:189], v[202:205], v[116:119]
	v_mfma_f32_16x16x32_bf16 v[108:111], v[194:197], v[202:205], v[108:111]
	v_mfma_f32_16x16x32_bf16 v[100:103], v[186:189], v[210:213], v[100:103]
	v_mfma_f32_16x16x32_bf16 v[92:95], v[194:197], v[210:213], v[92:95]
	v_mfma_f32_16x16x32_bf16 v[84:87], v[186:189], v[218:221], v[84:87]
	v_mfma_f32_16x16x32_bf16 v[76:79], v[194:197], v[218:221], v[76:79]
	v_mfma_f32_16x16x32_bf16 v[68:71], v[186:189], v[226:229], v[68:71]
	v_mfma_f32_16x16x32_bf16 v[64:67], v[194:197], v[226:229], v[64:67]
	s_setprio 0
	s_barrier
	s_add_i32 s0, s24, s41
	v_lshl_add_u64 v[166:167], v[166:167], 0, s[8:9]
	s_mov_b32 m0, s0
	ds_read_b128 v[198:201], v159 offset:49152
	ds_read_b128 v[202:205], v159 offset:50176
	ds_read_b128 v[206:209], v159 offset:51200
	ds_read_b128 v[210:213], v159 offset:52224
	ds_read_b128 v[214:217], v159 offset:53248
	ds_read_b128 v[218:221], v159 offset:54272
	ds_read_b128 v[222:225], v159 offset:55296
	ds_read_b128 v[226:229], v159 offset:56320
	global_load_lds_dwordx4 v[166:167], off
	s_add_i32 m0, s0, 0x2000
	s_add_u32 s0, s28, 0x40080
	v_lshl_add_u64 v[166:167], v[230:231], 0, s[8:9]
	s_addc_u32 s1, s29, 0
	s_add_i32 s24, s25, s41
	global_load_lds_dwordx4 v[166:167], off
	s_mov_b32 m0, s24
	s_nop 0
	global_load_lds_dwordx4 v130, s[0:1]
	s_add_i32 m0, s24, 0x2000
	s_nop 0
	global_load_lds_dwordx4 v134, s[0:1]
	v_lshl_add_u64 v[166:167], v[232:233], 0, s[8:9]
	s_mov_b32 m0, s47
	s_nop 0
	global_load_lds_dwordx4 v[166:167], off
	v_lshl_add_u64 v[166:167], v[234:235], 0, s[8:9]
	s_mov_b32 m0, s48
	s_nop 0
	global_load_lds_dwordx4 v[166:167], off
	s_waitcnt vmcnt(6)
	s_waitcnt lgkmcnt(0)
	s_barrier
	s_setprio 1
	s_waitcnt lgkmcnt(0)
	v_mfma_f32_16x16x32_bf16 v[60:63], v[162:165], v[198:201], v[60:63]
	v_mfma_f32_16x16x32_bf16 v[56:59], v[174:177], v[198:201], v[56:59]
	v_mfma_f32_16x16x32_bf16 v[48:51], v[162:165], v[206:209], v[48:51]
	v_mfma_f32_16x16x32_bf16 v[40:43], v[174:177], v[206:209], v[40:43]
	v_mfma_f32_16x16x32_bf16 v[32:35], v[162:165], v[214:217], v[32:35]
	v_mfma_f32_16x16x32_bf16 v[24:27], v[174:177], v[214:217], v[24:27]
	v_mfma_f32_16x16x32_bf16 v[16:19], v[162:165], v[222:225], v[16:19]
	v_mfma_f32_16x16x32_bf16 v[8:11], v[174:177], v[222:225], v[8:11]
	v_mfma_f32_16x16x32_bf16 v[60:63], v[170:173], v[202:205], v[60:63]
	v_mfma_f32_16x16x32_bf16 v[56:59], v[178:181], v[202:205], v[56:59]
	v_mfma_f32_16x16x32_bf16 v[48:51], v[170:173], v[210:213], v[48:51]
	v_mfma_f32_16x16x32_bf16 v[40:43], v[178:181], v[210:213], v[40:43]
	v_mfma_f32_16x16x32_bf16 v[32:35], v[170:173], v[218:221], v[32:35]
	v_mfma_f32_16x16x32_bf16 v[24:27], v[178:181], v[218:221], v[24:27]
	v_mfma_f32_16x16x32_bf16 v[16:19], v[170:173], v[226:229], v[16:19]
	v_mfma_f32_16x16x32_bf16 v[8:11], v[178:181], v[226:229], v[8:11]
	s_setprio 0
	s_setprio 1
	v_mfma_f32_16x16x32_bf16 v[52:55], v[182:185], v[198:201], v[52:55]
	v_mfma_f32_16x16x32_bf16 v[44:47], v[190:193], v[198:201], v[44:47]
	v_mfma_f32_16x16x32_bf16 v[36:39], v[182:185], v[206:209], v[36:39]
	v_mfma_f32_16x16x32_bf16 v[28:31], v[190:193], v[206:209], v[28:31]
	v_mfma_f32_16x16x32_bf16 v[20:23], v[182:185], v[214:217], v[20:23]
	v_mfma_f32_16x16x32_bf16 v[12:15], v[190:193], v[214:217], v[12:15]
	v_mfma_f32_16x16x32_bf16 v[4:7], v[182:185], v[222:225], v[4:7]
	v_mfma_f32_16x16x32_bf16 v[0:3], v[190:193], v[222:225], v[0:3]
	v_mfma_f32_16x16x32_bf16 v[52:55], v[186:189], v[202:205], v[52:55]
	v_mfma_f32_16x16x32_bf16 v[44:47], v[194:197], v[202:205], v[44:47]
	v_mfma_f32_16x16x32_bf16 v[36:39], v[186:189], v[210:213], v[36:39]
	v_mfma_f32_16x16x32_bf16 v[28:31], v[194:197], v[210:213], v[28:31]
	v_mfma_f32_16x16x32_bf16 v[20:23], v[186:189], v[218:221], v[20:23]
	v_mfma_f32_16x16x32_bf16 v[12:15], v[194:197], v[218:221], v[12:15]
	v_mfma_f32_16x16x32_bf16 v[4:7], v[186:189], v[226:229], v[4:7]
	v_mfma_f32_16x16x32_bf16 v[0:3], v[194:197], v[226:229], v[0:3]
	s_setprio 0
	s_barrier
	s_add_i32 s59, s59, 2
	s_add_u32 s57, s57, 0x100
	s_addc_u32 s58, s58, 0
	s_cmp_gt_u32 s59, 13
	s_mov_b64 s[24:25], s[26:27]
	s_cbranch_scc0 .LBB0_187
	s_and_b64 vcc, exec, s[12:13]
	s_cbranch_vccz .LBB0_190
	s_barrier
.LBB0_190:
	s_lshl_b32 s0, s22, 8
	s_add_i32 s0, s0, s46
	v_or_b32_e32 v162, s0, v151
	v_ashrrev_i32_e32 v163, 31, v162
	v_lshl_add_u64 v[164:165], v[162:163], 2, s[6:7]
	v_add_u32_e32 v166, 0x80, v162
	v_add_u32_e32 v170, 0x90, v162
	v_add_u32_e32 v172, 0xa0, v162
	v_add_u32_e32 v162, 0xb0, v162
	v_ashrrev_i32_e32 v167, 31, v166
	v_ashrrev_i32_e32 v171, 31, v170
	v_ashrrev_i32_e32 v173, 31, v172
	v_ashrrev_i32_e32 v163, 31, v162
	v_lshl_add_u64 v[166:167], v[166:167], 2, s[6:7]
	v_lshl_add_u64 v[170:171], v[170:171], 2, s[6:7]
	v_lshl_add_u64 v[172:173], v[172:173], 2, s[6:7]
	v_lshl_add_u64 v[162:163], v[162:163], 2, s[6:7]
	global_load_dword v174, v[164:165], off
	global_load_dword v176, v[164:165], off offset:64
	global_load_dword v178, v[164:165], off offset:128
	s_nop 0
	global_load_dword v164, v[164:165], off offset:192
	s_nop 0
	global_load_dword v156, v[166:167], off
	global_load_dword v154, v[170:171], off
	global_load_dword v152, v[172:173], off
	global_load_dword v150, v[162:163], off
	v_lshl_or_b32 v161, s54, 8, v155
	s_ashr_i32 s1, s0, 5
	v_ashrrev_i32_e32 v161, 4, v161
	v_mad_i64_i32 v[162:163], s[24:25], s1, v160, v[138:139]
	s_waitcnt vmcnt(0)
	v_pk_mul_f32 v[124:125], v[124:125], v[174:175] op_sel_hi:[1,0]
	v_pk_mul_f32 v[166:167], v[122:123], v[174:175] op_sel_hi:[1,0]
	v_pk_mul_f32 v[122:123], v[120:121], v[174:175] op_sel_hi:[1,0]
	v_pk_mul_f32 v[126:127], v[126:127], v[174:175] op_sel_hi:[1,0]
	v_cvt_pk_bf16_f32 v120, v124, v125
	v_mad_i64_i32 v[124:125], s[24:25], v161, s53, v[162:163]
	v_cvt_pk_bf16_f32 v121, v126, v127
	v_cvt_pk_bf16_f32 v122, v122, v123
	v_cvt_pk_bf16_f32 v123, v166, v167
	global_store_dwordx4 v[124:125], v[120:123], off
	v_pk_mul_f32 v[116:117], v[116:117], v[174:175] op_sel_hi:[1,0]
	v_pk_mul_f32 v[118:119], v[118:119], v[174:175] op_sel_hi:[1,0]
	v_or_b32_e32 v122, 8, v161
	v_pk_mul_f32 v[120:121], v[110:111], v[174:175] op_sel_hi:[1,0]
	v_pk_mul_f32 v[110:111], v[108:109], v[174:175] op_sel_hi:[1,0]
	v_cvt_pk_bf16_f32 v108, v116, v117
	v_cvt_pk_bf16_f32 v109, v118, v119
	v_mad_i64_i32 v[116:117], s[24:25], v122, s53, v[162:163]
	v_cvt_pk_bf16_f32 v110, v110, v111
	v_cvt_pk_bf16_f32 v111, v120, v121
	global_store_dwordx4 v[116:117], v[108:111], off
	v_pk_mul_f32 v[102:103], v[102:103], v[176:177] op_sel_hi:[1,0]
	v_pk_mul_f32 v[100:101], v[100:101], v[176:177] op_sel_hi:[1,0]
	v_pk_mul_f32 v[108:109], v[114:115], v[176:177] op_sel_hi:[1,0]
	v_pk_mul_f32 v[110:111], v[112:113], v[176:177] op_sel_hi:[1,0]
	v_pk_mul_f32 v[112:113], v[106:107], v[176:177] op_sel_hi:[1,0]
	v_pk_mul_f32 v[106:107], v[104:105], v[176:177] op_sel_hi:[1,0]
	v_cvt_pk_bf16_f32 v104, v110, v111
	v_cvt_pk_bf16_f32 v105, v108, v109
	s_or_b32 s1, s1, 1
	v_cvt_pk_bf16_f32 v106, v106, v107
	v_cvt_pk_bf16_f32 v107, v112, v113
	global_store_dwordx4 v[124:125], v[104:107], off offset:512
	v_pk_mul_f32 v[96:97], v[96:97], v[178:179] op_sel_hi:[1,0]
	v_pk_mul_f32 v[84:85], v[84:85], v[178:179] op_sel_hi:[1,0]
	v_pk_mul_f32 v[104:105], v[94:95], v[176:177] op_sel_hi:[1,0]
	v_pk_mul_f32 v[94:95], v[92:93], v[176:177] op_sel_hi:[1,0]
	v_cvt_pk_bf16_f32 v92, v100, v101
	v_cvt_pk_bf16_f32 v93, v102, v103
	v_pk_mul_f32 v[86:87], v[86:87], v[178:179] op_sel_hi:[1,0]
	v_cvt_pk_bf16_f32 v94, v94, v95
	v_cvt_pk_bf16_f32 v95, v104, v105
	global_store_dwordx4 v[116:117], v[92:95], off offset:512
	v_pk_mul_f32 v[70:71], v[70:71], v[164:165] op_sel_hi:[1,0]
	v_pk_mul_f32 v[68:69], v[68:69], v[164:165] op_sel_hi:[1,0]
	v_mad_i64_i32 v[92:93], s[24:25], s1, v160, v[138:139]
	v_pk_mul_f32 v[94:95], v[98:99], v[178:179] op_sel_hi:[1,0]
	v_pk_mul_f32 v[98:99], v[90:91], v[178:179] op_sel_hi:[1,0]
	v_pk_mul_f32 v[90:91], v[88:89], v[178:179] op_sel_hi:[1,0]
	v_cvt_pk_bf16_f32 v88, v96, v97
	v_cvt_pk_bf16_f32 v89, v94, v95
	v_mad_i64_i32 v[94:95], s[24:25], v161, s53, v[92:93]
	v_cvt_pk_bf16_f32 v90, v90, v91
	v_cvt_pk_bf16_f32 v91, v98, v99
	global_store_dwordx4 v[94:95], v[88:91], off
	s_add_i32 s1, s0, 0x80
	s_ashr_i32 s1, s1, 5
	v_pk_mul_f32 v[88:89], v[78:79], v[178:179] op_sel_hi:[1,0]
	v_pk_mul_f32 v[78:79], v[76:77], v[178:179] op_sel_hi:[1,0]
	v_cvt_pk_bf16_f32 v76, v84, v85
	v_cvt_pk_bf16_f32 v77, v86, v87
	v_mad_i64_i32 v[84:85], s[24:25], v122, s53, v[92:93]
	v_cvt_pk_bf16_f32 v78, v78, v79
	v_cvt_pk_bf16_f32 v79, v88, v89
	global_store_dwordx4 v[84:85], v[76:79], off
	v_pk_mul_f32 v[60:61], v[60:61], v[156:157] op_sel_hi:[1,0]
	v_pk_mul_f32 v[62:63], v[62:63], v[156:157] op_sel_hi:[1,0]
	v_pk_mul_f32 v[76:77], v[82:83], v[164:165] op_sel_hi:[1,0]
	v_pk_mul_f32 v[78:79], v[80:81], v[164:165] op_sel_hi:[1,0]
	v_pk_mul_f32 v[80:81], v[74:75], v[164:165] op_sel_hi:[1,0]
	v_pk_mul_f32 v[74:75], v[72:73], v[164:165] op_sel_hi:[1,0]
	v_cvt_pk_bf16_f32 v72, v78, v79
	v_cvt_pk_bf16_f32 v73, v76, v77
	v_pk_mul_f32 v[52:53], v[52:53], v[156:157] op_sel_hi:[1,0]
	v_cvt_pk_bf16_f32 v74, v74, v75
	v_cvt_pk_bf16_f32 v75, v80, v81
	global_store_dwordx4 v[94:95], v[72:75], off offset:512
	v_pk_mul_f32 v[54:55], v[54:55], v[156:157] op_sel_hi:[1,0]
	v_pk_mul_f32 v[48:49], v[48:49], v[154:155] op_sel_hi:[1,0]
	v_pk_mul_f32 v[72:73], v[66:67], v[164:165] op_sel_hi:[1,0]
	v_pk_mul_f32 v[66:67], v[64:65], v[164:165] op_sel_hi:[1,0]
	v_cvt_pk_bf16_f32 v64, v68, v69
	v_cvt_pk_bf16_f32 v65, v70, v71
	v_pk_mul_f32 v[36:37], v[36:37], v[154:155] op_sel_hi:[1,0]
	v_cvt_pk_bf16_f32 v66, v66, v67
	v_cvt_pk_bf16_f32 v67, v72, v73
	global_store_dwordx4 v[84:85], v[64:67], off offset:512
	v_pk_mul_f32 v[38:39], v[38:39], v[154:155] op_sel_hi:[1,0]
	v_pk_mul_f32 v[32:33], v[32:33], v[152:153] op_sel_hi:[1,0]
	v_mad_i64_i32 v[64:65], s[24:25], s1, v160, v[138:139]
	v_pk_mul_f32 v[66:67], v[58:59], v[156:157] op_sel_hi:[1,0]
	v_pk_mul_f32 v[58:59], v[56:57], v[156:157] op_sel_hi:[1,0]
	v_cvt_pk_bf16_f32 v56, v60, v61
	v_cvt_pk_bf16_f32 v57, v62, v63
	v_mad_i64_i32 v[60:61], s[24:25], v161, s53, v[64:65]
	v_cvt_pk_bf16_f32 v58, v58, v59
	v_cvt_pk_bf16_f32 v59, v66, v67
	global_store_dwordx4 v[60:61], v[56:59], off
	s_add_i32 s1, s0, 0x90
	s_ashr_i32 s1, s1, 5
	v_pk_mul_f32 v[56:57], v[46:47], v[156:157] op_sel_hi:[1,0]
	v_pk_mul_f32 v[46:47], v[44:45], v[156:157] op_sel_hi:[1,0]
	v_cvt_pk_bf16_f32 v44, v52, v53
	v_cvt_pk_bf16_f32 v45, v54, v55
	v_mad_i64_i32 v[52:53], s[24:25], v122, s53, v[64:65]
	v_cvt_pk_bf16_f32 v46, v46, v47
	v_cvt_pk_bf16_f32 v47, v56, v57
	global_store_dwordx4 v[52:53], v[44:47], off
	v_pk_mul_f32 v[20:21], v[20:21], v[152:153] op_sel_hi:[1,0]
	v_pk_mul_f32 v[22:23], v[22:23], v[152:153] op_sel_hi:[1,0]
	v_mad_i64_i32 v[44:45], s[24:25], s1, v160, v[140:141]
	v_pk_mul_f32 v[46:47], v[50:51], v[154:155] op_sel_hi:[1,0]
	v_pk_mul_f32 v[50:51], v[42:43], v[154:155] op_sel_hi:[1,0]
	v_pk_mul_f32 v[42:43], v[40:41], v[154:155] op_sel_hi:[1,0]
	v_cvt_pk_bf16_f32 v40, v48, v49
	v_cvt_pk_bf16_f32 v41, v46, v47
	v_mad_i64_i32 v[46:47], s[24:25], v161, s53, v[44:45]
	v_lshl_add_u64 v[46:47], v[46:47], 0, v[136:137]
	v_cvt_pk_bf16_f32 v42, v42, v43
	v_cvt_pk_bf16_f32 v43, v50, v51
	global_store_dwordx4 v[46:47], v[40:43], off
	s_add_i32 s1, s0, 0xa0
	s_ashr_i32 s1, s1, 5
	v_pk_mul_f32 v[40:41], v[30:31], v[154:155] op_sel_hi:[1,0]
	v_pk_mul_f32 v[30:31], v[28:29], v[154:155] op_sel_hi:[1,0]
	v_cvt_pk_bf16_f32 v28, v36, v37
	v_mad_i64_i32 v[36:37], s[24:25], v122, s53, v[44:45]
	v_cvt_pk_bf16_f32 v29, v38, v39
	v_cvt_pk_bf16_f32 v30, v30, v31
	v_cvt_pk_bf16_f32 v31, v40, v41
	v_lshl_add_u64 v[36:37], v[36:37], 0, v[136:137]
	global_store_dwordx4 v[36:37], v[28:31], off
	s_addk_i32 s0, 0xb0
	s_ashr_i32 s0, s0, 5
	v_mad_i64_i32 v[28:29], s[24:25], s1, v160, v[138:139]
	v_pk_mul_f32 v[30:31], v[34:35], v[152:153] op_sel_hi:[1,0]
	v_pk_mul_f32 v[34:35], v[26:27], v[152:153] op_sel_hi:[1,0]
	v_pk_mul_f32 v[26:27], v[24:25], v[152:153] op_sel_hi:[1,0]
	v_cvt_pk_bf16_f32 v24, v32, v33
	v_cvt_pk_bf16_f32 v25, v30, v31
	v_mad_i64_i32 v[30:31], s[24:25], v161, s53, v[28:29]
	v_cvt_pk_bf16_f32 v26, v26, v27
	v_cvt_pk_bf16_f32 v27, v34, v35
	global_store_dwordx4 v[30:31], v[24:27], off
	v_pk_mul_f32 v[16:17], v[16:17], v[150:151] op_sel_hi:[1,0]
	v_pk_mul_f32 v[4:5], v[4:5], v[150:151] op_sel_hi:[1,0]
	v_pk_mul_f32 v[24:25], v[14:15], v[152:153] op_sel_hi:[1,0]
	v_pk_mul_f32 v[14:15], v[12:13], v[152:153] op_sel_hi:[1,0]
	v_cvt_pk_bf16_f32 v12, v20, v21
	v_cvt_pk_bf16_f32 v13, v22, v23
	v_mad_i64_i32 v[20:21], s[24:25], v122, s53, v[28:29]
	v_cvt_pk_bf16_f32 v14, v14, v15
	v_cvt_pk_bf16_f32 v15, v24, v25
	global_store_dwordx4 v[20:21], v[12:15], off
	s_andn2_b64 vcc, exec, s[4:5]
	s_mov_b64 s[4:5], -1
	v_mad_i64_i32 v[12:13], s[0:1], s0, v160, v[140:141]
	v_pk_mul_f32 v[14:15], v[18:19], v[150:151] op_sel_hi:[1,0]
	v_pk_mul_f32 v[18:19], v[10:11], v[150:151] op_sel_hi:[1,0]
	v_pk_mul_f32 v[10:11], v[8:9], v[150:151] op_sel_hi:[1,0]
	v_cvt_pk_bf16_f32 v8, v16, v17
	v_cvt_pk_bf16_f32 v9, v14, v15
	v_mad_i64_i32 v[14:15], s[0:1], v161, s53, v[12:13]
	v_lshl_add_u64 v[14:15], v[14:15], 0, v[136:137]
	v_cvt_pk_bf16_f32 v10, v10, v11
	v_cvt_pk_bf16_f32 v11, v18, v19
	global_store_dwordx4 v[14:15], v[8:11], off
	v_pk_mul_f32 v[6:7], v[6:7], v[150:151] op_sel_hi:[1,0]
	s_nop 0
	v_pk_mul_f32 v[8:9], v[2:3], v[150:151] op_sel_hi:[1,0]
	v_pk_mul_f32 v[2:3], v[0:1], v[150:151] op_sel_hi:[1,0]
	v_cvt_pk_bf16_f32 v0, v4, v5
	v_mad_i64_i32 v[4:5], s[0:1], v122, s53, v[12:13]
	v_lshl_add_u64 v[4:5], v[4:5], 0, v[136:137]
	v_cvt_pk_bf16_f32 v1, v6, v7
	v_cvt_pk_bf16_f32 v2, v2, v3
	v_cvt_pk_bf16_f32 v3, v8, v9
	global_store_dwordx4 v[4:5], v[0:3], off
	s_cbranch_vccnz .LBB0_179
	s_andn2_b64 vcc, exec, s[2:3]
	s_cbranch_vccnz .LBB0_178
	s_mov_b32 s98, 1
	s_branch .LBB0_178

.LBB0_264:
	s_ashr_i32 s18, s49, 3
	s_ashr_i32 s19, s18, 31
	s_lshl_b64 s[18:19], s[18:19], 18
	s_add_u32 s24, s30, s18
	s_addc_u32 s25, s31, s19
	s_ashr_i32 s15, s14, 31
	s_lshl_b64 s[18:19], s[14:15], 18
	s_add_u32 s18, s24, s18
	s_addc_u32 s19, s25, s19
	s_and_b64 s[6:7], s[6:7], exec
	s_cselect_b32 s15, s19, s23
	s_cselect_b32 s50, s18, s22
	s_add_u32 s51, s22, 0x100
	s_addc_u32 s52, s23, 0
	s_mov_b32 s53, -2
	s_cmp_eq_u32 s98, 1
	s_cbranch_scc0 .Lrestag_265
	s_barrier
	s_mov_b32 s98, 0
.Lrestag_265:
	ds_read_b128 v[86:89], v84
	ds_read_b128 v[90:93], v84 offset:1024
	ds_read_b128 v[94:97], v84 offset:2048
	ds_read_b128 v[98:101], v84 offset:3072
	s_add_u32 s6, s20, 0x100
	s_addc_u32 s7, s21, 0
	s_cmp_eq_u32 s53, 4
	s_cselect_b32 s25, s17, s7
	s_cselect_b32 s24, s16, s6
	s_cselect_b32 s23, s15, s52
	s_cselect_b32 s22, s50, s51
	s_add_i32 m0, s34, 0xc000
	ds_read_b128 v[102:105], v85
	ds_read_b128 v[106:109], v85 offset:1024
	ds_read_b128 v[110:113], v85 offset:2048
	ds_read_b128 v[114:117], v85 offset:3072
	ds_read_b128 v[118:121], v85 offset:4096
	ds_read_b128 v[122:125], v85 offset:5120
	ds_read_b128 v[126:129], v85 offset:6144
	ds_read_b128 v[130:133], v85 offset:7168
	global_load_lds_dwordx4 v74, s[20:21]
	s_add_i32 m0, s34, 0xe000
	s_nop 0
	global_load_lds_dwordx4 v76, s[20:21]
	s_waitcnt vmcnt(8)
	s_waitcnt lgkmcnt(0)
	s_barrier
	s_setprio 1
	s_waitcnt lgkmcnt(0)
	v_mfma_f32_16x16x32_bf16 v[60:63], v[86:89], v[102:105], 0
	v_mfma_f32_16x16x32_bf16 v[56:59], v[94:97], v[102:105], 0
	v_mfma_f32_16x16x32_bf16 v[52:55], v[86:89], v[110:113], 0
	v_mfma_f32_16x16x32_bf16 v[48:51], v[94:97], v[110:113], 0
	v_mfma_f32_16x16x32_bf16 v[44:47], v[86:89], v[118:121], 0
	v_mfma_f32_16x16x32_bf16 v[40:43], v[94:97], v[118:121], 0
	v_mfma_f32_16x16x32_bf16 v[36:39], v[86:89], v[126:129], 0
	v_mfma_f32_16x16x32_bf16 v[32:35], v[94:97], v[126:129], 0
	v_mfma_f32_16x16x32_bf16 v[60:63], v[90:93], v[106:109], v[60:63]
	v_mfma_f32_16x16x32_bf16 v[56:59], v[98:101], v[106:109], v[56:59]
	v_mfma_f32_16x16x32_bf16 v[52:55], v[90:93], v[114:117], v[52:55]
	v_mfma_f32_16x16x32_bf16 v[48:51], v[98:101], v[114:117], v[48:51]
	v_mfma_f32_16x16x32_bf16 v[44:47], v[90:93], v[122:125], v[44:47]
	v_mfma_f32_16x16x32_bf16 v[40:43], v[98:101], v[122:125], v[40:43]
	v_mfma_f32_16x16x32_bf16 v[36:39], v[90:93], v[130:133], v[36:39]
	v_mfma_f32_16x16x32_bf16 v[32:35], v[98:101], v[130:133], v[32:35]
	s_setprio 0
	s_setprio 1
	s_setprio 0
	s_barrier
	s_add_i32 s20, s48, s33
	v_lshl_add_u64 v[134:135], s[22:23], 0, v[66:67]
	s_mov_b32 m0, s20
	ds_read_b128 v[102:105], v85 offset:16384
	ds_read_b128 v[106:109], v85 offset:17408
	ds_read_b128 v[110:113], v85 offset:18432
	ds_read_b128 v[114:117], v85 offset:19456
	ds_read_b128 v[118:121], v85 offset:20480
	ds_read_b128 v[122:125], v85 offset:21504
	ds_read_b128 v[126:129], v85 offset:22528
	ds_read_b128 v[130:133], v85 offset:23552
	global_load_lds_dwordx4 v[134:135], off
	s_add_i32 m0, s20, 0x2000
	s_add_u32 s20, s22, 0x20000
	v_lshl_add_u64 v[136:137], s[22:23], 0, v[70:71]
	s_addc_u32 s21, s23, 0
	global_load_lds_dwordx4 v[136:137], off
	s_mov_b32 m0, s35
	v_lshl_add_u64 v[140:141], s[24:25], 0, v[68:69]
	global_load_lds_dwordx4 v66, s[20:21]
	s_mov_b32 m0, s36
	s_nop 0
	global_load_lds_dwordx4 v70, s[20:21]
	v_lshl_add_u64 v[138:139], s[24:25], 0, v[64:65]
	s_mov_b32 m0, s34
	s_nop 0
	global_load_lds_dwordx4 v[138:139], off
	s_mov_b32 m0, s0
	s_nop 0
	global_load_lds_dwordx4 v[140:141], off
	s_waitcnt vmcnt(8)
	s_waitcnt lgkmcnt(0)
	s_barrier
	s_setprio 1
	s_waitcnt lgkmcnt(0)
	v_mfma_f32_16x16x32_bf16 v[28:31], v[86:89], v[102:105], 0
	v_mfma_f32_16x16x32_bf16 v[24:27], v[94:97], v[102:105], 0
	v_mfma_f32_16x16x32_bf16 v[20:23], v[86:89], v[110:113], 0
	v_mfma_f32_16x16x32_bf16 v[16:19], v[94:97], v[110:113], 0
	v_mfma_f32_16x16x32_bf16 v[12:15], v[86:89], v[118:121], 0
	v_mfma_f32_16x16x32_bf16 v[8:11], v[94:97], v[118:121], 0
	v_mfma_f32_16x16x32_bf16 v[4:7], v[86:89], v[126:129], 0
	v_mfma_f32_16x16x32_bf16 v[0:3], v[94:97], v[126:129], 0
	v_mfma_f32_16x16x32_bf16 v[28:31], v[90:93], v[106:109], v[28:31]
	v_mfma_f32_16x16x32_bf16 v[24:27], v[98:101], v[106:109], v[24:27]
	v_mfma_f32_16x16x32_bf16 v[20:23], v[90:93], v[114:117], v[20:23]
	v_mfma_f32_16x16x32_bf16 v[16:19], v[98:101], v[114:117], v[16:19]
	v_mfma_f32_16x16x32_bf16 v[12:15], v[90:93], v[122:125], v[12:15]
	v_mfma_f32_16x16x32_bf16 v[8:11], v[98:101], v[122:125], v[8:11]
	v_mfma_f32_16x16x32_bf16 v[4:7], v[90:93], v[130:133], v[4:7]
	v_mfma_f32_16x16x32_bf16 v[0:3], v[98:101], v[130:133], v[0:3]
	s_setprio 0
	s_setprio 1
	s_setprio 0
	s_barrier
	s_add_i32 s54, 0, 0x18000
	v_add_u32_e32 v98, s54, v83
	ds_read_b128 v[86:89], v98
	ds_read_b128 v[90:93], v98 offset:1024
	ds_read_b128 v[94:97], v98 offset:2048
	ds_read_b128 v[98:101], v98 offset:3072
	s_add_u32 s20, s24, 0x28000
	s_addc_u32 s21, s25, 0
	s_mov_b32 m0, s1
	ds_read_b128 v[102:105], v85 offset:32768
	ds_read_b128 v[106:109], v85 offset:33792
	ds_read_b128 v[110:113], v85 offset:34816
	ds_read_b128 v[114:117], v85 offset:35840
	ds_read_b128 v[118:121], v85 offset:36864
	ds_read_b128 v[122:125], v85 offset:37888
	ds_read_b128 v[126:129], v85 offset:38912
	ds_read_b128 v[130:133], v85 offset:39936
	global_load_lds_dwordx4 v64, s[20:21]
	s_mov_b32 m0, s37
	s_nop 0
	global_load_lds_dwordx4 v68, s[20:21]
	s_waitcnt vmcnt(8)
	s_waitcnt lgkmcnt(0)
	s_barrier
	s_setprio 1
	s_waitcnt lgkmcnt(0)
	v_mfma_f32_16x16x32_bf16 v[60:63], v[86:89], v[102:105], v[60:63]
	v_mfma_f32_16x16x32_bf16 v[56:59], v[94:97], v[102:105], v[56:59]
	v_mfma_f32_16x16x32_bf16 v[52:55], v[86:89], v[110:113], v[52:55]
	v_mfma_f32_16x16x32_bf16 v[48:51], v[94:97], v[110:113], v[48:51]
	v_mfma_f32_16x16x32_bf16 v[44:47], v[86:89], v[118:121], v[44:47]
	v_mfma_f32_16x16x32_bf16 v[40:43], v[94:97], v[118:121], v[40:43]
	v_mfma_f32_16x16x32_bf16 v[36:39], v[86:89], v[126:129], v[36:39]
	v_mfma_f32_16x16x32_bf16 v[32:35], v[94:97], v[126:129], v[32:35]
	v_mfma_f32_16x16x32_bf16 v[60:63], v[90:93], v[106:109], v[60:63]
	v_mfma_f32_16x16x32_bf16 v[56:59], v[98:101], v[106:109], v[56:59]
	v_mfma_f32_16x16x32_bf16 v[52:55], v[90:93], v[114:117], v[52:55]
	v_mfma_f32_16x16x32_bf16 v[48:51], v[98:101], v[114:117], v[48:51]
	v_mfma_f32_16x16x32_bf16 v[44:47], v[90:93], v[122:125], v[44:47]
	v_mfma_f32_16x16x32_bf16 v[40:43], v[98:101], v[122:125], v[40:43]
	v_mfma_f32_16x16x32_bf16 v[36:39], v[90:93], v[130:133], v[36:39]
	v_mfma_f32_16x16x32_bf16 v[32:35], v[98:101], v[130:133], v[32:35]
	s_setprio 0
	s_setprio 1
	s_setprio 0
	s_barrier
	s_add_i32 s20, s54, s33
	v_lshl_add_u64 v[134:135], v[134:135], 0, s[8:9]
	s_mov_b32 m0, s20
	ds_read_b128 v[102:105], v85 offset:49152
	ds_read_b128 v[106:109], v85 offset:50176
	ds_read_b128 v[110:113], v85 offset:51200
	ds_read_b128 v[114:117], v85 offset:52224
	ds_read_b128 v[118:121], v85 offset:53248
	ds_read_b128 v[122:125], v85 offset:54272
	ds_read_b128 v[126:129], v85 offset:55296
	ds_read_b128 v[130:133], v85 offset:56320
	global_load_lds_dwordx4 v[134:135], off
	s_add_i32 m0, s20, 0x2000
	s_add_u32 s20, s22, 0x20080
	v_lshl_add_u64 v[134:135], v[136:137], 0, s[8:9]
	s_addc_u32 s21, s23, 0
	global_load_lds_dwordx4 v[134:135], off
	s_mov_b32 m0, s44
	s_nop 0
	global_load_lds_dwordx4 v66, s[20:21]
	s_mov_b32 m0, s45
	s_nop 0
	global_load_lds_dwordx4 v70, s[20:21]
	v_lshl_add_u64 v[134:135], v[138:139], 0, s[8:9]
	s_mov_b32 m0, s42
	s_nop 0
	global_load_lds_dwordx4 v[134:135], off
	v_lshl_add_u64 v[134:135], v[140:141], 0, s[8:9]
	s_mov_b32 m0, s43
	s_nop 0
	global_load_lds_dwordx4 v[134:135], off
	s_waitcnt vmcnt(8)
	s_waitcnt lgkmcnt(0)
	s_barrier
	s_setprio 1
	s_waitcnt lgkmcnt(0)
	v_mfma_f32_16x16x32_bf16 v[28:31], v[86:89], v[102:105], v[28:31]
	v_mfma_f32_16x16x32_bf16 v[24:27], v[94:97], v[102:105], v[24:27]
	v_mfma_f32_16x16x32_bf16 v[20:23], v[86:89], v[110:113], v[20:23]
	v_mfma_f32_16x16x32_bf16 v[16:19], v[94:97], v[110:113], v[16:19]
	v_mfma_f32_16x16x32_bf16 v[12:15], v[86:89], v[118:121], v[12:15]
	v_mfma_f32_16x16x32_bf16 v[8:11], v[94:97], v[118:121], v[8:11]
	v_mfma_f32_16x16x32_bf16 v[4:7], v[86:89], v[126:129], v[4:7]
	v_mfma_f32_16x16x32_bf16 v[0:3], v[94:97], v[126:129], v[0:3]
	v_mfma_f32_16x16x32_bf16 v[28:31], v[90:93], v[106:109], v[28:31]
	v_mfma_f32_16x16x32_bf16 v[24:27], v[98:101], v[106:109], v[24:27]
	v_mfma_f32_16x16x32_bf16 v[20:23], v[90:93], v[114:117], v[20:23]
	v_mfma_f32_16x16x32_bf16 v[16:19], v[98:101], v[114:117], v[16:19]
	v_mfma_f32_16x16x32_bf16 v[12:15], v[90:93], v[122:125], v[12:15]
	v_mfma_f32_16x16x32_bf16 v[8:11], v[98:101], v[122:125], v[8:11]
	v_mfma_f32_16x16x32_bf16 v[4:7], v[90:93], v[130:133], v[4:7]
	v_mfma_f32_16x16x32_bf16 v[0:3], v[98:101], v[130:133], v[0:3]
	s_setprio 0
	s_setprio 1
	s_setprio 0
	s_barrier
	s_add_i32 s53, s53, 2
	s_add_u32 s51, s51, 0x100
	s_addc_u32 s52, s52, 0
	s_cmp_gt_u32 s53, 5
	s_mov_b64 s[20:21], s[6:7]
.LBB0_265:
	ds_read_b128 v[86:89], v84
	ds_read_b128 v[90:93], v84 offset:1024
	ds_read_b128 v[94:97], v84 offset:2048
	ds_read_b128 v[98:101], v84 offset:3072
	s_add_u32 s6, s20, 0x100
	s_addc_u32 s7, s21, 0
	s_cmp_eq_u32 s53, 4
	s_cselect_b32 s25, s17, s7
	s_cselect_b32 s24, s16, s6
	s_cselect_b32 s23, s15, s52
	s_cselect_b32 s22, s50, s51
	s_add_i32 m0, s34, 0xc000
	ds_read_b128 v[102:105], v85
	ds_read_b128 v[106:109], v85 offset:1024
	ds_read_b128 v[110:113], v85 offset:2048
	ds_read_b128 v[114:117], v85 offset:3072
	ds_read_b128 v[118:121], v85 offset:4096
	ds_read_b128 v[122:125], v85 offset:5120
	ds_read_b128 v[126:129], v85 offset:6144
	ds_read_b128 v[130:133], v85 offset:7168
	global_load_lds_dwordx4 v74, s[20:21]
	s_add_i32 m0, s34, 0xe000
	s_nop 0
	global_load_lds_dwordx4 v76, s[20:21]
	s_waitcnt vmcnt(8)
	s_waitcnt lgkmcnt(0)
	s_barrier
	s_setprio 1
	s_waitcnt lgkmcnt(0)
	v_mfma_f32_16x16x32_bf16 v[60:63], v[86:89], v[102:105], v[60:63]
	v_mfma_f32_16x16x32_bf16 v[56:59], v[94:97], v[102:105], v[56:59]
	v_mfma_f32_16x16x32_bf16 v[52:55], v[86:89], v[110:113], v[52:55]
	v_mfma_f32_16x16x32_bf16 v[48:51], v[94:97], v[110:113], v[48:51]
	v_mfma_f32_16x16x32_bf16 v[44:47], v[86:89], v[118:121], v[44:47]
	v_mfma_f32_16x16x32_bf16 v[40:43], v[94:97], v[118:121], v[40:43]
	v_mfma_f32_16x16x32_bf16 v[36:39], v[86:89], v[126:129], v[36:39]
	v_mfma_f32_16x16x32_bf16 v[32:35], v[94:97], v[126:129], v[32:35]
	v_mfma_f32_16x16x32_bf16 v[60:63], v[90:93], v[106:109], v[60:63]
	v_mfma_f32_16x16x32_bf16 v[56:59], v[98:101], v[106:109], v[56:59]
	v_mfma_f32_16x16x32_bf16 v[52:55], v[90:93], v[114:117], v[52:55]
	v_mfma_f32_16x16x32_bf16 v[48:51], v[98:101], v[114:117], v[48:51]
	v_mfma_f32_16x16x32_bf16 v[44:47], v[90:93], v[122:125], v[44:47]
	v_mfma_f32_16x16x32_bf16 v[40:43], v[98:101], v[122:125], v[40:43]
	v_mfma_f32_16x16x32_bf16 v[36:39], v[90:93], v[130:133], v[36:39]
	v_mfma_f32_16x16x32_bf16 v[32:35], v[98:101], v[130:133], v[32:35]
	s_setprio 0
	s_setprio 1
	s_setprio 0
	s_barrier
	s_add_i32 s20, s48, s33
	v_lshl_add_u64 v[134:135], s[22:23], 0, v[66:67]
	s_mov_b32 m0, s20
	ds_read_b128 v[102:105], v85 offset:16384
	ds_read_b128 v[106:109], v85 offset:17408
	ds_read_b128 v[110:113], v85 offset:18432
	ds_read_b128 v[114:117], v85 offset:19456
	ds_read_b128 v[118:121], v85 offset:20480
	ds_read_b128 v[122:125], v85 offset:21504
	ds_read_b128 v[126:129], v85 offset:22528
	ds_read_b128 v[130:133], v85 offset:23552
	global_load_lds_dwordx4 v[134:135], off
	s_add_i32 m0, s20, 0x2000
	s_add_u32 s20, s22, 0x20000
	v_lshl_add_u64 v[136:137], s[22:23], 0, v[70:71]
	s_addc_u32 s21, s23, 0
	global_load_lds_dwordx4 v[136:137], off
	s_mov_b32 m0, s35
	v_lshl_add_u64 v[140:141], s[24:25], 0, v[68:69]
	global_load_lds_dwordx4 v66, s[20:21]
	s_mov_b32 m0, s36
	s_nop 0
	global_load_lds_dwordx4 v70, s[20:21]
	v_lshl_add_u64 v[138:139], s[24:25], 0, v[64:65]
	s_mov_b32 m0, s34
	s_nop 0
	global_load_lds_dwordx4 v[138:139], off
	s_mov_b32 m0, s0
	s_nop 0
	global_load_lds_dwordx4 v[140:141], off
	s_waitcnt vmcnt(8)
	s_waitcnt lgkmcnt(0)
	s_barrier
	s_setprio 1
	s_waitcnt lgkmcnt(0)
	v_mfma_f32_16x16x32_bf16 v[28:31], v[86:89], v[102:105], v[28:31]
	v_mfma_f32_16x16x32_bf16 v[24:27], v[94:97], v[102:105], v[24:27]
	v_mfma_f32_16x16x32_bf16 v[20:23], v[86:89], v[110:113], v[20:23]
	v_mfma_f32_16x16x32_bf16 v[16:19], v[94:97], v[110:113], v[16:19]
	v_mfma_f32_16x16x32_bf16 v[12:15], v[86:89], v[118:121], v[12:15]
	v_mfma_f32_16x16x32_bf16 v[8:11], v[94:97], v[118:121], v[8:11]
	v_mfma_f32_16x16x32_bf16 v[4:7], v[86:89], v[126:129], v[4:7]
	v_mfma_f32_16x16x32_bf16 v[0:3], v[94:97], v[126:129], v[0:3]
	v_mfma_f32_16x16x32_bf16 v[28:31], v[90:93], v[106:109], v[28:31]
	v_mfma_f32_16x16x32_bf16 v[24:27], v[98:101], v[106:109], v[24:27]
	v_mfma_f32_16x16x32_bf16 v[20:23], v[90:93], v[114:117], v[20:23]
	v_mfma_f32_16x16x32_bf16 v[16:19], v[98:101], v[114:117], v[16:19]
	v_mfma_f32_16x16x32_bf16 v[12:15], v[90:93], v[122:125], v[12:15]
	v_mfma_f32_16x16x32_bf16 v[8:11], v[98:101], v[122:125], v[8:11]
	v_mfma_f32_16x16x32_bf16 v[4:7], v[90:93], v[130:133], v[4:7]
	v_mfma_f32_16x16x32_bf16 v[0:3], v[98:101], v[130:133], v[0:3]
	s_setprio 0
	s_setprio 1
	s_setprio 0
	s_barrier
	s_add_i32 s54, 0, 0x18000
	v_add_u32_e32 v98, s54, v83
	ds_read_b128 v[86:89], v98
	ds_read_b128 v[90:93], v98 offset:1024
	ds_read_b128 v[94:97], v98 offset:2048
	ds_read_b128 v[98:101], v98 offset:3072
	s_add_u32 s20, s24, 0x28000
	s_addc_u32 s21, s25, 0
	s_mov_b32 m0, s1
	ds_read_b128 v[102:105], v85 offset:32768
	ds_read_b128 v[106:109], v85 offset:33792
	ds_read_b128 v[110:113], v85 offset:34816
	ds_read_b128 v[114:117], v85 offset:35840
	ds_read_b128 v[118:121], v85 offset:36864
	ds_read_b128 v[122:125], v85 offset:37888
	ds_read_b128 v[126:129], v85 offset:38912
	ds_read_b128 v[130:133], v85 offset:39936
	global_load_lds_dwordx4 v64, s[20:21]
	s_mov_b32 m0, s37
	s_nop 0
	global_load_lds_dwordx4 v68, s[20:21]
	s_waitcnt vmcnt(8)
	s_waitcnt lgkmcnt(0)
	s_barrier
	s_setprio 1
	s_waitcnt lgkmcnt(0)
	v_mfma_f32_16x16x32_bf16 v[60:63], v[86:89], v[102:105], v[60:63]
	v_mfma_f32_16x16x32_bf16 v[56:59], v[94:97], v[102:105], v[56:59]
	v_mfma_f32_16x16x32_bf16 v[52:55], v[86:89], v[110:113], v[52:55]
	v_mfma_f32_16x16x32_bf16 v[48:51], v[94:97], v[110:113], v[48:51]
	v_mfma_f32_16x16x32_bf16 v[44:47], v[86:89], v[118:121], v[44:47]
	v_mfma_f32_16x16x32_bf16 v[40:43], v[94:97], v[118:121], v[40:43]
	v_mfma_f32_16x16x32_bf16 v[36:39], v[86:89], v[126:129], v[36:39]
	v_mfma_f32_16x16x32_bf16 v[32:35], v[94:97], v[126:129], v[32:35]
	v_mfma_f32_16x16x32_bf16 v[60:63], v[90:93], v[106:109], v[60:63]
	v_mfma_f32_16x16x32_bf16 v[56:59], v[98:101], v[106:109], v[56:59]
	v_mfma_f32_16x16x32_bf16 v[52:55], v[90:93], v[114:117], v[52:55]
	v_mfma_f32_16x16x32_bf16 v[48:51], v[98:101], v[114:117], v[48:51]
	v_mfma_f32_16x16x32_bf16 v[44:47], v[90:93], v[122:125], v[44:47]
	v_mfma_f32_16x16x32_bf16 v[40:43], v[98:101], v[122:125], v[40:43]
	v_mfma_f32_16x16x32_bf16 v[36:39], v[90:93], v[130:133], v[36:39]
	v_mfma_f32_16x16x32_bf16 v[32:35], v[98:101], v[130:133], v[32:35]
	s_setprio 0
	s_setprio 1
	s_setprio 0
	s_barrier
	s_add_i32 s20, s54, s33
	v_lshl_add_u64 v[134:135], v[134:135], 0, s[8:9]
	s_mov_b32 m0, s20
	ds_read_b128 v[102:105], v85 offset:49152
	ds_read_b128 v[106:109], v85 offset:50176
	ds_read_b128 v[110:113], v85 offset:51200
	ds_read_b128 v[114:117], v85 offset:52224
	ds_read_b128 v[118:121], v85 offset:53248
	ds_read_b128 v[122:125], v85 offset:54272
	ds_read_b128 v[126:129], v85 offset:55296
	ds_read_b128 v[130:133], v85 offset:56320
	global_load_lds_dwordx4 v[134:135], off
	s_add_i32 m0, s20, 0x2000
	s_add_u32 s20, s22, 0x20080
	v_lshl_add_u64 v[134:135], v[136:137], 0, s[8:9]
	s_addc_u32 s21, s23, 0
	global_load_lds_dwordx4 v[134:135], off
	s_mov_b32 m0, s44
	s_nop 0
	global_load_lds_dwordx4 v66, s[20:21]
	s_mov_b32 m0, s45
	s_nop 0
	global_load_lds_dwordx4 v70, s[20:21]
	v_lshl_add_u64 v[134:135], v[138:139], 0, s[8:9]
	s_mov_b32 m0, s42
	s_nop 0
	global_load_lds_dwordx4 v[134:135], off
	v_lshl_add_u64 v[134:135], v[140:141], 0, s[8:9]
	s_mov_b32 m0, s43
	s_nop 0
	global_load_lds_dwordx4 v[134:135], off
	s_waitcnt vmcnt(8)
	s_waitcnt lgkmcnt(0)
	s_barrier
	s_setprio 1
	s_waitcnt lgkmcnt(0)
	v_mfma_f32_16x16x32_bf16 v[28:31], v[86:89], v[102:105], v[28:31]
	v_mfma_f32_16x16x32_bf16 v[24:27], v[94:97], v[102:105], v[24:27]
	v_mfma_f32_16x16x32_bf16 v[20:23], v[86:89], v[110:113], v[20:23]
	v_mfma_f32_16x16x32_bf16 v[16:19], v[94:97], v[110:113], v[16:19]
	v_mfma_f32_16x16x32_bf16 v[12:15], v[86:89], v[118:121], v[12:15]
	v_mfma_f32_16x16x32_bf16 v[8:11], v[94:97], v[118:121], v[8:11]
	v_mfma_f32_16x16x32_bf16 v[4:7], v[86:89], v[126:129], v[4:7]
	v_mfma_f32_16x16x32_bf16 v[0:3], v[94:97], v[126:129], v[0:3]
	v_mfma_f32_16x16x32_bf16 v[28:31], v[90:93], v[106:109], v[28:31]
	v_mfma_f32_16x16x32_bf16 v[24:27], v[98:101], v[106:109], v[24:27]
	v_mfma_f32_16x16x32_bf16 v[20:23], v[90:93], v[114:117], v[20:23]
	v_mfma_f32_16x16x32_bf16 v[16:19], v[98:101], v[114:117], v[16:19]
	v_mfma_f32_16x16x32_bf16 v[12:15], v[90:93], v[122:125], v[12:15]
	v_mfma_f32_16x16x32_bf16 v[8:11], v[98:101], v[122:125], v[8:11]
	v_mfma_f32_16x16x32_bf16 v[4:7], v[90:93], v[130:133], v[4:7]
	v_mfma_f32_16x16x32_bf16 v[0:3], v[98:101], v[130:133], v[0:3]
	s_setprio 0
	s_setprio 1
	s_setprio 0
	s_barrier
	s_add_i32 s53, s53, 2
	s_add_u32 s51, s51, 0x100
	s_addc_u32 s52, s52, 0
	s_cmp_gt_u32 s53, 5
	s_mov_b64 s[20:21], s[6:7]
	s_cbranch_scc0 .LBB0_265
	s_and_b64 vcc, exec, s[12:13]
	s_cbranch_vccz .LBB0_268
	s_barrier
.LBB0_268:
	v_lshl_add_u32 v86, s41, 8, v82
	v_ashrrev_i32_e32 v87, 31, v86
	v_lshlrev_b64 v[88:89], 9, v[86:87]
	v_lshl_add_u64 v[88:89], v[72:73], 0, v[88:89]
	global_store_dwordx4 v[88:89], v[60:63], off
	global_store_dwordx4 v[88:89], v[56:59], off offset:64
	s_and_b64 vcc, exec, s[4:5]
	s_mov_b64 s[4:5], -1
	v_or_b32_e32 v56, 16, v86
	v_ashrrev_i32_e32 v57, 31, v56
	v_lshlrev_b64 v[56:57], 9, v[56:57]
	v_lshl_add_u64 v[56:57], v[72:73], 0, v[56:57]
	global_store_dwordx4 v[56:57], v[52:55], off
	global_store_dwordx4 v[56:57], v[48:51], off offset:64
	s_nop 1
	v_or_b32_e32 v48, 32, v86
	v_ashrrev_i32_e32 v49, 31, v48
	v_lshlrev_b64 v[48:49], 9, v[48:49]
	v_lshl_add_u64 v[48:49], v[72:73], 0, v[48:49]
	global_store_dwordx4 v[48:49], v[44:47], off
	global_store_dwordx4 v[48:49], v[40:43], off offset:64
	s_nop 1
	v_or_b32_e32 v40, 48, v86
	v_ashrrev_i32_e32 v41, 31, v40
	v_lshlrev_b64 v[40:41], 9, v[40:41]
	v_lshl_add_u64 v[40:41], v[72:73], 0, v[40:41]
	global_store_dwordx4 v[40:41], v[36:39], off
	global_store_dwordx4 v[40:41], v[32:35], off offset:64
	s_nop 1
	v_add_u32_e32 v32, 0x80, v86
	v_ashrrev_i32_e32 v33, 31, v32
	v_lshlrev_b64 v[32:33], 9, v[32:33]
	v_lshl_add_u64 v[32:33], v[72:73], 0, v[32:33]
	global_store_dwordx4 v[32:33], v[28:31], off
	global_store_dwordx4 v[32:33], v[24:27], off offset:64
	s_nop 1
	v_add_u32_e32 v24, 0x90, v86
	v_ashrrev_i32_e32 v25, 31, v24
	v_lshlrev_b64 v[24:25], 9, v[24:25]
	v_lshl_add_u64 v[24:25], v[72:73], 0, v[24:25]
	global_store_dwordx4 v[24:25], v[20:23], off
	global_store_dwordx4 v[24:25], v[16:19], off offset:64
	s_nop 1
	v_add_u32_e32 v16, 0xa0, v86
	v_ashrrev_i32_e32 v17, 31, v16
	v_lshlrev_b64 v[16:17], 9, v[16:17]
	v_lshl_add_u64 v[16:17], v[72:73], 0, v[16:17]
	global_store_dwordx4 v[16:17], v[12:15], off
	global_store_dwordx4 v[16:17], v[8:11], off offset:64
	s_nop 1
	v_add_u32_e32 v8, 0xb0, v86
	v_ashrrev_i32_e32 v9, 31, v8
	v_lshlrev_b64 v[8:9], 9, v[8:9]
	v_lshl_add_u64 v[8:9], v[72:73], 0, v[8:9]
	global_store_dwordx4 v[8:9], v[4:7], off
	global_store_dwordx4 v[8:9], v[0:3], off offset:64
	s_cbranch_vccnz .LBB0_255
	s_andn2_b64 vcc, exec, s[2:3]
	s_cbranch_vccnz .LBB0_254
	s_mov_b32 s98, 1
	s_branch .LBB0_254

.LBB0_401:
	s_add_u32 s52, s22, 0x100
	s_addc_u32 s53, s23, 0
	s_mov_b32 s54, -2
	s_cmp_eq_u32 s98, 1
	s_cbranch_scc0 .Lrestag_402
	s_barrier
	s_mov_b32 s98, 0
.Lrestag_402:
	ds_read_b128 v[120:123], v205
	ds_read_b128 v[124:127], v205 offset:1024
	ds_read_b128 v[132:135], v205 offset:2048
	ds_read_b128 v[140:143], v205 offset:3072
	ds_read_b128 v[144:147], v206
	ds_read_b128 v[148:151], v206 offset:1024
	ds_read_b128 v[152:155], v206 offset:2048
	ds_read_b128 v[156:159], v206 offset:3072
	s_add_u32 s22, s20, 0x100
	s_addc_u32 s23, s21, 0
	s_cmp_eq_u32 s54, 6
	s_cselect_b32 s27, s7, s23
	s_cselect_b32 s26, s6, s22
	s_cselect_b32 s25, s19, s53
	s_cselect_b32 s24, s18, s52
	s_add_i32 m0, s35, 0xc000
	ds_read_b128 v[180:183], v207
	ds_read_b128 v[184:187], v207 offset:1024
	ds_read_b128 v[188:191], v207 offset:2048
	ds_read_b128 v[192:195], v207 offset:3072
	ds_read_b128 v[196:199], v207 offset:4096
	ds_read_b128 v[208:211], v207 offset:5120
	ds_read_b128 v[212:215], v207 offset:6144
	ds_read_b128 v[216:219], v207 offset:7168
	global_load_lds_dwordx4 v172, s[20:21]
	s_add_i32 m0, s35, 0xe000
	s_nop 0
	global_load_lds_dwordx4 v174, s[20:21]
	s_nop 0
	s_waitcnt lgkmcnt(0)
	s_barrier
	s_setprio 1
	s_waitcnt lgkmcnt(0)
	v_mfma_f32_16x16x32_bf16 v[136:139], v[120:123], v[180:183], 0
	v_mfma_f32_16x16x32_bf16 v[128:131], v[132:135], v[180:183], 0
	v_mfma_f32_16x16x32_bf16 v[116:119], v[120:123], v[188:191], 0
	v_mfma_f32_16x16x32_bf16 v[112:115], v[132:135], v[188:191], 0
	v_mfma_f32_16x16x32_bf16 v[108:111], v[120:123], v[196:199], 0
	v_mfma_f32_16x16x32_bf16 v[104:107], v[132:135], v[196:199], 0
	v_mfma_f32_16x16x32_bf16 v[100:103], v[120:123], v[212:215], 0
	v_mfma_f32_16x16x32_bf16 v[96:99], v[132:135], v[212:215], 0
	v_mfma_f32_16x16x32_bf16 v[136:139], v[124:127], v[184:187], v[136:139]
	v_mfma_f32_16x16x32_bf16 v[128:131], v[140:143], v[184:187], v[128:131]
	v_mfma_f32_16x16x32_bf16 v[116:119], v[124:127], v[192:195], v[116:119]
	v_mfma_f32_16x16x32_bf16 v[112:115], v[140:143], v[192:195], v[112:115]
	v_mfma_f32_16x16x32_bf16 v[108:111], v[124:127], v[208:211], v[108:111]
	v_mfma_f32_16x16x32_bf16 v[104:107], v[140:143], v[208:211], v[104:107]
	v_mfma_f32_16x16x32_bf16 v[100:103], v[124:127], v[216:219], v[100:103]
	v_mfma_f32_16x16x32_bf16 v[96:99], v[140:143], v[216:219], v[96:99]
	s_setprio 0
	s_setprio 1
	v_mfma_f32_16x16x32_bf16 v[60:63], v[144:147], v[180:183], 0
	v_mfma_f32_16x16x32_bf16 v[56:59], v[152:155], v[180:183], 0
	v_mfma_f32_16x16x32_bf16 v[52:55], v[144:147], v[188:191], 0
	v_mfma_f32_16x16x32_bf16 v[48:51], v[152:155], v[188:191], 0
	v_mfma_f32_16x16x32_bf16 v[44:47], v[144:147], v[196:199], 0
	v_mfma_f32_16x16x32_bf16 v[40:43], v[152:155], v[196:199], 0
	v_mfma_f32_16x16x32_bf16 v[36:39], v[144:147], v[212:215], 0
	v_mfma_f32_16x16x32_bf16 v[32:35], v[152:155], v[212:215], 0
	v_mfma_f32_16x16x32_bf16 v[60:63], v[148:151], v[184:187], v[60:63]
	v_mfma_f32_16x16x32_bf16 v[56:59], v[156:159], v[184:187], v[56:59]
	v_mfma_f32_16x16x32_bf16 v[52:55], v[148:151], v[192:195], v[52:55]
	v_mfma_f32_16x16x32_bf16 v[48:51], v[156:159], v[192:195], v[48:51]
	v_mfma_f32_16x16x32_bf16 v[44:47], v[148:151], v[208:211], v[44:47]
	v_mfma_f32_16x16x32_bf16 v[40:43], v[156:159], v[208:211], v[40:43]
	v_mfma_f32_16x16x32_bf16 v[36:39], v[148:151], v[216:219], v[36:39]
	v_mfma_f32_16x16x32_bf16 v[32:35], v[156:159], v[216:219], v[32:35]
	s_setprio 0
	s_barrier
	s_add_i32 s0, s46, s34
	v_lshl_add_u64 v[200:201], s[24:25], 0, v[162:163]
	s_mov_b32 m0, s0
	ds_read_b128 v[180:183], v207 offset:16384
	ds_read_b128 v[184:187], v207 offset:17408
	ds_read_b128 v[188:191], v207 offset:18432
	ds_read_b128 v[192:195], v207 offset:19456
	ds_read_b128 v[196:199], v207 offset:20480
	ds_read_b128 v[208:211], v207 offset:21504
	ds_read_b128 v[212:215], v207 offset:22528
	ds_read_b128 v[216:219], v207 offset:23552
	global_load_lds_dwordx4 v[200:201], off
	s_add_i32 m0, s0, 0x2000
	s_add_u32 s0, s24, 0x28000
	v_lshl_add_u64 v[220:221], s[24:25], 0, v[166:167]
	s_addc_u32 s1, s25, 0
	s_add_i32 s20, s47, s34
	global_load_lds_dwordx4 v[220:221], off
	s_mov_b32 m0, s20
	v_lshl_add_u64 v[224:225], s[26:27], 0, v[164:165]
	global_load_lds_dwordx4 v162, s[0:1]
	s_add_i32 m0, s20, 0x2000
	s_nop 0
	global_load_lds_dwordx4 v166, s[0:1]
	v_lshl_add_u64 v[222:223], s[26:27], 0, v[160:161]
	s_nop 0
	s_waitcnt lgkmcnt(0)
	s_barrier
	s_setprio 1
	s_waitcnt lgkmcnt(0)
	v_mfma_f32_16x16x32_bf16 v[92:95], v[120:123], v[180:183], 0
	v_mfma_f32_16x16x32_bf16 v[88:91], v[132:135], v[180:183], 0
	v_mfma_f32_16x16x32_bf16 v[84:87], v[120:123], v[188:191], 0
	v_mfma_f32_16x16x32_bf16 v[80:83], v[132:135], v[188:191], 0
	v_mfma_f32_16x16x32_bf16 v[76:79], v[120:123], v[196:199], 0
	v_mfma_f32_16x16x32_bf16 v[72:75], v[132:135], v[196:199], 0
	v_mfma_f32_16x16x32_bf16 v[68:71], v[120:123], v[212:215], 0
	v_mfma_f32_16x16x32_bf16 v[64:67], v[132:135], v[212:215], 0
	v_mfma_f32_16x16x32_bf16 v[92:95], v[124:127], v[184:187], v[92:95]
	v_mfma_f32_16x16x32_bf16 v[88:91], v[140:143], v[184:187], v[88:91]
	v_mfma_f32_16x16x32_bf16 v[84:87], v[124:127], v[192:195], v[84:87]
	v_mfma_f32_16x16x32_bf16 v[80:83], v[140:143], v[192:195], v[80:83]
	v_mfma_f32_16x16x32_bf16 v[76:79], v[124:127], v[208:211], v[76:79]
	v_mfma_f32_16x16x32_bf16 v[72:75], v[140:143], v[208:211], v[72:75]
	v_mfma_f32_16x16x32_bf16 v[68:71], v[124:127], v[216:219], v[68:71]
	v_mfma_f32_16x16x32_bf16 v[64:67], v[140:143], v[216:219], v[64:67]
	s_setprio 0
	s_setprio 1
	v_mfma_f32_16x16x32_bf16 v[28:31], v[144:147], v[180:183], 0
	v_mfma_f32_16x16x32_bf16 v[24:27], v[152:155], v[180:183], 0
	v_mfma_f32_16x16x32_bf16 v[20:23], v[144:147], v[188:191], 0
	v_mfma_f32_16x16x32_bf16 v[16:19], v[152:155], v[188:191], 0
	v_mfma_f32_16x16x32_bf16 v[12:15], v[144:147], v[196:199], 0
	v_mfma_f32_16x16x32_bf16 v[8:11], v[152:155], v[196:199], 0
	v_mfma_f32_16x16x32_bf16 v[4:7], v[144:147], v[212:215], 0
	v_mfma_f32_16x16x32_bf16 v[0:3], v[152:155], v[212:215], 0
	v_mfma_f32_16x16x32_bf16 v[28:31], v[148:151], v[184:187], v[28:31]
	v_mfma_f32_16x16x32_bf16 v[24:27], v[156:159], v[184:187], v[24:27]
	v_mfma_f32_16x16x32_bf16 v[20:23], v[148:151], v[192:195], v[20:23]
	v_mfma_f32_16x16x32_bf16 v[16:19], v[156:159], v[192:195], v[16:19]
	v_mfma_f32_16x16x32_bf16 v[12:15], v[148:151], v[208:211], v[12:15]
	v_mfma_f32_16x16x32_bf16 v[8:11], v[156:159], v[208:211], v[8:11]
	v_mfma_f32_16x16x32_bf16 v[4:7], v[148:151], v[216:219], v[4:7]
	v_mfma_f32_16x16x32_bf16 v[0:3], v[156:159], v[216:219], v[0:3]
	s_setprio 0
	s_barrier
	s_add_i32 s20, 0, 0x18000
	s_add_i32 s21, 0, 0x1c000
	v_add_u32_e32 v140, s20, v203
	v_add_u32_e32 v156, s21, v203
	ds_read_b128 v[120:123], v140
	ds_read_b128 v[124:127], v140 offset:1024
	ds_read_b128 v[132:135], v140 offset:2048
	ds_read_b128 v[140:143], v140 offset:3072
	ds_read_b128 v[144:147], v156
	ds_read_b128 v[148:151], v156 offset:1024
	ds_read_b128 v[152:155], v156 offset:2048
	ds_read_b128 v[156:159], v156 offset:3072
	s_add_u32 s0, s26, 0x28000
	s_addc_u32 s1, s27, 0
	s_mov_b32 m0, s37
	ds_read_b128 v[180:183], v207 offset:32768
	ds_read_b128 v[184:187], v207 offset:33792
	ds_read_b128 v[188:191], v207 offset:34816
	ds_read_b128 v[192:195], v207 offset:35840
	ds_read_b128 v[196:199], v207 offset:36864
	ds_read_b128 v[208:211], v207 offset:37888
	ds_read_b128 v[212:215], v207 offset:38912
	ds_read_b128 v[216:219], v207 offset:39936
	global_load_lds_dwordx4 v160, s[0:1]
	s_mov_b32 m0, s40
	s_nop 0
	global_load_lds_dwordx4 v164, s[0:1]
	s_mov_b32 m0, s35
	s_nop 0
	global_load_lds_dwordx4 v[222:223], off
	s_mov_b32 m0, s36
	s_nop 0
	global_load_lds_dwordx4 v[224:225], off
	s_waitcnt vmcnt(8)
	s_waitcnt lgkmcnt(0)
	s_barrier
	s_setprio 1
	s_waitcnt lgkmcnt(0)
	v_mfma_f32_16x16x32_bf16 v[136:139], v[120:123], v[180:183], v[136:139]
	v_mfma_f32_16x16x32_bf16 v[128:131], v[132:135], v[180:183], v[128:131]
	v_mfma_f32_16x16x32_bf16 v[116:119], v[120:123], v[188:191], v[116:119]
	v_mfma_f32_16x16x32_bf16 v[112:115], v[132:135], v[188:191], v[112:115]
	v_mfma_f32_16x16x32_bf16 v[108:111], v[120:123], v[196:199], v[108:111]
	v_mfma_f32_16x16x32_bf16 v[104:107], v[132:135], v[196:199], v[104:107]
	v_mfma_f32_16x16x32_bf16 v[100:103], v[120:123], v[212:215], v[100:103]
	v_mfma_f32_16x16x32_bf16 v[96:99], v[132:135], v[212:215], v[96:99]
	v_mfma_f32_16x16x32_bf16 v[136:139], v[124:127], v[184:187], v[136:139]
	v_mfma_f32_16x16x32_bf16 v[128:131], v[140:143], v[184:187], v[128:131]
	v_mfma_f32_16x16x32_bf16 v[116:119], v[124:127], v[192:195], v[116:119]
	v_mfma_f32_16x16x32_bf16 v[112:115], v[140:143], v[192:195], v[112:115]
	v_mfma_f32_16x16x32_bf16 v[108:111], v[124:127], v[208:211], v[108:111]
	v_mfma_f32_16x16x32_bf16 v[104:107], v[140:143], v[208:211], v[104:107]
	v_mfma_f32_16x16x32_bf16 v[100:103], v[124:127], v[216:219], v[100:103]
	v_mfma_f32_16x16x32_bf16 v[96:99], v[140:143], v[216:219], v[96:99]
	s_setprio 0
	s_setprio 1
	v_mfma_f32_16x16x32_bf16 v[60:63], v[144:147], v[180:183], v[60:63]
	v_mfma_f32_16x16x32_bf16 v[56:59], v[152:155], v[180:183], v[56:59]
	v_mfma_f32_16x16x32_bf16 v[52:55], v[144:147], v[188:191], v[52:55]
	v_mfma_f32_16x16x32_bf16 v[48:51], v[152:155], v[188:191], v[48:51]
	v_mfma_f32_16x16x32_bf16 v[44:47], v[144:147], v[196:199], v[44:47]
	v_mfma_f32_16x16x32_bf16 v[40:43], v[152:155], v[196:199], v[40:43]
	v_mfma_f32_16x16x32_bf16 v[36:39], v[144:147], v[212:215], v[36:39]
	v_mfma_f32_16x16x32_bf16 v[32:35], v[152:155], v[212:215], v[32:35]
	v_mfma_f32_16x16x32_bf16 v[60:63], v[148:151], v[184:187], v[60:63]
	v_mfma_f32_16x16x32_bf16 v[56:59], v[156:159], v[184:187], v[56:59]
	v_mfma_f32_16x16x32_bf16 v[52:55], v[148:151], v[192:195], v[52:55]
	v_mfma_f32_16x16x32_bf16 v[48:51], v[156:159], v[192:195], v[48:51]
	v_mfma_f32_16x16x32_bf16 v[44:47], v[148:151], v[208:211], v[44:47]
	v_mfma_f32_16x16x32_bf16 v[40:43], v[156:159], v[208:211], v[40:43]
	v_mfma_f32_16x16x32_bf16 v[36:39], v[148:151], v[216:219], v[36:39]
	v_mfma_f32_16x16x32_bf16 v[32:35], v[156:159], v[216:219], v[32:35]
	s_setprio 0
	s_barrier
	s_add_i32 s0, s20, s34
	v_lshl_add_u64 v[200:201], v[200:201], 0, s[14:15]
	s_mov_b32 m0, s0
	ds_read_b128 v[180:183], v207 offset:49152
	ds_read_b128 v[184:187], v207 offset:50176
	ds_read_b128 v[188:191], v207 offset:51200
	ds_read_b128 v[192:195], v207 offset:52224
	ds_read_b128 v[196:199], v207 offset:53248
	ds_read_b128 v[208:211], v207 offset:54272
	ds_read_b128 v[212:215], v207 offset:55296
	ds_read_b128 v[216:219], v207 offset:56320
	global_load_lds_dwordx4 v[200:201], off
	s_add_i32 m0, s0, 0x2000
	s_add_u32 s0, s24, 0x28080
	v_lshl_add_u64 v[200:201], v[220:221], 0, s[14:15]
	s_addc_u32 s1, s25, 0
	s_add_i32 s20, s21, s34
	global_load_lds_dwordx4 v[200:201], off
	s_mov_b32 m0, s20
	s_nop 0
	global_load_lds_dwordx4 v162, s[0:1]
	s_add_i32 m0, s20, 0x2000
	s_nop 0
	global_load_lds_dwordx4 v166, s[0:1]
	v_lshl_add_u64 v[200:201], v[222:223], 0, s[14:15]
	s_mov_b32 m0, s42
	s_nop 0
	global_load_lds_dwordx4 v[200:201], off
	v_lshl_add_u64 v[200:201], v[224:225], 0, s[14:15]
	s_mov_b32 m0, s43
	s_nop 0
	global_load_lds_dwordx4 v[200:201], off
	s_waitcnt vmcnt(6)
	s_waitcnt lgkmcnt(0)
	s_barrier
	s_setprio 1
	s_waitcnt lgkmcnt(0)
	v_mfma_f32_16x16x32_bf16 v[92:95], v[120:123], v[180:183], v[92:95]
	v_mfma_f32_16x16x32_bf16 v[88:91], v[132:135], v[180:183], v[88:91]
	v_mfma_f32_16x16x32_bf16 v[84:87], v[120:123], v[188:191], v[84:87]
	v_mfma_f32_16x16x32_bf16 v[80:83], v[132:135], v[188:191], v[80:83]
	v_mfma_f32_16x16x32_bf16 v[76:79], v[120:123], v[196:199], v[76:79]
	v_mfma_f32_16x16x32_bf16 v[72:75], v[132:135], v[196:199], v[72:75]
	v_mfma_f32_16x16x32_bf16 v[68:71], v[120:123], v[212:215], v[68:71]
	v_mfma_f32_16x16x32_bf16 v[64:67], v[132:135], v[212:215], v[64:67]
	v_mfma_f32_16x16x32_bf16 v[92:95], v[124:127], v[184:187], v[92:95]
	v_mfma_f32_16x16x32_bf16 v[88:91], v[140:143], v[184:187], v[88:91]
	v_mfma_f32_16x16x32_bf16 v[84:87], v[124:127], v[192:195], v[84:87]
	v_mfma_f32_16x16x32_bf16 v[80:83], v[140:143], v[192:195], v[80:83]
	v_mfma_f32_16x16x32_bf16 v[76:79], v[124:127], v[208:211], v[76:79]
	v_mfma_f32_16x16x32_bf16 v[72:75], v[140:143], v[208:211], v[72:75]
	v_mfma_f32_16x16x32_bf16 v[68:71], v[124:127], v[216:219], v[68:71]
	v_mfma_f32_16x16x32_bf16 v[64:67], v[140:143], v[216:219], v[64:67]
	s_setprio 0
	s_setprio 1
	v_mfma_f32_16x16x32_bf16 v[28:31], v[144:147], v[180:183], v[28:31]
	v_mfma_f32_16x16x32_bf16 v[24:27], v[152:155], v[180:183], v[24:27]
	v_mfma_f32_16x16x32_bf16 v[20:23], v[144:147], v[188:191], v[20:23]
	v_mfma_f32_16x16x32_bf16 v[16:19], v[152:155], v[188:191], v[16:19]
	v_mfma_f32_16x16x32_bf16 v[12:15], v[144:147], v[196:199], v[12:15]
	v_mfma_f32_16x16x32_bf16 v[8:11], v[152:155], v[196:199], v[8:11]
	v_mfma_f32_16x16x32_bf16 v[4:7], v[144:147], v[212:215], v[4:7]
	v_mfma_f32_16x16x32_bf16 v[0:3], v[152:155], v[212:215], v[0:3]
	v_mfma_f32_16x16x32_bf16 v[28:31], v[148:151], v[184:187], v[28:31]
	v_mfma_f32_16x16x32_bf16 v[24:27], v[156:159], v[184:187], v[24:27]
	v_mfma_f32_16x16x32_bf16 v[20:23], v[148:151], v[192:195], v[20:23]
	v_mfma_f32_16x16x32_bf16 v[16:19], v[156:159], v[192:195], v[16:19]
	v_mfma_f32_16x16x32_bf16 v[12:15], v[148:151], v[208:211], v[12:15]
	v_mfma_f32_16x16x32_bf16 v[8:11], v[156:159], v[208:211], v[8:11]
	v_mfma_f32_16x16x32_bf16 v[4:7], v[148:151], v[216:219], v[4:7]
	v_mfma_f32_16x16x32_bf16 v[0:3], v[156:159], v[216:219], v[0:3]
	s_setprio 0
	s_barrier
	s_add_i32 s54, s54, 2
	s_add_u32 s52, s52, 0x100
	s_addc_u32 s53, s53, 0
	s_cmp_gt_u32 s54, 7
	s_mov_b64 s[20:21], s[22:23]
.LBB0_402:
	ds_read_b128 v[120:123], v205
	ds_read_b128 v[124:127], v205 offset:1024
	ds_read_b128 v[132:135], v205 offset:2048
	ds_read_b128 v[140:143], v205 offset:3072
	ds_read_b128 v[144:147], v206
	ds_read_b128 v[148:151], v206 offset:1024
	ds_read_b128 v[152:155], v206 offset:2048
	ds_read_b128 v[156:159], v206 offset:3072
	s_add_u32 s22, s20, 0x100
	s_addc_u32 s23, s21, 0
	s_cmp_eq_u32 s54, 6
	s_cselect_b32 s27, s7, s23
	s_cselect_b32 s26, s6, s22
	s_cselect_b32 s25, s19, s53
	s_cselect_b32 s24, s18, s52
	s_add_i32 m0, s35, 0xc000
	ds_read_b128 v[180:183], v207
	ds_read_b128 v[184:187], v207 offset:1024
	ds_read_b128 v[188:191], v207 offset:2048
	ds_read_b128 v[192:195], v207 offset:3072
	ds_read_b128 v[196:199], v207 offset:4096
	ds_read_b128 v[208:211], v207 offset:5120
	ds_read_b128 v[212:215], v207 offset:6144
	ds_read_b128 v[216:219], v207 offset:7168
	global_load_lds_dwordx4 v172, s[20:21]
	s_add_i32 m0, s35, 0xe000
	s_nop 0
	global_load_lds_dwordx4 v174, s[20:21]
	s_waitcnt vmcnt(8)
	s_waitcnt lgkmcnt(0)
	s_barrier
	s_setprio 1
	s_waitcnt lgkmcnt(0)
	v_mfma_f32_16x16x32_bf16 v[136:139], v[120:123], v[180:183], v[136:139]
	v_mfma_f32_16x16x32_bf16 v[128:131], v[132:135], v[180:183], v[128:131]
	v_mfma_f32_16x16x32_bf16 v[116:119], v[120:123], v[188:191], v[116:119]
	v_mfma_f32_16x16x32_bf16 v[112:115], v[132:135], v[188:191], v[112:115]
	v_mfma_f32_16x16x32_bf16 v[108:111], v[120:123], v[196:199], v[108:111]
	v_mfma_f32_16x16x32_bf16 v[104:107], v[132:135], v[196:199], v[104:107]
	v_mfma_f32_16x16x32_bf16 v[100:103], v[120:123], v[212:215], v[100:103]
	v_mfma_f32_16x16x32_bf16 v[96:99], v[132:135], v[212:215], v[96:99]
	v_mfma_f32_16x16x32_bf16 v[136:139], v[124:127], v[184:187], v[136:139]
	v_mfma_f32_16x16x32_bf16 v[128:131], v[140:143], v[184:187], v[128:131]
	v_mfma_f32_16x16x32_bf16 v[116:119], v[124:127], v[192:195], v[116:119]
	v_mfma_f32_16x16x32_bf16 v[112:115], v[140:143], v[192:195], v[112:115]
	v_mfma_f32_16x16x32_bf16 v[108:111], v[124:127], v[208:211], v[108:111]
	v_mfma_f32_16x16x32_bf16 v[104:107], v[140:143], v[208:211], v[104:107]
	v_mfma_f32_16x16x32_bf16 v[100:103], v[124:127], v[216:219], v[100:103]
	v_mfma_f32_16x16x32_bf16 v[96:99], v[140:143], v[216:219], v[96:99]
	s_setprio 0
	s_setprio 1
	v_mfma_f32_16x16x32_bf16 v[60:63], v[144:147], v[180:183], v[60:63]
	v_mfma_f32_16x16x32_bf16 v[56:59], v[152:155], v[180:183], v[56:59]
	v_mfma_f32_16x16x32_bf16 v[52:55], v[144:147], v[188:191], v[52:55]
	v_mfma_f32_16x16x32_bf16 v[48:51], v[152:155], v[188:191], v[48:51]
	v_mfma_f32_16x16x32_bf16 v[44:47], v[144:147], v[196:199], v[44:47]
	v_mfma_f32_16x16x32_bf16 v[40:43], v[152:155], v[196:199], v[40:43]
	v_mfma_f32_16x16x32_bf16 v[36:39], v[144:147], v[212:215], v[36:39]
	v_mfma_f32_16x16x32_bf16 v[32:35], v[152:155], v[212:215], v[32:35]
	v_mfma_f32_16x16x32_bf16 v[60:63], v[148:151], v[184:187], v[60:63]
	v_mfma_f32_16x16x32_bf16 v[56:59], v[156:159], v[184:187], v[56:59]
	v_mfma_f32_16x16x32_bf16 v[52:55], v[148:151], v[192:195], v[52:55]
	v_mfma_f32_16x16x32_bf16 v[48:51], v[156:159], v[192:195], v[48:51]
	v_mfma_f32_16x16x32_bf16 v[44:47], v[148:151], v[208:211], v[44:47]
	v_mfma_f32_16x16x32_bf16 v[40:43], v[156:159], v[208:211], v[40:43]
	v_mfma_f32_16x16x32_bf16 v[36:39], v[148:151], v[216:219], v[36:39]
	v_mfma_f32_16x16x32_bf16 v[32:35], v[156:159], v[216:219], v[32:35]
	s_setprio 0
	s_barrier
	s_add_i32 s0, s46, s34
	v_lshl_add_u64 v[200:201], s[24:25], 0, v[162:163]
	s_mov_b32 m0, s0
	ds_read_b128 v[180:183], v207 offset:16384
	ds_read_b128 v[184:187], v207 offset:17408
	ds_read_b128 v[188:191], v207 offset:18432
	ds_read_b128 v[192:195], v207 offset:19456
	ds_read_b128 v[196:199], v207 offset:20480
	ds_read_b128 v[208:211], v207 offset:21504
	ds_read_b128 v[212:215], v207 offset:22528
	ds_read_b128 v[216:219], v207 offset:23552
	global_load_lds_dwordx4 v[200:201], off
	s_add_i32 m0, s0, 0x2000
	s_add_u32 s0, s24, 0x28000
	v_lshl_add_u64 v[220:221], s[24:25], 0, v[166:167]
	s_addc_u32 s1, s25, 0
	s_add_i32 s20, s47, s34
	global_load_lds_dwordx4 v[220:221], off
	s_mov_b32 m0, s20
	v_lshl_add_u64 v[224:225], s[26:27], 0, v[164:165]
	global_load_lds_dwordx4 v162, s[0:1]
	s_add_i32 m0, s20, 0x2000
	s_nop 0
	global_load_lds_dwordx4 v166, s[0:1]
	v_lshl_add_u64 v[222:223], s[26:27], 0, v[160:161]
	s_waitcnt vmcnt(6)
	s_waitcnt lgkmcnt(0)
	s_barrier
	s_setprio 1
	s_waitcnt lgkmcnt(0)
	v_mfma_f32_16x16x32_bf16 v[92:95], v[120:123], v[180:183], v[92:95]
	v_mfma_f32_16x16x32_bf16 v[88:91], v[132:135], v[180:183], v[88:91]
	v_mfma_f32_16x16x32_bf16 v[84:87], v[120:123], v[188:191], v[84:87]
	v_mfma_f32_16x16x32_bf16 v[80:83], v[132:135], v[188:191], v[80:83]
	v_mfma_f32_16x16x32_bf16 v[76:79], v[120:123], v[196:199], v[76:79]
	v_mfma_f32_16x16x32_bf16 v[72:75], v[132:135], v[196:199], v[72:75]
	v_mfma_f32_16x16x32_bf16 v[68:71], v[120:123], v[212:215], v[68:71]
	v_mfma_f32_16x16x32_bf16 v[64:67], v[132:135], v[212:215], v[64:67]
	v_mfma_f32_16x16x32_bf16 v[92:95], v[124:127], v[184:187], v[92:95]
	v_mfma_f32_16x16x32_bf16 v[88:91], v[140:143], v[184:187], v[88:91]
	v_mfma_f32_16x16x32_bf16 v[84:87], v[124:127], v[192:195], v[84:87]
	v_mfma_f32_16x16x32_bf16 v[80:83], v[140:143], v[192:195], v[80:83]
	v_mfma_f32_16x16x32_bf16 v[76:79], v[124:127], v[208:211], v[76:79]
	v_mfma_f32_16x16x32_bf16 v[72:75], v[140:143], v[208:211], v[72:75]
	v_mfma_f32_16x16x32_bf16 v[68:71], v[124:127], v[216:219], v[68:71]
	v_mfma_f32_16x16x32_bf16 v[64:67], v[140:143], v[216:219], v[64:67]
	s_setprio 0
	s_setprio 1
	v_mfma_f32_16x16x32_bf16 v[28:31], v[144:147], v[180:183], v[28:31]
	v_mfma_f32_16x16x32_bf16 v[24:27], v[152:155], v[180:183], v[24:27]
	v_mfma_f32_16x16x32_bf16 v[20:23], v[144:147], v[188:191], v[20:23]
	v_mfma_f32_16x16x32_bf16 v[16:19], v[152:155], v[188:191], v[16:19]
	v_mfma_f32_16x16x32_bf16 v[12:15], v[144:147], v[196:199], v[12:15]
	v_mfma_f32_16x16x32_bf16 v[8:11], v[152:155], v[196:199], v[8:11]
	v_mfma_f32_16x16x32_bf16 v[4:7], v[144:147], v[212:215], v[4:7]
	v_mfma_f32_16x16x32_bf16 v[0:3], v[152:155], v[212:215], v[0:3]
	v_mfma_f32_16x16x32_bf16 v[28:31], v[148:151], v[184:187], v[28:31]
	v_mfma_f32_16x16x32_bf16 v[24:27], v[156:159], v[184:187], v[24:27]
	v_mfma_f32_16x16x32_bf16 v[20:23], v[148:151], v[192:195], v[20:23]
	v_mfma_f32_16x16x32_bf16 v[16:19], v[156:159], v[192:195], v[16:19]
	v_mfma_f32_16x16x32_bf16 v[12:15], v[148:151], v[208:211], v[12:15]
	v_mfma_f32_16x16x32_bf16 v[8:11], v[156:159], v[208:211], v[8:11]
	v_mfma_f32_16x16x32_bf16 v[4:7], v[148:151], v[216:219], v[4:7]
	v_mfma_f32_16x16x32_bf16 v[0:3], v[156:159], v[216:219], v[0:3]
	s_setprio 0
	s_barrier
	s_add_i32 s20, 0, 0x18000
	s_add_i32 s21, 0, 0x1c000
	v_add_u32_e32 v140, s20, v203
	v_add_u32_e32 v156, s21, v203
	ds_read_b128 v[120:123], v140
	ds_read_b128 v[124:127], v140 offset:1024
	ds_read_b128 v[132:135], v140 offset:2048
	ds_read_b128 v[140:143], v140 offset:3072
	ds_read_b128 v[144:147], v156
	ds_read_b128 v[148:151], v156 offset:1024
	ds_read_b128 v[152:155], v156 offset:2048
	ds_read_b128 v[156:159], v156 offset:3072
	s_add_u32 s0, s26, 0x28000
	s_addc_u32 s1, s27, 0
	s_mov_b32 m0, s37
	ds_read_b128 v[180:183], v207 offset:32768
	ds_read_b128 v[184:187], v207 offset:33792
	ds_read_b128 v[188:191], v207 offset:34816
	ds_read_b128 v[192:195], v207 offset:35840
	ds_read_b128 v[196:199], v207 offset:36864
	ds_read_b128 v[208:211], v207 offset:37888
	ds_read_b128 v[212:215], v207 offset:38912
	ds_read_b128 v[216:219], v207 offset:39936
	global_load_lds_dwordx4 v160, s[0:1]
	s_mov_b32 m0, s40
	s_nop 0
	global_load_lds_dwordx4 v164, s[0:1]
	s_mov_b32 m0, s35
	s_nop 0
	global_load_lds_dwordx4 v[222:223], off
	s_mov_b32 m0, s36
	s_nop 0
	global_load_lds_dwordx4 v[224:225], off
	s_waitcnt vmcnt(8)
	s_waitcnt lgkmcnt(0)
	s_barrier
	s_setprio 1
	s_waitcnt lgkmcnt(0)
	v_mfma_f32_16x16x32_bf16 v[136:139], v[120:123], v[180:183], v[136:139]
	v_mfma_f32_16x16x32_bf16 v[128:131], v[132:135], v[180:183], v[128:131]
	v_mfma_f32_16x16x32_bf16 v[116:119], v[120:123], v[188:191], v[116:119]
	v_mfma_f32_16x16x32_bf16 v[112:115], v[132:135], v[188:191], v[112:115]
	v_mfma_f32_16x16x32_bf16 v[108:111], v[120:123], v[196:199], v[108:111]
	v_mfma_f32_16x16x32_bf16 v[104:107], v[132:135], v[196:199], v[104:107]
	v_mfma_f32_16x16x32_bf16 v[100:103], v[120:123], v[212:215], v[100:103]
	v_mfma_f32_16x16x32_bf16 v[96:99], v[132:135], v[212:215], v[96:99]
	v_mfma_f32_16x16x32_bf16 v[136:139], v[124:127], v[184:187], v[136:139]
	v_mfma_f32_16x16x32_bf16 v[128:131], v[140:143], v[184:187], v[128:131]
	v_mfma_f32_16x16x32_bf16 v[116:119], v[124:127], v[192:195], v[116:119]
	v_mfma_f32_16x16x32_bf16 v[112:115], v[140:143], v[192:195], v[112:115]
	v_mfma_f32_16x16x32_bf16 v[108:111], v[124:127], v[208:211], v[108:111]
	v_mfma_f32_16x16x32_bf16 v[104:107], v[140:143], v[208:211], v[104:107]
	v_mfma_f32_16x16x32_bf16 v[100:103], v[124:127], v[216:219], v[100:103]
	v_mfma_f32_16x16x32_bf16 v[96:99], v[140:143], v[216:219], v[96:99]
	s_setprio 0
	s_setprio 1
	v_mfma_f32_16x16x32_bf16 v[60:63], v[144:147], v[180:183], v[60:63]
	v_mfma_f32_16x16x32_bf16 v[56:59], v[152:155], v[180:183], v[56:59]
	v_mfma_f32_16x16x32_bf16 v[52:55], v[144:147], v[188:191], v[52:55]
	v_mfma_f32_16x16x32_bf16 v[48:51], v[152:155], v[188:191], v[48:51]
	v_mfma_f32_16x16x32_bf16 v[44:47], v[144:147], v[196:199], v[44:47]
	v_mfma_f32_16x16x32_bf16 v[40:43], v[152:155], v[196:199], v[40:43]
	v_mfma_f32_16x16x32_bf16 v[36:39], v[144:147], v[212:215], v[36:39]
	v_mfma_f32_16x16x32_bf16 v[32:35], v[152:155], v[212:215], v[32:35]
	v_mfma_f32_16x16x32_bf16 v[60:63], v[148:151], v[184:187], v[60:63]
	v_mfma_f32_16x16x32_bf16 v[56:59], v[156:159], v[184:187], v[56:59]
	v_mfma_f32_16x16x32_bf16 v[52:55], v[148:151], v[192:195], v[52:55]
	v_mfma_f32_16x16x32_bf16 v[48:51], v[156:159], v[192:195], v[48:51]
	v_mfma_f32_16x16x32_bf16 v[44:47], v[148:151], v[208:211], v[44:47]
	v_mfma_f32_16x16x32_bf16 v[40:43], v[156:159], v[208:211], v[40:43]
	v_mfma_f32_16x16x32_bf16 v[36:39], v[148:151], v[216:219], v[36:39]
	v_mfma_f32_16x16x32_bf16 v[32:35], v[156:159], v[216:219], v[32:35]
	s_setprio 0
	s_barrier
	s_add_i32 s0, s20, s34
	v_lshl_add_u64 v[200:201], v[200:201], 0, s[14:15]
	s_mov_b32 m0, s0
	ds_read_b128 v[180:183], v207 offset:49152
	ds_read_b128 v[184:187], v207 offset:50176
	ds_read_b128 v[188:191], v207 offset:51200
	ds_read_b128 v[192:195], v207 offset:52224
	ds_read_b128 v[196:199], v207 offset:53248
	ds_read_b128 v[208:211], v207 offset:54272
	ds_read_b128 v[212:215], v207 offset:55296
	ds_read_b128 v[216:219], v207 offset:56320
	global_load_lds_dwordx4 v[200:201], off
	s_add_i32 m0, s0, 0x2000
	s_add_u32 s0, s24, 0x28080
	v_lshl_add_u64 v[200:201], v[220:221], 0, s[14:15]
	s_addc_u32 s1, s25, 0
	s_add_i32 s20, s21, s34
	global_load_lds_dwordx4 v[200:201], off
	s_mov_b32 m0, s20
	s_nop 0
	global_load_lds_dwordx4 v162, s[0:1]
	s_add_i32 m0, s20, 0x2000
	s_nop 0
	global_load_lds_dwordx4 v166, s[0:1]
	v_lshl_add_u64 v[200:201], v[222:223], 0, s[14:15]
	s_mov_b32 m0, s42
	s_nop 0
	global_load_lds_dwordx4 v[200:201], off
	v_lshl_add_u64 v[200:201], v[224:225], 0, s[14:15]
	s_mov_b32 m0, s43
	s_nop 0
	global_load_lds_dwordx4 v[200:201], off
	s_waitcnt vmcnt(6)
	s_waitcnt lgkmcnt(0)
	s_barrier
	s_setprio 1
	s_waitcnt lgkmcnt(0)
	v_mfma_f32_16x16x32_bf16 v[92:95], v[120:123], v[180:183], v[92:95]
	v_mfma_f32_16x16x32_bf16 v[88:91], v[132:135], v[180:183], v[88:91]
	v_mfma_f32_16x16x32_bf16 v[84:87], v[120:123], v[188:191], v[84:87]
	v_mfma_f32_16x16x32_bf16 v[80:83], v[132:135], v[188:191], v[80:83]
	v_mfma_f32_16x16x32_bf16 v[76:79], v[120:123], v[196:199], v[76:79]
	v_mfma_f32_16x16x32_bf16 v[72:75], v[132:135], v[196:199], v[72:75]
	v_mfma_f32_16x16x32_bf16 v[68:71], v[120:123], v[212:215], v[68:71]
	v_mfma_f32_16x16x32_bf16 v[64:67], v[132:135], v[212:215], v[64:67]
	v_mfma_f32_16x16x32_bf16 v[92:95], v[124:127], v[184:187], v[92:95]
	v_mfma_f32_16x16x32_bf16 v[88:91], v[140:143], v[184:187], v[88:91]
	v_mfma_f32_16x16x32_bf16 v[84:87], v[124:127], v[192:195], v[84:87]
	v_mfma_f32_16x16x32_bf16 v[80:83], v[140:143], v[192:195], v[80:83]
	v_mfma_f32_16x16x32_bf16 v[76:79], v[124:127], v[208:211], v[76:79]
	v_mfma_f32_16x16x32_bf16 v[72:75], v[140:143], v[208:211], v[72:75]
	v_mfma_f32_16x16x32_bf16 v[68:71], v[124:127], v[216:219], v[68:71]
	v_mfma_f32_16x16x32_bf16 v[64:67], v[140:143], v[216:219], v[64:67]
	s_setprio 0
	s_setprio 1
	v_mfma_f32_16x16x32_bf16 v[28:31], v[144:147], v[180:183], v[28:31]
	v_mfma_f32_16x16x32_bf16 v[24:27], v[152:155], v[180:183], v[24:27]
	v_mfma_f32_16x16x32_bf16 v[20:23], v[144:147], v[188:191], v[20:23]
	v_mfma_f32_16x16x32_bf16 v[16:19], v[152:155], v[188:191], v[16:19]
	v_mfma_f32_16x16x32_bf16 v[12:15], v[144:147], v[196:199], v[12:15]
	v_mfma_f32_16x16x32_bf16 v[8:11], v[152:155], v[196:199], v[8:11]
	v_mfma_f32_16x16x32_bf16 v[4:7], v[144:147], v[212:215], v[4:7]
	v_mfma_f32_16x16x32_bf16 v[0:3], v[152:155], v[212:215], v[0:3]
	v_mfma_f32_16x16x32_bf16 v[28:31], v[148:151], v[184:187], v[28:31]
	v_mfma_f32_16x16x32_bf16 v[24:27], v[156:159], v[184:187], v[24:27]
	v_mfma_f32_16x16x32_bf16 v[20:23], v[148:151], v[192:195], v[20:23]
	v_mfma_f32_16x16x32_bf16 v[16:19], v[156:159], v[192:195], v[16:19]
	v_mfma_f32_16x16x32_bf16 v[12:15], v[148:151], v[208:211], v[12:15]
	v_mfma_f32_16x16x32_bf16 v[8:11], v[156:159], v[208:211], v[8:11]
	v_mfma_f32_16x16x32_bf16 v[4:7], v[148:151], v[216:219], v[4:7]
	v_mfma_f32_16x16x32_bf16 v[0:3], v[156:159], v[216:219], v[0:3]
	s_setprio 0
	s_barrier
	s_add_i32 s54, s54, 2
	s_add_u32 s52, s52, 0x100
	s_addc_u32 s53, s53, 0
	s_cmp_gt_u32 s54, 7
	s_mov_b64 s[20:21], s[22:23]
	s_cbranch_scc0 .LBB0_402
	s_and_b64 vcc, exec, s[16:17]
	s_cbranch_vccz .LBB0_405
	s_barrier
.LBB0_405:
	v_lshl_or_b32 v182, s51, 8, v204
	s_lshl_b32 s0, s50, 1
	v_ashrrev_i32_e32 v183, 31, v182
	s_and_b32 s0, s0, -16
	v_lshlrev_b64 v[192:193], 1, v[182:183]
	s_ashr_i32 s1, s0, 31
	v_lshl_add_u32 v180, s50, 8, v202
	v_lshl_add_u64 v[132:133], s[2:3], 0, v[192:193]
	v_lshl_add_u64 v[184:185], s[0:1], 2, v[170:171]
	v_mad_i64_i32 v[134:135], s[0:1], v180, s33, v[132:133]
	v_or_b32_e32 v186, 16, v180
	v_or_b32_e32 v188, 32, v180
	global_load_dwordx4 v[120:123], v[184:185], off offset:16
	global_load_dwordx4 v[124:127], v[184:185], off
	v_mad_i64_i32 v[140:141], s[0:1], v186, s33, v[132:133]
	global_load_dwordx4 v[208:211], v[134:135], off
	global_load_dwordx4 v[212:215], v[140:141], off
	v_mad_i64_i32 v[134:135], s[0:1], v188, s33, v[132:133]
	v_or_b32_e32 v190, 48, v180
	v_add_u32_e32 v194, 0x80, v180
	v_mad_i64_i32 v[140:141], s[0:1], v190, s33, v[132:133]
	global_load_dwordx4 v[156:159], v[134:135], off
	global_load_dwordx4 v[152:155], v[140:141], off
	v_mad_i64_i32 v[134:135], s[0:1], v194, s33, v[132:133]
	v_add_u32_e32 v196, 0x90, v180
	v_add_u32_e32 v198, 0xa0, v180
	v_add_u32_e32 v200, 0xb0, v180
	v_mad_i64_i32 v[140:141], s[0:1], v196, s33, v[132:133]
	global_load_dwordx4 v[148:151], v[134:135], off
	global_load_dwordx4 v[144:147], v[140:141], off
	v_mad_i64_i32 v[134:135], s[0:1], v198, s33, v[132:133]
	v_mad_i64_i32 v[132:133], s[0:1], v200, s33, v[132:133]
	global_load_dwordx4 v[140:143], v[134:135], off
	s_nop 0
	global_load_dwordx4 v[132:135], v[132:133], off
	v_ashrrev_i32_e32 v181, 31, v180
	v_ashrrev_i32_e32 v187, 31, v186
	v_ashrrev_i32_e32 v189, 31, v188
	v_ashrrev_i32_e32 v191, 31, v190
	v_ashrrev_i32_e32 v195, 31, v194
	v_ashrrev_i32_e32 v197, 31, v196
	v_ashrrev_i32_e32 v199, 31, v198
	v_ashrrev_i32_e32 v201, 31, v200
	s_waitcnt vmcnt(0)
	v_lshlrev_b32_e32 v183, 16, v208
	v_fma_f32 v136, v124, v183, v136
	v_and_b32_e32 v183, 0xffff0000, v208
	v_fma_f32 v137, v125, v183, v137
	v_lshlrev_b32_e32 v183, 16, v209
	v_fma_f32 v138, v126, v183, v138
	v_and_b32_e32 v183, 0xffff0000, v209
	v_mul_f32_e32 v208, 0x3d372713, v136
	v_mul_f32_e32 v209, 0x3d372713, v137
	v_mul_f32_e32 v208, v136, v208
	v_mul_f32_e32 v209, v137, v209
	v_fma_f32 v208, v136, v208, v136
	v_fma_f32 v209, v137, v209, v137
	v_mul_f32_e32 v208, 0x3fcc422a, v208
	v_mul_f32_e32 v209, 0x3fcc422a, v209
	v_mul_f32_e32 v208, 0xbfb8aa3b, v208
	v_mul_f32_e32 v209, 0xbfb8aa3b, v209
	v_fmac_f32_e32 v139, v127, v183
	v_lshlrev_b32_e32 v183, 16, v210
	v_exp_f32_e32 v208, v208
	v_exp_f32_e32 v209, v209
	v_fma_f32 v128, v120, v183, v128
	v_and_b32_e32 v183, 0xffff0000, v210
	v_fma_f32 v129, v121, v183, v129
	v_lshlrev_b32_e32 v183, 16, v211
	v_fma_f32 v130, v122, v183, v130
	v_and_b32_e32 v183, 0xffff0000, v211
	v_fmac_f32_e32 v131, v123, v183
	v_add_f32_e32 v183, 1.0, v208
	v_add_f32_e32 v208, 1.0, v209
	v_mul_f32_e32 v209, 0x3d372713, v138
	v_rcp_f32_e32 v183, v183
	v_rcp_f32_e32 v208, v208
	v_mul_f32_e32 v209, v138, v209
	v_fma_f32 v209, v138, v209, v138
	v_mul_f32_e32 v209, 0x3fcc422a, v209
	v_mul_f32_e32 v209, 0xbfb8aa3b, v209
	v_exp_f32_e32 v209, v209
	v_mul_f32_e32 v136, v136, v183
	v_mul_f32_e32 v137, v137, v208
	v_mul_f32_e32 v183, 0x3d372713, v139
	v_mul_f32_e32 v208, 0x3d372713, v128
	v_mul_f32_e32 v183, v139, v183
	v_mul_f32_e32 v208, v128, v208
	v_fma_f32 v183, v139, v183, v139
	v_fma_f32 v208, v128, v208, v128
	v_mul_f32_e32 v183, 0x3fcc422a, v183
	v_mul_f32_e32 v208, 0x3fcc422a, v208
	v_cvt_pk_bf16_f32 v136, v136, v137
	v_add_f32_e32 v137, 1.0, v209
	v_mul_f32_e32 v183, 0xbfb8aa3b, v183
	v_mul_f32_e32 v208, 0xbfb8aa3b, v208
	v_rcp_f32_e32 v137, v137
	v_exp_f32_e32 v183, v183
	v_exp_f32_e32 v208, v208
	v_mul_f32_e32 v137, v138, v137
	v_add_f32_e32 v138, 1.0, v183
	v_add_f32_e32 v183, 1.0, v208
	v_rcp_f32_e32 v138, v138
	v_rcp_f32_e32 v183, v183
	v_mul_f32_e32 v208, 0x3d372713, v129
	v_mul_f32_e32 v208, v129, v208
	v_mul_f32_e32 v138, v139, v138
	v_mul_f32_e32 v128, v128, v183
	v_mul_f32_e32 v139, 0x3d372713, v130
	v_mul_f32_e32 v183, 0x3d372713, v131
	v_fma_f32 v208, v129, v208, v129
	v_mul_f32_e32 v139, v130, v139
	v_mul_f32_e32 v183, v131, v183
	v_mul_f32_e32 v208, 0x3fcc422a, v208
	v_fma_f32 v139, v130, v139, v130
	v_fma_f32 v183, v131, v183, v131
	v_mul_f32_e32 v208, 0xbfb8aa3b, v208
	v_mul_f32_e32 v139, 0x3fcc422a, v139
	v_mul_f32_e32 v183, 0x3fcc422a, v183
	v_exp_f32_e32 v208, v208
	v_mul_f32_e32 v139, 0xbfb8aa3b, v139
	v_mul_f32_e32 v183, 0xbfb8aa3b, v183
	v_exp_f32_e32 v139, v139
	v_exp_f32_e32 v183, v183
	v_cvt_pk_bf16_f32 v137, v137, v138
	v_add_f32_e32 v138, 1.0, v208
	v_rcp_f32_e32 v138, v138
	v_add_f32_e32 v139, 1.0, v139
	v_add_f32_e32 v183, 1.0, v183
	v_rcp_f32_e32 v139, v139
	v_rcp_f32_e32 v183, v183
	v_mul_f32_e32 v129, v129, v138
	v_cvt_pk_bf16_f32 v138, v128, v129
	v_mul_f32_e32 v128, v130, v139
	v_mul_f32_e32 v129, v131, v183
	v_cvt_pk_bf16_f32 v139, v128, v129
	v_lshlrev_b64 v[128:129], 10, v[180:181]
	v_lshlrev_b32_e32 v130, 16, v212
	v_lshl_add_u64 v[128:129], s[12:13], 0, v[128:129]
	v_fma_f32 v116, v124, v130, v116
	v_and_b32_e32 v130, 0xffff0000, v212
	v_lshl_add_u64 v[128:129], v[128:129], 0, v[192:193]
	v_fma_f32 v117, v125, v130, v117
	global_store_dwordx4 v[128:129], v[136:139], off
	v_mul_f32_e32 v131, 0x3d372713, v116
	v_mul_f32_e32 v131, v116, v131
	v_mul_f32_e32 v136, 0x3d372713, v117
	v_mul_f32_e32 v136, v117, v136
	v_fma_f32 v131, v116, v131, v116
	v_fma_f32 v136, v117, v136, v117
	v_lshlrev_b32_e32 v130, 16, v213
	v_mul_f32_e32 v131, 0x3fcc422a, v131
	v_mul_f32_e32 v136, 0x3fcc422a, v136
	v_fma_f32 v118, v126, v130, v118
	v_and_b32_e32 v130, 0xffff0000, v213
	v_mul_f32_e32 v131, 0xbfb8aa3b, v131
	v_mul_f32_e32 v136, 0xbfb8aa3b, v136
	v_fmac_f32_e32 v119, v127, v130
	v_lshlrev_b32_e32 v130, 16, v214
	v_exp_f32_e32 v131, v131
	v_exp_f32_e32 v136, v136
	v_fma_f32 v112, v120, v130, v112
	v_and_b32_e32 v130, 0xffff0000, v214
	v_fma_f32 v113, v121, v130, v113
	v_lshlrev_b32_e32 v130, 16, v215
	v_fma_f32 v114, v122, v130, v114
	v_and_b32_e32 v130, 0xffff0000, v215
	v_fmac_f32_e32 v115, v123, v130
	v_add_f32_e32 v130, 1.0, v131
	v_add_f32_e32 v131, 1.0, v136
	v_mul_f32_e32 v136, 0x3d372713, v118
	v_rcp_f32_e32 v130, v130
	v_rcp_f32_e32 v131, v131
	v_mul_f32_e32 v136, v118, v136
	v_fma_f32 v136, v118, v136, v118
	v_mul_f32_e32 v136, 0x3fcc422a, v136
	v_mul_f32_e32 v136, 0xbfb8aa3b, v136
	v_exp_f32_e32 v136, v136
	v_mul_f32_e32 v116, v116, v130
	v_mul_f32_e32 v117, v117, v131
	v_mul_f32_e32 v130, 0x3d372713, v119
	v_mul_f32_e32 v131, 0x3d372713, v112
	v_mul_f32_e32 v130, v119, v130
	v_mul_f32_e32 v131, v112, v131
	v_fma_f32 v130, v119, v130, v119
	v_fma_f32 v131, v112, v131, v112
	v_mul_f32_e32 v130, 0x3fcc422a, v130
	v_mul_f32_e32 v131, 0x3fcc422a, v131
	v_cvt_pk_bf16_f32 v116, v116, v117
	v_add_f32_e32 v117, 1.0, v136
	v_mul_f32_e32 v130, 0xbfb8aa3b, v130
	v_mul_f32_e32 v131, 0xbfb8aa3b, v131
	v_rcp_f32_e32 v117, v117
	v_exp_f32_e32 v130, v130
	v_exp_f32_e32 v131, v131
	v_mul_f32_e32 v117, v118, v117
	v_add_f32_e32 v118, 1.0, v130
	v_add_f32_e32 v130, 1.0, v131
	v_rcp_f32_e32 v118, v118
	v_rcp_f32_e32 v130, v130
	v_mul_f32_e32 v131, 0x3d372713, v113
	v_mul_f32_e32 v131, v113, v131
	v_mul_f32_e32 v118, v119, v118
	v_mul_f32_e32 v112, v112, v130
	v_mul_f32_e32 v119, 0x3d372713, v114
	v_mul_f32_e32 v130, 0x3d372713, v115
	v_fma_f32 v131, v113, v131, v113
	v_mul_f32_e32 v119, v114, v119
	v_mul_f32_e32 v130, v115, v130
	v_mul_f32_e32 v131, 0x3fcc422a, v131
	v_fma_f32 v119, v114, v119, v114
	v_fma_f32 v130, v115, v130, v115
	v_mul_f32_e32 v131, 0xbfb8aa3b, v131
	v_mul_f32_e32 v119, 0x3fcc422a, v119
	v_mul_f32_e32 v130, 0x3fcc422a, v130
	v_exp_f32_e32 v131, v131
	v_mul_f32_e32 v119, 0xbfb8aa3b, v119
	v_mul_f32_e32 v130, 0xbfb8aa3b, v130
	v_exp_f32_e32 v119, v119
	v_exp_f32_e32 v130, v130
	v_cvt_pk_bf16_f32 v117, v117, v118
	v_add_f32_e32 v118, 1.0, v131
	v_rcp_f32_e32 v118, v118
	v_add_f32_e32 v119, 1.0, v119
	v_add_f32_e32 v130, 1.0, v130
	v_rcp_f32_e32 v119, v119
	v_rcp_f32_e32 v130, v130
	v_mul_f32_e32 v113, v113, v118
	v_cvt_pk_bf16_f32 v118, v112, v113
	v_mul_f32_e32 v112, v114, v119
	v_mul_f32_e32 v113, v115, v130
	v_cvt_pk_bf16_f32 v119, v112, v113
	v_lshlrev_b64 v[112:113], 10, v[186:187]
	v_lshlrev_b32_e32 v114, 16, v156
	v_lshl_add_u64 v[112:113], s[12:13], 0, v[112:113]
	v_fma_f32 v108, v124, v114, v108
	v_and_b32_e32 v114, 0xffff0000, v156
	v_lshl_add_u64 v[112:113], v[112:113], 0, v[192:193]
	v_fma_f32 v109, v125, v114, v109
	global_store_dwordx4 v[112:113], v[116:119], off
	v_mul_f32_e32 v115, 0x3d372713, v108
	v_mul_f32_e32 v115, v108, v115
	v_mul_f32_e32 v116, 0x3d372713, v109
	v_mul_f32_e32 v116, v109, v116
	v_fma_f32 v115, v108, v115, v108
	v_fma_f32 v116, v109, v116, v109
	v_lshlrev_b32_e32 v114, 16, v157
	v_mul_f32_e32 v115, 0x3fcc422a, v115
	v_mul_f32_e32 v116, 0x3fcc422a, v116
	v_fma_f32 v110, v126, v114, v110
	v_and_b32_e32 v114, 0xffff0000, v157
	v_mul_f32_e32 v115, 0xbfb8aa3b, v115
	v_mul_f32_e32 v116, 0xbfb8aa3b, v116
	v_fmac_f32_e32 v111, v127, v114
	v_lshlrev_b32_e32 v114, 16, v158
	v_exp_f32_e32 v115, v115
	v_exp_f32_e32 v116, v116
	v_fma_f32 v104, v120, v114, v104
	v_and_b32_e32 v114, 0xffff0000, v158
	v_fma_f32 v105, v121, v114, v105
	v_lshlrev_b32_e32 v114, 16, v159
	v_fma_f32 v106, v122, v114, v106
	v_and_b32_e32 v114, 0xffff0000, v159
	v_fmac_f32_e32 v107, v123, v114
	v_add_f32_e32 v114, 1.0, v115
	v_add_f32_e32 v115, 1.0, v116
	v_mul_f32_e32 v116, 0x3d372713, v110
	v_rcp_f32_e32 v114, v114
	v_rcp_f32_e32 v115, v115
	v_mul_f32_e32 v116, v110, v116
	v_fma_f32 v116, v110, v116, v110
	v_mul_f32_e32 v116, 0x3fcc422a, v116
	v_mul_f32_e32 v116, 0xbfb8aa3b, v116
	v_exp_f32_e32 v116, v116
	v_mul_f32_e32 v108, v108, v114
	v_mul_f32_e32 v109, v109, v115
	v_mul_f32_e32 v114, 0x3d372713, v111
	v_mul_f32_e32 v115, 0x3d372713, v104
	v_mul_f32_e32 v114, v111, v114
	v_mul_f32_e32 v115, v104, v115
	v_fma_f32 v114, v111, v114, v111
	v_fma_f32 v115, v104, v115, v104
	v_mul_f32_e32 v114, 0x3fcc422a, v114
	v_mul_f32_e32 v115, 0x3fcc422a, v115
	v_cvt_pk_bf16_f32 v108, v108, v109
	v_add_f32_e32 v109, 1.0, v116
	v_mul_f32_e32 v114, 0xbfb8aa3b, v114
	v_mul_f32_e32 v115, 0xbfb8aa3b, v115
	v_rcp_f32_e32 v109, v109
	v_exp_f32_e32 v114, v114
	v_exp_f32_e32 v115, v115
	v_mul_f32_e32 v109, v110, v109
	v_add_f32_e32 v110, 1.0, v114
	v_add_f32_e32 v114, 1.0, v115
	v_rcp_f32_e32 v110, v110
	v_rcp_f32_e32 v114, v114
	v_mul_f32_e32 v115, 0x3d372713, v105
	v_mul_f32_e32 v115, v105, v115
	v_mul_f32_e32 v110, v111, v110
	v_mul_f32_e32 v104, v104, v114
	v_mul_f32_e32 v111, 0x3d372713, v106
	v_mul_f32_e32 v114, 0x3d372713, v107
	v_fma_f32 v115, v105, v115, v105
	v_mul_f32_e32 v111, v106, v111
	v_mul_f32_e32 v114, v107, v114
	v_mul_f32_e32 v115, 0x3fcc422a, v115
	v_fma_f32 v111, v106, v111, v106
	v_fma_f32 v114, v107, v114, v107
	v_mul_f32_e32 v115, 0xbfb8aa3b, v115
	v_mul_f32_e32 v111, 0x3fcc422a, v111
	v_mul_f32_e32 v114, 0x3fcc422a, v114
	v_exp_f32_e32 v115, v115
	v_mul_f32_e32 v111, 0xbfb8aa3b, v111
	v_mul_f32_e32 v114, 0xbfb8aa3b, v114
	v_exp_f32_e32 v111, v111
	v_exp_f32_e32 v114, v114
	v_cvt_pk_bf16_f32 v109, v109, v110
	v_add_f32_e32 v110, 1.0, v115
	v_rcp_f32_e32 v110, v110
	v_add_f32_e32 v111, 1.0, v111
	v_add_f32_e32 v114, 1.0, v114
	v_rcp_f32_e32 v111, v111
	v_rcp_f32_e32 v114, v114
	v_mul_f32_e32 v105, v105, v110
	v_cvt_pk_bf16_f32 v110, v104, v105
	v_mul_f32_e32 v104, v106, v111
	v_mul_f32_e32 v105, v107, v114
	v_cvt_pk_bf16_f32 v111, v104, v105
	v_lshlrev_b64 v[104:105], 10, v[188:189]
	v_lshlrev_b32_e32 v106, 16, v152
	v_lshl_add_u64 v[104:105], s[12:13], 0, v[104:105]
	v_fma_f32 v100, v124, v106, v100
	v_and_b32_e32 v106, 0xffff0000, v152
	v_lshl_add_u64 v[104:105], v[104:105], 0, v[192:193]
	v_fma_f32 v101, v125, v106, v101
	global_store_dwordx4 v[104:105], v[108:111], off
	v_mul_f32_e32 v107, 0x3d372713, v100
	v_mul_f32_e32 v107, v100, v107
	v_mul_f32_e32 v108, 0x3d372713, v101
	v_mul_f32_e32 v108, v101, v108
	v_fma_f32 v107, v100, v107, v100
	v_fma_f32 v108, v101, v108, v101
	v_lshlrev_b32_e32 v106, 16, v153
	v_mul_f32_e32 v107, 0x3fcc422a, v107
	v_mul_f32_e32 v108, 0x3fcc422a, v108
	v_fma_f32 v102, v126, v106, v102
	v_and_b32_e32 v106, 0xffff0000, v153
	v_mul_f32_e32 v107, 0xbfb8aa3b, v107
	v_mul_f32_e32 v108, 0xbfb8aa3b, v108
	v_fmac_f32_e32 v103, v127, v106
	v_lshlrev_b32_e32 v106, 16, v154
	v_exp_f32_e32 v107, v107
	v_exp_f32_e32 v108, v108
	v_fma_f32 v96, v120, v106, v96
	v_and_b32_e32 v106, 0xffff0000, v154
	v_fma_f32 v97, v121, v106, v97
	v_lshlrev_b32_e32 v106, 16, v155
	v_fma_f32 v98, v122, v106, v98
	v_and_b32_e32 v106, 0xffff0000, v155
	v_fmac_f32_e32 v99, v123, v106
	v_add_f32_e32 v106, 1.0, v107
	v_add_f32_e32 v107, 1.0, v108
	v_mul_f32_e32 v108, 0x3d372713, v102
	v_rcp_f32_e32 v106, v106
	v_mul_f32_e32 v108, v102, v108
	v_fma_f32 v108, v102, v108, v102
	v_mul_f32_e32 v108, 0x3fcc422a, v108
	v_rcp_f32_e32 v107, v107
	v_mul_f32_e32 v108, 0xbfb8aa3b, v108
	v_exp_f32_e32 v108, v108
	v_mul_f32_e32 v100, v100, v106
	v_mul_f32_e32 v106, 0x3d372713, v103
	v_mul_f32_e32 v106, v103, v106
	v_fma_f32 v106, v103, v106, v103
	v_mul_f32_e32 v101, v101, v107
	v_mul_f32_e32 v106, 0x3fcc422a, v106
	v_mul_f32_e32 v107, 0x3d372713, v96
	v_cvt_pk_bf16_f32 v100, v100, v101
	v_add_f32_e32 v101, 1.0, v108
	v_mul_f32_e32 v106, 0xbfb8aa3b, v106
	v_mul_f32_e32 v107, v96, v107
	v_rcp_f32_e32 v101, v101
	v_exp_f32_e32 v106, v106
	v_fma_f32 v107, v96, v107, v96
	v_mul_f32_e32 v107, 0x3fcc422a, v107
	v_mul_f32_e32 v107, 0xbfb8aa3b, v107
	v_exp_f32_e32 v107, v107
	v_mul_f32_e32 v101, v102, v101
	v_add_f32_e32 v102, 1.0, v106
	v_rcp_f32_e32 v102, v102
	v_add_f32_e32 v106, 1.0, v107
	v_rcp_f32_e32 v106, v106
	v_mul_f32_e32 v107, 0x3d372713, v97
	v_mul_f32_e32 v102, v103, v102
	v_mul_f32_e32 v103, 0x3d372713, v98
	v_mul_f32_e32 v107, v97, v107
	v_mul_f32_e32 v103, v98, v103
	v_fma_f32 v107, v97, v107, v97
	v_fma_f32 v103, v98, v103, v98
	v_mul_f32_e32 v107, 0x3fcc422a, v107
	v_mul_f32_e32 v96, v96, v106
	v_mul_f32_e32 v103, 0x3fcc422a, v103
	v_mul_f32_e32 v106, 0x3d372713, v99
	v_mul_f32_e32 v107, 0xbfb8aa3b, v107
	v_mul_f32_e32 v103, 0xbfb8aa3b, v103
	v_mul_f32_e32 v106, v99, v106
	v_exp_f32_e32 v107, v107
	v_exp_f32_e32 v103, v103
	v_fma_f32 v106, v99, v106, v99
	v_mul_f32_e32 v106, 0x3fcc422a, v106
	v_mul_f32_e32 v106, 0xbfb8aa3b, v106
	v_exp_f32_e32 v106, v106
	v_cvt_pk_bf16_f32 v101, v101, v102
	v_add_f32_e32 v102, 1.0, v107
	v_add_f32_e32 v103, 1.0, v103
	v_rcp_f32_e32 v102, v102
	v_rcp_f32_e32 v103, v103
	v_add_f32_e32 v106, 1.0, v106
	v_rcp_f32_e32 v106, v106
	v_mul_f32_e32 v97, v97, v102
	v_cvt_pk_bf16_f32 v102, v96, v97
	v_mul_f32_e32 v96, v98, v103
	v_lshlrev_b32_e32 v98, 16, v148
	v_fma_f32 v92, v124, v98, v92
	v_and_b32_e32 v98, 0xffff0000, v148
	v_fma_f32 v93, v125, v98, v93
	v_lshlrev_b32_e32 v98, 16, v149
	v_mul_f32_e32 v97, v99, v106
	v_fma_f32 v94, v126, v98, v94
	v_and_b32_e32 v98, 0xffff0000, v149
	v_cvt_pk_bf16_f32 v103, v96, v97
	v_lshlrev_b64 v[96:97], 10, v[190:191]
	v_fmac_f32_e32 v95, v127, v98
	v_lshlrev_b32_e32 v98, 16, v150
	v_lshl_add_u64 v[96:97], s[12:13], 0, v[96:97]
	v_fma_f32 v98, v120, v98, v88
	v_and_b32_e32 v88, 0xffff0000, v150
	v_lshl_add_u64 v[96:97], v[96:97], 0, v[192:193]
	v_fma_f32 v99, v121, v88, v89
	v_lshlrev_b32_e32 v88, 16, v151
	global_store_dwordx4 v[96:97], v[100:103], off
	v_mul_f32_e32 v89, 0x3d372713, v92
	v_mul_f32_e32 v89, v92, v89
	v_fma_f32 v100, v122, v88, v90
	v_mul_f32_e32 v90, 0x3d372713, v93
	v_mul_f32_e32 v90, v93, v90
	v_fma_f32 v89, v92, v89, v92
	v_fma_f32 v90, v93, v90, v93
	v_mul_f32_e32 v89, 0x3fcc422a, v89
	v_mul_f32_e32 v90, 0x3fcc422a, v90
	v_mul_f32_e32 v89, 0xbfb8aa3b, v89
	v_mul_f32_e32 v90, 0xbfb8aa3b, v90
	v_exp_f32_e32 v89, v89
	v_exp_f32_e32 v90, v90
	v_and_b32_e32 v88, 0xffff0000, v151
	v_fmac_f32_e32 v91, v123, v88
	v_add_f32_e32 v88, 1.0, v89
	v_add_f32_e32 v89, 1.0, v90
	v_mul_f32_e32 v90, 0x3d372713, v94
	v_mul_f32_e32 v90, v94, v90
	v_fma_f32 v90, v94, v90, v94
	v_mul_f32_e32 v90, 0x3fcc422a, v90
	v_rcp_f32_e32 v88, v88
	v_rcp_f32_e32 v89, v89
	v_mul_f32_e32 v90, 0xbfb8aa3b, v90
	v_exp_f32_e32 v90, v90
	v_mul_f32_e32 v88, v92, v88
	v_mul_f32_e32 v89, v93, v89
	v_cvt_pk_bf16_f32 v88, v88, v89
	v_add_f32_e32 v89, 1.0, v90
	v_mul_f32_e32 v90, 0x3d372713, v95
	v_mul_f32_e32 v90, v95, v90
	v_mul_f32_e32 v92, 0x3d372713, v98
	v_fma_f32 v90, v95, v90, v95
	v_mul_f32_e32 v92, v98, v92
	v_mul_f32_e32 v90, 0x3fcc422a, v90
	v_fma_f32 v92, v98, v92, v98
	v_mul_f32_e32 v90, 0xbfb8aa3b, v90
	v_mul_f32_e32 v92, 0x3fcc422a, v92
	v_exp_f32_e32 v90, v90
	v_mul_f32_e32 v92, 0xbfb8aa3b, v92
	v_exp_f32_e32 v92, v92
	v_mul_f32_e32 v93, 0x3d372713, v99
	v_mul_f32_e32 v93, v99, v93
	v_fma_f32 v93, v99, v93, v99
	v_add_f32_e32 v90, 1.0, v90
	v_mul_f32_e32 v93, 0x3fcc422a, v93
	v_rcp_f32_e32 v89, v89
	v_rcp_f32_e32 v90, v90
	v_add_f32_e32 v92, 1.0, v92
	v_mul_f32_e32 v93, 0xbfb8aa3b, v93
	v_rcp_f32_e32 v92, v92
	v_exp_f32_e32 v93, v93
	v_mul_f32_e32 v89, v94, v89
	v_mul_f32_e32 v90, v95, v90
	v_cvt_pk_bf16_f32 v89, v89, v90
	v_mul_f32_e32 v90, v98, v92
	v_add_f32_e32 v92, 1.0, v93
	v_mul_f32_e32 v93, 0x3d372713, v100
	v_mul_f32_e32 v94, 0x3d372713, v91
	v_mul_f32_e32 v93, v100, v93
	v_mul_f32_e32 v94, v91, v94
	v_fma_f32 v93, v100, v93, v100
	v_fma_f32 v94, v91, v94, v91
	v_mul_f32_e32 v93, 0x3fcc422a, v93
	v_mul_f32_e32 v94, 0x3fcc422a, v94
	v_mul_f32_e32 v93, 0xbfb8aa3b, v93
	v_mul_f32_e32 v94, 0xbfb8aa3b, v94
	v_exp_f32_e32 v93, v93
	v_exp_f32_e32 v94, v94
	v_rcp_f32_e32 v92, v92
	v_add_f32_e32 v93, 1.0, v93
	v_add_f32_e32 v94, 1.0, v94
	v_rcp_f32_e32 v93, v93
	v_rcp_f32_e32 v94, v94
	v_mul_f32_e32 v92, v99, v92
	v_cvt_pk_bf16_f32 v90, v90, v92
	v_mul_f32_e32 v92, v100, v93
	v_mul_f32_e32 v91, v91, v94
	v_cvt_pk_bf16_f32 v91, v92, v91
	v_lshlrev_b64 v[92:93], 10, v[194:195]
	v_lshl_add_u64 v[92:93], s[12:13], 0, v[92:93]
	v_lshl_add_u64 v[98:99], v[92:93], 0, v[192:193]
	global_store_dwordx4 v[98:99], v[88:91], off
	s_nop 1
	v_lshlrev_b32_e32 v88, 16, v144
	v_fma_f32 v84, v124, v88, v84
	v_and_b32_e32 v88, 0xffff0000, v144
	v_fma_f32 v85, v125, v88, v85
	v_lshlrev_b32_e32 v88, 16, v145
	v_fma_f32 v86, v126, v88, v86
	v_and_b32_e32 v88, 0xffff0000, v145
	v_fmac_f32_e32 v87, v127, v88
	v_lshlrev_b32_e32 v88, 16, v146
	v_fma_f32 v88, v120, v88, v80
	v_and_b32_e32 v80, 0xffff0000, v146
	v_fma_f32 v89, v121, v80, v81
	v_lshlrev_b32_e32 v80, 16, v147
	v_fma_f32 v90, v122, v80, v82
	v_mul_f32_e32 v81, 0x3d372713, v84
	v_mul_f32_e32 v82, 0x3d372713, v85
	v_mul_f32_e32 v81, v84, v81
	v_mul_f32_e32 v82, v85, v82
	v_fma_f32 v81, v84, v81, v84
	v_fma_f32 v82, v85, v82, v85
	v_mul_f32_e32 v81, 0x3fcc422a, v81
	v_mul_f32_e32 v82, 0x3fcc422a, v82
	v_mul_f32_e32 v81, 0xbfb8aa3b, v81
	v_mul_f32_e32 v82, 0xbfb8aa3b, v82
	v_exp_f32_e32 v81, v81
	v_exp_f32_e32 v82, v82
	v_and_b32_e32 v80, 0xffff0000, v147
	v_fmac_f32_e32 v83, v123, v80
	v_add_f32_e32 v80, 1.0, v81
	v_add_f32_e32 v81, 1.0, v82
	v_mul_f32_e32 v82, 0x3d372713, v86
	v_mul_f32_e32 v82, v86, v82
	v_fma_f32 v82, v86, v82, v86
	v_mul_f32_e32 v82, 0x3fcc422a, v82
	v_rcp_f32_e32 v80, v80
	v_rcp_f32_e32 v81, v81
	v_mul_f32_e32 v82, 0xbfb8aa3b, v82
	v_exp_f32_e32 v82, v82
	v_mul_f32_e32 v80, v84, v80
	v_mul_f32_e32 v81, v85, v81
	v_cvt_pk_bf16_f32 v80, v80, v81
	v_add_f32_e32 v81, 1.0, v82
	v_mul_f32_e32 v82, 0x3d372713, v87
	v_mul_f32_e32 v82, v87, v82
	v_mul_f32_e32 v84, 0x3d372713, v88
	v_fma_f32 v82, v87, v82, v87
	v_mul_f32_e32 v84, v88, v84
	v_mul_f32_e32 v82, 0x3fcc422a, v82
	v_fma_f32 v84, v88, v84, v88
	v_mul_f32_e32 v82, 0xbfb8aa3b, v82
	v_mul_f32_e32 v84, 0x3fcc422a, v84
	v_exp_f32_e32 v82, v82
	v_mul_f32_e32 v84, 0xbfb8aa3b, v84
	v_exp_f32_e32 v84, v84
	v_mul_f32_e32 v85, 0x3d372713, v89
	v_mul_f32_e32 v85, v89, v85
	v_fma_f32 v85, v89, v85, v89
	v_add_f32_e32 v82, 1.0, v82
	v_mul_f32_e32 v85, 0x3fcc422a, v85
	v_rcp_f32_e32 v81, v81
	v_rcp_f32_e32 v82, v82
	v_add_f32_e32 v84, 1.0, v84
	v_mul_f32_e32 v85, 0xbfb8aa3b, v85
	v_rcp_f32_e32 v84, v84
	v_exp_f32_e32 v85, v85
	v_mul_f32_e32 v81, v86, v81
	v_mul_f32_e32 v82, v87, v82
	v_cvt_pk_bf16_f32 v81, v81, v82
	v_mul_f32_e32 v82, v88, v84
	v_add_f32_e32 v84, 1.0, v85
	v_mul_f32_e32 v85, 0x3d372713, v90
	v_mul_f32_e32 v86, 0x3d372713, v83
	v_mul_f32_e32 v85, v90, v85
	v_mul_f32_e32 v86, v83, v86
	v_fma_f32 v85, v90, v85, v90
	v_fma_f32 v86, v83, v86, v83
	v_mul_f32_e32 v85, 0x3fcc422a, v85
	v_mul_f32_e32 v86, 0x3fcc422a, v86
	v_mul_f32_e32 v85, 0xbfb8aa3b, v85
	v_mul_f32_e32 v86, 0xbfb8aa3b, v86
	v_exp_f32_e32 v85, v85
	v_exp_f32_e32 v86, v86
	v_rcp_f32_e32 v84, v84
	v_add_f32_e32 v85, 1.0, v85
	v_add_f32_e32 v86, 1.0, v86
	v_rcp_f32_e32 v85, v85
	v_rcp_f32_e32 v86, v86
	v_mul_f32_e32 v84, v89, v84
	v_cvt_pk_bf16_f32 v82, v82, v84
	v_mul_f32_e32 v84, v90, v85
	v_mul_f32_e32 v83, v83, v86
	v_cvt_pk_bf16_f32 v83, v84, v83
	v_lshlrev_b64 v[84:85], 10, v[196:197]
	v_lshl_add_u64 v[84:85], s[12:13], 0, v[84:85]
	v_lshl_add_u64 v[100:101], v[84:85], 0, v[192:193]
	global_store_dwordx4 v[100:101], v[80:83], off
	s_nop 1
	v_lshlrev_b32_e32 v80, 16, v140
	v_fma_f32 v76, v124, v80, v76
	v_and_b32_e32 v80, 0xffff0000, v140
	v_fma_f32 v77, v125, v80, v77
	v_lshlrev_b32_e32 v80, 16, v141
	v_fma_f32 v78, v126, v80, v78
	v_and_b32_e32 v80, 0xffff0000, v141
	v_fmac_f32_e32 v79, v127, v80
	v_lshlrev_b32_e32 v80, 16, v142
	v_fma_f32 v80, v120, v80, v72
	v_and_b32_e32 v72, 0xffff0000, v142
	v_fma_f32 v81, v121, v72, v73
	v_lshlrev_b32_e32 v72, 16, v143
	v_fma_f32 v82, v122, v72, v74
	v_mul_f32_e32 v73, 0x3d372713, v76
	v_mul_f32_e32 v74, 0x3d372713, v77
	v_mul_f32_e32 v73, v76, v73
	v_mul_f32_e32 v74, v77, v74
	v_fma_f32 v73, v76, v73, v76
	v_fma_f32 v74, v77, v74, v77
	v_mul_f32_e32 v73, 0x3fcc422a, v73
	v_mul_f32_e32 v74, 0x3fcc422a, v74
	v_mul_f32_e32 v73, 0xbfb8aa3b, v73
	v_mul_f32_e32 v74, 0xbfb8aa3b, v74
	v_exp_f32_e32 v73, v73
	v_exp_f32_e32 v74, v74
	v_and_b32_e32 v72, 0xffff0000, v143
	v_fmac_f32_e32 v75, v123, v72
	v_add_f32_e32 v72, 1.0, v73
	v_add_f32_e32 v73, 1.0, v74
	v_mul_f32_e32 v74, 0x3d372713, v78
	v_mul_f32_e32 v74, v78, v74
	v_fma_f32 v74, v78, v74, v78
	v_mul_f32_e32 v74, 0x3fcc422a, v74
	v_rcp_f32_e32 v72, v72
	v_rcp_f32_e32 v73, v73
	v_mul_f32_e32 v74, 0xbfb8aa3b, v74
	v_exp_f32_e32 v74, v74
	v_mul_f32_e32 v72, v76, v72
	v_mul_f32_e32 v73, v77, v73
	v_cvt_pk_bf16_f32 v72, v72, v73
	v_add_f32_e32 v73, 1.0, v74
	v_mul_f32_e32 v74, 0x3d372713, v79
	v_mul_f32_e32 v74, v79, v74
	v_mul_f32_e32 v76, 0x3d372713, v80
	v_fma_f32 v74, v79, v74, v79
	v_mul_f32_e32 v76, v80, v76
	v_mul_f32_e32 v74, 0x3fcc422a, v74
	v_fma_f32 v76, v80, v76, v80
	v_mul_f32_e32 v74, 0xbfb8aa3b, v74
	v_mul_f32_e32 v76, 0x3fcc422a, v76
	v_exp_f32_e32 v74, v74
	v_mul_f32_e32 v76, 0xbfb8aa3b, v76
	v_exp_f32_e32 v76, v76
	v_mul_f32_e32 v77, 0x3d372713, v81
	v_mul_f32_e32 v77, v81, v77
	v_fma_f32 v77, v81, v77, v81
	v_add_f32_e32 v74, 1.0, v74
	v_mul_f32_e32 v77, 0x3fcc422a, v77
	v_rcp_f32_e32 v73, v73
	v_rcp_f32_e32 v74, v74
	v_add_f32_e32 v76, 1.0, v76
	v_mul_f32_e32 v77, 0xbfb8aa3b, v77
	v_rcp_f32_e32 v76, v76
	v_exp_f32_e32 v77, v77
	v_mul_f32_e32 v73, v78, v73
	v_mul_f32_e32 v74, v79, v74
	v_cvt_pk_bf16_f32 v73, v73, v74
	v_mul_f32_e32 v74, v80, v76
	v_add_f32_e32 v76, 1.0, v77
	v_mul_f32_e32 v77, 0x3d372713, v82
	v_mul_f32_e32 v78, 0x3d372713, v75
	v_mul_f32_e32 v77, v82, v77
	v_mul_f32_e32 v78, v75, v78
	v_fma_f32 v77, v82, v77, v82
	v_fma_f32 v78, v75, v78, v75
	v_mul_f32_e32 v77, 0x3fcc422a, v77
	v_mul_f32_e32 v78, 0x3fcc422a, v78
	v_mul_f32_e32 v77, 0xbfb8aa3b, v77
	v_mul_f32_e32 v78, 0xbfb8aa3b, v78
	v_exp_f32_e32 v77, v77
	v_exp_f32_e32 v78, v78
	v_rcp_f32_e32 v76, v76
	v_add_f32_e32 v77, 1.0, v77
	v_add_f32_e32 v78, 1.0, v78
	v_rcp_f32_e32 v77, v77
	v_rcp_f32_e32 v78, v78
	v_mul_f32_e32 v76, v81, v76
	v_cvt_pk_bf16_f32 v74, v74, v76
	v_mul_f32_e32 v76, v82, v77
	v_mul_f32_e32 v75, v75, v78
	v_cvt_pk_bf16_f32 v75, v76, v75
	v_lshlrev_b64 v[76:77], 10, v[198:199]
	v_lshl_add_u64 v[76:77], s[12:13], 0, v[76:77]
	v_lshl_add_u64 v[102:103], v[76:77], 0, v[192:193]
	global_store_dwordx4 v[102:103], v[72:75], off
	s_nop 1
	v_lshlrev_b32_e32 v72, 16, v132
	v_fma_f32 v68, v124, v72, v68
	v_and_b32_e32 v72, 0xffff0000, v132
	v_fma_f32 v69, v125, v72, v69
	v_lshlrev_b32_e32 v72, 16, v133
	v_fma_f32 v70, v126, v72, v70
	v_and_b32_e32 v72, 0xffff0000, v133
	v_fmac_f32_e32 v71, v127, v72
	v_lshlrev_b32_e32 v72, 16, v134
	v_fma_f32 v72, v120, v72, v64
	v_and_b32_e32 v64, 0xffff0000, v134
	v_fma_f32 v73, v121, v64, v65
	v_lshlrev_b32_e32 v64, 16, v135
	v_fma_f32 v74, v122, v64, v66
	v_mul_f32_e32 v65, 0x3d372713, v68
	v_mul_f32_e32 v66, 0x3d372713, v69
	v_mul_f32_e32 v65, v68, v65
	v_mul_f32_e32 v66, v69, v66
	v_fma_f32 v65, v68, v65, v68
	v_fma_f32 v66, v69, v66, v69
	v_mul_f32_e32 v65, 0x3fcc422a, v65
	v_mul_f32_e32 v66, 0x3fcc422a, v66
	v_mul_f32_e32 v65, 0xbfb8aa3b, v65
	v_mul_f32_e32 v66, 0xbfb8aa3b, v66
	v_exp_f32_e32 v65, v65
	v_exp_f32_e32 v66, v66
	v_and_b32_e32 v64, 0xffff0000, v135
	v_fmac_f32_e32 v67, v123, v64
	v_add_f32_e32 v64, 1.0, v65
	v_add_f32_e32 v65, 1.0, v66
	v_mul_f32_e32 v66, 0x3d372713, v70
	v_mul_f32_e32 v66, v70, v66
	v_fma_f32 v66, v70, v66, v70
	v_mul_f32_e32 v66, 0x3fcc422a, v66
	v_rcp_f32_e32 v64, v64
	v_rcp_f32_e32 v65, v65
	v_mul_f32_e32 v66, 0xbfb8aa3b, v66
	v_exp_f32_e32 v66, v66
	v_mul_f32_e32 v64, v68, v64
	v_mul_f32_e32 v65, v69, v65
	v_cvt_pk_bf16_f32 v64, v64, v65
	v_add_f32_e32 v65, 1.0, v66
	v_mul_f32_e32 v66, 0x3d372713, v71
	v_mul_f32_e32 v66, v71, v66
	v_mul_f32_e32 v68, 0x3d372713, v72
	v_fma_f32 v66, v71, v66, v71
	v_mul_f32_e32 v68, v72, v68
	v_mul_f32_e32 v66, 0x3fcc422a, v66
	v_fma_f32 v68, v72, v68, v72
	v_mul_f32_e32 v66, 0xbfb8aa3b, v66
	v_mul_f32_e32 v68, 0x3fcc422a, v68
	v_exp_f32_e32 v66, v66
	v_mul_f32_e32 v68, 0xbfb8aa3b, v68
	v_exp_f32_e32 v68, v68
	v_mul_f32_e32 v69, 0x3d372713, v73
	v_mul_f32_e32 v69, v73, v69
	v_fma_f32 v69, v73, v69, v73
	v_add_f32_e32 v66, 1.0, v66
	v_mul_f32_e32 v69, 0x3fcc422a, v69
	v_rcp_f32_e32 v65, v65
	v_rcp_f32_e32 v66, v66
	v_add_f32_e32 v68, 1.0, v68
	v_mul_f32_e32 v69, 0xbfb8aa3b, v69
	v_rcp_f32_e32 v68, v68
	v_exp_f32_e32 v69, v69
	v_mul_f32_e32 v65, v70, v65
	v_mul_f32_e32 v66, v71, v66
	v_cvt_pk_bf16_f32 v65, v65, v66
	v_mul_f32_e32 v66, v72, v68
	v_add_f32_e32 v68, 1.0, v69
	v_mul_f32_e32 v69, 0x3d372713, v74
	v_mul_f32_e32 v70, 0x3d372713, v67
	v_mul_f32_e32 v69, v74, v69
	v_mul_f32_e32 v70, v67, v70
	v_fma_f32 v69, v74, v69, v74
	v_fma_f32 v70, v67, v70, v67
	v_mul_f32_e32 v69, 0x3fcc422a, v69
	v_mul_f32_e32 v70, 0x3fcc422a, v70
	v_mul_f32_e32 v69, 0xbfb8aa3b, v69
	v_mul_f32_e32 v70, 0xbfb8aa3b, v70
	v_exp_f32_e32 v69, v69
	v_exp_f32_e32 v70, v70
	v_rcp_f32_e32 v68, v68
	v_add_f32_e32 v69, 1.0, v69
	v_add_f32_e32 v70, 1.0, v70
	v_rcp_f32_e32 v69, v69
	v_rcp_f32_e32 v70, v70
	v_mul_f32_e32 v68, v73, v68
	v_cvt_pk_bf16_f32 v66, v66, v68
	v_mul_f32_e32 v68, v74, v69
	v_mul_f32_e32 v67, v67, v70
	v_cvt_pk_bf16_f32 v67, v68, v67
	v_lshlrev_b64 v[68:69], 10, v[200:201]
	v_lshl_add_u64 v[68:69], s[12:13], 0, v[68:69]
	v_lshl_add_u64 v[106:107], v[68:69], 0, v[192:193]
	global_store_dwordx4 v[106:107], v[64:67], off
	v_or_b32_e32 v72, 0x80, v182
	v_ashrrev_i32_e32 v73, 31, v72
	v_mov_b64_e32 v[74:75], s[2:3]
	v_mad_i64_i32 v[76:77], s[0:1], v180, s33, v[74:75]
	v_lshlrev_b64 v[72:73], 1, v[72:73]
	v_lshl_add_u64 v[76:77], v[76:77], 0, v[72:73]
	v_mad_i64_i32 v[78:79], s[0:1], v186, s33, v[74:75]
	global_load_dwordx4 v[64:67], v[184:185], off offset:16
	global_load_dwordx4 v[68:71], v[184:185], off
	v_lshl_add_u64 v[78:79], v[78:79], 0, v[72:73]
	global_load_dwordx4 v[108:111], v[76:77], off
	global_load_dwordx4 v[114:117], v[78:79], off
	v_mad_i64_i32 v[76:77], s[0:1], v188, s33, v[74:75]
	v_lshl_add_u64 v[76:77], v[76:77], 0, v[72:73]
	v_mad_i64_i32 v[78:79], s[0:1], v190, s33, v[74:75]
	v_lshl_add_u64 v[78:79], v[78:79], 0, v[72:73]
	global_load_dwordx4 v[92:95], v[76:77], off
	global_load_dwordx4 v[88:91], v[78:79], off
	v_mad_i64_i32 v[76:77], s[0:1], v194, s33, v[74:75]
	v_lshl_add_u64 v[76:77], v[76:77], 0, v[72:73]
	v_mad_i64_i32 v[78:79], s[0:1], v196, s33, v[74:75]
	v_lshl_add_u64 v[78:79], v[78:79], 0, v[72:73]
	global_load_dwordx4 v[84:87], v[76:77], off
	global_load_dwordx4 v[80:83], v[78:79], off
	v_mad_i64_i32 v[76:77], s[0:1], v198, s33, v[74:75]
	v_mad_i64_i32 v[74:75], s[0:1], v200, s33, v[74:75]
	v_lshl_add_u64 v[76:77], v[76:77], 0, v[72:73]
	v_lshl_add_u64 v[72:73], v[74:75], 0, v[72:73]
	global_load_dwordx4 v[76:79], v[76:77], off
	s_nop 0
	global_load_dwordx4 v[72:75], v[72:73], off
	s_waitcnt vmcnt(7)
	v_lshlrev_b32_e32 v118, 16, v108
	v_and_b32_e32 v108, 0xffff0000, v108
	v_fma_f32 v61, v69, v108, v61
	v_lshlrev_b32_e32 v108, 16, v109
	v_fma_f32 v62, v70, v108, v62
	v_and_b32_e32 v108, 0xffff0000, v109
	v_fmac_f32_e32 v63, v71, v108
	v_lshlrev_b32_e32 v108, 16, v110
	v_fma_f32 v108, v64, v108, v56
	v_and_b32_e32 v56, 0xffff0000, v110
	v_fma_f32 v60, v68, v118, v60
	v_fma_f32 v109, v65, v56, v57
	v_lshlrev_b32_e32 v56, 16, v111
	v_fma_f32 v110, v66, v56, v58
	v_mul_f32_e32 v57, 0x3d372713, v60
	v_mul_f32_e32 v58, 0x3d372713, v61
	v_mul_f32_e32 v57, v60, v57
	v_mul_f32_e32 v58, v61, v58
	v_fma_f32 v57, v60, v57, v60
	v_fma_f32 v58, v61, v58, v61
	v_mul_f32_e32 v57, 0x3fcc422a, v57
	v_mul_f32_e32 v58, 0x3fcc422a, v58
	v_mul_f32_e32 v57, 0xbfb8aa3b, v57
	v_mul_f32_e32 v58, 0xbfb8aa3b, v58
	v_exp_f32_e32 v57, v57
	v_exp_f32_e32 v58, v58
	v_and_b32_e32 v56, 0xffff0000, v111
	v_fmac_f32_e32 v59, v67, v56
	v_add_f32_e32 v56, 1.0, v57
	v_add_f32_e32 v57, 1.0, v58
	v_mul_f32_e32 v58, 0x3d372713, v62
	v_mul_f32_e32 v58, v62, v58
	v_fma_f32 v58, v62, v58, v62
	v_mul_f32_e32 v58, 0x3fcc422a, v58
	v_rcp_f32_e32 v56, v56
	v_rcp_f32_e32 v57, v57
	v_mul_f32_e32 v58, 0xbfb8aa3b, v58
	v_exp_f32_e32 v58, v58
	v_mul_f32_e32 v56, v60, v56
	v_mul_f32_e32 v57, v61, v57
	v_cvt_pk_bf16_f32 v56, v56, v57
	v_add_f32_e32 v57, 1.0, v58
	v_mul_f32_e32 v58, 0x3d372713, v63
	v_mul_f32_e32 v58, v63, v58
	v_mul_f32_e32 v60, 0x3d372713, v108
	v_fma_f32 v58, v63, v58, v63
	v_mul_f32_e32 v60, v108, v60
	v_mul_f32_e32 v58, 0x3fcc422a, v58
	v_fma_f32 v60, v108, v60, v108
	v_mul_f32_e32 v58, 0xbfb8aa3b, v58
	v_mul_f32_e32 v60, 0x3fcc422a, v60
	v_exp_f32_e32 v58, v58
	v_mul_f32_e32 v60, 0xbfb8aa3b, v60
	v_exp_f32_e32 v60, v60
	v_mul_f32_e32 v61, 0x3d372713, v109
	v_mul_f32_e32 v61, v109, v61
	v_fma_f32 v61, v109, v61, v109
	v_add_f32_e32 v58, 1.0, v58
	v_mul_f32_e32 v61, 0x3fcc422a, v61
	v_rcp_f32_e32 v57, v57
	v_rcp_f32_e32 v58, v58
	v_add_f32_e32 v60, 1.0, v60
	v_mul_f32_e32 v61, 0xbfb8aa3b, v61
	v_rcp_f32_e32 v60, v60
	v_exp_f32_e32 v61, v61
	v_mul_f32_e32 v57, v62, v57
	v_mul_f32_e32 v58, v63, v58
	v_mul_f32_e32 v62, 0x3d372713, v59
	v_cvt_pk_bf16_f32 v57, v57, v58
	v_mul_f32_e32 v58, v108, v60
	v_add_f32_e32 v60, 1.0, v61
	v_mul_f32_e32 v61, 0x3d372713, v110
	v_mul_f32_e32 v62, v59, v62
	v_mul_f32_e32 v61, v110, v61
	v_fma_f32 v62, v59, v62, v59
	v_fma_f32 v61, v110, v61, v110
	v_mul_f32_e32 v62, 0x3fcc422a, v62
	v_mul_f32_e32 v61, 0x3fcc422a, v61
	v_mul_f32_e32 v62, 0xbfb8aa3b, v62
	v_mul_f32_e32 v61, 0xbfb8aa3b, v61
	v_exp_f32_e32 v62, v62
	v_exp_f32_e32 v61, v61
	v_rcp_f32_e32 v60, v60
	v_add_f32_e32 v62, 1.0, v62
	v_add_f32_e32 v61, 1.0, v61
	v_rcp_f32_e32 v62, v62
	v_rcp_f32_e32 v61, v61
	v_mul_f32_e32 v60, v109, v60
	v_cvt_pk_bf16_f32 v58, v58, v60
	v_mul_f32_e32 v59, v59, v62
	v_mul_f32_e32 v60, v110, v61
	v_cvt_pk_bf16_f32 v59, v60, v59
	global_store_dwordx4 v[128:129], v[56:59], off offset:256
	s_waitcnt vmcnt(7)
	s_nop 0
	v_lshlrev_b32_e32 v56, 16, v114
	v_fma_f32 v52, v68, v56, v52
	v_and_b32_e32 v56, 0xffff0000, v114
	v_fma_f32 v53, v69, v56, v53
	v_lshlrev_b32_e32 v56, 16, v115
	v_fma_f32 v54, v70, v56, v54
	v_and_b32_e32 v56, 0xffff0000, v115
	v_fmac_f32_e32 v55, v71, v56
	v_lshlrev_b32_e32 v56, 16, v116
	v_fma_f32 v56, v64, v56, v48
	v_and_b32_e32 v48, 0xffff0000, v116
	v_fma_f32 v57, v65, v48, v49
	v_lshlrev_b32_e32 v48, 16, v117
	v_fma_f32 v58, v66, v48, v50
	v_mul_f32_e32 v49, 0x3d372713, v52
	v_mul_f32_e32 v50, 0x3d372713, v53
	v_mul_f32_e32 v49, v52, v49
	v_mul_f32_e32 v50, v53, v50
	v_fma_f32 v49, v52, v49, v52
	v_fma_f32 v50, v53, v50, v53
	v_mul_f32_e32 v49, 0x3fcc422a, v49
	v_mul_f32_e32 v50, 0x3fcc422a, v50
	v_mul_f32_e32 v49, 0xbfb8aa3b, v49
	v_mul_f32_e32 v50, 0xbfb8aa3b, v50
	v_exp_f32_e32 v49, v49
	v_exp_f32_e32 v50, v50
	v_and_b32_e32 v48, 0xffff0000, v117
	v_fmac_f32_e32 v51, v67, v48
	v_add_f32_e32 v48, 1.0, v49
	v_add_f32_e32 v49, 1.0, v50
	v_mul_f32_e32 v50, 0x3d372713, v54
	v_mul_f32_e32 v50, v54, v50
	v_fma_f32 v50, v54, v50, v54
	v_mul_f32_e32 v50, 0x3fcc422a, v50
	v_rcp_f32_e32 v48, v48
	v_rcp_f32_e32 v49, v49
	v_mul_f32_e32 v50, 0xbfb8aa3b, v50
	v_exp_f32_e32 v50, v50
	v_mul_f32_e32 v48, v52, v48
	v_mul_f32_e32 v49, v53, v49
	v_cvt_pk_bf16_f32 v48, v48, v49
	v_add_f32_e32 v49, 1.0, v50
	v_mul_f32_e32 v50, 0x3d372713, v55
	v_mul_f32_e32 v50, v55, v50
	v_mul_f32_e32 v52, 0x3d372713, v56
	v_fma_f32 v50, v55, v50, v55
	v_mul_f32_e32 v52, v56, v52
	v_mul_f32_e32 v50, 0x3fcc422a, v50
	v_fma_f32 v52, v56, v52, v56
	v_mul_f32_e32 v50, 0xbfb8aa3b, v50
	v_mul_f32_e32 v52, 0x3fcc422a, v52
	v_exp_f32_e32 v50, v50
	v_mul_f32_e32 v52, 0xbfb8aa3b, v52
	v_exp_f32_e32 v52, v52
	v_mul_f32_e32 v53, 0x3d372713, v57
	v_mul_f32_e32 v53, v57, v53
	v_fma_f32 v53, v57, v53, v57
	v_add_f32_e32 v50, 1.0, v50
	v_mul_f32_e32 v53, 0x3fcc422a, v53
	v_rcp_f32_e32 v49, v49
	v_rcp_f32_e32 v50, v50
	v_add_f32_e32 v52, 1.0, v52
	v_mul_f32_e32 v53, 0xbfb8aa3b, v53
	v_rcp_f32_e32 v52, v52
	v_exp_f32_e32 v53, v53
	v_mul_f32_e32 v49, v54, v49
	v_mul_f32_e32 v50, v55, v50
	v_mul_f32_e32 v54, 0x3d372713, v51
	v_cvt_pk_bf16_f32 v49, v49, v50
	v_mul_f32_e32 v50, v56, v52
	v_add_f32_e32 v52, 1.0, v53
	v_mul_f32_e32 v53, 0x3d372713, v58
	v_mul_f32_e32 v54, v51, v54
	v_mul_f32_e32 v53, v58, v53
	v_fma_f32 v54, v51, v54, v51
	v_fma_f32 v53, v58, v53, v58
	v_mul_f32_e32 v54, 0x3fcc422a, v54
	v_mul_f32_e32 v53, 0x3fcc422a, v53
	v_mul_f32_e32 v54, 0xbfb8aa3b, v54
	v_mul_f32_e32 v53, 0xbfb8aa3b, v53
	v_exp_f32_e32 v54, v54
	v_exp_f32_e32 v53, v53
	v_rcp_f32_e32 v52, v52
	v_add_f32_e32 v54, 1.0, v54
	v_add_f32_e32 v53, 1.0, v53
	v_rcp_f32_e32 v54, v54
	v_rcp_f32_e32 v53, v53
	v_mul_f32_e32 v52, v57, v52
	v_cvt_pk_bf16_f32 v50, v50, v52
	v_mul_f32_e32 v51, v51, v54
	v_mul_f32_e32 v52, v58, v53
	v_cvt_pk_bf16_f32 v51, v52, v51
	global_store_dwordx4 v[112:113], v[48:51], off offset:256
	s_waitcnt vmcnt(7)
	s_nop 0
	v_lshlrev_b32_e32 v48, 16, v92
	v_fma_f32 v44, v68, v48, v44
	v_and_b32_e32 v48, 0xffff0000, v92
	v_fma_f32 v45, v69, v48, v45
	v_lshlrev_b32_e32 v48, 16, v93
	v_fma_f32 v46, v70, v48, v46
	v_and_b32_e32 v48, 0xffff0000, v93
	v_fmac_f32_e32 v47, v71, v48
	v_lshlrev_b32_e32 v48, 16, v94
	v_fma_f32 v48, v64, v48, v40
	v_and_b32_e32 v40, 0xffff0000, v94
	v_fma_f32 v49, v65, v40, v41
	v_lshlrev_b32_e32 v40, 16, v95
	v_fma_f32 v50, v66, v40, v42
	v_mul_f32_e32 v41, 0x3d372713, v44
	v_mul_f32_e32 v42, 0x3d372713, v45
	v_mul_f32_e32 v41, v44, v41
	v_mul_f32_e32 v42, v45, v42
	v_fma_f32 v41, v44, v41, v44
	v_fma_f32 v42, v45, v42, v45
	v_mul_f32_e32 v41, 0x3fcc422a, v41
	v_mul_f32_e32 v42, 0x3fcc422a, v42
	v_mul_f32_e32 v41, 0xbfb8aa3b, v41
	v_mul_f32_e32 v42, 0xbfb8aa3b, v42
	v_exp_f32_e32 v41, v41
	v_exp_f32_e32 v42, v42
	v_and_b32_e32 v40, 0xffff0000, v95
	v_fmac_f32_e32 v43, v67, v40
	v_add_f32_e32 v40, 1.0, v41
	v_add_f32_e32 v41, 1.0, v42
	v_mul_f32_e32 v42, 0x3d372713, v46
	v_mul_f32_e32 v42, v46, v42
	v_fma_f32 v42, v46, v42, v46
	v_mul_f32_e32 v42, 0x3fcc422a, v42
	v_rcp_f32_e32 v40, v40
	v_rcp_f32_e32 v41, v41
	v_mul_f32_e32 v42, 0xbfb8aa3b, v42
	v_exp_f32_e32 v42, v42
	v_mul_f32_e32 v40, v44, v40
	v_mul_f32_e32 v41, v45, v41
	v_cvt_pk_bf16_f32 v40, v40, v41
	v_add_f32_e32 v41, 1.0, v42
	v_mul_f32_e32 v42, 0x3d372713, v47
	v_mul_f32_e32 v42, v47, v42
	v_mul_f32_e32 v44, 0x3d372713, v48
	v_fma_f32 v42, v47, v42, v47
	v_mul_f32_e32 v44, v48, v44
	v_mul_f32_e32 v42, 0x3fcc422a, v42
	v_fma_f32 v44, v48, v44, v48
	v_mul_f32_e32 v42, 0xbfb8aa3b, v42
	v_mul_f32_e32 v44, 0x3fcc422a, v44
	v_exp_f32_e32 v42, v42
	v_mul_f32_e32 v44, 0xbfb8aa3b, v44
	v_exp_f32_e32 v44, v44
	v_mul_f32_e32 v45, 0x3d372713, v49
	v_mul_f32_e32 v45, v49, v45
	v_fma_f32 v45, v49, v45, v49
	v_add_f32_e32 v42, 1.0, v42
	v_mul_f32_e32 v45, 0x3fcc422a, v45
	v_rcp_f32_e32 v41, v41
	v_rcp_f32_e32 v42, v42
	v_add_f32_e32 v44, 1.0, v44
	v_mul_f32_e32 v45, 0xbfb8aa3b, v45
	v_rcp_f32_e32 v44, v44
	v_exp_f32_e32 v45, v45
	v_mul_f32_e32 v41, v46, v41
	v_mul_f32_e32 v42, v47, v42
	v_mul_f32_e32 v46, 0x3d372713, v43
	v_cvt_pk_bf16_f32 v41, v41, v42
	v_mul_f32_e32 v42, v48, v44
	v_add_f32_e32 v44, 1.0, v45
	v_mul_f32_e32 v45, 0x3d372713, v50
	v_mul_f32_e32 v46, v43, v46
	v_mul_f32_e32 v45, v50, v45
	v_fma_f32 v46, v43, v46, v43
	v_fma_f32 v45, v50, v45, v50
	v_mul_f32_e32 v46, 0x3fcc422a, v46
	v_mul_f32_e32 v45, 0x3fcc422a, v45
	v_mul_f32_e32 v46, 0xbfb8aa3b, v46
	v_mul_f32_e32 v45, 0xbfb8aa3b, v45
	v_exp_f32_e32 v46, v46
	v_exp_f32_e32 v45, v45
	v_rcp_f32_e32 v44, v44
	v_add_f32_e32 v46, 1.0, v46
	v_add_f32_e32 v45, 1.0, v45
	v_rcp_f32_e32 v46, v46
	v_rcp_f32_e32 v45, v45
	v_mul_f32_e32 v44, v49, v44
	v_cvt_pk_bf16_f32 v42, v42, v44
	v_mul_f32_e32 v43, v43, v46
	v_mul_f32_e32 v44, v50, v45
	v_cvt_pk_bf16_f32 v43, v44, v43
	global_store_dwordx4 v[104:105], v[40:43], off offset:256
	s_waitcnt vmcnt(7)
	s_nop 0
	v_lshlrev_b32_e32 v40, 16, v88
	v_fma_f32 v36, v68, v40, v36
	v_and_b32_e32 v40, 0xffff0000, v88
	v_fma_f32 v37, v69, v40, v37
	v_lshlrev_b32_e32 v40, 16, v89
	v_fma_f32 v38, v70, v40, v38
	v_and_b32_e32 v40, 0xffff0000, v89
	v_fmac_f32_e32 v39, v71, v40
	v_lshlrev_b32_e32 v40, 16, v90
	v_fma_f32 v40, v64, v40, v32
	v_and_b32_e32 v32, 0xffff0000, v90
	v_fma_f32 v41, v65, v32, v33
	v_lshlrev_b32_e32 v32, 16, v91
	v_fma_f32 v42, v66, v32, v34
	v_mul_f32_e32 v33, 0x3d372713, v36
	v_mul_f32_e32 v34, 0x3d372713, v37
	v_mul_f32_e32 v33, v36, v33
	v_mul_f32_e32 v34, v37, v34
	v_fma_f32 v33, v36, v33, v36
	v_fma_f32 v34, v37, v34, v37
	v_mul_f32_e32 v33, 0x3fcc422a, v33
	v_mul_f32_e32 v34, 0x3fcc422a, v34
	v_mul_f32_e32 v33, 0xbfb8aa3b, v33
	v_mul_f32_e32 v34, 0xbfb8aa3b, v34
	v_exp_f32_e32 v33, v33
	v_exp_f32_e32 v34, v34
	v_and_b32_e32 v32, 0xffff0000, v91
	v_fmac_f32_e32 v35, v67, v32
	v_add_f32_e32 v32, 1.0, v33
	v_add_f32_e32 v33, 1.0, v34
	v_mul_f32_e32 v34, 0x3d372713, v38
	v_mul_f32_e32 v34, v38, v34
	v_fma_f32 v34, v38, v34, v38
	v_mul_f32_e32 v34, 0x3fcc422a, v34
	v_rcp_f32_e32 v32, v32
	v_rcp_f32_e32 v33, v33
	v_mul_f32_e32 v34, 0xbfb8aa3b, v34
	v_exp_f32_e32 v34, v34
	v_mul_f32_e32 v32, v36, v32
	v_mul_f32_e32 v33, v37, v33
	v_cvt_pk_bf16_f32 v32, v32, v33
	v_add_f32_e32 v33, 1.0, v34
	v_mul_f32_e32 v34, 0x3d372713, v39
	v_mul_f32_e32 v34, v39, v34
	v_mul_f32_e32 v36, 0x3d372713, v40
	v_fma_f32 v34, v39, v34, v39
	v_mul_f32_e32 v36, v40, v36
	v_mul_f32_e32 v34, 0x3fcc422a, v34
	v_fma_f32 v36, v40, v36, v40
	v_mul_f32_e32 v34, 0xbfb8aa3b, v34
	v_mul_f32_e32 v36, 0x3fcc422a, v36
	v_exp_f32_e32 v34, v34
	v_mul_f32_e32 v36, 0xbfb8aa3b, v36
	v_exp_f32_e32 v36, v36
	v_mul_f32_e32 v37, 0x3d372713, v41
	v_mul_f32_e32 v37, v41, v37
	v_fma_f32 v37, v41, v37, v41
	v_add_f32_e32 v34, 1.0, v34
	v_mul_f32_e32 v37, 0x3fcc422a, v37
	v_rcp_f32_e32 v33, v33
	v_rcp_f32_e32 v34, v34
	v_add_f32_e32 v36, 1.0, v36
	v_mul_f32_e32 v37, 0xbfb8aa3b, v37
	v_rcp_f32_e32 v36, v36
	v_exp_f32_e32 v37, v37
	v_mul_f32_e32 v33, v38, v33
	v_mul_f32_e32 v34, v39, v34
	v_mul_f32_e32 v38, 0x3d372713, v35
	v_cvt_pk_bf16_f32 v33, v33, v34
	v_mul_f32_e32 v34, v40, v36
	v_add_f32_e32 v36, 1.0, v37
	v_mul_f32_e32 v37, 0x3d372713, v42
	v_mul_f32_e32 v38, v35, v38
	v_mul_f32_e32 v37, v42, v37
	v_fma_f32 v38, v35, v38, v35
	v_fma_f32 v37, v42, v37, v42
	v_mul_f32_e32 v38, 0x3fcc422a, v38
	v_mul_f32_e32 v37, 0x3fcc422a, v37
	v_mul_f32_e32 v38, 0xbfb8aa3b, v38
	v_mul_f32_e32 v37, 0xbfb8aa3b, v37
	v_exp_f32_e32 v38, v38
	v_exp_f32_e32 v37, v37
	v_rcp_f32_e32 v36, v36
	v_add_f32_e32 v38, 1.0, v38
	v_add_f32_e32 v37, 1.0, v37
	v_rcp_f32_e32 v38, v38
	v_rcp_f32_e32 v37, v37
	v_mul_f32_e32 v36, v41, v36
	v_cvt_pk_bf16_f32 v34, v34, v36
	v_mul_f32_e32 v35, v35, v38
	v_mul_f32_e32 v36, v42, v37
	v_cvt_pk_bf16_f32 v35, v36, v35
	global_store_dwordx4 v[96:97], v[32:35], off offset:256
	s_waitcnt vmcnt(7)
	s_nop 0
	v_lshlrev_b32_e32 v32, 16, v84
	v_fma_f32 v28, v68, v32, v28
	v_and_b32_e32 v32, 0xffff0000, v84
	v_fma_f32 v29, v69, v32, v29
	v_lshlrev_b32_e32 v32, 16, v85
	v_fma_f32 v30, v70, v32, v30
	v_and_b32_e32 v32, 0xffff0000, v85
	v_fmac_f32_e32 v31, v71, v32
	v_lshlrev_b32_e32 v32, 16, v86
	v_fma_f32 v32, v64, v32, v24
	v_and_b32_e32 v24, 0xffff0000, v86
	v_fma_f32 v33, v65, v24, v25
	v_lshlrev_b32_e32 v24, 16, v87
	v_fma_f32 v34, v66, v24, v26
	v_mul_f32_e32 v25, 0x3d372713, v28
	v_mul_f32_e32 v26, 0x3d372713, v29
	v_mul_f32_e32 v25, v28, v25
	v_mul_f32_e32 v26, v29, v26
	v_fma_f32 v25, v28, v25, v28
	v_fma_f32 v26, v29, v26, v29
	v_mul_f32_e32 v25, 0x3fcc422a, v25
	v_mul_f32_e32 v26, 0x3fcc422a, v26
	v_mul_f32_e32 v25, 0xbfb8aa3b, v25
	v_mul_f32_e32 v26, 0xbfb8aa3b, v26
	v_exp_f32_e32 v25, v25
	v_exp_f32_e32 v26, v26
	v_and_b32_e32 v24, 0xffff0000, v87
	v_fmac_f32_e32 v27, v67, v24
	v_add_f32_e32 v24, 1.0, v25
	v_add_f32_e32 v25, 1.0, v26
	v_mul_f32_e32 v26, 0x3d372713, v30
	v_mul_f32_e32 v26, v30, v26
	v_fma_f32 v26, v30, v26, v30
	v_mul_f32_e32 v26, 0x3fcc422a, v26
	v_rcp_f32_e32 v24, v24
	v_rcp_f32_e32 v25, v25
	v_mul_f32_e32 v26, 0xbfb8aa3b, v26
	v_exp_f32_e32 v26, v26
	v_mul_f32_e32 v24, v28, v24
	v_mul_f32_e32 v25, v29, v25
	v_cvt_pk_bf16_f32 v24, v24, v25
	v_add_f32_e32 v25, 1.0, v26
	v_mul_f32_e32 v26, 0x3d372713, v31
	v_mul_f32_e32 v26, v31, v26
	v_mul_f32_e32 v28, 0x3d372713, v32
	v_fma_f32 v26, v31, v26, v31
	v_mul_f32_e32 v28, v32, v28
	v_mul_f32_e32 v26, 0x3fcc422a, v26
	v_fma_f32 v28, v32, v28, v32
	v_mul_f32_e32 v26, 0xbfb8aa3b, v26
	v_mul_f32_e32 v28, 0x3fcc422a, v28
	v_exp_f32_e32 v26, v26
	v_mul_f32_e32 v28, 0xbfb8aa3b, v28
	v_exp_f32_e32 v28, v28
	v_mul_f32_e32 v29, 0x3d372713, v33
	v_mul_f32_e32 v29, v33, v29
	v_fma_f32 v29, v33, v29, v33
	v_add_f32_e32 v26, 1.0, v26
	v_mul_f32_e32 v29, 0x3fcc422a, v29
	v_rcp_f32_e32 v25, v25
	v_rcp_f32_e32 v26, v26
	v_add_f32_e32 v28, 1.0, v28
	v_mul_f32_e32 v29, 0xbfb8aa3b, v29
	v_rcp_f32_e32 v28, v28
	v_exp_f32_e32 v29, v29
	v_mul_f32_e32 v25, v30, v25
	v_mul_f32_e32 v26, v31, v26
	v_mul_f32_e32 v30, 0x3d372713, v27
	v_cvt_pk_bf16_f32 v25, v25, v26
	v_mul_f32_e32 v26, v32, v28
	v_add_f32_e32 v28, 1.0, v29
	v_mul_f32_e32 v29, 0x3d372713, v34
	v_mul_f32_e32 v30, v27, v30
	v_mul_f32_e32 v29, v34, v29
	v_fma_f32 v30, v27, v30, v27
	v_fma_f32 v29, v34, v29, v34
	v_mul_f32_e32 v30, 0x3fcc422a, v30
	v_mul_f32_e32 v29, 0x3fcc422a, v29
	v_mul_f32_e32 v30, 0xbfb8aa3b, v30
	v_mul_f32_e32 v29, 0xbfb8aa3b, v29
	v_exp_f32_e32 v30, v30
	v_exp_f32_e32 v29, v29
	v_rcp_f32_e32 v28, v28
	v_add_f32_e32 v30, 1.0, v30
	v_add_f32_e32 v29, 1.0, v29
	v_rcp_f32_e32 v30, v30
	v_rcp_f32_e32 v29, v29
	v_mul_f32_e32 v28, v33, v28
	v_cvt_pk_bf16_f32 v26, v26, v28
	v_mul_f32_e32 v27, v27, v30
	v_mul_f32_e32 v28, v34, v29
	v_cvt_pk_bf16_f32 v27, v28, v27
	global_store_dwordx4 v[98:99], v[24:27], off offset:256
	s_waitcnt vmcnt(7)
	s_nop 0
	v_lshlrev_b32_e32 v24, 16, v80
	v_fma_f32 v20, v68, v24, v20
	v_and_b32_e32 v24, 0xffff0000, v80
	v_fma_f32 v21, v69, v24, v21
	v_lshlrev_b32_e32 v24, 16, v81
	v_fma_f32 v22, v70, v24, v22
	v_and_b32_e32 v24, 0xffff0000, v81
	v_fmac_f32_e32 v23, v71, v24
	v_lshlrev_b32_e32 v24, 16, v82
	v_fma_f32 v24, v64, v24, v16
	v_and_b32_e32 v16, 0xffff0000, v82
	v_fma_f32 v25, v65, v16, v17
	v_lshlrev_b32_e32 v16, 16, v83
	v_fma_f32 v26, v66, v16, v18
	v_mul_f32_e32 v17, 0x3d372713, v20
	v_mul_f32_e32 v18, 0x3d372713, v21
	v_mul_f32_e32 v17, v20, v17
	v_mul_f32_e32 v18, v21, v18
	v_fma_f32 v17, v20, v17, v20
	v_fma_f32 v18, v21, v18, v21
	v_mul_f32_e32 v17, 0x3fcc422a, v17
	v_mul_f32_e32 v18, 0x3fcc422a, v18
	v_mul_f32_e32 v17, 0xbfb8aa3b, v17
	v_mul_f32_e32 v18, 0xbfb8aa3b, v18
	v_exp_f32_e32 v17, v17
	v_exp_f32_e32 v18, v18
	v_and_b32_e32 v16, 0xffff0000, v83
	v_fmac_f32_e32 v19, v67, v16
	v_add_f32_e32 v16, 1.0, v17
	v_add_f32_e32 v17, 1.0, v18
	v_mul_f32_e32 v18, 0x3d372713, v22
	v_mul_f32_e32 v18, v22, v18
	v_fma_f32 v18, v22, v18, v22
	v_mul_f32_e32 v18, 0x3fcc422a, v18
	v_rcp_f32_e32 v16, v16
	v_rcp_f32_e32 v17, v17
	v_mul_f32_e32 v18, 0xbfb8aa3b, v18
	v_exp_f32_e32 v18, v18
	v_mul_f32_e32 v16, v20, v16
	v_mul_f32_e32 v17, v21, v17
	v_cvt_pk_bf16_f32 v16, v16, v17
	v_add_f32_e32 v17, 1.0, v18
	v_mul_f32_e32 v18, 0x3d372713, v23
	v_mul_f32_e32 v18, v23, v18
	v_mul_f32_e32 v20, 0x3d372713, v24
	v_fma_f32 v18, v23, v18, v23
	v_mul_f32_e32 v20, v24, v20
	v_mul_f32_e32 v18, 0x3fcc422a, v18
	v_fma_f32 v20, v24, v20, v24
	v_mul_f32_e32 v18, 0xbfb8aa3b, v18
	v_mul_f32_e32 v20, 0x3fcc422a, v20
	v_exp_f32_e32 v18, v18
	v_mul_f32_e32 v20, 0xbfb8aa3b, v20
	v_exp_f32_e32 v20, v20
	v_mul_f32_e32 v21, 0x3d372713, v25
	v_mul_f32_e32 v21, v25, v21
	v_fma_f32 v21, v25, v21, v25
	v_add_f32_e32 v18, 1.0, v18
	v_mul_f32_e32 v21, 0x3fcc422a, v21
	v_rcp_f32_e32 v17, v17
	v_rcp_f32_e32 v18, v18
	v_add_f32_e32 v20, 1.0, v20
	v_mul_f32_e32 v21, 0xbfb8aa3b, v21
	v_rcp_f32_e32 v20, v20
	v_exp_f32_e32 v21, v21
	v_mul_f32_e32 v17, v22, v17
	v_mul_f32_e32 v18, v23, v18
	v_mul_f32_e32 v22, 0x3d372713, v19
	v_cvt_pk_bf16_f32 v17, v17, v18
	v_mul_f32_e32 v18, v24, v20
	v_add_f32_e32 v20, 1.0, v21
	v_mul_f32_e32 v21, 0x3d372713, v26
	v_mul_f32_e32 v22, v19, v22
	v_mul_f32_e32 v21, v26, v21
	v_fma_f32 v22, v19, v22, v19
	v_fma_f32 v21, v26, v21, v26
	v_mul_f32_e32 v22, 0x3fcc422a, v22
	v_mul_f32_e32 v21, 0x3fcc422a, v21
	v_mul_f32_e32 v22, 0xbfb8aa3b, v22
	v_mul_f32_e32 v21, 0xbfb8aa3b, v21
	v_exp_f32_e32 v22, v22
	v_exp_f32_e32 v21, v21
	v_rcp_f32_e32 v20, v20
	v_add_f32_e32 v22, 1.0, v22
	v_add_f32_e32 v21, 1.0, v21
	v_rcp_f32_e32 v22, v22
	v_rcp_f32_e32 v21, v21
	v_mul_f32_e32 v20, v25, v20
	v_cvt_pk_bf16_f32 v18, v18, v20
	v_mul_f32_e32 v19, v19, v22
	v_mul_f32_e32 v20, v26, v21
	v_cvt_pk_bf16_f32 v19, v20, v19
	global_store_dwordx4 v[100:101], v[16:19], off offset:256
	s_waitcnt vmcnt(7)
	s_nop 0
	v_lshlrev_b32_e32 v16, 16, v76
	v_fma_f32 v12, v68, v16, v12
	v_and_b32_e32 v16, 0xffff0000, v76
	v_fma_f32 v13, v69, v16, v13
	v_lshlrev_b32_e32 v16, 16, v77
	v_fma_f32 v14, v70, v16, v14
	v_and_b32_e32 v16, 0xffff0000, v77
	v_fmac_f32_e32 v15, v71, v16
	v_lshlrev_b32_e32 v16, 16, v78
	v_fma_f32 v16, v64, v16, v8
	v_and_b32_e32 v8, 0xffff0000, v78
	v_fma_f32 v17, v65, v8, v9
	v_lshlrev_b32_e32 v8, 16, v79
	v_fma_f32 v18, v66, v8, v10
	v_mul_f32_e32 v9, 0x3d372713, v12
	v_mul_f32_e32 v10, 0x3d372713, v13
	v_mul_f32_e32 v9, v12, v9
	v_mul_f32_e32 v10, v13, v10
	v_fma_f32 v9, v12, v9, v12
	v_fma_f32 v10, v13, v10, v13
	v_mul_f32_e32 v9, 0x3fcc422a, v9
	v_mul_f32_e32 v10, 0x3fcc422a, v10
	v_mul_f32_e32 v9, 0xbfb8aa3b, v9
	v_mul_f32_e32 v10, 0xbfb8aa3b, v10
	v_exp_f32_e32 v9, v9
	v_exp_f32_e32 v10, v10
	v_and_b32_e32 v8, 0xffff0000, v79
	v_fmac_f32_e32 v11, v67, v8
	v_add_f32_e32 v8, 1.0, v9
	v_add_f32_e32 v9, 1.0, v10
	v_mul_f32_e32 v10, 0x3d372713, v14
	v_mul_f32_e32 v10, v14, v10
	v_fma_f32 v10, v14, v10, v14
	v_mul_f32_e32 v10, 0x3fcc422a, v10
	v_rcp_f32_e32 v8, v8
	v_rcp_f32_e32 v9, v9
	v_mul_f32_e32 v10, 0xbfb8aa3b, v10
	v_exp_f32_e32 v10, v10
	v_mul_f32_e32 v8, v12, v8
	v_mul_f32_e32 v9, v13, v9
	v_cvt_pk_bf16_f32 v8, v8, v9
	v_add_f32_e32 v9, 1.0, v10
	v_mul_f32_e32 v10, 0x3d372713, v15
	v_mul_f32_e32 v10, v15, v10
	v_mul_f32_e32 v12, 0x3d372713, v16
	v_fma_f32 v10, v15, v10, v15
	v_mul_f32_e32 v12, v16, v12
	v_mul_f32_e32 v10, 0x3fcc422a, v10
	v_fma_f32 v12, v16, v12, v16
	v_mul_f32_e32 v10, 0xbfb8aa3b, v10
	v_mul_f32_e32 v12, 0x3fcc422a, v12
	v_exp_f32_e32 v10, v10
	v_mul_f32_e32 v12, 0xbfb8aa3b, v12
	v_exp_f32_e32 v12, v12
	v_mul_f32_e32 v13, 0x3d372713, v17
	v_mul_f32_e32 v13, v17, v13
	v_fma_f32 v13, v17, v13, v17
	v_add_f32_e32 v10, 1.0, v10
	v_mul_f32_e32 v13, 0x3fcc422a, v13
	v_rcp_f32_e32 v9, v9
	v_rcp_f32_e32 v10, v10
	v_add_f32_e32 v12, 1.0, v12
	v_mul_f32_e32 v13, 0xbfb8aa3b, v13
	v_rcp_f32_e32 v12, v12
	v_exp_f32_e32 v13, v13
	v_mul_f32_e32 v9, v14, v9
	v_mul_f32_e32 v10, v15, v10
	v_mul_f32_e32 v14, 0x3d372713, v11
	v_cvt_pk_bf16_f32 v9, v9, v10
	v_mul_f32_e32 v10, v16, v12
	v_add_f32_e32 v12, 1.0, v13
	v_mul_f32_e32 v13, 0x3d372713, v18
	v_mul_f32_e32 v14, v11, v14
	v_mul_f32_e32 v13, v18, v13
	v_fma_f32 v14, v11, v14, v11
	v_fma_f32 v13, v18, v13, v18
	v_mul_f32_e32 v14, 0x3fcc422a, v14
	v_mul_f32_e32 v13, 0x3fcc422a, v13
	v_mul_f32_e32 v14, 0xbfb8aa3b, v14
	v_mul_f32_e32 v13, 0xbfb8aa3b, v13
	v_exp_f32_e32 v14, v14
	v_exp_f32_e32 v13, v13
	v_rcp_f32_e32 v12, v12
	v_add_f32_e32 v14, 1.0, v14
	v_add_f32_e32 v13, 1.0, v13
	v_rcp_f32_e32 v14, v14
	v_rcp_f32_e32 v13, v13
	v_mul_f32_e32 v12, v17, v12
	v_cvt_pk_bf16_f32 v10, v10, v12
	v_mul_f32_e32 v11, v11, v14
	v_mul_f32_e32 v12, v18, v13
	v_cvt_pk_bf16_f32 v11, v12, v11
	global_store_dwordx4 v[102:103], v[8:11], off offset:256
	s_waitcnt vmcnt(7)
	s_nop 0
	v_lshlrev_b32_e32 v8, 16, v72
	v_fma_f32 v4, v68, v8, v4
	v_and_b32_e32 v8, 0xffff0000, v72
	v_fma_f32 v5, v69, v8, v5
	v_lshlrev_b32_e32 v8, 16, v73
	v_fma_f32 v6, v70, v8, v6
	v_and_b32_e32 v8, 0xffff0000, v73
	v_fmac_f32_e32 v7, v71, v8
	v_lshlrev_b32_e32 v8, 16, v74
	v_fma_f32 v8, v64, v8, v0
	v_and_b32_e32 v0, 0xffff0000, v74
	v_fma_f32 v9, v65, v0, v1
	v_lshlrev_b32_e32 v0, 16, v75
	v_fma_f32 v10, v66, v0, v2
	v_mul_f32_e32 v1, 0x3d372713, v4
	v_mul_f32_e32 v2, 0x3d372713, v5
	v_mul_f32_e32 v1, v4, v1
	v_mul_f32_e32 v2, v5, v2
	v_fma_f32 v1, v4, v1, v4
	v_fma_f32 v2, v5, v2, v5
	v_mul_f32_e32 v1, 0x3fcc422a, v1
	v_mul_f32_e32 v2, 0x3fcc422a, v2
	v_mul_f32_e32 v1, 0xbfb8aa3b, v1
	v_mul_f32_e32 v2, 0xbfb8aa3b, v2
	v_exp_f32_e32 v1, v1
	v_exp_f32_e32 v2, v2
	v_and_b32_e32 v0, 0xffff0000, v75
	v_fmac_f32_e32 v3, v67, v0
	v_add_f32_e32 v0, 1.0, v1
	v_add_f32_e32 v1, 1.0, v2
	v_mul_f32_e32 v2, 0x3d372713, v6
	v_mul_f32_e32 v2, v6, v2
	v_fma_f32 v2, v6, v2, v6
	v_mul_f32_e32 v2, 0x3fcc422a, v2
	v_rcp_f32_e32 v0, v0
	v_rcp_f32_e32 v1, v1
	v_mul_f32_e32 v2, 0xbfb8aa3b, v2
	v_exp_f32_e32 v2, v2
	v_mul_f32_e32 v0, v4, v0
	v_mul_f32_e32 v1, v5, v1
	v_cvt_pk_bf16_f32 v0, v0, v1
	v_add_f32_e32 v1, 1.0, v2
	v_mul_f32_e32 v2, 0x3d372713, v7
	v_mul_f32_e32 v2, v7, v2
	v_mul_f32_e32 v4, 0x3d372713, v8
	v_fma_f32 v2, v7, v2, v7
	v_mul_f32_e32 v4, v8, v4
	v_mul_f32_e32 v2, 0x3fcc422a, v2
	v_fma_f32 v4, v8, v4, v8
	v_mul_f32_e32 v2, 0xbfb8aa3b, v2
	v_mul_f32_e32 v4, 0x3fcc422a, v4
	v_exp_f32_e32 v2, v2
	v_mul_f32_e32 v4, 0xbfb8aa3b, v4
	v_exp_f32_e32 v4, v4
	v_mul_f32_e32 v5, 0x3d372713, v9
	v_mul_f32_e32 v5, v9, v5
	v_fma_f32 v5, v9, v5, v9
	v_add_f32_e32 v2, 1.0, v2
	v_mul_f32_e32 v5, 0x3fcc422a, v5
	v_rcp_f32_e32 v1, v1
	v_rcp_f32_e32 v2, v2
	v_add_f32_e32 v4, 1.0, v4
	v_mul_f32_e32 v5, 0xbfb8aa3b, v5
	v_rcp_f32_e32 v4, v4
	v_exp_f32_e32 v5, v5
	v_mul_f32_e32 v1, v6, v1
	v_mul_f32_e32 v2, v7, v2
	v_mul_f32_e32 v6, 0x3d372713, v3
	v_cvt_pk_bf16_f32 v1, v1, v2
	v_mul_f32_e32 v2, v8, v4
	v_add_f32_e32 v4, 1.0, v5
	v_mul_f32_e32 v5, 0x3d372713, v10
	v_mul_f32_e32 v6, v3, v6
	v_mul_f32_e32 v5, v10, v5
	v_fma_f32 v6, v3, v6, v3
	v_fma_f32 v5, v10, v5, v10
	v_mul_f32_e32 v6, 0x3fcc422a, v6
	v_mul_f32_e32 v5, 0x3fcc422a, v5
	v_mul_f32_e32 v6, 0xbfb8aa3b, v6
	v_mul_f32_e32 v5, 0xbfb8aa3b, v5
	v_exp_f32_e32 v6, v6
	v_exp_f32_e32 v5, v5
	v_rcp_f32_e32 v4, v4
	v_add_f32_e32 v6, 1.0, v6
	v_add_f32_e32 v5, 1.0, v5
	v_rcp_f32_e32 v6, v6
	v_rcp_f32_e32 v5, v5
	v_mul_f32_e32 v4, v9, v4
	v_cvt_pk_bf16_f32 v2, v2, v4
	v_mul_f32_e32 v3, v3, v6
	v_mul_f32_e32 v4, v10, v5
	v_cvt_pk_bf16_f32 v3, v4, v3
	global_store_dwordx4 v[106:107], v[0:3], off offset:256
	s_and_b64 vcc, exec, s[4:5]
	s_mov_b64 s[4:5], -1
	s_cbranch_vccnz .LBB0_390
	s_andn2_b64 vcc, exec, s[8:9]
	s_cbranch_vccnz .LBB0_389
	s_mov_b32 s98, 1
	s_branch .LBB0_389

.LBB0_479:
	s_ashr_i32 s23, s22, 31
	s_lshl_b64 s[0:1], s[22:23], 13
	s_add_u32 s24, s47, s0
	s_addc_u32 s25, s48, s1
	s_and_b64 s[0:1], s[6:7], exec
	s_cselect_b32 s23, s25, s35
	s_cselect_b32 s29, s24, s34
	s_ashr_i32 s21, s20, 31
	s_lshl_b64 s[0:1], s[20:21], 19
	s_add_u32 s26, s49, s0
	s_addc_u32 s27, s50, s1
	s_and_b64 s[0:1], s[6:7], exec
	s_cselect_b32 s21, s27, s37
	s_cselect_b32 s31, s26, s36
	s_add_u32 s63, s36, 0x100
	s_addc_u32 s64, s37, 0
	s_mov_b32 s65, -2
	s_waitcnt lgkmcnt(0)
	s_cmp_eq_u32 s98, 1
	s_cbranch_scc0 .Lrestag_480
	s_barrier
	s_mov_b32 s98, 0
.Lrestag_480:
	ds_read_b128 v[100:103], v210
	ds_read_b128 v[116:119], v210 offset:1024
	ds_read_b128 v[136:139], v210 offset:2048
	ds_read_b128 v[140:143], v210 offset:3072
	ds_read_b128 v[144:147], v211
	ds_read_b128 v[148:151], v211 offset:1024
	ds_read_b128 v[152:155], v211 offset:2048
	ds_read_b128 v[178:181], v211 offset:3072
	s_add_u32 s36, s34, 0x1000000
	s_addc_u32 s37, s35, 0
	s_cmp_eq_u32 s65, 12
	s_cselect_b32 s44, s29, s36
	s_cselect_b32 s45, s23, s37
	s_cselect_b32 s42, s31, s63
	s_cselect_b32 s43, s21, s64
	s_add_u32 s40, s44, 0x800000
	s_addc_u32 s41, s45, 0
	s_add_i32 m0, s52, 0xc000
	ds_read_b128 v[182:185], v212
	ds_read_b128 v[186:189], v212 offset:1024
	ds_read_b128 v[190:193], v212 offset:2048
	ds_read_b128 v[194:197], v212 offset:3072
	ds_read_b128 v[198:201], v212 offset:4096
	ds_read_b128 v[202:205], v212 offset:5120
	ds_read_b128 v[214:217], v212 offset:6144
	ds_read_b128 v[218:221], v212 offset:7168
	global_load_lds_dwordx4 v170, s[34:35]
	s_add_i32 m0, s52, 0xe000
	s_nop 0
	global_load_lds_dwordx4 v172, s[34:35]
	s_nop 0
	s_waitcnt lgkmcnt(0)
	s_barrier
	s_setprio 1
	s_waitcnt lgkmcnt(0)
	v_mfma_f32_16x16x32_bf16 v[132:135], v[100:103], v[182:185], 0
	v_mfma_f32_16x16x32_bf16 v[124:127], v[136:139], v[182:185], 0
	v_mfma_f32_16x16x32_bf16 v[112:115], v[100:103], v[190:193], 0
	v_mfma_f32_16x16x32_bf16 v[104:107], v[136:139], v[190:193], 0
	v_mfma_f32_16x16x32_bf16 v[92:95], v[100:103], v[198:201], 0
	v_mfma_f32_16x16x32_bf16 v[84:87], v[136:139], v[198:201], 0
	v_mfma_f32_16x16x32_bf16 v[76:79], v[100:103], v[214:217], 0
	v_mfma_f32_16x16x32_bf16 v[68:71], v[136:139], v[214:217], 0
	v_mfma_f32_16x16x32_bf16 v[132:135], v[116:119], v[186:189], v[132:135]
	v_mfma_f32_16x16x32_bf16 v[124:127], v[140:143], v[186:189], v[124:127]
	v_mfma_f32_16x16x32_bf16 v[112:115], v[116:119], v[194:197], v[112:115]
	v_mfma_f32_16x16x32_bf16 v[104:107], v[140:143], v[194:197], v[104:107]
	v_mfma_f32_16x16x32_bf16 v[92:95], v[116:119], v[202:205], v[92:95]
	v_mfma_f32_16x16x32_bf16 v[84:87], v[140:143], v[202:205], v[84:87]
	v_mfma_f32_16x16x32_bf16 v[76:79], v[116:119], v[218:221], v[76:79]
	v_mfma_f32_16x16x32_bf16 v[68:71], v[140:143], v[218:221], v[68:71]
	s_setprio 0
	s_setprio 1
	v_mfma_f32_16x16x32_bf16 v[128:131], v[144:147], v[182:185], 0
	v_mfma_f32_16x16x32_bf16 v[120:123], v[152:155], v[182:185], 0
	v_mfma_f32_16x16x32_bf16 v[108:111], v[144:147], v[190:193], 0
	v_mfma_f32_16x16x32_bf16 v[96:99], v[152:155], v[190:193], 0
	v_mfma_f32_16x16x32_bf16 v[88:91], v[144:147], v[198:201], 0
	v_mfma_f32_16x16x32_bf16 v[80:83], v[152:155], v[198:201], 0
	v_mfma_f32_16x16x32_bf16 v[72:75], v[144:147], v[214:217], 0
	v_mfma_f32_16x16x32_bf16 v[64:67], v[152:155], v[214:217], 0
	v_mfma_f32_16x16x32_bf16 v[128:131], v[148:151], v[186:189], v[128:131]
	v_mfma_f32_16x16x32_bf16 v[120:123], v[178:181], v[186:189], v[120:123]
	v_mfma_f32_16x16x32_bf16 v[108:111], v[148:151], v[194:197], v[108:111]
	v_mfma_f32_16x16x32_bf16 v[96:99], v[178:181], v[194:197], v[96:99]
	v_mfma_f32_16x16x32_bf16 v[88:91], v[148:151], v[202:205], v[88:91]
	v_mfma_f32_16x16x32_bf16 v[80:83], v[178:181], v[202:205], v[80:83]
	v_mfma_f32_16x16x32_bf16 v[72:75], v[148:151], v[218:221], v[72:75]
	v_mfma_f32_16x16x32_bf16 v[64:67], v[178:181], v[218:221], v[64:67]
	s_setprio 0
	s_barrier
	s_add_i32 s0, s60, s51
	v_lshl_add_u64 v[206:207], s[42:43], 0, v[158:159]
	s_mov_b32 m0, s0
	ds_read_b128 v[182:185], v212 offset:16384
	ds_read_b128 v[186:189], v212 offset:17408
	ds_read_b128 v[190:193], v212 offset:18432
	ds_read_b128 v[194:197], v212 offset:19456
	ds_read_b128 v[198:201], v212 offset:20480
	ds_read_b128 v[202:205], v212 offset:21504
	ds_read_b128 v[214:217], v212 offset:22528
	ds_read_b128 v[218:221], v212 offset:23552
	global_load_lds_dwordx4 v[206:207], off
	s_add_i32 m0, s0, 0x2000
	s_add_u32 s0, s42, 0x40000
	v_lshl_add_u64 v[222:223], s[42:43], 0, v[162:163]
	s_addc_u32 s1, s43, 0
	s_add_i32 s34, s61, s51
	global_load_lds_dwordx4 v[222:223], off
	s_mov_b32 m0, s34
	s_nop 0
	global_load_lds_dwordx4 v158, s[0:1]
	s_add_i32 m0, s34, 0x2000
	s_nop 0
	global_load_lds_dwordx4 v162, s[0:1]
	s_nop 0
	s_waitcnt lgkmcnt(0)
	s_barrier
	s_setprio 1
	s_waitcnt lgkmcnt(0)
	v_mfma_f32_16x16x32_bf16 v[60:63], v[100:103], v[182:185], 0
	v_mfma_f32_16x16x32_bf16 v[52:55], v[136:139], v[182:185], 0
	v_mfma_f32_16x16x32_bf16 v[44:47], v[100:103], v[190:193], 0
	v_mfma_f32_16x16x32_bf16 v[36:39], v[136:139], v[190:193], 0
	v_mfma_f32_16x16x32_bf16 v[28:31], v[100:103], v[198:201], 0
	v_mfma_f32_16x16x32_bf16 v[20:23], v[136:139], v[198:201], 0
	v_mfma_f32_16x16x32_bf16 v[12:15], v[100:103], v[214:217], 0
	v_mfma_f32_16x16x32_bf16 v[4:7], v[136:139], v[214:217], 0
	v_mfma_f32_16x16x32_bf16 v[60:63], v[116:119], v[186:189], v[60:63]
	v_mfma_f32_16x16x32_bf16 v[52:55], v[140:143], v[186:189], v[52:55]
	v_mfma_f32_16x16x32_bf16 v[44:47], v[116:119], v[194:197], v[44:47]
	v_mfma_f32_16x16x32_bf16 v[36:39], v[140:143], v[194:197], v[36:39]
	v_mfma_f32_16x16x32_bf16 v[28:31], v[116:119], v[202:205], v[28:31]
	v_mfma_f32_16x16x32_bf16 v[20:23], v[140:143], v[202:205], v[20:23]
	v_mfma_f32_16x16x32_bf16 v[12:15], v[116:119], v[218:221], v[12:15]
	v_mfma_f32_16x16x32_bf16 v[4:7], v[140:143], v[218:221], v[4:7]
	s_setprio 0
	s_setprio 1
	v_mfma_f32_16x16x32_bf16 v[56:59], v[144:147], v[182:185], 0
	v_mfma_f32_16x16x32_bf16 v[48:51], v[152:155], v[182:185], 0
	v_mfma_f32_16x16x32_bf16 v[40:43], v[144:147], v[190:193], 0
	v_mfma_f32_16x16x32_bf16 v[32:35], v[152:155], v[190:193], 0
	v_mfma_f32_16x16x32_bf16 v[24:27], v[144:147], v[198:201], 0
	v_mfma_f32_16x16x32_bf16 v[16:19], v[152:155], v[198:201], 0
	v_mfma_f32_16x16x32_bf16 v[8:11], v[144:147], v[214:217], 0
	v_mfma_f32_16x16x32_bf16 v[0:3], v[152:155], v[214:217], 0
	v_mfma_f32_16x16x32_bf16 v[56:59], v[148:151], v[186:189], v[56:59]
	v_mfma_f32_16x16x32_bf16 v[48:51], v[178:181], v[186:189], v[48:51]
	v_mfma_f32_16x16x32_bf16 v[40:43], v[148:151], v[194:197], v[40:43]
	v_mfma_f32_16x16x32_bf16 v[32:35], v[178:181], v[194:197], v[32:35]
	v_mfma_f32_16x16x32_bf16 v[24:27], v[148:151], v[202:205], v[24:27]
	v_mfma_f32_16x16x32_bf16 v[16:19], v[178:181], v[202:205], v[16:19]
	v_mfma_f32_16x16x32_bf16 v[8:11], v[148:151], v[218:221], v[8:11]
	v_mfma_f32_16x16x32_bf16 v[0:3], v[178:181], v[218:221], v[0:3]
	s_setprio 0
	s_barrier
	s_add_i32 s34, 0, 0x18000
	s_add_i32 s35, 0, 0x1c000
	v_add_u32_e32 v140, s34, v209
	v_add_u32_e32 v178, s35, v209
	ds_read_b128 v[100:103], v140
	ds_read_b128 v[116:119], v140 offset:1024
	ds_read_b128 v[136:139], v140 offset:2048
	ds_read_b128 v[140:143], v140 offset:3072
	ds_read_b128 v[144:147], v178
	ds_read_b128 v[148:151], v178 offset:1024
	ds_read_b128 v[152:155], v178 offset:2048
	ds_read_b128 v[178:181], v178 offset:3072
	s_add_u32 s0, s44, 0x1000
	s_addc_u32 s1, s45, 0
	s_mov_b32 m0, s54
	ds_read_b128 v[182:185], v212 offset:32768
	ds_read_b128 v[186:189], v212 offset:33792
	ds_read_b128 v[190:193], v212 offset:34816
	ds_read_b128 v[194:197], v212 offset:35840
	ds_read_b128 v[198:201], v212 offset:36864
	ds_read_b128 v[202:205], v212 offset:37888
	ds_read_b128 v[214:217], v212 offset:38912
	ds_read_b128 v[218:221], v212 offset:39936
	global_load_lds_dwordx4 v156, s[0:1]
	s_mov_b32 m0, s55
	s_nop 0
	global_load_lds_dwordx4 v160, s[0:1]
	s_mov_b32 m0, s52
	s_nop 0
	global_load_lds_dwordx4 v156, s[44:45]
	s_mov_b32 m0, s53
	s_nop 0
	global_load_lds_dwordx4 v160, s[44:45]
	s_waitcnt vmcnt(8)
	s_waitcnt lgkmcnt(0)
	s_barrier
	s_setprio 1
	s_waitcnt lgkmcnt(0)
	v_mfma_f32_16x16x32_bf16 v[132:135], v[100:103], v[182:185], v[132:135]
	v_mfma_f32_16x16x32_bf16 v[124:127], v[136:139], v[182:185], v[124:127]
	v_mfma_f32_16x16x32_bf16 v[112:115], v[100:103], v[190:193], v[112:115]
	v_mfma_f32_16x16x32_bf16 v[104:107], v[136:139], v[190:193], v[104:107]
	v_mfma_f32_16x16x32_bf16 v[92:95], v[100:103], v[198:201], v[92:95]
	v_mfma_f32_16x16x32_bf16 v[84:87], v[136:139], v[198:201], v[84:87]
	v_mfma_f32_16x16x32_bf16 v[76:79], v[100:103], v[214:217], v[76:79]
	v_mfma_f32_16x16x32_bf16 v[68:71], v[136:139], v[214:217], v[68:71]
	v_mfma_f32_16x16x32_bf16 v[132:135], v[116:119], v[186:189], v[132:135]
	v_mfma_f32_16x16x32_bf16 v[124:127], v[140:143], v[186:189], v[124:127]
	v_mfma_f32_16x16x32_bf16 v[112:115], v[116:119], v[194:197], v[112:115]
	v_mfma_f32_16x16x32_bf16 v[104:107], v[140:143], v[194:197], v[104:107]
	v_mfma_f32_16x16x32_bf16 v[92:95], v[116:119], v[202:205], v[92:95]
	v_mfma_f32_16x16x32_bf16 v[84:87], v[140:143], v[202:205], v[84:87]
	v_mfma_f32_16x16x32_bf16 v[76:79], v[116:119], v[218:221], v[76:79]
	v_mfma_f32_16x16x32_bf16 v[68:71], v[140:143], v[218:221], v[68:71]
	s_setprio 0
	s_setprio 1
	v_mfma_f32_16x16x32_bf16 v[128:131], v[144:147], v[182:185], v[128:131]
	v_mfma_f32_16x16x32_bf16 v[120:123], v[152:155], v[182:185], v[120:123]
	v_mfma_f32_16x16x32_bf16 v[108:111], v[144:147], v[190:193], v[108:111]
	v_mfma_f32_16x16x32_bf16 v[96:99], v[152:155], v[190:193], v[96:99]
	v_mfma_f32_16x16x32_bf16 v[88:91], v[144:147], v[198:201], v[88:91]
	v_mfma_f32_16x16x32_bf16 v[80:83], v[152:155], v[198:201], v[80:83]
	v_mfma_f32_16x16x32_bf16 v[72:75], v[144:147], v[214:217], v[72:75]
	v_mfma_f32_16x16x32_bf16 v[64:67], v[152:155], v[214:217], v[64:67]
	v_mfma_f32_16x16x32_bf16 v[128:131], v[148:151], v[186:189], v[128:131]
	v_mfma_f32_16x16x32_bf16 v[120:123], v[178:181], v[186:189], v[120:123]
	v_mfma_f32_16x16x32_bf16 v[108:111], v[148:151], v[194:197], v[108:111]
	v_mfma_f32_16x16x32_bf16 v[96:99], v[178:181], v[194:197], v[96:99]
	v_mfma_f32_16x16x32_bf16 v[88:91], v[148:151], v[202:205], v[88:91]
	v_mfma_f32_16x16x32_bf16 v[80:83], v[178:181], v[202:205], v[80:83]
	v_mfma_f32_16x16x32_bf16 v[72:75], v[148:151], v[218:221], v[72:75]
	v_mfma_f32_16x16x32_bf16 v[64:67], v[178:181], v[218:221], v[64:67]
	s_setprio 0
	s_barrier
	s_add_i32 s0, s34, s51
	v_lshl_add_u64 v[206:207], v[206:207], 0, s[16:17]
	s_mov_b32 m0, s0
	ds_read_b128 v[182:185], v212 offset:49152
	ds_read_b128 v[186:189], v212 offset:50176
	ds_read_b128 v[190:193], v212 offset:51200
	ds_read_b128 v[194:197], v212 offset:52224
	ds_read_b128 v[198:201], v212 offset:53248
	ds_read_b128 v[202:205], v212 offset:54272
	ds_read_b128 v[214:217], v212 offset:55296
	ds_read_b128 v[218:221], v212 offset:56320
	global_load_lds_dwordx4 v[206:207], off
	s_add_i32 m0, s0, 0x2000
	s_add_u32 s0, s42, 0x40080
	v_lshl_add_u64 v[206:207], v[222:223], 0, s[16:17]
	s_addc_u32 s1, s43, 0
	s_add_i32 s34, s35, s51
	global_load_lds_dwordx4 v[206:207], off
	s_mov_b32 m0, s34
	s_nop 0
	global_load_lds_dwordx4 v158, s[0:1]
	s_add_i32 m0, s34, 0x2000
	s_nop 0
	global_load_lds_dwordx4 v162, s[0:1]
	s_mov_b32 m0, s56
	s_nop 0
	global_load_lds_dwordx4 v156, s[40:41]
	s_mov_b32 m0, s57
	s_nop 0
	global_load_lds_dwordx4 v160, s[40:41]
	s_waitcnt vmcnt(6)
	s_waitcnt lgkmcnt(0)
	s_barrier
	s_setprio 1
	s_waitcnt lgkmcnt(0)
	v_mfma_f32_16x16x32_bf16 v[60:63], v[100:103], v[182:185], v[60:63]
	v_mfma_f32_16x16x32_bf16 v[52:55], v[136:139], v[182:185], v[52:55]
	v_mfma_f32_16x16x32_bf16 v[44:47], v[100:103], v[190:193], v[44:47]
	v_mfma_f32_16x16x32_bf16 v[36:39], v[136:139], v[190:193], v[36:39]
	v_mfma_f32_16x16x32_bf16 v[28:31], v[100:103], v[198:201], v[28:31]
	v_mfma_f32_16x16x32_bf16 v[20:23], v[136:139], v[198:201], v[20:23]
	v_mfma_f32_16x16x32_bf16 v[12:15], v[100:103], v[214:217], v[12:15]
	v_mfma_f32_16x16x32_bf16 v[4:7], v[136:139], v[214:217], v[4:7]
	v_mfma_f32_16x16x32_bf16 v[60:63], v[116:119], v[186:189], v[60:63]
	v_mfma_f32_16x16x32_bf16 v[52:55], v[140:143], v[186:189], v[52:55]
	v_mfma_f32_16x16x32_bf16 v[44:47], v[116:119], v[194:197], v[44:47]
	v_mfma_f32_16x16x32_bf16 v[36:39], v[140:143], v[194:197], v[36:39]
	v_mfma_f32_16x16x32_bf16 v[28:31], v[116:119], v[202:205], v[28:31]
	v_mfma_f32_16x16x32_bf16 v[20:23], v[140:143], v[202:205], v[20:23]
	v_mfma_f32_16x16x32_bf16 v[12:15], v[116:119], v[218:221], v[12:15]
	v_mfma_f32_16x16x32_bf16 v[4:7], v[140:143], v[218:221], v[4:7]
	s_setprio 0
	s_setprio 1
	v_mfma_f32_16x16x32_bf16 v[56:59], v[144:147], v[182:185], v[56:59]
	v_mfma_f32_16x16x32_bf16 v[48:51], v[152:155], v[182:185], v[48:51]
	v_mfma_f32_16x16x32_bf16 v[40:43], v[144:147], v[190:193], v[40:43]
	v_mfma_f32_16x16x32_bf16 v[32:35], v[152:155], v[190:193], v[32:35]
	v_mfma_f32_16x16x32_bf16 v[24:27], v[144:147], v[198:201], v[24:27]
	v_mfma_f32_16x16x32_bf16 v[16:19], v[152:155], v[198:201], v[16:19]
	v_mfma_f32_16x16x32_bf16 v[8:11], v[144:147], v[214:217], v[8:11]
	v_mfma_f32_16x16x32_bf16 v[0:3], v[152:155], v[214:217], v[0:3]
	v_mfma_f32_16x16x32_bf16 v[56:59], v[148:151], v[186:189], v[56:59]
	v_mfma_f32_16x16x32_bf16 v[48:51], v[178:181], v[186:189], v[48:51]
	v_mfma_f32_16x16x32_bf16 v[40:43], v[148:151], v[194:197], v[40:43]
	v_mfma_f32_16x16x32_bf16 v[32:35], v[178:181], v[194:197], v[32:35]
	v_mfma_f32_16x16x32_bf16 v[24:27], v[148:151], v[202:205], v[24:27]
	v_mfma_f32_16x16x32_bf16 v[16:19], v[178:181], v[202:205], v[16:19]
	v_mfma_f32_16x16x32_bf16 v[8:11], v[148:151], v[218:221], v[8:11]
	v_mfma_f32_16x16x32_bf16 v[0:3], v[178:181], v[218:221], v[0:3]
	s_setprio 0
	s_barrier
	s_add_i32 s65, s65, 2
	s_add_u32 s63, s63, 0x100
	s_addc_u32 s64, s64, 0
	s_cmp_gt_u32 s65, 13
	s_mov_b64 s[34:35], s[36:37]
.LBB0_480:
	ds_read_b128 v[100:103], v210
	ds_read_b128 v[116:119], v210 offset:1024
	ds_read_b128 v[136:139], v210 offset:2048
	ds_read_b128 v[140:143], v210 offset:3072
	ds_read_b128 v[144:147], v211
	ds_read_b128 v[148:151], v211 offset:1024
	ds_read_b128 v[152:155], v211 offset:2048
	ds_read_b128 v[178:181], v211 offset:3072
	s_add_u32 s36, s34, 0x1000000
	s_addc_u32 s37, s35, 0
	s_cmp_eq_u32 s65, 12
	s_cselect_b32 s44, s29, s36
	s_cselect_b32 s45, s23, s37
	s_cselect_b32 s42, s31, s63
	s_cselect_b32 s43, s21, s64
	s_add_u32 s40, s44, 0x800000
	s_addc_u32 s41, s45, 0
	s_add_i32 m0, s52, 0xc000
	ds_read_b128 v[182:185], v212
	ds_read_b128 v[186:189], v212 offset:1024
	ds_read_b128 v[190:193], v212 offset:2048
	ds_read_b128 v[194:197], v212 offset:3072
	ds_read_b128 v[198:201], v212 offset:4096
	ds_read_b128 v[202:205], v212 offset:5120
	ds_read_b128 v[214:217], v212 offset:6144
	ds_read_b128 v[218:221], v212 offset:7168
	global_load_lds_dwordx4 v170, s[34:35]
	s_add_i32 m0, s52, 0xe000
	s_nop 0
	global_load_lds_dwordx4 v172, s[34:35]
	s_waitcnt vmcnt(8)
	s_waitcnt lgkmcnt(0)
	s_barrier
	s_setprio 1
	s_waitcnt lgkmcnt(0)
	v_mfma_f32_16x16x32_bf16 v[132:135], v[100:103], v[182:185], v[132:135]
	v_mfma_f32_16x16x32_bf16 v[124:127], v[136:139], v[182:185], v[124:127]
	v_mfma_f32_16x16x32_bf16 v[112:115], v[100:103], v[190:193], v[112:115]
	v_mfma_f32_16x16x32_bf16 v[104:107], v[136:139], v[190:193], v[104:107]
	v_mfma_f32_16x16x32_bf16 v[92:95], v[100:103], v[198:201], v[92:95]
	v_mfma_f32_16x16x32_bf16 v[84:87], v[136:139], v[198:201], v[84:87]
	v_mfma_f32_16x16x32_bf16 v[76:79], v[100:103], v[214:217], v[76:79]
	v_mfma_f32_16x16x32_bf16 v[68:71], v[136:139], v[214:217], v[68:71]
	v_mfma_f32_16x16x32_bf16 v[132:135], v[116:119], v[186:189], v[132:135]
	v_mfma_f32_16x16x32_bf16 v[124:127], v[140:143], v[186:189], v[124:127]
	v_mfma_f32_16x16x32_bf16 v[112:115], v[116:119], v[194:197], v[112:115]
	v_mfma_f32_16x16x32_bf16 v[104:107], v[140:143], v[194:197], v[104:107]
	v_mfma_f32_16x16x32_bf16 v[92:95], v[116:119], v[202:205], v[92:95]
	v_mfma_f32_16x16x32_bf16 v[84:87], v[140:143], v[202:205], v[84:87]
	v_mfma_f32_16x16x32_bf16 v[76:79], v[116:119], v[218:221], v[76:79]
	v_mfma_f32_16x16x32_bf16 v[68:71], v[140:143], v[218:221], v[68:71]
	s_setprio 0
	s_setprio 1
	v_mfma_f32_16x16x32_bf16 v[128:131], v[144:147], v[182:185], v[128:131]
	v_mfma_f32_16x16x32_bf16 v[120:123], v[152:155], v[182:185], v[120:123]
	v_mfma_f32_16x16x32_bf16 v[108:111], v[144:147], v[190:193], v[108:111]
	v_mfma_f32_16x16x32_bf16 v[96:99], v[152:155], v[190:193], v[96:99]
	v_mfma_f32_16x16x32_bf16 v[88:91], v[144:147], v[198:201], v[88:91]
	v_mfma_f32_16x16x32_bf16 v[80:83], v[152:155], v[198:201], v[80:83]
	v_mfma_f32_16x16x32_bf16 v[72:75], v[144:147], v[214:217], v[72:75]
	v_mfma_f32_16x16x32_bf16 v[64:67], v[152:155], v[214:217], v[64:67]
	v_mfma_f32_16x16x32_bf16 v[128:131], v[148:151], v[186:189], v[128:131]
	v_mfma_f32_16x16x32_bf16 v[120:123], v[178:181], v[186:189], v[120:123]
	v_mfma_f32_16x16x32_bf16 v[108:111], v[148:151], v[194:197], v[108:111]
	v_mfma_f32_16x16x32_bf16 v[96:99], v[178:181], v[194:197], v[96:99]
	v_mfma_f32_16x16x32_bf16 v[88:91], v[148:151], v[202:205], v[88:91]
	v_mfma_f32_16x16x32_bf16 v[80:83], v[178:181], v[202:205], v[80:83]
	v_mfma_f32_16x16x32_bf16 v[72:75], v[148:151], v[218:221], v[72:75]
	v_mfma_f32_16x16x32_bf16 v[64:67], v[178:181], v[218:221], v[64:67]
	s_setprio 0
	s_barrier
	s_add_i32 s0, s60, s51
	v_lshl_add_u64 v[206:207], s[42:43], 0, v[158:159]
	s_mov_b32 m0, s0
	ds_read_b128 v[182:185], v212 offset:16384
	ds_read_b128 v[186:189], v212 offset:17408
	ds_read_b128 v[190:193], v212 offset:18432
	ds_read_b128 v[194:197], v212 offset:19456
	ds_read_b128 v[198:201], v212 offset:20480
	ds_read_b128 v[202:205], v212 offset:21504
	ds_read_b128 v[214:217], v212 offset:22528
	ds_read_b128 v[218:221], v212 offset:23552
	global_load_lds_dwordx4 v[206:207], off
	s_add_i32 m0, s0, 0x2000
	s_add_u32 s0, s42, 0x40000
	v_lshl_add_u64 v[222:223], s[42:43], 0, v[162:163]
	s_addc_u32 s1, s43, 0
	s_add_i32 s34, s61, s51
	global_load_lds_dwordx4 v[222:223], off
	s_mov_b32 m0, s34
	s_nop 0
	global_load_lds_dwordx4 v158, s[0:1]
	s_add_i32 m0, s34, 0x2000
	s_nop 0
	global_load_lds_dwordx4 v162, s[0:1]
	s_waitcnt vmcnt(6)
	s_waitcnt lgkmcnt(0)
	s_barrier
	s_setprio 1
	s_waitcnt lgkmcnt(0)
	v_mfma_f32_16x16x32_bf16 v[60:63], v[100:103], v[182:185], v[60:63]
	v_mfma_f32_16x16x32_bf16 v[52:55], v[136:139], v[182:185], v[52:55]
	v_mfma_f32_16x16x32_bf16 v[44:47], v[100:103], v[190:193], v[44:47]
	v_mfma_f32_16x16x32_bf16 v[36:39], v[136:139], v[190:193], v[36:39]
	v_mfma_f32_16x16x32_bf16 v[28:31], v[100:103], v[198:201], v[28:31]
	v_mfma_f32_16x16x32_bf16 v[20:23], v[136:139], v[198:201], v[20:23]
	v_mfma_f32_16x16x32_bf16 v[12:15], v[100:103], v[214:217], v[12:15]
	v_mfma_f32_16x16x32_bf16 v[4:7], v[136:139], v[214:217], v[4:7]
	v_mfma_f32_16x16x32_bf16 v[60:63], v[116:119], v[186:189], v[60:63]
	v_mfma_f32_16x16x32_bf16 v[52:55], v[140:143], v[186:189], v[52:55]
	v_mfma_f32_16x16x32_bf16 v[44:47], v[116:119], v[194:197], v[44:47]
	v_mfma_f32_16x16x32_bf16 v[36:39], v[140:143], v[194:197], v[36:39]
	v_mfma_f32_16x16x32_bf16 v[28:31], v[116:119], v[202:205], v[28:31]
	v_mfma_f32_16x16x32_bf16 v[20:23], v[140:143], v[202:205], v[20:23]
	v_mfma_f32_16x16x32_bf16 v[12:15], v[116:119], v[218:221], v[12:15]
	v_mfma_f32_16x16x32_bf16 v[4:7], v[140:143], v[218:221], v[4:7]
	s_setprio 0
	s_setprio 1
	v_mfma_f32_16x16x32_bf16 v[56:59], v[144:147], v[182:185], v[56:59]
	v_mfma_f32_16x16x32_bf16 v[48:51], v[152:155], v[182:185], v[48:51]
	v_mfma_f32_16x16x32_bf16 v[40:43], v[144:147], v[190:193], v[40:43]
	v_mfma_f32_16x16x32_bf16 v[32:35], v[152:155], v[190:193], v[32:35]
	v_mfma_f32_16x16x32_bf16 v[24:27], v[144:147], v[198:201], v[24:27]
	v_mfma_f32_16x16x32_bf16 v[16:19], v[152:155], v[198:201], v[16:19]
	v_mfma_f32_16x16x32_bf16 v[8:11], v[144:147], v[214:217], v[8:11]
	v_mfma_f32_16x16x32_bf16 v[0:3], v[152:155], v[214:217], v[0:3]
	v_mfma_f32_16x16x32_bf16 v[56:59], v[148:151], v[186:189], v[56:59]
	v_mfma_f32_16x16x32_bf16 v[48:51], v[178:181], v[186:189], v[48:51]
	v_mfma_f32_16x16x32_bf16 v[40:43], v[148:151], v[194:197], v[40:43]
	v_mfma_f32_16x16x32_bf16 v[32:35], v[178:181], v[194:197], v[32:35]
	v_mfma_f32_16x16x32_bf16 v[24:27], v[148:151], v[202:205], v[24:27]
	v_mfma_f32_16x16x32_bf16 v[16:19], v[178:181], v[202:205], v[16:19]
	v_mfma_f32_16x16x32_bf16 v[8:11], v[148:151], v[218:221], v[8:11]
	v_mfma_f32_16x16x32_bf16 v[0:3], v[178:181], v[218:221], v[0:3]
	s_setprio 0
	s_barrier
	s_add_i32 s34, 0, 0x18000
	s_add_i32 s35, 0, 0x1c000
	v_add_u32_e32 v140, s34, v209
	v_add_u32_e32 v178, s35, v209
	ds_read_b128 v[100:103], v140
	ds_read_b128 v[116:119], v140 offset:1024
	ds_read_b128 v[136:139], v140 offset:2048
	ds_read_b128 v[140:143], v140 offset:3072
	ds_read_b128 v[144:147], v178
	ds_read_b128 v[148:151], v178 offset:1024
	ds_read_b128 v[152:155], v178 offset:2048
	ds_read_b128 v[178:181], v178 offset:3072
	s_add_u32 s0, s44, 0x1000
	s_addc_u32 s1, s45, 0
	s_mov_b32 m0, s54
	ds_read_b128 v[182:185], v212 offset:32768
	ds_read_b128 v[186:189], v212 offset:33792
	ds_read_b128 v[190:193], v212 offset:34816
	ds_read_b128 v[194:197], v212 offset:35840
	ds_read_b128 v[198:201], v212 offset:36864
	ds_read_b128 v[202:205], v212 offset:37888
	ds_read_b128 v[214:217], v212 offset:38912
	ds_read_b128 v[218:221], v212 offset:39936
	global_load_lds_dwordx4 v156, s[0:1]
	s_mov_b32 m0, s55
	s_nop 0
	global_load_lds_dwordx4 v160, s[0:1]
	s_mov_b32 m0, s52
	s_nop 0
	global_load_lds_dwordx4 v156, s[44:45]
	s_mov_b32 m0, s53
	s_nop 0
	global_load_lds_dwordx4 v160, s[44:45]
	s_waitcnt vmcnt(8)
	s_waitcnt lgkmcnt(0)
	s_barrier
	s_setprio 1
	s_waitcnt lgkmcnt(0)
	v_mfma_f32_16x16x32_bf16 v[132:135], v[100:103], v[182:185], v[132:135]
	v_mfma_f32_16x16x32_bf16 v[124:127], v[136:139], v[182:185], v[124:127]
	v_mfma_f32_16x16x32_bf16 v[112:115], v[100:103], v[190:193], v[112:115]
	v_mfma_f32_16x16x32_bf16 v[104:107], v[136:139], v[190:193], v[104:107]
	v_mfma_f32_16x16x32_bf16 v[92:95], v[100:103], v[198:201], v[92:95]
	v_mfma_f32_16x16x32_bf16 v[84:87], v[136:139], v[198:201], v[84:87]
	v_mfma_f32_16x16x32_bf16 v[76:79], v[100:103], v[214:217], v[76:79]
	v_mfma_f32_16x16x32_bf16 v[68:71], v[136:139], v[214:217], v[68:71]
	v_mfma_f32_16x16x32_bf16 v[132:135], v[116:119], v[186:189], v[132:135]
	v_mfma_f32_16x16x32_bf16 v[124:127], v[140:143], v[186:189], v[124:127]
	v_mfma_f32_16x16x32_bf16 v[112:115], v[116:119], v[194:197], v[112:115]
	v_mfma_f32_16x16x32_bf16 v[104:107], v[140:143], v[194:197], v[104:107]
	v_mfma_f32_16x16x32_bf16 v[92:95], v[116:119], v[202:205], v[92:95]
	v_mfma_f32_16x16x32_bf16 v[84:87], v[140:143], v[202:205], v[84:87]
	v_mfma_f32_16x16x32_bf16 v[76:79], v[116:119], v[218:221], v[76:79]
	v_mfma_f32_16x16x32_bf16 v[68:71], v[140:143], v[218:221], v[68:71]
	s_setprio 0
	s_setprio 1
	v_mfma_f32_16x16x32_bf16 v[128:131], v[144:147], v[182:185], v[128:131]
	v_mfma_f32_16x16x32_bf16 v[120:123], v[152:155], v[182:185], v[120:123]
	v_mfma_f32_16x16x32_bf16 v[108:111], v[144:147], v[190:193], v[108:111]
	v_mfma_f32_16x16x32_bf16 v[96:99], v[152:155], v[190:193], v[96:99]
	v_mfma_f32_16x16x32_bf16 v[88:91], v[144:147], v[198:201], v[88:91]
	v_mfma_f32_16x16x32_bf16 v[80:83], v[152:155], v[198:201], v[80:83]
	v_mfma_f32_16x16x32_bf16 v[72:75], v[144:147], v[214:217], v[72:75]
	v_mfma_f32_16x16x32_bf16 v[64:67], v[152:155], v[214:217], v[64:67]
	v_mfma_f32_16x16x32_bf16 v[128:131], v[148:151], v[186:189], v[128:131]
	v_mfma_f32_16x16x32_bf16 v[120:123], v[178:181], v[186:189], v[120:123]
	v_mfma_f32_16x16x32_bf16 v[108:111], v[148:151], v[194:197], v[108:111]
	v_mfma_f32_16x16x32_bf16 v[96:99], v[178:181], v[194:197], v[96:99]
	v_mfma_f32_16x16x32_bf16 v[88:91], v[148:151], v[202:205], v[88:91]
	v_mfma_f32_16x16x32_bf16 v[80:83], v[178:181], v[202:205], v[80:83]
	v_mfma_f32_16x16x32_bf16 v[72:75], v[148:151], v[218:221], v[72:75]
	v_mfma_f32_16x16x32_bf16 v[64:67], v[178:181], v[218:221], v[64:67]
	s_setprio 0
	s_barrier
	s_add_i32 s0, s34, s51
	v_lshl_add_u64 v[206:207], v[206:207], 0, s[16:17]
	s_mov_b32 m0, s0
	ds_read_b128 v[182:185], v212 offset:49152
	ds_read_b128 v[186:189], v212 offset:50176
	ds_read_b128 v[190:193], v212 offset:51200
	ds_read_b128 v[194:197], v212 offset:52224
	ds_read_b128 v[198:201], v212 offset:53248
	ds_read_b128 v[202:205], v212 offset:54272
	ds_read_b128 v[214:217], v212 offset:55296
	ds_read_b128 v[218:221], v212 offset:56320
	global_load_lds_dwordx4 v[206:207], off
	s_add_i32 m0, s0, 0x2000
	s_add_u32 s0, s42, 0x40080
	v_lshl_add_u64 v[206:207], v[222:223], 0, s[16:17]
	s_addc_u32 s1, s43, 0
	s_add_i32 s34, s35, s51
	global_load_lds_dwordx4 v[206:207], off
	s_mov_b32 m0, s34
	s_nop 0
	global_load_lds_dwordx4 v158, s[0:1]
	s_add_i32 m0, s34, 0x2000
	s_nop 0
	global_load_lds_dwordx4 v162, s[0:1]
	s_mov_b32 m0, s56
	s_nop 0
	global_load_lds_dwordx4 v156, s[40:41]
	s_mov_b32 m0, s57
	s_nop 0
	global_load_lds_dwordx4 v160, s[40:41]
	s_waitcnt vmcnt(6)
	s_waitcnt lgkmcnt(0)
	s_barrier
	s_setprio 1
	s_waitcnt lgkmcnt(0)
	v_mfma_f32_16x16x32_bf16 v[60:63], v[100:103], v[182:185], v[60:63]
	v_mfma_f32_16x16x32_bf16 v[52:55], v[136:139], v[182:185], v[52:55]
	v_mfma_f32_16x16x32_bf16 v[44:47], v[100:103], v[190:193], v[44:47]
	v_mfma_f32_16x16x32_bf16 v[36:39], v[136:139], v[190:193], v[36:39]
	v_mfma_f32_16x16x32_bf16 v[28:31], v[100:103], v[198:201], v[28:31]
	v_mfma_f32_16x16x32_bf16 v[20:23], v[136:139], v[198:201], v[20:23]
	v_mfma_f32_16x16x32_bf16 v[12:15], v[100:103], v[214:217], v[12:15]
	v_mfma_f32_16x16x32_bf16 v[4:7], v[136:139], v[214:217], v[4:7]
	v_mfma_f32_16x16x32_bf16 v[60:63], v[116:119], v[186:189], v[60:63]
	v_mfma_f32_16x16x32_bf16 v[52:55], v[140:143], v[186:189], v[52:55]
	v_mfma_f32_16x16x32_bf16 v[44:47], v[116:119], v[194:197], v[44:47]
	v_mfma_f32_16x16x32_bf16 v[36:39], v[140:143], v[194:197], v[36:39]
	v_mfma_f32_16x16x32_bf16 v[28:31], v[116:119], v[202:205], v[28:31]
	v_mfma_f32_16x16x32_bf16 v[20:23], v[140:143], v[202:205], v[20:23]
	v_mfma_f32_16x16x32_bf16 v[12:15], v[116:119], v[218:221], v[12:15]
	v_mfma_f32_16x16x32_bf16 v[4:7], v[140:143], v[218:221], v[4:7]
	s_setprio 0
	s_setprio 1
	v_mfma_f32_16x16x32_bf16 v[56:59], v[144:147], v[182:185], v[56:59]
	v_mfma_f32_16x16x32_bf16 v[48:51], v[152:155], v[182:185], v[48:51]
	v_mfma_f32_16x16x32_bf16 v[40:43], v[144:147], v[190:193], v[40:43]
	v_mfma_f32_16x16x32_bf16 v[32:35], v[152:155], v[190:193], v[32:35]
	v_mfma_f32_16x16x32_bf16 v[24:27], v[144:147], v[198:201], v[24:27]
	v_mfma_f32_16x16x32_bf16 v[16:19], v[152:155], v[198:201], v[16:19]
	v_mfma_f32_16x16x32_bf16 v[8:11], v[144:147], v[214:217], v[8:11]
	v_mfma_f32_16x16x32_bf16 v[0:3], v[152:155], v[214:217], v[0:3]
	v_mfma_f32_16x16x32_bf16 v[56:59], v[148:151], v[186:189], v[56:59]
	v_mfma_f32_16x16x32_bf16 v[48:51], v[178:181], v[186:189], v[48:51]
	v_mfma_f32_16x16x32_bf16 v[40:43], v[148:151], v[194:197], v[40:43]
	v_mfma_f32_16x16x32_bf16 v[32:35], v[178:181], v[194:197], v[32:35]
	v_mfma_f32_16x16x32_bf16 v[24:27], v[148:151], v[202:205], v[24:27]
	v_mfma_f32_16x16x32_bf16 v[16:19], v[178:181], v[202:205], v[16:19]
	v_mfma_f32_16x16x32_bf16 v[8:11], v[148:151], v[218:221], v[8:11]
	v_mfma_f32_16x16x32_bf16 v[0:3], v[178:181], v[218:221], v[0:3]
	s_setprio 0
	s_barrier
	s_add_i32 s65, s65, 2
	s_add_u32 s63, s63, 0x100
	s_addc_u32 s64, s64, 0
	s_cmp_gt_u32 s65, 13
	s_mov_b64 s[34:35], s[36:37]
	s_cbranch_scc0 .LBB0_480
	s_and_b64 vcc, exec, s[18:19]
	s_cbranch_vccz .LBB0_483
	s_barrier

.LBB0_499:
	s_or_b64 exec, exec, s[28:29]
	s_andn2_b64 vcc, exec, s[6:7]
	s_mov_b64 s[6:7], -1
	s_cbranch_vccnz .LBB0_472
	s_andn2_b64 vcc, exec, s[8:9]
	s_cbranch_vccnz .LBB0_471
	s_mov_b32 s98, 1
	s_branch .LBB0_471

.LBB0_576:
	s_ashr_i32 s43, s42, 31
	s_lshl_b64 s[0:1], s[42:43], 19
	s_add_u32 s44, s22, s0
	s_addc_u32 s45, s23, s1
	s_and_b64 s[0:1], s[4:5], exec
	s_cselect_b32 s43, s45, s51
	s_cselect_b32 s67, s44, s50
	s_ashr_i32 s41, s40, 31
	s_lshl_b64 s[0:1], s[40:41], 19
	s_add_u32 s46, s39, s0
	s_addc_u32 s47, s58, s1
	s_and_b64 s[0:1], s[4:5], exec
	s_cselect_b32 s41, s47, s53
	s_cselect_b32 s68, s46, s52
	s_add_u32 s69, s52, 0x100
	s_addc_u32 s75, s53, 0
	s_mov_b32 s76, -2
	s_waitcnt vmcnt(0)
	s_cmp_eq_u32 s98, 1
	s_cbranch_scc0 .Lrestag_577
	s_barrier
	s_mov_b32 s98, 0
.Lrestag_577:
	s_add_u32 s52, s50, 0x100
	s_addc_u32 s53, s51, 0
	s_add_i32 s0, 0, 0x10000
	s_cmp_eq_u32 s76, 12
	s_cselect_b32 s57, s43, s53
	s_cselect_b32 s56, s67, s52
	s_cselect_b32 s55, s41, s75
	s_cselect_b32 s54, s68, s69
	s_add_i32 s12, 0, 0x14000
	v_add_u32_e32 v154, s0, v188
	v_add_u32_e32 v166, s12, v188
	ds_read_b128 v[142:145], v154
	ds_read_b128 v[146:149], v154 offset:1024
	ds_read_b128 v[150:153], v154 offset:2048
	ds_read_b128 v[154:157], v154 offset:3072
	ds_read_b128 v[158:161], v166
	ds_read_b128 v[162:165], v166 offset:1024
	ds_read_b128 v[184:187], v166 offset:2048
	ds_read_b128 v[190:193], v166 offset:3072
	s_add_i32 m0, s49, 0xc000
	ds_read_b128 v[194:197], v189
	ds_read_b128 v[198:201], v189 offset:1024
	ds_read_b128 v[202:205], v189 offset:2048
	ds_read_b128 v[206:209], v189 offset:3072
	ds_read_b128 v[210:213], v189 offset:4096
	ds_read_b128 v[214:217], v189 offset:5120
	ds_read_b128 v[228:231], v189 offset:6144
	ds_read_b128 v[232:235], v189 offset:7168
	global_load_lds_dwordx4 v138, s[50:51]
	s_add_i32 m0, s49, 0xe000
	s_nop 0
	global_load_lds_dwordx4 v140, s[50:51]
	s_nop 0
	s_waitcnt lgkmcnt(0)
	s_barrier
	s_setprio 1
	s_waitcnt lgkmcnt(0)
	v_mfma_f32_16x16x32_bf16 v[124:127], v[142:145], v[194:197], 0
	v_mfma_f32_16x16x32_bf16 v[120:123], v[150:153], v[194:197], 0
	v_mfma_f32_16x16x32_bf16 v[108:111], v[142:145], v[202:205], 0
	v_mfma_f32_16x16x32_bf16 v[104:107], v[150:153], v[202:205], 0
	v_mfma_f32_16x16x32_bf16 v[92:95], v[142:145], v[210:213], 0
	v_mfma_f32_16x16x32_bf16 v[88:91], v[150:153], v[210:213], 0
	v_mfma_f32_16x16x32_bf16 v[76:79], v[142:145], v[228:231], 0
	v_mfma_f32_16x16x32_bf16 v[72:75], v[150:153], v[228:231], 0
	v_mfma_f32_16x16x32_bf16 v[124:127], v[146:149], v[198:201], v[124:127]
	v_mfma_f32_16x16x32_bf16 v[120:123], v[154:157], v[198:201], v[120:123]
	v_mfma_f32_16x16x32_bf16 v[108:111], v[146:149], v[206:209], v[108:111]
	v_mfma_f32_16x16x32_bf16 v[104:107], v[154:157], v[206:209], v[104:107]
	v_mfma_f32_16x16x32_bf16 v[92:95], v[146:149], v[214:217], v[92:95]
	v_mfma_f32_16x16x32_bf16 v[88:91], v[154:157], v[214:217], v[88:91]
	v_mfma_f32_16x16x32_bf16 v[76:79], v[146:149], v[232:235], v[76:79]
	v_mfma_f32_16x16x32_bf16 v[72:75], v[154:157], v[232:235], v[72:75]
	s_setprio 0
	s_setprio 1
	v_mfma_f32_16x16x32_bf16 v[116:119], v[158:161], v[194:197], 0
	v_mfma_f32_16x16x32_bf16 v[112:115], v[184:187], v[194:197], 0
	v_mfma_f32_16x16x32_bf16 v[100:103], v[158:161], v[202:205], 0
	v_mfma_f32_16x16x32_bf16 v[96:99], v[184:187], v[202:205], 0
	v_mfma_f32_16x16x32_bf16 v[84:87], v[158:161], v[210:213], 0
	v_mfma_f32_16x16x32_bf16 v[80:83], v[184:187], v[210:213], 0
	v_mfma_f32_16x16x32_bf16 v[68:71], v[158:161], v[228:231], 0
	v_mfma_f32_16x16x32_bf16 v[64:67], v[184:187], v[228:231], 0
	v_mfma_f32_16x16x32_bf16 v[116:119], v[162:165], v[198:201], v[116:119]
	v_mfma_f32_16x16x32_bf16 v[112:115], v[190:193], v[198:201], v[112:115]
	v_mfma_f32_16x16x32_bf16 v[100:103], v[162:165], v[206:209], v[100:103]
	v_mfma_f32_16x16x32_bf16 v[96:99], v[190:193], v[206:209], v[96:99]
	v_mfma_f32_16x16x32_bf16 v[84:87], v[162:165], v[214:217], v[84:87]
	v_mfma_f32_16x16x32_bf16 v[80:83], v[190:193], v[214:217], v[80:83]
	v_mfma_f32_16x16x32_bf16 v[68:71], v[162:165], v[232:235], v[68:71]
	v_mfma_f32_16x16x32_bf16 v[64:67], v[190:193], v[232:235], v[64:67]
	s_setprio 0
	s_barrier
	s_add_i32 s0, s0, s59
	v_lshl_add_u64 v[166:167], s[54:55], 0, v[130:131]
	s_mov_b32 m0, s0
	ds_read_b128 v[194:197], v189 offset:16384
	ds_read_b128 v[198:201], v189 offset:17408
	ds_read_b128 v[202:205], v189 offset:18432
	ds_read_b128 v[206:209], v189 offset:19456
	ds_read_b128 v[210:213], v189 offset:20480
	ds_read_b128 v[214:217], v189 offset:21504
	ds_read_b128 v[228:231], v189 offset:22528
	ds_read_b128 v[232:235], v189 offset:23552
	global_load_lds_dwordx4 v[166:167], off
	s_add_i32 m0, s0, 0x2000
	s_add_u32 s0, s54, 0x40000
	v_lshl_add_u64 v[218:219], s[54:55], 0, v[134:135]
	s_addc_u32 s1, s55, 0
	s_add_i32 s12, s12, s59
	global_load_lds_dwordx4 v[218:219], off
	s_mov_b32 m0, s12
	v_lshl_add_u64 v[238:239], s[56:57], 0, v[132:133]
	global_load_lds_dwordx4 v130, s[0:1]
	s_add_i32 m0, s12, 0x2000
	s_nop 0
	global_load_lds_dwordx4 v134, s[0:1]
	v_lshl_add_u64 v[236:237], s[56:57], 0, v[128:129]
	s_nop 0
	s_waitcnt lgkmcnt(0)
	s_barrier
	s_setprio 1
	s_waitcnt lgkmcnt(0)
	v_mfma_f32_16x16x32_bf16 v[60:63], v[142:145], v[194:197], 0
	v_mfma_f32_16x16x32_bf16 v[56:59], v[150:153], v[194:197], 0
	v_mfma_f32_16x16x32_bf16 v[44:47], v[142:145], v[202:205], 0
	v_mfma_f32_16x16x32_bf16 v[40:43], v[150:153], v[202:205], 0
	v_mfma_f32_16x16x32_bf16 v[28:31], v[142:145], v[210:213], 0
	v_mfma_f32_16x16x32_bf16 v[24:27], v[150:153], v[210:213], 0
	v_mfma_f32_16x16x32_bf16 v[12:15], v[142:145], v[228:231], 0
	v_mfma_f32_16x16x32_bf16 v[8:11], v[150:153], v[228:231], 0
	v_mfma_f32_16x16x32_bf16 v[60:63], v[146:149], v[198:201], v[60:63]
	v_mfma_f32_16x16x32_bf16 v[56:59], v[154:157], v[198:201], v[56:59]
	v_mfma_f32_16x16x32_bf16 v[44:47], v[146:149], v[206:209], v[44:47]
	v_mfma_f32_16x16x32_bf16 v[40:43], v[154:157], v[206:209], v[40:43]
	v_mfma_f32_16x16x32_bf16 v[28:31], v[146:149], v[214:217], v[28:31]
	v_mfma_f32_16x16x32_bf16 v[24:27], v[154:157], v[214:217], v[24:27]
	v_mfma_f32_16x16x32_bf16 v[12:15], v[146:149], v[232:235], v[12:15]
	v_mfma_f32_16x16x32_bf16 v[8:11], v[154:157], v[232:235], v[8:11]
	s_setprio 0
	s_setprio 1
	v_mfma_f32_16x16x32_bf16 v[52:55], v[158:161], v[194:197], 0
	v_mfma_f32_16x16x32_bf16 v[48:51], v[184:187], v[194:197], 0
	v_mfma_f32_16x16x32_bf16 v[36:39], v[158:161], v[202:205], 0
	v_mfma_f32_16x16x32_bf16 v[32:35], v[184:187], v[202:205], 0
	v_mfma_f32_16x16x32_bf16 v[20:23], v[158:161], v[210:213], 0
	v_mfma_f32_16x16x32_bf16 v[16:19], v[184:187], v[210:213], 0
	v_mfma_f32_16x16x32_bf16 v[4:7], v[158:161], v[228:231], 0
	v_mfma_f32_16x16x32_bf16 v[0:3], v[184:187], v[228:231], 0
	v_mfma_f32_16x16x32_bf16 v[52:55], v[162:165], v[198:201], v[52:55]
	v_mfma_f32_16x16x32_bf16 v[48:51], v[190:193], v[198:201], v[48:51]
	v_mfma_f32_16x16x32_bf16 v[36:39], v[162:165], v[206:209], v[36:39]
	v_mfma_f32_16x16x32_bf16 v[32:35], v[190:193], v[206:209], v[32:35]
	v_mfma_f32_16x16x32_bf16 v[20:23], v[162:165], v[214:217], v[20:23]
	v_mfma_f32_16x16x32_bf16 v[16:19], v[190:193], v[214:217], v[16:19]
	v_mfma_f32_16x16x32_bf16 v[4:7], v[162:165], v[232:235], v[4:7]
	v_mfma_f32_16x16x32_bf16 v[0:3], v[190:193], v[232:235], v[0:3]
	s_setprio 0
	s_barrier
	s_add_i32 s12, 0, 0x18000
	s_add_i32 s13, 0, 0x1c000
	v_add_u32_e32 v154, s12, v188
	v_add_u32_e32 v170, s13, v188
	ds_read_b128 v[142:145], v154
	ds_read_b128 v[146:149], v154 offset:1024
	ds_read_b128 v[150:153], v154 offset:2048
	ds_read_b128 v[154:157], v154 offset:3072
	ds_read_b128 v[158:161], v170
	ds_read_b128 v[162:165], v170 offset:1024
	ds_read_b128 v[184:187], v170 offset:2048
	ds_read_b128 v[190:193], v170 offset:3072
	s_add_u32 s0, s56, 0x40000
	s_addc_u32 s1, s57, 0
	s_mov_b32 m0, s61
	ds_read_b128 v[194:197], v189 offset:32768
	ds_read_b128 v[198:201], v189 offset:33792
	ds_read_b128 v[202:205], v189 offset:34816
	ds_read_b128 v[206:209], v189 offset:35840
	ds_read_b128 v[210:213], v189 offset:36864
	ds_read_b128 v[214:217], v189 offset:37888
	ds_read_b128 v[228:231], v189 offset:38912
	ds_read_b128 v[232:235], v189 offset:39936
	global_load_lds_dwordx4 v128, s[0:1]
	s_mov_b32 m0, s62
	s_nop 0
	global_load_lds_dwordx4 v132, s[0:1]
	s_mov_b32 m0, s49
	s_nop 0
	global_load_lds_dwordx4 v[236:237], off
	s_mov_b32 m0, s60
	s_nop 0
	global_load_lds_dwordx4 v[238:239], off
	s_waitcnt vmcnt(8)
	s_waitcnt lgkmcnt(0)
	s_barrier
	s_setprio 1
	s_waitcnt lgkmcnt(0)
	v_mfma_f32_16x16x32_bf16 v[124:127], v[142:145], v[194:197], v[124:127]
	v_mfma_f32_16x16x32_bf16 v[120:123], v[150:153], v[194:197], v[120:123]
	v_mfma_f32_16x16x32_bf16 v[108:111], v[142:145], v[202:205], v[108:111]
	v_mfma_f32_16x16x32_bf16 v[104:107], v[150:153], v[202:205], v[104:107]
	v_mfma_f32_16x16x32_bf16 v[92:95], v[142:145], v[210:213], v[92:95]
	v_mfma_f32_16x16x32_bf16 v[88:91], v[150:153], v[210:213], v[88:91]
	v_mfma_f32_16x16x32_bf16 v[76:79], v[142:145], v[228:231], v[76:79]
	v_mfma_f32_16x16x32_bf16 v[72:75], v[150:153], v[228:231], v[72:75]
	v_mfma_f32_16x16x32_bf16 v[124:127], v[146:149], v[198:201], v[124:127]
	v_mfma_f32_16x16x32_bf16 v[120:123], v[154:157], v[198:201], v[120:123]
	v_mfma_f32_16x16x32_bf16 v[108:111], v[146:149], v[206:209], v[108:111]
	v_mfma_f32_16x16x32_bf16 v[104:107], v[154:157], v[206:209], v[104:107]
	v_mfma_f32_16x16x32_bf16 v[92:95], v[146:149], v[214:217], v[92:95]
	v_mfma_f32_16x16x32_bf16 v[88:91], v[154:157], v[214:217], v[88:91]
	v_mfma_f32_16x16x32_bf16 v[76:79], v[146:149], v[232:235], v[76:79]
	v_mfma_f32_16x16x32_bf16 v[72:75], v[154:157], v[232:235], v[72:75]
	s_setprio 0
	s_setprio 1
	v_mfma_f32_16x16x32_bf16 v[116:119], v[158:161], v[194:197], v[116:119]
	v_mfma_f32_16x16x32_bf16 v[112:115], v[184:187], v[194:197], v[112:115]
	v_mfma_f32_16x16x32_bf16 v[100:103], v[158:161], v[202:205], v[100:103]
	v_mfma_f32_16x16x32_bf16 v[96:99], v[184:187], v[202:205], v[96:99]
	v_mfma_f32_16x16x32_bf16 v[84:87], v[158:161], v[210:213], v[84:87]
	v_mfma_f32_16x16x32_bf16 v[80:83], v[184:187], v[210:213], v[80:83]
	v_mfma_f32_16x16x32_bf16 v[68:71], v[158:161], v[228:231], v[68:71]
	v_mfma_f32_16x16x32_bf16 v[64:67], v[184:187], v[228:231], v[64:67]
	v_mfma_f32_16x16x32_bf16 v[116:119], v[162:165], v[198:201], v[116:119]
	v_mfma_f32_16x16x32_bf16 v[112:115], v[190:193], v[198:201], v[112:115]
	v_mfma_f32_16x16x32_bf16 v[100:103], v[162:165], v[206:209], v[100:103]
	v_mfma_f32_16x16x32_bf16 v[96:99], v[190:193], v[206:209], v[96:99]
	v_mfma_f32_16x16x32_bf16 v[84:87], v[162:165], v[214:217], v[84:87]
	v_mfma_f32_16x16x32_bf16 v[80:83], v[190:193], v[214:217], v[80:83]
	v_mfma_f32_16x16x32_bf16 v[68:71], v[162:165], v[232:235], v[68:71]
	v_mfma_f32_16x16x32_bf16 v[64:67], v[190:193], v[232:235], v[64:67]
	s_setprio 0
	s_barrier
	s_add_i32 s0, s12, s59
	v_lshl_add_u64 v[166:167], v[166:167], 0, s[16:17]
	s_mov_b32 m0, s0
	ds_read_b128 v[194:197], v189 offset:49152
	ds_read_b128 v[198:201], v189 offset:50176
	ds_read_b128 v[202:205], v189 offset:51200
	ds_read_b128 v[206:209], v189 offset:52224
	ds_read_b128 v[210:213], v189 offset:53248
	ds_read_b128 v[214:217], v189 offset:54272
	ds_read_b128 v[228:231], v189 offset:55296
	ds_read_b128 v[232:235], v189 offset:56320
	global_load_lds_dwordx4 v[166:167], off
	s_add_i32 m0, s0, 0x2000
	s_add_u32 s0, s54, 0x40080
	v_lshl_add_u64 v[166:167], v[218:219], 0, s[16:17]
	s_addc_u32 s1, s55, 0
	s_add_i32 s12, s13, s59
	global_load_lds_dwordx4 v[166:167], off
	s_mov_b32 m0, s12
	s_nop 0
	global_load_lds_dwordx4 v130, s[0:1]
	s_add_i32 m0, s12, 0x2000
	s_nop 0
	global_load_lds_dwordx4 v134, s[0:1]
	v_lshl_add_u64 v[166:167], v[236:237], 0, s[16:17]
	s_mov_b32 m0, s64
	s_nop 0
	global_load_lds_dwordx4 v[166:167], off
	v_lshl_add_u64 v[166:167], v[238:239], 0, s[16:17]
	s_mov_b32 m0, s65
	s_nop 0
	global_load_lds_dwordx4 v[166:167], off
	s_waitcnt vmcnt(6)
	s_waitcnt lgkmcnt(0)
	s_barrier
	s_setprio 1
	s_waitcnt lgkmcnt(0)
	v_mfma_f32_16x16x32_bf16 v[60:63], v[142:145], v[194:197], v[60:63]
	v_mfma_f32_16x16x32_bf16 v[56:59], v[150:153], v[194:197], v[56:59]
	v_mfma_f32_16x16x32_bf16 v[44:47], v[142:145], v[202:205], v[44:47]
	v_mfma_f32_16x16x32_bf16 v[40:43], v[150:153], v[202:205], v[40:43]
	v_mfma_f32_16x16x32_bf16 v[28:31], v[142:145], v[210:213], v[28:31]
	v_mfma_f32_16x16x32_bf16 v[24:27], v[150:153], v[210:213], v[24:27]
	v_mfma_f32_16x16x32_bf16 v[12:15], v[142:145], v[228:231], v[12:15]
	v_mfma_f32_16x16x32_bf16 v[8:11], v[150:153], v[228:231], v[8:11]
	v_mfma_f32_16x16x32_bf16 v[60:63], v[146:149], v[198:201], v[60:63]
	v_mfma_f32_16x16x32_bf16 v[56:59], v[154:157], v[198:201], v[56:59]
	v_mfma_f32_16x16x32_bf16 v[44:47], v[146:149], v[206:209], v[44:47]
	v_mfma_f32_16x16x32_bf16 v[40:43], v[154:157], v[206:209], v[40:43]
	v_mfma_f32_16x16x32_bf16 v[28:31], v[146:149], v[214:217], v[28:31]
	v_mfma_f32_16x16x32_bf16 v[24:27], v[154:157], v[214:217], v[24:27]
	v_mfma_f32_16x16x32_bf16 v[12:15], v[146:149], v[232:235], v[12:15]
	v_mfma_f32_16x16x32_bf16 v[8:11], v[154:157], v[232:235], v[8:11]
	s_setprio 0
	s_setprio 1
	v_mfma_f32_16x16x32_bf16 v[52:55], v[158:161], v[194:197], v[52:55]
	v_mfma_f32_16x16x32_bf16 v[48:51], v[184:187], v[194:197], v[48:51]
	v_mfma_f32_16x16x32_bf16 v[36:39], v[158:161], v[202:205], v[36:39]
	v_mfma_f32_16x16x32_bf16 v[32:35], v[184:187], v[202:205], v[32:35]
	v_mfma_f32_16x16x32_bf16 v[20:23], v[158:161], v[210:213], v[20:23]
	v_mfma_f32_16x16x32_bf16 v[16:19], v[184:187], v[210:213], v[16:19]
	v_mfma_f32_16x16x32_bf16 v[4:7], v[158:161], v[228:231], v[4:7]
	v_mfma_f32_16x16x32_bf16 v[0:3], v[184:187], v[228:231], v[0:3]
	v_mfma_f32_16x16x32_bf16 v[52:55], v[162:165], v[198:201], v[52:55]
	v_mfma_f32_16x16x32_bf16 v[48:51], v[190:193], v[198:201], v[48:51]
	v_mfma_f32_16x16x32_bf16 v[36:39], v[162:165], v[206:209], v[36:39]
	v_mfma_f32_16x16x32_bf16 v[32:35], v[190:193], v[206:209], v[32:35]
	v_mfma_f32_16x16x32_bf16 v[20:23], v[162:165], v[214:217], v[20:23]
	v_mfma_f32_16x16x32_bf16 v[16:19], v[190:193], v[214:217], v[16:19]
	v_mfma_f32_16x16x32_bf16 v[4:7], v[162:165], v[232:235], v[4:7]
	v_mfma_f32_16x16x32_bf16 v[0:3], v[190:193], v[232:235], v[0:3]
	s_setprio 0
	s_barrier
	s_add_i32 s76, s76, 2
	s_add_u32 s69, s69, 0x100
	s_addc_u32 s75, s75, 0
	s_cmp_gt_u32 s76, 13
	s_mov_b64 s[50:51], s[52:53]
.LBB0_577:
	s_add_u32 s52, s50, 0x100
	s_addc_u32 s53, s51, 0
	s_add_i32 s0, 0, 0x10000
	s_cmp_eq_u32 s76, 12
	s_cselect_b32 s57, s43, s53
	s_cselect_b32 s56, s67, s52
	s_cselect_b32 s55, s41, s75
	s_cselect_b32 s54, s68, s69
	s_add_i32 s12, 0, 0x14000
	v_add_u32_e32 v154, s0, v188
	v_add_u32_e32 v166, s12, v188
	ds_read_b128 v[142:145], v154
	ds_read_b128 v[146:149], v154 offset:1024
	ds_read_b128 v[150:153], v154 offset:2048
	ds_read_b128 v[154:157], v154 offset:3072
	ds_read_b128 v[158:161], v166
	ds_read_b128 v[162:165], v166 offset:1024
	ds_read_b128 v[184:187], v166 offset:2048
	ds_read_b128 v[190:193], v166 offset:3072
	s_add_i32 m0, s49, 0xc000
	ds_read_b128 v[194:197], v189
	ds_read_b128 v[198:201], v189 offset:1024
	ds_read_b128 v[202:205], v189 offset:2048
	ds_read_b128 v[206:209], v189 offset:3072
	ds_read_b128 v[210:213], v189 offset:4096
	ds_read_b128 v[214:217], v189 offset:5120
	ds_read_b128 v[228:231], v189 offset:6144
	ds_read_b128 v[232:235], v189 offset:7168
	global_load_lds_dwordx4 v138, s[50:51]
	s_add_i32 m0, s49, 0xe000
	s_nop 0
	global_load_lds_dwordx4 v140, s[50:51]
	s_waitcnt vmcnt(8)
	s_waitcnt lgkmcnt(0)
	s_barrier
	s_setprio 1
	s_waitcnt lgkmcnt(0)
	v_mfma_f32_16x16x32_bf16 v[124:127], v[142:145], v[194:197], v[124:127]
	v_mfma_f32_16x16x32_bf16 v[120:123], v[150:153], v[194:197], v[120:123]
	v_mfma_f32_16x16x32_bf16 v[108:111], v[142:145], v[202:205], v[108:111]
	v_mfma_f32_16x16x32_bf16 v[104:107], v[150:153], v[202:205], v[104:107]
	v_mfma_f32_16x16x32_bf16 v[92:95], v[142:145], v[210:213], v[92:95]
	v_mfma_f32_16x16x32_bf16 v[88:91], v[150:153], v[210:213], v[88:91]
	v_mfma_f32_16x16x32_bf16 v[76:79], v[142:145], v[228:231], v[76:79]
	v_mfma_f32_16x16x32_bf16 v[72:75], v[150:153], v[228:231], v[72:75]
	v_mfma_f32_16x16x32_bf16 v[124:127], v[146:149], v[198:201], v[124:127]
	v_mfma_f32_16x16x32_bf16 v[120:123], v[154:157], v[198:201], v[120:123]
	v_mfma_f32_16x16x32_bf16 v[108:111], v[146:149], v[206:209], v[108:111]
	v_mfma_f32_16x16x32_bf16 v[104:107], v[154:157], v[206:209], v[104:107]
	v_mfma_f32_16x16x32_bf16 v[92:95], v[146:149], v[214:217], v[92:95]
	v_mfma_f32_16x16x32_bf16 v[88:91], v[154:157], v[214:217], v[88:91]
	v_mfma_f32_16x16x32_bf16 v[76:79], v[146:149], v[232:235], v[76:79]
	v_mfma_f32_16x16x32_bf16 v[72:75], v[154:157], v[232:235], v[72:75]
	s_setprio 0
	s_setprio 1
	v_mfma_f32_16x16x32_bf16 v[116:119], v[158:161], v[194:197], v[116:119]
	v_mfma_f32_16x16x32_bf16 v[112:115], v[184:187], v[194:197], v[112:115]
	v_mfma_f32_16x16x32_bf16 v[100:103], v[158:161], v[202:205], v[100:103]
	v_mfma_f32_16x16x32_bf16 v[96:99], v[184:187], v[202:205], v[96:99]
	v_mfma_f32_16x16x32_bf16 v[84:87], v[158:161], v[210:213], v[84:87]
	v_mfma_f32_16x16x32_bf16 v[80:83], v[184:187], v[210:213], v[80:83]
	v_mfma_f32_16x16x32_bf16 v[68:71], v[158:161], v[228:231], v[68:71]
	v_mfma_f32_16x16x32_bf16 v[64:67], v[184:187], v[228:231], v[64:67]
	v_mfma_f32_16x16x32_bf16 v[116:119], v[162:165], v[198:201], v[116:119]
	v_mfma_f32_16x16x32_bf16 v[112:115], v[190:193], v[198:201], v[112:115]
	v_mfma_f32_16x16x32_bf16 v[100:103], v[162:165], v[206:209], v[100:103]
	v_mfma_f32_16x16x32_bf16 v[96:99], v[190:193], v[206:209], v[96:99]
	v_mfma_f32_16x16x32_bf16 v[84:87], v[162:165], v[214:217], v[84:87]
	v_mfma_f32_16x16x32_bf16 v[80:83], v[190:193], v[214:217], v[80:83]
	v_mfma_f32_16x16x32_bf16 v[68:71], v[162:165], v[232:235], v[68:71]
	v_mfma_f32_16x16x32_bf16 v[64:67], v[190:193], v[232:235], v[64:67]
	s_setprio 0
	s_barrier
	s_add_i32 s0, s0, s59
	v_lshl_add_u64 v[166:167], s[54:55], 0, v[130:131]
	s_mov_b32 m0, s0
	ds_read_b128 v[194:197], v189 offset:16384
	ds_read_b128 v[198:201], v189 offset:17408
	ds_read_b128 v[202:205], v189 offset:18432
	ds_read_b128 v[206:209], v189 offset:19456
	ds_read_b128 v[210:213], v189 offset:20480
	ds_read_b128 v[214:217], v189 offset:21504
	ds_read_b128 v[228:231], v189 offset:22528
	ds_read_b128 v[232:235], v189 offset:23552
	global_load_lds_dwordx4 v[166:167], off
	s_add_i32 m0, s0, 0x2000
	s_add_u32 s0, s54, 0x40000
	v_lshl_add_u64 v[218:219], s[54:55], 0, v[134:135]
	s_addc_u32 s1, s55, 0
	s_add_i32 s12, s12, s59
	global_load_lds_dwordx4 v[218:219], off
	s_mov_b32 m0, s12
	v_lshl_add_u64 v[238:239], s[56:57], 0, v[132:133]
	global_load_lds_dwordx4 v130, s[0:1]
	s_add_i32 m0, s12, 0x2000
	s_nop 0
	global_load_lds_dwordx4 v134, s[0:1]
	v_lshl_add_u64 v[236:237], s[56:57], 0, v[128:129]
	s_waitcnt vmcnt(6)
	s_waitcnt lgkmcnt(0)
	s_barrier
	s_setprio 1
	s_waitcnt lgkmcnt(0)
	v_mfma_f32_16x16x32_bf16 v[60:63], v[142:145], v[194:197], v[60:63]
	v_mfma_f32_16x16x32_bf16 v[56:59], v[150:153], v[194:197], v[56:59]
	v_mfma_f32_16x16x32_bf16 v[44:47], v[142:145], v[202:205], v[44:47]
	v_mfma_f32_16x16x32_bf16 v[40:43], v[150:153], v[202:205], v[40:43]
	v_mfma_f32_16x16x32_bf16 v[28:31], v[142:145], v[210:213], v[28:31]
	v_mfma_f32_16x16x32_bf16 v[24:27], v[150:153], v[210:213], v[24:27]
	v_mfma_f32_16x16x32_bf16 v[12:15], v[142:145], v[228:231], v[12:15]
	v_mfma_f32_16x16x32_bf16 v[8:11], v[150:153], v[228:231], v[8:11]
	v_mfma_f32_16x16x32_bf16 v[60:63], v[146:149], v[198:201], v[60:63]
	v_mfma_f32_16x16x32_bf16 v[56:59], v[154:157], v[198:201], v[56:59]
	v_mfma_f32_16x16x32_bf16 v[44:47], v[146:149], v[206:209], v[44:47]
	v_mfma_f32_16x16x32_bf16 v[40:43], v[154:157], v[206:209], v[40:43]
	v_mfma_f32_16x16x32_bf16 v[28:31], v[146:149], v[214:217], v[28:31]
	v_mfma_f32_16x16x32_bf16 v[24:27], v[154:157], v[214:217], v[24:27]
	v_mfma_f32_16x16x32_bf16 v[12:15], v[146:149], v[232:235], v[12:15]
	v_mfma_f32_16x16x32_bf16 v[8:11], v[154:157], v[232:235], v[8:11]
	s_setprio 0
	s_setprio 1
	v_mfma_f32_16x16x32_bf16 v[52:55], v[158:161], v[194:197], v[52:55]
	v_mfma_f32_16x16x32_bf16 v[48:51], v[184:187], v[194:197], v[48:51]
	v_mfma_f32_16x16x32_bf16 v[36:39], v[158:161], v[202:205], v[36:39]
	v_mfma_f32_16x16x32_bf16 v[32:35], v[184:187], v[202:205], v[32:35]
	v_mfma_f32_16x16x32_bf16 v[20:23], v[158:161], v[210:213], v[20:23]
	v_mfma_f32_16x16x32_bf16 v[16:19], v[184:187], v[210:213], v[16:19]
	v_mfma_f32_16x16x32_bf16 v[4:7], v[158:161], v[228:231], v[4:7]
	v_mfma_f32_16x16x32_bf16 v[0:3], v[184:187], v[228:231], v[0:3]
	v_mfma_f32_16x16x32_bf16 v[52:55], v[162:165], v[198:201], v[52:55]
	v_mfma_f32_16x16x32_bf16 v[48:51], v[190:193], v[198:201], v[48:51]
	v_mfma_f32_16x16x32_bf16 v[36:39], v[162:165], v[206:209], v[36:39]
	v_mfma_f32_16x16x32_bf16 v[32:35], v[190:193], v[206:209], v[32:35]
	v_mfma_f32_16x16x32_bf16 v[20:23], v[162:165], v[214:217], v[20:23]
	v_mfma_f32_16x16x32_bf16 v[16:19], v[190:193], v[214:217], v[16:19]
	v_mfma_f32_16x16x32_bf16 v[4:7], v[162:165], v[232:235], v[4:7]
	v_mfma_f32_16x16x32_bf16 v[0:3], v[190:193], v[232:235], v[0:3]
	s_setprio 0
	s_barrier
	s_add_i32 s12, 0, 0x18000
	s_add_i32 s13, 0, 0x1c000
	v_add_u32_e32 v154, s12, v188
	v_add_u32_e32 v170, s13, v188
	ds_read_b128 v[142:145], v154
	ds_read_b128 v[146:149], v154 offset:1024
	ds_read_b128 v[150:153], v154 offset:2048
	ds_read_b128 v[154:157], v154 offset:3072
	ds_read_b128 v[158:161], v170
	ds_read_b128 v[162:165], v170 offset:1024
	ds_read_b128 v[184:187], v170 offset:2048
	ds_read_b128 v[190:193], v170 offset:3072
	s_add_u32 s0, s56, 0x40000
	s_addc_u32 s1, s57, 0
	s_mov_b32 m0, s61
	ds_read_b128 v[194:197], v189 offset:32768
	ds_read_b128 v[198:201], v189 offset:33792
	ds_read_b128 v[202:205], v189 offset:34816
	ds_read_b128 v[206:209], v189 offset:35840
	ds_read_b128 v[210:213], v189 offset:36864
	ds_read_b128 v[214:217], v189 offset:37888
	ds_read_b128 v[228:231], v189 offset:38912
	ds_read_b128 v[232:235], v189 offset:39936
	global_load_lds_dwordx4 v128, s[0:1]
	s_mov_b32 m0, s62
	s_nop 0
	global_load_lds_dwordx4 v132, s[0:1]
	s_mov_b32 m0, s49
	s_nop 0
	global_load_lds_dwordx4 v[236:237], off
	s_mov_b32 m0, s60
	s_nop 0
	global_load_lds_dwordx4 v[238:239], off
	s_waitcnt vmcnt(8)
	s_waitcnt lgkmcnt(0)
	s_barrier
	s_setprio 1
	s_waitcnt lgkmcnt(0)
	v_mfma_f32_16x16x32_bf16 v[124:127], v[142:145], v[194:197], v[124:127]
	v_mfma_f32_16x16x32_bf16 v[120:123], v[150:153], v[194:197], v[120:123]
	v_mfma_f32_16x16x32_bf16 v[108:111], v[142:145], v[202:205], v[108:111]
	v_mfma_f32_16x16x32_bf16 v[104:107], v[150:153], v[202:205], v[104:107]
	v_mfma_f32_16x16x32_bf16 v[92:95], v[142:145], v[210:213], v[92:95]
	v_mfma_f32_16x16x32_bf16 v[88:91], v[150:153], v[210:213], v[88:91]
	v_mfma_f32_16x16x32_bf16 v[76:79], v[142:145], v[228:231], v[76:79]
	v_mfma_f32_16x16x32_bf16 v[72:75], v[150:153], v[228:231], v[72:75]
	v_mfma_f32_16x16x32_bf16 v[124:127], v[146:149], v[198:201], v[124:127]
	v_mfma_f32_16x16x32_bf16 v[120:123], v[154:157], v[198:201], v[120:123]
	v_mfma_f32_16x16x32_bf16 v[108:111], v[146:149], v[206:209], v[108:111]
	v_mfma_f32_16x16x32_bf16 v[104:107], v[154:157], v[206:209], v[104:107]
	v_mfma_f32_16x16x32_bf16 v[92:95], v[146:149], v[214:217], v[92:95]
	v_mfma_f32_16x16x32_bf16 v[88:91], v[154:157], v[214:217], v[88:91]
	v_mfma_f32_16x16x32_bf16 v[76:79], v[146:149], v[232:235], v[76:79]
	v_mfma_f32_16x16x32_bf16 v[72:75], v[154:157], v[232:235], v[72:75]
	s_setprio 0
	s_setprio 1
	v_mfma_f32_16x16x32_bf16 v[116:119], v[158:161], v[194:197], v[116:119]
	v_mfma_f32_16x16x32_bf16 v[112:115], v[184:187], v[194:197], v[112:115]
	v_mfma_f32_16x16x32_bf16 v[100:103], v[158:161], v[202:205], v[100:103]
	v_mfma_f32_16x16x32_bf16 v[96:99], v[184:187], v[202:205], v[96:99]
	v_mfma_f32_16x16x32_bf16 v[84:87], v[158:161], v[210:213], v[84:87]
	v_mfma_f32_16x16x32_bf16 v[80:83], v[184:187], v[210:213], v[80:83]
	v_mfma_f32_16x16x32_bf16 v[68:71], v[158:161], v[228:231], v[68:71]
	v_mfma_f32_16x16x32_bf16 v[64:67], v[184:187], v[228:231], v[64:67]
	v_mfma_f32_16x16x32_bf16 v[116:119], v[162:165], v[198:201], v[116:119]
	v_mfma_f32_16x16x32_bf16 v[112:115], v[190:193], v[198:201], v[112:115]
	v_mfma_f32_16x16x32_bf16 v[100:103], v[162:165], v[206:209], v[100:103]
	v_mfma_f32_16x16x32_bf16 v[96:99], v[190:193], v[206:209], v[96:99]
	v_mfma_f32_16x16x32_bf16 v[84:87], v[162:165], v[214:217], v[84:87]
	v_mfma_f32_16x16x32_bf16 v[80:83], v[190:193], v[214:217], v[80:83]
	v_mfma_f32_16x16x32_bf16 v[68:71], v[162:165], v[232:235], v[68:71]
	v_mfma_f32_16x16x32_bf16 v[64:67], v[190:193], v[232:235], v[64:67]
	s_setprio 0
	s_barrier
	s_add_i32 s0, s12, s59
	v_lshl_add_u64 v[166:167], v[166:167], 0, s[16:17]
	s_mov_b32 m0, s0
	ds_read_b128 v[194:197], v189 offset:49152
	ds_read_b128 v[198:201], v189 offset:50176
	ds_read_b128 v[202:205], v189 offset:51200
	ds_read_b128 v[206:209], v189 offset:52224
	ds_read_b128 v[210:213], v189 offset:53248
	ds_read_b128 v[214:217], v189 offset:54272
	ds_read_b128 v[228:231], v189 offset:55296
	ds_read_b128 v[232:235], v189 offset:56320
	global_load_lds_dwordx4 v[166:167], off
	s_add_i32 m0, s0, 0x2000
	s_add_u32 s0, s54, 0x40080
	v_lshl_add_u64 v[166:167], v[218:219], 0, s[16:17]
	s_addc_u32 s1, s55, 0
	s_add_i32 s12, s13, s59
	global_load_lds_dwordx4 v[166:167], off
	s_mov_b32 m0, s12
	s_nop 0
	global_load_lds_dwordx4 v130, s[0:1]
	s_add_i32 m0, s12, 0x2000
	s_nop 0
	global_load_lds_dwordx4 v134, s[0:1]
	v_lshl_add_u64 v[166:167], v[236:237], 0, s[16:17]
	s_mov_b32 m0, s64
	s_nop 0
	global_load_lds_dwordx4 v[166:167], off
	v_lshl_add_u64 v[166:167], v[238:239], 0, s[16:17]
	s_mov_b32 m0, s65
	s_nop 0
	global_load_lds_dwordx4 v[166:167], off
	s_waitcnt vmcnt(6)
	s_waitcnt lgkmcnt(0)
	s_barrier
	s_setprio 1
	s_waitcnt lgkmcnt(0)
	v_mfma_f32_16x16x32_bf16 v[60:63], v[142:145], v[194:197], v[60:63]
	v_mfma_f32_16x16x32_bf16 v[56:59], v[150:153], v[194:197], v[56:59]
	v_mfma_f32_16x16x32_bf16 v[44:47], v[142:145], v[202:205], v[44:47]
	v_mfma_f32_16x16x32_bf16 v[40:43], v[150:153], v[202:205], v[40:43]
	v_mfma_f32_16x16x32_bf16 v[28:31], v[142:145], v[210:213], v[28:31]
	v_mfma_f32_16x16x32_bf16 v[24:27], v[150:153], v[210:213], v[24:27]
	v_mfma_f32_16x16x32_bf16 v[12:15], v[142:145], v[228:231], v[12:15]
	v_mfma_f32_16x16x32_bf16 v[8:11], v[150:153], v[228:231], v[8:11]
	v_mfma_f32_16x16x32_bf16 v[60:63], v[146:149], v[198:201], v[60:63]
	v_mfma_f32_16x16x32_bf16 v[56:59], v[154:157], v[198:201], v[56:59]
	v_mfma_f32_16x16x32_bf16 v[44:47], v[146:149], v[206:209], v[44:47]
	v_mfma_f32_16x16x32_bf16 v[40:43], v[154:157], v[206:209], v[40:43]
	v_mfma_f32_16x16x32_bf16 v[28:31], v[146:149], v[214:217], v[28:31]
	v_mfma_f32_16x16x32_bf16 v[24:27], v[154:157], v[214:217], v[24:27]
	v_mfma_f32_16x16x32_bf16 v[12:15], v[146:149], v[232:235], v[12:15]
	v_mfma_f32_16x16x32_bf16 v[8:11], v[154:157], v[232:235], v[8:11]
	s_setprio 0
	s_setprio 1
	v_mfma_f32_16x16x32_bf16 v[52:55], v[158:161], v[194:197], v[52:55]
	v_mfma_f32_16x16x32_bf16 v[48:51], v[184:187], v[194:197], v[48:51]
	v_mfma_f32_16x16x32_bf16 v[36:39], v[158:161], v[202:205], v[36:39]
	v_mfma_f32_16x16x32_bf16 v[32:35], v[184:187], v[202:205], v[32:35]
	v_mfma_f32_16x16x32_bf16 v[20:23], v[158:161], v[210:213], v[20:23]
	v_mfma_f32_16x16x32_bf16 v[16:19], v[184:187], v[210:213], v[16:19]
	v_mfma_f32_16x16x32_bf16 v[4:7], v[158:161], v[228:231], v[4:7]
	v_mfma_f32_16x16x32_bf16 v[0:3], v[184:187], v[228:231], v[0:3]
	v_mfma_f32_16x16x32_bf16 v[52:55], v[162:165], v[198:201], v[52:55]
	v_mfma_f32_16x16x32_bf16 v[48:51], v[190:193], v[198:201], v[48:51]
	v_mfma_f32_16x16x32_bf16 v[36:39], v[162:165], v[206:209], v[36:39]
	v_mfma_f32_16x16x32_bf16 v[32:35], v[190:193], v[206:209], v[32:35]
	v_mfma_f32_16x16x32_bf16 v[20:23], v[162:165], v[214:217], v[20:23]
	v_mfma_f32_16x16x32_bf16 v[16:19], v[190:193], v[214:217], v[16:19]
	v_mfma_f32_16x16x32_bf16 v[4:7], v[162:165], v[232:235], v[4:7]
	v_mfma_f32_16x16x32_bf16 v[0:3], v[190:193], v[232:235], v[0:3]
	s_setprio 0
	s_barrier
	s_add_i32 s76, s76, 2
	s_add_u32 s69, s69, 0x100
	s_addc_u32 s75, s75, 0
	s_cmp_gt_u32 s76, 13
	s_mov_b64 s[50:51], s[52:53]
	s_cbranch_scc0 .LBB0_577
	s_and_b64 vcc, exec, s[36:37]
	s_cbranch_vccz .LBB0_580
	s_barrier
.LBB0_580:
	s_lshl_b32 s0, s66, 2
	s_and_b32 s0, s0, 12
	s_cmp_lt_u32 s66, 4
	s_cselect_b64 vcc, -1, 0
	s_or_b32 s12, s0, s63
	s_cmp_gt_i32 s66, 3
	v_lshl_add_u32 v204, s48, 8, v137
	s_cselect_b32 s1, s9, s29
	s_cselect_b32 s0, s8, s28
	v_lshlrev_b32_e32 v150, 2, v136
	v_add_u32_e32 v164, 0x80, v204
	v_add_u32_e32 v162, 0x90, v204
	global_load_dwordx4 v[142:145], v150, s[0:1] offset:16
	global_load_dwordx4 v[146:149], v150, s[0:1]
	global_load_dwordx4 v[196:199], v150, s[0:1] offset:144
	global_load_dwordx4 v[200:203], v150, s[0:1] offset:128
	v_ashrrev_i32_e32 v205, 31, v204
	v_or_b32_e32 v186, 16, v204
	v_or_b32_e32 v184, 32, v204
	v_or_b32_e32 v166, 48, v204
	v_ashrrev_i32_e32 v165, 31, v164
	v_ashrrev_i32_e32 v163, 31, v162
	v_add_u32_e32 v160, 0xa0, v204
	v_add_u32_e32 v150, 0xb0, v204
	v_lshl_add_u64 v[152:153], v[204:205], 2, s[34:35]
	v_ashrrev_i32_e32 v187, 31, v186
	v_ashrrev_i32_e32 v185, 31, v184
	v_ashrrev_i32_e32 v167, 31, v166
	v_lshl_add_u64 v[190:191], v[164:165], 2, s[34:35]
	v_lshl_add_u64 v[192:193], v[162:163], 2, s[34:35]
	v_ashrrev_i32_e32 v161, 31, v160
	v_ashrrev_i32_e32 v151, 31, v150
	v_lshl_add_u64 v[154:155], v[186:187], 2, s[34:35]
	v_lshl_add_u64 v[156:157], v[184:185], 2, s[34:35]
	v_lshl_add_u64 v[158:159], v[166:167], 2, s[34:35]
	v_lshl_add_u64 v[206:207], v[160:161], 2, s[34:35]
	v_lshl_add_u64 v[208:209], v[150:151], 2, s[34:35]
	global_load_dword v195, v[152:153], off
	global_load_dword v210, v[154:155], off
	global_load_dword v211, v[156:157], off
	global_load_dword v212, v[158:159], off
	global_load_dword v194, v[190:191], off
	s_nop 0
	global_load_dword v193, v[192:193], off
	s_nop 0
	global_load_dword v192, v[206:207], off
	global_load_dword v191, v[208:209], off
	s_mov_b32 s0, 0x1e000000
	s_cselect_b32 s0, s0, 0x8000000
	v_cndmask_b32_e32 v170, 1.0, v225, vcc
	s_add_u32 s0, s6, s0
	s_addc_u32 s1, s7, 0
	s_waitcnt vmcnt(0)
	v_pk_mul_f32 v[152:153], v[170:171], v[144:145] op_sel_hi:[0,1]
	v_pk_mul_f32 v[156:157], v[170:171], v[148:149] op_sel_hi:[0,1]
	v_pk_mul_f32 v[158:159], v[170:171], v[146:147] op_sel_hi:[0,1]
	v_pk_mul_f32 v[154:155], v[170:171], v[142:143] op_sel_hi:[0,1]
	v_pk_mul_f32 v[146:147], v[170:171], v[202:203] op_sel_hi:[0,1]
	v_pk_mul_f32 v[148:149], v[170:171], v[200:201] op_sel_hi:[0,1]
	v_pk_mul_f32 v[142:143], v[170:171], v[198:199] op_sel_hi:[0,1]
	v_pk_mul_f32 v[144:145], v[170:171], v[196:197] op_sel_hi:[0,1]
	v_and_b32_e32 v170, 64, v169
	v_add_u32_e32 v213, 64, v170
	v_fmamk_f32 v170, v195, 0x3a800000, v220
	v_rsq_f32_e32 v170, v170
	v_xor_b32_e32 v190, 16, v169
	v_cmp_lt_i32_e32 vcc, v190, v213
	s_lshl_b32 s12, s12, 7
	v_pk_mul_f32 v[124:125], v[124:125], v[170:171] op_sel_hi:[1,0]
	v_pk_mul_f32 v[126:127], v[126:127], v[170:171] op_sel_hi:[1,0]
	v_pk_mul_f32 v[198:199], v[124:125], v[124:125]
	v_pk_mul_f32 v[196:197], v[126:127], v[126:127]
	v_pk_mul_f32 v[120:121], v[120:121], v[170:171] op_sel_hi:[1,0]
	v_pk_mov_b32 v[200:201], v[198:199], v[196:197] op_sel:[1,0]
	v_mov_b32_e32 v199, v197
	v_pk_mul_f32 v[122:123], v[122:123], v[170:171] op_sel_hi:[1,0]
	v_pk_add_f32 v[196:197], v[200:201], v[198:199]
	v_pk_mul_f32 v[198:199], v[122:123], v[122:123]
	v_pk_mul_f32 v[200:201], v[120:121], v[120:121]
	v_pk_add_f32 v[196:197], v[196:197], v[196:197] op_sel_hi:[0,1]
	v_pk_mov_b32 v[202:203], v[200:201], v[198:199] op_sel:[1,0]
	v_mov_b32_e32 v201, v199
	v_pk_add_f32 v[198:199], v[202:203], v[200:201]
	v_pk_mul_f32 v[202:203], v[116:117], v[170:171] op_sel_hi:[1,0]
	v_pk_mul_f32 v[200:201], v[118:119], v[170:171] op_sel_hi:[1,0]
	v_mul_f32_e32 v116, v202, v202
	v_pk_fma_f32 v[116:117], v[202:203], v[202:203], v[116:117] op_sel_hi:[1,1,0]
	v_pk_add_f32 v[198:199], v[198:199], v[198:199] op_sel_hi:[0,1]
	v_mul_f32_e32 v116, v200, v200
	v_pk_fma_f32 v[118:119], v[200:201], v[200:201], v[116:117] op_sel_hi:[1,1,0]
	v_pk_mul_f32 v[206:207], v[114:115], v[170:171] op_sel_hi:[1,0]
	v_pk_mul_f32 v[208:209], v[112:113], v[170:171] op_sel_hi:[1,0]
	v_mul_f32_e32 v196, v206, v206
	v_mul_f32_e32 v116, v208, v208
	v_mul_f32_e32 v118, v209, v209
	v_mul_f32_e32 v198, v207, v207
	v_pk_add_f32 v[112:113], v[116:117], v[118:119]
	v_pk_add_f32 v[114:115], v[196:197], v[198:199]
	v_cndmask_b32_e32 v190, v169, v190, vcc
	v_pk_add_f32 v[112:113], v[112:113], v[114:115]
	v_lshlrev_b32_e32 v190, 2, v190
	v_add_f32_e32 v112, v112, v113
	ds_bpermute_b32 v113, v190, v112
	v_xor_b32_e32 v114, 32, v169
	v_cmp_lt_i32_e32 vcc, v114, v213
	s_add_u32 s0, s0, s12
	s_addc_u32 s1, s1, 0
	v_cndmask_b32_e32 v114, v169, v114, vcc
	v_lshlrev_b32_e32 v114, 2, v114
	s_waitcnt lgkmcnt(0)
	v_add_f32_e32 v112, v112, v113
	ds_bpermute_b32 v113, v114, v112
	v_lshlrev_b32_e32 v170, 1, v136
	v_lshlrev_b64 v[116:117], 11, v[204:205]
	v_fmamk_f32 v115, v210, 0x3a800000, v220
	s_andn2_b64 vcc, exec, s[4:5]
	s_waitcnt lgkmcnt(0)
	v_add_f32_e32 v112, v112, v113
	v_fmamk_f32 v112, v112, 0x3c800000, v220
	v_rsq_f32_e32 v196, v112
	v_lshl_add_u64 v[112:113], s[0:1], 0, v[170:171]
	v_lshl_add_u64 v[198:199], v[112:113], 0, v[116:117]
	s_mov_b64 s[4:5], -1
	v_pk_mul_f32 v[116:117], v[124:125], v[196:197] op_sel_hi:[1,0]
	v_pk_mul_f32 v[118:119], v[126:127], v[196:197] op_sel_hi:[1,0]
	v_pk_mul_f32 v[116:117], v[158:159], v[116:117]
	v_pk_mul_f32 v[118:119], v[156:157], v[118:119]
	v_pk_mul_f32 v[120:121], v[120:121], v[196:197] op_sel_hi:[1,0]
	v_pk_mul_f32 v[122:123], v[122:123], v[196:197] op_sel_hi:[1,0]
	v_pk_mul_f32 v[120:121], v[154:155], v[120:121]
	v_cvt_pk_bf16_f32 v116, v116, v117
	v_cvt_pk_bf16_f32 v117, v118, v119
	v_pk_mul_f32 v[122:123], v[152:153], v[122:123]
	v_cvt_pk_bf16_f32 v118, v120, v121
	v_pk_mul_f32 v[120:121], v[200:201], v[196:197] op_sel_hi:[1,0]
	v_cvt_pk_bf16_f32 v119, v122, v123
	global_store_dwordx4 v[198:199], v[116:119], off
	v_pk_mul_f32 v[120:121], v[146:147], v[120:121]
	s_nop 0
	v_rsq_f32_e32 v118, v115
	v_pk_mul_f32 v[116:117], v[202:203], v[196:197] op_sel_hi:[1,0]
	v_pk_mul_f32 v[108:109], v[108:109], v[118:119] op_sel_hi:[1,0]
	v_pk_mul_f32 v[110:111], v[110:111], v[118:119] op_sel_hi:[1,0]
	v_pk_mul_f32 v[124:125], v[108:109], v[108:109]
	v_pk_mul_f32 v[122:123], v[110:111], v[110:111]
	v_pk_mul_f32 v[104:105], v[104:105], v[118:119] op_sel_hi:[1,0]
	v_pk_mov_b32 v[126:127], v[124:125], v[122:123] op_sel:[1,0]
	v_mov_b32_e32 v125, v123
	v_pk_add_f32 v[122:123], v[126:127], v[124:125]
	v_pk_mul_f32 v[106:107], v[106:107], v[118:119] op_sel_hi:[1,0]
	v_pk_add_f32 v[122:123], v[122:123], v[122:123] op_sel_hi:[0,1]
	v_pk_mul_f32 v[124:125], v[106:107], v[106:107]
	v_pk_mul_f32 v[126:127], v[104:105], v[104:105]
	v_pk_mul_f32 v[100:101], v[100:101], v[118:119] op_sel_hi:[1,0]
	v_pk_mov_b32 v[200:201], v[126:127], v[124:125] op_sel:[1,0]
	v_mov_b32_e32 v127, v125
	v_pk_mul_f32 v[102:103], v[102:103], v[118:119] op_sel_hi:[1,0]
	v_mul_f32_e32 v122, v100, v100
	v_pk_add_f32 v[124:125], v[200:201], v[126:127]
	v_pk_fma_f32 v[126:127], v[100:101], v[100:101], v[122:123] op_sel_hi:[1,1,0]
	v_mul_f32_e32 v122, v102, v102
	v_pk_add_f32 v[124:125], v[124:125], v[124:125] op_sel_hi:[0,1]
	v_pk_fma_f32 v[200:201], v[102:103], v[102:103], v[122:123] op_sel_hi:[1,1,0]
	v_pk_mul_f32 v[202:203], v[98:99], v[118:119] op_sel_hi:[1,0]
	v_pk_mul_f32 v[118:119], v[96:97], v[118:119] op_sel_hi:[1,0]
	v_mul_f32_e32 v122, v202, v202
	v_mul_f32_e32 v126, v118, v118
	v_mul_f32_e32 v200, v119, v119
	v_mul_f32_e32 v124, v203, v203
	v_pk_add_f32 v[96:97], v[126:127], v[200:201]
	v_pk_add_f32 v[98:99], v[122:123], v[124:125]
	v_pk_mul_f32 v[116:117], v[148:149], v[116:117]
	v_pk_add_f32 v[96:97], v[96:97], v[98:99]
	v_pk_mul_f32 v[98:99], v[206:207], v[196:197] op_sel_hi:[1,0]
	v_add_f32_e32 v115, v96, v97
	ds_bpermute_b32 v124, v190, v115
	v_pk_mul_f32 v[96:97], v[208:209], v[196:197] op_sel_hi:[1,0]
	v_pk_mul_f32 v[122:123], v[142:143], v[98:99]
	v_pk_mul_f32 v[98:99], v[144:145], v[96:97]
	v_cvt_pk_bf16_f32 v96, v116, v117
	s_waitcnt lgkmcnt(0)
	v_add_f32_e32 v115, v115, v124
	ds_bpermute_b32 v124, v114, v115
	v_cvt_pk_bf16_f32 v97, v120, v121
	v_cvt_pk_bf16_f32 v98, v98, v99
	v_cvt_pk_bf16_f32 v99, v122, v123
	global_store_dwordx4 v[198:199], v[96:99], off offset:64
	s_waitcnt lgkmcnt(0)
	v_add_f32_e32 v115, v115, v124
	v_fmamk_f32 v115, v115, 0x3c800000, v220
	v_rsq_f32_e32 v116, v115
	v_lshlrev_b64 v[96:97], 11, v[186:187]
	v_lshl_add_u64 v[120:121], v[112:113], 0, v[96:97]
	v_pk_mul_f32 v[96:97], v[108:109], v[116:117] op_sel_hi:[1,0]
	v_pk_mul_f32 v[98:99], v[110:111], v[116:117] op_sel_hi:[1,0]
	v_pk_mul_f32 v[96:97], v[158:159], v[96:97]
	v_pk_mul_f32 v[98:99], v[156:157], v[98:99]
	v_pk_mul_f32 v[104:105], v[104:105], v[116:117] op_sel_hi:[1,0]
	v_pk_mul_f32 v[106:107], v[106:107], v[116:117] op_sel_hi:[1,0]
	v_pk_mul_f32 v[104:105], v[154:155], v[104:105]
	v_cvt_pk_bf16_f32 v96, v96, v97
	v_cvt_pk_bf16_f32 v97, v98, v99
	v_pk_mul_f32 v[106:107], v[152:153], v[106:107]
	v_cvt_pk_bf16_f32 v98, v104, v105
	s_nop 0
	v_cvt_pk_bf16_f32 v99, v106, v107
	global_store_dwordx4 v[120:121], v[96:99], off
	s_nop 1
	v_fmamk_f32 v98, v211, 0x3a800000, v220
	v_rsq_f32_e32 v98, v98
	v_pk_mul_f32 v[96:97], v[100:101], v[116:117] op_sel_hi:[1,0]
	v_pk_mul_f32 v[100:101], v[102:103], v[116:117] op_sel_hi:[1,0]
	v_pk_mul_f32 v[96:97], v[148:149], v[96:97]
	v_pk_mul_f32 v[92:93], v[92:93], v[98:99] op_sel_hi:[1,0]
	v_pk_mul_f32 v[94:95], v[94:95], v[98:99] op_sel_hi:[1,0]
	v_pk_mul_f32 v[104:105], v[92:93], v[92:93]
	v_pk_mul_f32 v[102:103], v[94:95], v[94:95]
	v_pk_mul_f32 v[88:89], v[88:89], v[98:99] op_sel_hi:[1,0]
	v_pk_mov_b32 v[106:107], v[104:105], v[102:103] op_sel:[1,0]
	v_mov_b32_e32 v105, v103
	v_pk_add_f32 v[102:103], v[106:107], v[104:105]
	v_pk_mul_f32 v[90:91], v[90:91], v[98:99] op_sel_hi:[1,0]
	v_pk_add_f32 v[102:103], v[102:103], v[102:103] op_sel_hi:[0,1]
	v_pk_mul_f32 v[104:105], v[90:91], v[90:91]
	v_pk_mul_f32 v[106:107], v[88:89], v[88:89]
	v_pk_mul_f32 v[84:85], v[84:85], v[98:99] op_sel_hi:[1,0]
	v_pk_mov_b32 v[108:109], v[106:107], v[104:105] op_sel:[1,0]
	v_mov_b32_e32 v107, v105
	v_pk_mul_f32 v[86:87], v[86:87], v[98:99] op_sel_hi:[1,0]
	v_mul_f32_e32 v102, v84, v84
	v_pk_add_f32 v[104:105], v[108:109], v[106:107]
	v_pk_fma_f32 v[106:107], v[84:85], v[84:85], v[102:103] op_sel_hi:[1,1,0]
	v_mul_f32_e32 v102, v86, v86
	v_pk_add_f32 v[104:105], v[104:105], v[104:105] op_sel_hi:[0,1]
	v_pk_fma_f32 v[108:109], v[86:87], v[86:87], v[102:103] op_sel_hi:[1,1,0]
	v_pk_mul_f32 v[110:111], v[82:83], v[98:99] op_sel_hi:[1,0]
	v_pk_mul_f32 v[98:99], v[80:81], v[98:99] op_sel_hi:[1,0]
	v_mul_f32_e32 v102, v110, v110
	v_mul_f32_e32 v106, v98, v98
	v_mul_f32_e32 v108, v99, v99
	v_mul_f32_e32 v104, v111, v111
	v_pk_add_f32 v[80:81], v[106:107], v[108:109]
	v_pk_add_f32 v[82:83], v[102:103], v[104:105]
	v_pk_mul_f32 v[100:101], v[146:147], v[100:101]
	v_pk_add_f32 v[80:81], v[80:81], v[82:83]
	v_pk_mul_f32 v[82:83], v[202:203], v[116:117] op_sel_hi:[1,0]
	v_add_f32_e32 v104, v80, v81
	ds_bpermute_b32 v105, v190, v104
	v_pk_mul_f32 v[80:81], v[118:119], v[116:117] op_sel_hi:[1,0]
	v_pk_mul_f32 v[102:103], v[142:143], v[82:83]
	v_pk_mul_f32 v[82:83], v[144:145], v[80:81]
	v_cvt_pk_bf16_f32 v80, v96, v97
	s_waitcnt lgkmcnt(0)
	v_add_f32_e32 v104, v104, v105
	ds_bpermute_b32 v105, v114, v104
	v_cvt_pk_bf16_f32 v81, v100, v101
	v_cvt_pk_bf16_f32 v82, v82, v83
	v_cvt_pk_bf16_f32 v83, v102, v103
	global_store_dwordx4 v[120:121], v[80:83], off offset:64
	s_waitcnt lgkmcnt(0)
	v_add_f32_e32 v96, v104, v105
	v_fmamk_f32 v96, v96, 0x3c800000, v220
	v_rsq_f32_e32 v96, v96
	v_lshlrev_b64 v[80:81], 11, v[184:185]
	v_lshl_add_u64 v[100:101], v[112:113], 0, v[80:81]
	v_pk_mul_f32 v[80:81], v[92:93], v[96:97] op_sel_hi:[1,0]
	v_pk_mul_f32 v[82:83], v[94:95], v[96:97] op_sel_hi:[1,0]
	v_pk_mul_f32 v[80:81], v[158:159], v[80:81]
	v_pk_mul_f32 v[82:83], v[156:157], v[82:83]
	v_pk_mul_f32 v[88:89], v[88:89], v[96:97] op_sel_hi:[1,0]
	v_pk_mul_f32 v[90:91], v[90:91], v[96:97] op_sel_hi:[1,0]
	v_pk_mul_f32 v[88:89], v[154:155], v[88:89]
	v_cvt_pk_bf16_f32 v80, v80, v81
	v_cvt_pk_bf16_f32 v81, v82, v83
	v_pk_mul_f32 v[90:91], v[152:153], v[90:91]
	v_cvt_pk_bf16_f32 v82, v88, v89
	s_nop 0
	v_cvt_pk_bf16_f32 v83, v90, v91
	global_store_dwordx4 v[100:101], v[80:83], off
	s_nop 1
	v_fmamk_f32 v82, v212, 0x3a800000, v220
	v_rsq_f32_e32 v82, v82
	v_pk_mul_f32 v[80:81], v[84:85], v[96:97] op_sel_hi:[1,0]
	v_pk_mul_f32 v[84:85], v[86:87], v[96:97] op_sel_hi:[1,0]
	v_pk_mul_f32 v[80:81], v[148:149], v[80:81]
	v_pk_mul_f32 v[76:77], v[76:77], v[82:83] op_sel_hi:[1,0]
	v_pk_mul_f32 v[78:79], v[78:79], v[82:83] op_sel_hi:[1,0]
	v_pk_mul_f32 v[88:89], v[76:77], v[76:77]
	v_pk_mul_f32 v[86:87], v[78:79], v[78:79]
	v_pk_mul_f32 v[72:73], v[72:73], v[82:83] op_sel_hi:[1,0]
	v_pk_mov_b32 v[90:91], v[88:89], v[86:87] op_sel:[1,0]
	v_mov_b32_e32 v89, v87
	v_pk_add_f32 v[86:87], v[90:91], v[88:89]
	v_pk_mul_f32 v[74:75], v[74:75], v[82:83] op_sel_hi:[1,0]
	v_pk_add_f32 v[86:87], v[86:87], v[86:87] op_sel_hi:[0,1]
	v_pk_mul_f32 v[88:89], v[74:75], v[74:75]
	v_pk_mul_f32 v[90:91], v[72:73], v[72:73]
	v_pk_mul_f32 v[68:69], v[68:69], v[82:83] op_sel_hi:[1,0]
	v_pk_mov_b32 v[92:93], v[90:91], v[88:89] op_sel:[1,0]
	v_mov_b32_e32 v91, v89
	v_pk_mul_f32 v[70:71], v[70:71], v[82:83] op_sel_hi:[1,0]
	v_mul_f32_e32 v86, v68, v68
	v_pk_add_f32 v[88:89], v[92:93], v[90:91]
	v_pk_fma_f32 v[90:91], v[68:69], v[68:69], v[86:87] op_sel_hi:[1,1,0]
	v_mul_f32_e32 v86, v70, v70
	v_pk_add_f32 v[88:89], v[88:89], v[88:89] op_sel_hi:[0,1]
	v_pk_fma_f32 v[92:93], v[70:71], v[70:71], v[86:87] op_sel_hi:[1,1,0]
	v_pk_mul_f32 v[94:95], v[66:67], v[82:83] op_sel_hi:[1,0]
	v_pk_mul_f32 v[82:83], v[64:65], v[82:83] op_sel_hi:[1,0]
	v_mul_f32_e32 v86, v94, v94
	v_mul_f32_e32 v90, v82, v82
	v_mul_f32_e32 v92, v83, v83
	v_mul_f32_e32 v88, v95, v95
	v_pk_add_f32 v[64:65], v[90:91], v[92:93]
	v_pk_add_f32 v[66:67], v[86:87], v[88:89]
	v_pk_mul_f32 v[84:85], v[146:147], v[84:85]
	v_pk_add_f32 v[64:65], v[64:65], v[66:67]
	v_pk_mul_f32 v[66:67], v[110:111], v[96:97] op_sel_hi:[1,0]
	v_add_f32_e32 v88, v64, v65
	ds_bpermute_b32 v89, v190, v88
	v_pk_mul_f32 v[64:65], v[98:99], v[96:97] op_sel_hi:[1,0]
	v_pk_mul_f32 v[86:87], v[142:143], v[66:67]
	v_pk_mul_f32 v[66:67], v[144:145], v[64:65]
	v_cvt_pk_bf16_f32 v64, v80, v81
	s_waitcnt lgkmcnt(0)
	v_add_f32_e32 v88, v88, v89
	ds_bpermute_b32 v89, v114, v88
	v_cvt_pk_bf16_f32 v65, v84, v85
	v_cvt_pk_bf16_f32 v66, v66, v67
	v_cvt_pk_bf16_f32 v67, v86, v87
	global_store_dwordx4 v[100:101], v[64:67], off offset:64
	s_waitcnt lgkmcnt(0)
	v_add_f32_e32 v80, v88, v89
	v_fmamk_f32 v80, v80, 0x3c800000, v220
	v_rsq_f32_e32 v80, v80
	v_lshlrev_b64 v[64:65], 11, v[166:167]
	v_lshl_add_u64 v[84:85], v[112:113], 0, v[64:65]
	v_pk_mul_f32 v[64:65], v[76:77], v[80:81] op_sel_hi:[1,0]
	v_pk_mul_f32 v[66:67], v[78:79], v[80:81] op_sel_hi:[1,0]
	v_pk_mul_f32 v[64:65], v[158:159], v[64:65]
	v_pk_mul_f32 v[66:67], v[156:157], v[66:67]
	v_pk_mul_f32 v[72:73], v[72:73], v[80:81] op_sel_hi:[1,0]
	v_pk_mul_f32 v[74:75], v[74:75], v[80:81] op_sel_hi:[1,0]
	v_pk_mul_f32 v[72:73], v[154:155], v[72:73]
	v_cvt_pk_bf16_f32 v64, v64, v65
	v_cvt_pk_bf16_f32 v65, v66, v67
	v_pk_mul_f32 v[74:75], v[152:153], v[74:75]
	v_cvt_pk_bf16_f32 v66, v72, v73
	s_nop 0
	v_cvt_pk_bf16_f32 v67, v74, v75
	global_store_dwordx4 v[84:85], v[64:67], off
	s_nop 1
	v_fmamk_f32 v66, v194, 0x3a800000, v220
	v_rsq_f32_e32 v66, v66
	v_pk_mul_f32 v[64:65], v[68:69], v[80:81] op_sel_hi:[1,0]
	v_pk_mul_f32 v[68:69], v[70:71], v[80:81] op_sel_hi:[1,0]
	v_pk_mul_f32 v[64:65], v[148:149], v[64:65]
	v_pk_mul_f32 v[60:61], v[60:61], v[66:67] op_sel_hi:[1,0]
	v_pk_mul_f32 v[62:63], v[62:63], v[66:67] op_sel_hi:[1,0]
	v_pk_mul_f32 v[72:73], v[60:61], v[60:61]
	v_pk_mul_f32 v[70:71], v[62:63], v[62:63]
	v_pk_mul_f32 v[56:57], v[56:57], v[66:67] op_sel_hi:[1,0]
	v_pk_mov_b32 v[74:75], v[72:73], v[70:71] op_sel:[1,0]
	v_mov_b32_e32 v73, v71
	v_pk_add_f32 v[70:71], v[74:75], v[72:73]
	v_pk_mul_f32 v[58:59], v[58:59], v[66:67] op_sel_hi:[1,0]
	v_pk_add_f32 v[70:71], v[70:71], v[70:71] op_sel_hi:[0,1]
	v_pk_mul_f32 v[72:73], v[58:59], v[58:59]
	v_pk_mul_f32 v[74:75], v[56:57], v[56:57]
	v_pk_mul_f32 v[52:53], v[52:53], v[66:67] op_sel_hi:[1,0]
	v_pk_mov_b32 v[76:77], v[74:75], v[72:73] op_sel:[1,0]
	v_mov_b32_e32 v75, v73
	v_pk_mul_f32 v[54:55], v[54:55], v[66:67] op_sel_hi:[1,0]
	v_mul_f32_e32 v70, v52, v52
	v_pk_add_f32 v[72:73], v[76:77], v[74:75]
	v_pk_fma_f32 v[74:75], v[52:53], v[52:53], v[70:71] op_sel_hi:[1,1,0]
	v_mul_f32_e32 v70, v54, v54
	v_pk_add_f32 v[72:73], v[72:73], v[72:73] op_sel_hi:[0,1]
	v_pk_fma_f32 v[76:77], v[54:55], v[54:55], v[70:71] op_sel_hi:[1,1,0]
	v_pk_mul_f32 v[78:79], v[50:51], v[66:67] op_sel_hi:[1,0]
	v_pk_mul_f32 v[66:67], v[48:49], v[66:67] op_sel_hi:[1,0]
	v_mul_f32_e32 v70, v78, v78
	v_mul_f32_e32 v74, v66, v66
	v_mul_f32_e32 v76, v67, v67
	v_mul_f32_e32 v72, v79, v79
	v_pk_add_f32 v[48:49], v[74:75], v[76:77]
	v_pk_add_f32 v[50:51], v[70:71], v[72:73]
	v_pk_mul_f32 v[68:69], v[146:147], v[68:69]
	v_pk_add_f32 v[48:49], v[48:49], v[50:51]
	v_pk_mul_f32 v[50:51], v[94:95], v[80:81] op_sel_hi:[1,0]
	v_add_f32_e32 v72, v48, v49
	ds_bpermute_b32 v73, v190, v72
	v_pk_mul_f32 v[48:49], v[82:83], v[80:81] op_sel_hi:[1,0]
	v_pk_mul_f32 v[70:71], v[142:143], v[50:51]
	v_pk_mul_f32 v[50:51], v[144:145], v[48:49]
	v_cvt_pk_bf16_f32 v48, v64, v65
	s_waitcnt lgkmcnt(0)
	v_add_f32_e32 v72, v72, v73
	ds_bpermute_b32 v73, v114, v72
	v_cvt_pk_bf16_f32 v49, v68, v69
	v_cvt_pk_bf16_f32 v50, v50, v51
	v_cvt_pk_bf16_f32 v51, v70, v71
	global_store_dwordx4 v[84:85], v[48:51], off offset:64
	s_waitcnt lgkmcnt(0)
	v_add_f32_e32 v64, v72, v73
	v_fmamk_f32 v64, v64, 0x3c800000, v220
	v_rsq_f32_e32 v64, v64
	v_lshlrev_b64 v[48:49], 11, v[164:165]
	v_lshl_add_u64 v[68:69], v[112:113], 0, v[48:49]
	v_pk_mul_f32 v[48:49], v[60:61], v[64:65] op_sel_hi:[1,0]
	v_pk_mul_f32 v[50:51], v[62:63], v[64:65] op_sel_hi:[1,0]
	v_pk_mul_f32 v[48:49], v[158:159], v[48:49]
	v_pk_mul_f32 v[50:51], v[156:157], v[50:51]
	v_pk_mul_f32 v[56:57], v[56:57], v[64:65] op_sel_hi:[1,0]
	v_pk_mul_f32 v[58:59], v[58:59], v[64:65] op_sel_hi:[1,0]
	v_pk_mul_f32 v[56:57], v[154:155], v[56:57]
	v_cvt_pk_bf16_f32 v48, v48, v49
	v_cvt_pk_bf16_f32 v49, v50, v51
	v_pk_mul_f32 v[58:59], v[152:153], v[58:59]
	v_cvt_pk_bf16_f32 v50, v56, v57
	s_nop 0
	v_cvt_pk_bf16_f32 v51, v58, v59
	global_store_dwordx4 v[68:69], v[48:51], off
	s_nop 1
	v_fmamk_f32 v50, v193, 0x3a800000, v220
	v_rsq_f32_e32 v50, v50
	v_pk_mul_f32 v[48:49], v[52:53], v[64:65] op_sel_hi:[1,0]
	v_pk_mul_f32 v[52:53], v[54:55], v[64:65] op_sel_hi:[1,0]
	v_pk_mul_f32 v[48:49], v[148:149], v[48:49]
	v_pk_mul_f32 v[44:45], v[44:45], v[50:51] op_sel_hi:[1,0]
	v_pk_mul_f32 v[46:47], v[46:47], v[50:51] op_sel_hi:[1,0]
	v_pk_mul_f32 v[56:57], v[44:45], v[44:45]
	v_pk_mul_f32 v[54:55], v[46:47], v[46:47]
	v_pk_mul_f32 v[40:41], v[40:41], v[50:51] op_sel_hi:[1,0]
	v_pk_mov_b32 v[58:59], v[56:57], v[54:55] op_sel:[1,0]
	v_mov_b32_e32 v57, v55
	v_pk_add_f32 v[54:55], v[58:59], v[56:57]
	v_pk_mul_f32 v[42:43], v[42:43], v[50:51] op_sel_hi:[1,0]
	v_pk_add_f32 v[54:55], v[54:55], v[54:55] op_sel_hi:[0,1]
	v_pk_mul_f32 v[56:57], v[42:43], v[42:43]
	v_pk_mul_f32 v[58:59], v[40:41], v[40:41]
	v_pk_mul_f32 v[36:37], v[36:37], v[50:51] op_sel_hi:[1,0]
	v_pk_mov_b32 v[60:61], v[58:59], v[56:57] op_sel:[1,0]
	v_mov_b32_e32 v59, v57
	v_pk_mul_f32 v[38:39], v[38:39], v[50:51] op_sel_hi:[1,0]
	v_mul_f32_e32 v54, v36, v36
	v_pk_add_f32 v[56:57], v[60:61], v[58:59]
	v_pk_fma_f32 v[58:59], v[36:37], v[36:37], v[54:55] op_sel_hi:[1,1,0]
	v_mul_f32_e32 v54, v38, v38
	v_pk_add_f32 v[56:57], v[56:57], v[56:57] op_sel_hi:[0,1]
	v_pk_fma_f32 v[60:61], v[38:39], v[38:39], v[54:55] op_sel_hi:[1,1,0]
	v_pk_mul_f32 v[62:63], v[34:35], v[50:51] op_sel_hi:[1,0]
	v_pk_mul_f32 v[50:51], v[32:33], v[50:51] op_sel_hi:[1,0]
	v_mul_f32_e32 v54, v62, v62
	v_mul_f32_e32 v58, v50, v50
	v_mul_f32_e32 v60, v51, v51
	v_mul_f32_e32 v56, v63, v63
	v_pk_add_f32 v[32:33], v[58:59], v[60:61]
	v_pk_add_f32 v[34:35], v[54:55], v[56:57]
	v_pk_mul_f32 v[52:53], v[146:147], v[52:53]
	v_pk_add_f32 v[32:33], v[32:33], v[34:35]
	v_pk_mul_f32 v[34:35], v[78:79], v[64:65] op_sel_hi:[1,0]
	v_add_f32_e32 v56, v32, v33
	ds_bpermute_b32 v57, v190, v56
	v_pk_mul_f32 v[32:33], v[66:67], v[64:65] op_sel_hi:[1,0]
	v_pk_mul_f32 v[54:55], v[142:143], v[34:35]
	v_pk_mul_f32 v[34:35], v[144:145], v[32:33]
	v_cvt_pk_bf16_f32 v32, v48, v49
	s_waitcnt lgkmcnt(0)
	v_add_f32_e32 v56, v56, v57
	ds_bpermute_b32 v57, v114, v56
	v_cvt_pk_bf16_f32 v33, v52, v53
	v_cvt_pk_bf16_f32 v34, v34, v35
	v_cvt_pk_bf16_f32 v35, v54, v55
	global_store_dwordx4 v[68:69], v[32:35], off offset:64
	s_waitcnt lgkmcnt(0)
	v_add_f32_e32 v48, v56, v57
	v_fmamk_f32 v48, v48, 0x3c800000, v220
	v_rsq_f32_e32 v48, v48
	v_lshlrev_b64 v[32:33], 11, v[162:163]
	v_lshl_add_u64 v[52:53], v[112:113], 0, v[32:33]
	v_pk_mul_f32 v[32:33], v[44:45], v[48:49] op_sel_hi:[1,0]
	v_pk_mul_f32 v[34:35], v[46:47], v[48:49] op_sel_hi:[1,0]
	v_pk_mul_f32 v[32:33], v[158:159], v[32:33]
	v_pk_mul_f32 v[34:35], v[156:157], v[34:35]
	v_pk_mul_f32 v[40:41], v[40:41], v[48:49] op_sel_hi:[1,0]
	v_pk_mul_f32 v[42:43], v[42:43], v[48:49] op_sel_hi:[1,0]
	v_pk_mul_f32 v[40:41], v[154:155], v[40:41]
	v_cvt_pk_bf16_f32 v32, v32, v33
	v_cvt_pk_bf16_f32 v33, v34, v35
	v_pk_mul_f32 v[42:43], v[152:153], v[42:43]
	v_cvt_pk_bf16_f32 v34, v40, v41
	s_nop 0
	v_cvt_pk_bf16_f32 v35, v42, v43
	global_store_dwordx4 v[52:53], v[32:35], off
	s_nop 1
	v_fmamk_f32 v34, v192, 0x3a800000, v220
	v_rsq_f32_e32 v34, v34
	v_pk_mul_f32 v[32:33], v[36:37], v[48:49] op_sel_hi:[1,0]
	v_pk_mul_f32 v[36:37], v[38:39], v[48:49] op_sel_hi:[1,0]
	v_pk_mul_f32 v[32:33], v[148:149], v[32:33]
	v_pk_mul_f32 v[28:29], v[28:29], v[34:35] op_sel_hi:[1,0]
	v_pk_mul_f32 v[30:31], v[30:31], v[34:35] op_sel_hi:[1,0]
	v_pk_mul_f32 v[40:41], v[28:29], v[28:29]
	v_pk_mul_f32 v[38:39], v[30:31], v[30:31]
	v_pk_mul_f32 v[24:25], v[24:25], v[34:35] op_sel_hi:[1,0]
	v_pk_mov_b32 v[42:43], v[40:41], v[38:39] op_sel:[1,0]
	v_mov_b32_e32 v41, v39
	v_pk_add_f32 v[38:39], v[42:43], v[40:41]
	v_pk_mul_f32 v[26:27], v[26:27], v[34:35] op_sel_hi:[1,0]
	v_pk_add_f32 v[38:39], v[38:39], v[38:39] op_sel_hi:[0,1]
	v_pk_mul_f32 v[40:41], v[26:27], v[26:27]
	v_pk_mul_f32 v[42:43], v[24:25], v[24:25]
	v_pk_mul_f32 v[20:21], v[20:21], v[34:35] op_sel_hi:[1,0]
	v_pk_mov_b32 v[44:45], v[42:43], v[40:41] op_sel:[1,0]
	v_mov_b32_e32 v43, v41
	v_pk_mul_f32 v[22:23], v[22:23], v[34:35] op_sel_hi:[1,0]
	v_mul_f32_e32 v38, v20, v20
	v_pk_add_f32 v[40:41], v[44:45], v[42:43]
	v_pk_fma_f32 v[42:43], v[20:21], v[20:21], v[38:39] op_sel_hi:[1,1,0]
	v_mul_f32_e32 v38, v22, v22
	v_pk_add_f32 v[40:41], v[40:41], v[40:41] op_sel_hi:[0,1]
	v_pk_fma_f32 v[44:45], v[22:23], v[22:23], v[38:39] op_sel_hi:[1,1,0]
	v_pk_mul_f32 v[46:47], v[18:19], v[34:35] op_sel_hi:[1,0]
	v_pk_mul_f32 v[34:35], v[16:17], v[34:35] op_sel_hi:[1,0]
	v_mul_f32_e32 v38, v46, v46
	v_mul_f32_e32 v42, v34, v34
	v_mul_f32_e32 v44, v35, v35
	v_mul_f32_e32 v40, v47, v47
	v_pk_add_f32 v[16:17], v[42:43], v[44:45]
	v_pk_add_f32 v[18:19], v[38:39], v[40:41]
	v_pk_mul_f32 v[36:37], v[146:147], v[36:37]
	v_pk_add_f32 v[16:17], v[16:17], v[18:19]
	v_pk_mul_f32 v[18:19], v[62:63], v[48:49] op_sel_hi:[1,0]
	v_add_f32_e32 v40, v16, v17
	ds_bpermute_b32 v41, v190, v40
	v_pk_mul_f32 v[16:17], v[50:51], v[48:49] op_sel_hi:[1,0]
	v_pk_mul_f32 v[38:39], v[142:143], v[18:19]
	v_pk_mul_f32 v[18:19], v[144:145], v[16:17]
	v_cvt_pk_bf16_f32 v16, v32, v33
	s_waitcnt lgkmcnt(0)
	v_add_f32_e32 v40, v40, v41
	ds_bpermute_b32 v41, v114, v40
	v_cvt_pk_bf16_f32 v17, v36, v37
	v_cvt_pk_bf16_f32 v18, v18, v19
	v_cvt_pk_bf16_f32 v19, v38, v39
	global_store_dwordx4 v[52:53], v[16:19], off offset:64
	s_waitcnt lgkmcnt(0)
	v_add_f32_e32 v32, v40, v41
	v_fmamk_f32 v32, v32, 0x3c800000, v220
	v_rsq_f32_e32 v32, v32
	v_lshlrev_b64 v[16:17], 11, v[160:161]
	v_lshl_add_u64 v[36:37], v[112:113], 0, v[16:17]
	v_pk_mul_f32 v[16:17], v[28:29], v[32:33] op_sel_hi:[1,0]
	v_pk_mul_f32 v[18:19], v[30:31], v[32:33] op_sel_hi:[1,0]
	v_pk_mul_f32 v[16:17], v[158:159], v[16:17]
	v_pk_mul_f32 v[18:19], v[156:157], v[18:19]
	v_pk_mul_f32 v[24:25], v[24:25], v[32:33] op_sel_hi:[1,0]
	v_pk_mul_f32 v[26:27], v[26:27], v[32:33] op_sel_hi:[1,0]
	v_pk_mul_f32 v[24:25], v[154:155], v[24:25]
	v_cvt_pk_bf16_f32 v16, v16, v17
	v_cvt_pk_bf16_f32 v17, v18, v19
	v_pk_mul_f32 v[26:27], v[152:153], v[26:27]
	v_cvt_pk_bf16_f32 v18, v24, v25
	s_nop 0
	v_cvt_pk_bf16_f32 v19, v26, v27
	global_store_dwordx4 v[36:37], v[16:19], off
	s_nop 1
	v_fmamk_f32 v18, v191, 0x3a800000, v220
	v_rsq_f32_e32 v18, v18
	v_pk_mul_f32 v[16:17], v[20:21], v[32:33] op_sel_hi:[1,0]
	v_pk_mul_f32 v[20:21], v[22:23], v[32:33] op_sel_hi:[1,0]
	v_pk_mul_f32 v[16:17], v[148:149], v[16:17]
	v_pk_mul_f32 v[12:13], v[12:13], v[18:19] op_sel_hi:[1,0]
	v_pk_mul_f32 v[14:15], v[14:15], v[18:19] op_sel_hi:[1,0]
	v_pk_mul_f32 v[24:25], v[12:13], v[12:13]
	v_pk_mul_f32 v[22:23], v[14:15], v[14:15]
	v_pk_mul_f32 v[8:9], v[8:9], v[18:19] op_sel_hi:[1,0]
	v_pk_mov_b32 v[26:27], v[24:25], v[22:23] op_sel:[1,0]
	v_mov_b32_e32 v25, v23
	v_pk_add_f32 v[22:23], v[26:27], v[24:25]
	v_pk_mul_f32 v[10:11], v[10:11], v[18:19] op_sel_hi:[1,0]
	v_pk_add_f32 v[22:23], v[22:23], v[22:23] op_sel_hi:[0,1]
	v_pk_mul_f32 v[24:25], v[10:11], v[10:11]
	v_pk_mul_f32 v[26:27], v[8:9], v[8:9]
	v_pk_mul_f32 v[4:5], v[4:5], v[18:19] op_sel_hi:[1,0]
	v_pk_mov_b32 v[28:29], v[26:27], v[24:25] op_sel:[1,0]
	v_mov_b32_e32 v27, v25
	v_pk_mul_f32 v[6:7], v[6:7], v[18:19] op_sel_hi:[1,0]
	v_mul_f32_e32 v22, v4, v4
	v_pk_add_f32 v[24:25], v[28:29], v[26:27]
	v_pk_fma_f32 v[26:27], v[4:5], v[4:5], v[22:23] op_sel_hi:[1,1,0]
	v_mul_f32_e32 v22, v6, v6
	v_pk_add_f32 v[24:25], v[24:25], v[24:25] op_sel_hi:[0,1]
	v_pk_fma_f32 v[28:29], v[6:7], v[6:7], v[22:23] op_sel_hi:[1,1,0]
	v_pk_mul_f32 v[30:31], v[2:3], v[18:19] op_sel_hi:[1,0]
	v_pk_mul_f32 v[18:19], v[0:1], v[18:19] op_sel_hi:[1,0]
	v_mul_f32_e32 v22, v30, v30
	v_mul_f32_e32 v26, v18, v18
	v_mul_f32_e32 v28, v19, v19
	v_mul_f32_e32 v24, v31, v31
	v_pk_add_f32 v[0:1], v[26:27], v[28:29]
	v_pk_add_f32 v[2:3], v[22:23], v[24:25]
	v_pk_mul_f32 v[20:21], v[146:147], v[20:21]
	v_pk_add_f32 v[0:1], v[0:1], v[2:3]
	v_pk_mul_f32 v[2:3], v[46:47], v[32:33] op_sel_hi:[1,0]
	v_add_f32_e32 v24, v0, v1
	ds_bpermute_b32 v25, v190, v24
	v_pk_mul_f32 v[0:1], v[34:35], v[32:33] op_sel_hi:[1,0]
	v_pk_mul_f32 v[22:23], v[142:143], v[2:3]
	v_pk_mul_f32 v[2:3], v[144:145], v[0:1]
	v_cvt_pk_bf16_f32 v0, v16, v17
	s_waitcnt lgkmcnt(0)
	v_add_f32_e32 v24, v24, v25
	ds_bpermute_b32 v25, v114, v24
	v_cvt_pk_bf16_f32 v1, v20, v21
	v_cvt_pk_bf16_f32 v2, v2, v3
	v_cvt_pk_bf16_f32 v3, v22, v23
	global_store_dwordx4 v[36:37], v[0:3], off offset:64
	s_waitcnt lgkmcnt(0)
	v_add_f32_e32 v16, v24, v25
	v_fmamk_f32 v16, v16, 0x3c800000, v220
	v_rsq_f32_e32 v16, v16
	v_lshlrev_b64 v[0:1], 11, v[150:151]
	v_lshl_add_u64 v[20:21], v[112:113], 0, v[0:1]
	v_pk_mul_f32 v[0:1], v[12:13], v[16:17] op_sel_hi:[1,0]
	v_pk_mul_f32 v[2:3], v[14:15], v[16:17] op_sel_hi:[1,0]
	v_pk_mul_f32 v[0:1], v[158:159], v[0:1]
	v_pk_mul_f32 v[2:3], v[156:157], v[2:3]
	v_pk_mul_f32 v[8:9], v[8:9], v[16:17] op_sel_hi:[1,0]
	v_pk_mul_f32 v[10:11], v[10:11], v[16:17] op_sel_hi:[1,0]
	v_pk_mul_f32 v[8:9], v[154:155], v[8:9]
	v_pk_mul_f32 v[10:11], v[152:153], v[10:11]
	v_cvt_pk_bf16_f32 v0, v0, v1
	v_cvt_pk_bf16_f32 v1, v2, v3
	v_cvt_pk_bf16_f32 v2, v8, v9
	s_nop 0
	v_cvt_pk_bf16_f32 v3, v10, v11
	global_store_dwordx4 v[20:21], v[0:3], off
	s_nop 1
	v_pk_mul_f32 v[0:1], v[4:5], v[16:17] op_sel_hi:[1,0]
	v_pk_mul_f32 v[2:3], v[6:7], v[16:17] op_sel_hi:[1,0]
	v_pk_mul_f32 v[0:1], v[148:149], v[0:1]
	v_pk_mul_f32 v[2:3], v[146:147], v[2:3]
	v_pk_mul_f32 v[4:5], v[18:19], v[16:17] op_sel_hi:[1,0]
	v_pk_mul_f32 v[6:7], v[30:31], v[16:17] op_sel_hi:[1,0]
	v_pk_mul_f32 v[4:5], v[144:145], v[4:5]
	v_pk_mul_f32 v[6:7], v[142:143], v[6:7]
	v_cvt_pk_bf16_f32 v0, v0, v1
	v_cvt_pk_bf16_f32 v1, v2, v3
	v_cvt_pk_bf16_f32 v2, v4, v5
	s_nop 0
	v_cvt_pk_bf16_f32 v3, v6, v7
	global_store_dwordx4 v[20:21], v[0:3], off offset:64
	s_cbranch_vccnz .LBB0_569
	s_andn2_b64 vcc, exec, s[30:31]
	s_cbranch_vccnz .LBB0_568
	s_mov_b32 s98, 1
	s_branch .LBB0_568

.LBB0_600:
	s_ashr_i32 s37, s36, 31
	s_lshl_b64 s[0:1], s[36:37], 19
	s_add_u32 s40, s22, s0
	s_addc_u32 s41, s23, s1
	s_and_b64 s[0:1], s[4:5], exec
	s_cselect_b32 s37, s41, s47
	s_cselect_b32 s62, s40, s46
	s_ashr_i32 s35, s34, 31
	s_lshl_b64 s[0:1], s[34:35], 19
	s_add_u32 s42, s39, s0
	s_addc_u32 s43, s54, s1
	s_and_b64 s[0:1], s[4:5], exec
	s_cselect_b32 s35, s43, s49
	s_cselect_b32 s63, s42, s48
	s_add_u32 s64, s48, 0x100
	s_addc_u32 s65, s49, 0
	s_mov_b32 s66, -2
	s_waitcnt vmcnt(0)
	s_cmp_eq_u32 s98, 1
	s_cbranch_scc0 .Lrestag_601
	s_barrier
	s_mov_b32 s98, 0
.Lrestag_601:
	s_add_u32 s48, s46, 0x100
	s_addc_u32 s49, s47, 0
	s_add_i32 s0, 0, 0x10000
	s_cmp_eq_u32 s66, 12
	s_cselect_b32 s53, s37, s49
	s_cselect_b32 s52, s62, s48
	v_add_u32_e32 v146, s0, v149
	s_cselect_b32 s51, s35, s65
	s_cselect_b32 s50, s63, s64
	s_add_i32 s12, 0, 0x14000
	ds_read_b128 v[128:131], v146
	ds_read_b128 v[132:135], v146 offset:1024
	ds_read_b128 v[152:155], v146 offset:2048
	ds_read_b128 v[156:159], v146 offset:3072
	v_add_u32_e32 v146, s12, v149
	ds_read_b128 v[160:163], v146
	ds_read_b128 v[164:167], v146 offset:1024
	ds_read_b128 v[184:187], v146 offset:2048
	ds_read_b128 v[188:191], v146 offset:3072
	s_add_i32 m0, s45, 0xc000
	ds_read_b128 v[192:195], v151
	ds_read_b128 v[196:199], v151 offset:1024
	ds_read_b128 v[200:203], v151 offset:2048
	ds_read_b128 v[204:207], v151 offset:3072
	ds_read_b128 v[208:211], v151 offset:4096
	ds_read_b128 v[212:215], v151 offset:5120
	ds_read_b128 v[216:219], v151 offset:6144
	ds_read_b128 v[228:231], v151 offset:7168
	global_load_lds_dwordx4 v142, s[46:47]
	s_add_i32 m0, s45, 0xe000
	s_nop 0
	global_load_lds_dwordx4 v144, s[46:47]
	s_nop 0
	s_waitcnt lgkmcnt(0)
	s_barrier
	s_setprio 1
	s_waitcnt lgkmcnt(0)
	v_mfma_f32_16x16x32_bf16 v[124:127], v[128:131], v[192:195], 0
	v_mfma_f32_16x16x32_bf16 v[120:123], v[152:155], v[192:195], 0
	v_mfma_f32_16x16x32_bf16 v[116:119], v[128:131], v[200:203], 0
	v_mfma_f32_16x16x32_bf16 v[112:115], v[152:155], v[200:203], 0
	v_mfma_f32_16x16x32_bf16 v[108:111], v[128:131], v[208:211], 0
	v_mfma_f32_16x16x32_bf16 v[104:107], v[152:155], v[208:211], 0
	v_mfma_f32_16x16x32_bf16 v[100:103], v[128:131], v[216:219], 0
	v_mfma_f32_16x16x32_bf16 v[96:99], v[152:155], v[216:219], 0
	v_mfma_f32_16x16x32_bf16 v[124:127], v[132:135], v[196:199], v[124:127]
	v_mfma_f32_16x16x32_bf16 v[120:123], v[156:159], v[196:199], v[120:123]
	v_mfma_f32_16x16x32_bf16 v[116:119], v[132:135], v[204:207], v[116:119]
	v_mfma_f32_16x16x32_bf16 v[112:115], v[156:159], v[204:207], v[112:115]
	v_mfma_f32_16x16x32_bf16 v[108:111], v[132:135], v[212:215], v[108:111]
	v_mfma_f32_16x16x32_bf16 v[104:107], v[156:159], v[212:215], v[104:107]
	v_mfma_f32_16x16x32_bf16 v[100:103], v[132:135], v[228:231], v[100:103]
	v_mfma_f32_16x16x32_bf16 v[96:99], v[156:159], v[228:231], v[96:99]
	s_setprio 0
	s_setprio 1
	v_mfma_f32_16x16x32_bf16 v[68:71], v[160:163], v[192:195], 0
	v_mfma_f32_16x16x32_bf16 v[60:63], v[184:187], v[192:195], 0
	v_mfma_f32_16x16x32_bf16 v[52:55], v[160:163], v[200:203], 0
	v_mfma_f32_16x16x32_bf16 v[48:51], v[184:187], v[200:203], 0
	v_mfma_f32_16x16x32_bf16 v[44:47], v[160:163], v[208:211], 0
	v_mfma_f32_16x16x32_bf16 v[40:43], v[184:187], v[208:211], 0
	v_mfma_f32_16x16x32_bf16 v[36:39], v[160:163], v[216:219], 0
	v_mfma_f32_16x16x32_bf16 v[32:35], v[184:187], v[216:219], 0
	v_mfma_f32_16x16x32_bf16 v[68:71], v[164:167], v[196:199], v[68:71]
	v_mfma_f32_16x16x32_bf16 v[60:63], v[188:191], v[196:199], v[60:63]
	v_mfma_f32_16x16x32_bf16 v[52:55], v[164:167], v[204:207], v[52:55]
	v_mfma_f32_16x16x32_bf16 v[48:51], v[188:191], v[204:207], v[48:51]
	v_mfma_f32_16x16x32_bf16 v[44:47], v[164:167], v[212:215], v[44:47]
	v_mfma_f32_16x16x32_bf16 v[40:43], v[188:191], v[212:215], v[40:43]
	v_mfma_f32_16x16x32_bf16 v[36:39], v[164:167], v[228:231], v[36:39]
	v_mfma_f32_16x16x32_bf16 v[32:35], v[188:191], v[228:231], v[32:35]
	s_setprio 0
	s_barrier
	s_add_i32 s0, s0, s55
	v_lshl_add_u64 v[146:147], s[50:51], 0, v[170:171]
	s_mov_b32 m0, s0
	ds_read_b128 v[192:195], v151 offset:16384
	ds_read_b128 v[196:199], v151 offset:17408
	ds_read_b128 v[200:203], v151 offset:18432
	ds_read_b128 v[204:207], v151 offset:19456
	ds_read_b128 v[208:211], v151 offset:20480
	ds_read_b128 v[212:215], v151 offset:21504
	ds_read_b128 v[216:219], v151 offset:22528
	ds_read_b128 v[228:231], v151 offset:23552
	global_load_lds_dwordx4 v[146:147], off
	s_add_i32 m0, s0, 0x2000
	s_add_u32 s0, s50, 0x40000
	v_lshl_add_u64 v[232:233], s[50:51], 0, v[140:141]
	s_addc_u32 s1, s51, 0
	s_add_i32 s12, s12, s55
	global_load_lds_dwordx4 v[232:233], off
	s_mov_b32 m0, s12
	v_lshl_add_u64 v[236:237], s[52:53], 0, v[138:139]
	global_load_lds_dwordx4 v170, s[0:1]
	s_add_i32 m0, s12, 0x2000
	s_nop 0
	global_load_lds_dwordx4 v140, s[0:1]
	v_lshl_add_u64 v[234:235], s[52:53], 0, v[136:137]
	s_nop 0
	s_waitcnt lgkmcnt(0)
	s_barrier
	s_setprio 1
	s_waitcnt lgkmcnt(0)
	v_mfma_f32_16x16x32_bf16 v[92:95], v[128:131], v[192:195], 0
	v_mfma_f32_16x16x32_bf16 v[88:91], v[152:155], v[192:195], 0
	v_mfma_f32_16x16x32_bf16 v[84:87], v[128:131], v[200:203], 0
	v_mfma_f32_16x16x32_bf16 v[80:83], v[152:155], v[200:203], 0
	v_mfma_f32_16x16x32_bf16 v[76:79], v[128:131], v[208:211], 0
	v_mfma_f32_16x16x32_bf16 v[72:75], v[152:155], v[208:211], 0
	v_mfma_f32_16x16x32_bf16 v[64:67], v[128:131], v[216:219], 0
	v_mfma_f32_16x16x32_bf16 v[56:59], v[152:155], v[216:219], 0
	v_mfma_f32_16x16x32_bf16 v[92:95], v[132:135], v[196:199], v[92:95]
	v_mfma_f32_16x16x32_bf16 v[88:91], v[156:159], v[196:199], v[88:91]
	v_mfma_f32_16x16x32_bf16 v[84:87], v[132:135], v[204:207], v[84:87]
	v_mfma_f32_16x16x32_bf16 v[80:83], v[156:159], v[204:207], v[80:83]
	v_mfma_f32_16x16x32_bf16 v[76:79], v[132:135], v[212:215], v[76:79]
	v_mfma_f32_16x16x32_bf16 v[72:75], v[156:159], v[212:215], v[72:75]
	v_mfma_f32_16x16x32_bf16 v[64:67], v[132:135], v[228:231], v[64:67]
	v_mfma_f32_16x16x32_bf16 v[56:59], v[156:159], v[228:231], v[56:59]
	s_setprio 0
	s_setprio 1
	v_mfma_f32_16x16x32_bf16 v[28:31], v[160:163], v[192:195], 0
	v_mfma_f32_16x16x32_bf16 v[24:27], v[184:187], v[192:195], 0
	v_mfma_f32_16x16x32_bf16 v[20:23], v[160:163], v[200:203], 0
	v_mfma_f32_16x16x32_bf16 v[16:19], v[184:187], v[200:203], 0
	v_mfma_f32_16x16x32_bf16 v[12:15], v[160:163], v[208:211], 0
	v_mfma_f32_16x16x32_bf16 v[8:11], v[184:187], v[208:211], 0
	v_mfma_f32_16x16x32_bf16 v[4:7], v[160:163], v[216:219], 0
	v_mfma_f32_16x16x32_bf16 v[0:3], v[184:187], v[216:219], 0
	v_mfma_f32_16x16x32_bf16 v[28:31], v[164:167], v[196:199], v[28:31]
	v_mfma_f32_16x16x32_bf16 v[24:27], v[188:191], v[196:199], v[24:27]
	v_mfma_f32_16x16x32_bf16 v[20:23], v[164:167], v[204:207], v[20:23]
	v_mfma_f32_16x16x32_bf16 v[16:19], v[188:191], v[204:207], v[16:19]
	v_mfma_f32_16x16x32_bf16 v[12:15], v[164:167], v[212:215], v[12:15]
	v_mfma_f32_16x16x32_bf16 v[8:11], v[188:191], v[212:215], v[8:11]
	v_mfma_f32_16x16x32_bf16 v[4:7], v[164:167], v[228:231], v[4:7]
	v_mfma_f32_16x16x32_bf16 v[0:3], v[188:191], v[228:231], v[0:3]
	s_setprio 0
	s_barrier
	s_add_i32 s12, 0, 0x18000
	s_add_i32 s13, 0, 0x1c000
	v_add_u32_e32 v156, s12, v149
	v_add_u32_e32 v188, s13, v149
	ds_read_b128 v[128:131], v156
	ds_read_b128 v[132:135], v156 offset:1024
	ds_read_b128 v[152:155], v156 offset:2048
	ds_read_b128 v[156:159], v156 offset:3072
	ds_read_b128 v[160:163], v188
	ds_read_b128 v[164:167], v188 offset:1024
	ds_read_b128 v[184:187], v188 offset:2048
	ds_read_b128 v[188:191], v188 offset:3072
	s_add_u32 s0, s52, 0x40000
	s_addc_u32 s1, s53, 0
	s_mov_b32 m0, s57
	ds_read_b128 v[192:195], v151 offset:32768
	ds_read_b128 v[196:199], v151 offset:33792
	ds_read_b128 v[200:203], v151 offset:34816
	ds_read_b128 v[204:207], v151 offset:35840
	ds_read_b128 v[208:211], v151 offset:36864
	ds_read_b128 v[212:215], v151 offset:37888
	ds_read_b128 v[216:219], v151 offset:38912
	ds_read_b128 v[228:231], v151 offset:39936
	global_load_lds_dwordx4 v136, s[0:1]
	s_mov_b32 m0, s58
	s_nop 0
	global_load_lds_dwordx4 v138, s[0:1]
	s_mov_b32 m0, s45
	s_nop 0
	global_load_lds_dwordx4 v[234:235], off
	s_mov_b32 m0, s56
	s_nop 0
	global_load_lds_dwordx4 v[236:237], off
	s_waitcnt vmcnt(8)
	s_waitcnt lgkmcnt(0)
	s_barrier
	s_setprio 1
	s_waitcnt lgkmcnt(0)
	v_mfma_f32_16x16x32_bf16 v[124:127], v[128:131], v[192:195], v[124:127]
	v_mfma_f32_16x16x32_bf16 v[120:123], v[152:155], v[192:195], v[120:123]
	v_mfma_f32_16x16x32_bf16 v[116:119], v[128:131], v[200:203], v[116:119]
	v_mfma_f32_16x16x32_bf16 v[112:115], v[152:155], v[200:203], v[112:115]
	v_mfma_f32_16x16x32_bf16 v[108:111], v[128:131], v[208:211], v[108:111]
	v_mfma_f32_16x16x32_bf16 v[104:107], v[152:155], v[208:211], v[104:107]
	v_mfma_f32_16x16x32_bf16 v[100:103], v[128:131], v[216:219], v[100:103]
	v_mfma_f32_16x16x32_bf16 v[96:99], v[152:155], v[216:219], v[96:99]
	v_mfma_f32_16x16x32_bf16 v[124:127], v[132:135], v[196:199], v[124:127]
	v_mfma_f32_16x16x32_bf16 v[120:123], v[156:159], v[196:199], v[120:123]
	v_mfma_f32_16x16x32_bf16 v[116:119], v[132:135], v[204:207], v[116:119]
	v_mfma_f32_16x16x32_bf16 v[112:115], v[156:159], v[204:207], v[112:115]
	v_mfma_f32_16x16x32_bf16 v[108:111], v[132:135], v[212:215], v[108:111]
	v_mfma_f32_16x16x32_bf16 v[104:107], v[156:159], v[212:215], v[104:107]
	v_mfma_f32_16x16x32_bf16 v[100:103], v[132:135], v[228:231], v[100:103]
	v_mfma_f32_16x16x32_bf16 v[96:99], v[156:159], v[228:231], v[96:99]
	s_setprio 0
	s_setprio 1
	v_mfma_f32_16x16x32_bf16 v[68:71], v[160:163], v[192:195], v[68:71]
	v_mfma_f32_16x16x32_bf16 v[60:63], v[184:187], v[192:195], v[60:63]
	v_mfma_f32_16x16x32_bf16 v[52:55], v[160:163], v[200:203], v[52:55]
	v_mfma_f32_16x16x32_bf16 v[48:51], v[184:187], v[200:203], v[48:51]
	v_mfma_f32_16x16x32_bf16 v[44:47], v[160:163], v[208:211], v[44:47]
	v_mfma_f32_16x16x32_bf16 v[40:43], v[184:187], v[208:211], v[40:43]
	v_mfma_f32_16x16x32_bf16 v[36:39], v[160:163], v[216:219], v[36:39]
	v_mfma_f32_16x16x32_bf16 v[32:35], v[184:187], v[216:219], v[32:35]
	v_mfma_f32_16x16x32_bf16 v[68:71], v[164:167], v[196:199], v[68:71]
	v_mfma_f32_16x16x32_bf16 v[60:63], v[188:191], v[196:199], v[60:63]
	v_mfma_f32_16x16x32_bf16 v[52:55], v[164:167], v[204:207], v[52:55]
	v_mfma_f32_16x16x32_bf16 v[48:51], v[188:191], v[204:207], v[48:51]
	v_mfma_f32_16x16x32_bf16 v[44:47], v[164:167], v[212:215], v[44:47]
	v_mfma_f32_16x16x32_bf16 v[40:43], v[188:191], v[212:215], v[40:43]
	v_mfma_f32_16x16x32_bf16 v[36:39], v[164:167], v[228:231], v[36:39]
	v_mfma_f32_16x16x32_bf16 v[32:35], v[188:191], v[228:231], v[32:35]
	s_setprio 0
	s_barrier
	s_add_i32 s0, s12, s55
	v_lshl_add_u64 v[146:147], v[146:147], 0, s[16:17]
	s_mov_b32 m0, s0
	ds_read_b128 v[192:195], v151 offset:49152
	ds_read_b128 v[196:199], v151 offset:50176
	ds_read_b128 v[200:203], v151 offset:51200
	ds_read_b128 v[204:207], v151 offset:52224
	ds_read_b128 v[208:211], v151 offset:53248
	ds_read_b128 v[212:215], v151 offset:54272
	ds_read_b128 v[216:219], v151 offset:55296
	ds_read_b128 v[228:231], v151 offset:56320
	global_load_lds_dwordx4 v[146:147], off
	s_add_i32 m0, s0, 0x2000
	s_add_u32 s0, s50, 0x40080
	v_lshl_add_u64 v[146:147], v[232:233], 0, s[16:17]
	s_addc_u32 s1, s51, 0
	s_add_i32 s12, s13, s55
	global_load_lds_dwordx4 v[146:147], off
	s_mov_b32 m0, s12
	s_nop 0
	global_load_lds_dwordx4 v170, s[0:1]
	s_add_i32 m0, s12, 0x2000
	s_nop 0
	global_load_lds_dwordx4 v140, s[0:1]
	v_lshl_add_u64 v[146:147], v[234:235], 0, s[16:17]
	s_mov_b32 m0, s59
	s_nop 0
	global_load_lds_dwordx4 v[146:147], off
	v_lshl_add_u64 v[146:147], v[236:237], 0, s[16:17]
	s_mov_b32 m0, s60
	s_nop 0
	global_load_lds_dwordx4 v[146:147], off
	s_waitcnt vmcnt(6)
	s_waitcnt lgkmcnt(0)
	s_barrier
	s_setprio 1
	s_waitcnt lgkmcnt(0)
	v_mfma_f32_16x16x32_bf16 v[92:95], v[128:131], v[192:195], v[92:95]
	v_mfma_f32_16x16x32_bf16 v[88:91], v[152:155], v[192:195], v[88:91]
	v_mfma_f32_16x16x32_bf16 v[84:87], v[128:131], v[200:203], v[84:87]
	v_mfma_f32_16x16x32_bf16 v[80:83], v[152:155], v[200:203], v[80:83]
	v_mfma_f32_16x16x32_bf16 v[76:79], v[128:131], v[208:211], v[76:79]
	v_mfma_f32_16x16x32_bf16 v[72:75], v[152:155], v[208:211], v[72:75]
	v_mfma_f32_16x16x32_bf16 v[64:67], v[128:131], v[216:219], v[64:67]
	v_mfma_f32_16x16x32_bf16 v[56:59], v[152:155], v[216:219], v[56:59]
	v_mfma_f32_16x16x32_bf16 v[92:95], v[132:135], v[196:199], v[92:95]
	v_mfma_f32_16x16x32_bf16 v[88:91], v[156:159], v[196:199], v[88:91]
	v_mfma_f32_16x16x32_bf16 v[84:87], v[132:135], v[204:207], v[84:87]
	v_mfma_f32_16x16x32_bf16 v[80:83], v[156:159], v[204:207], v[80:83]
	v_mfma_f32_16x16x32_bf16 v[76:79], v[132:135], v[212:215], v[76:79]
	v_mfma_f32_16x16x32_bf16 v[72:75], v[156:159], v[212:215], v[72:75]
	v_mfma_f32_16x16x32_bf16 v[64:67], v[132:135], v[228:231], v[64:67]
	v_mfma_f32_16x16x32_bf16 v[56:59], v[156:159], v[228:231], v[56:59]
	s_setprio 0
	s_setprio 1
	v_mfma_f32_16x16x32_bf16 v[28:31], v[160:163], v[192:195], v[28:31]
	v_mfma_f32_16x16x32_bf16 v[24:27], v[184:187], v[192:195], v[24:27]
	v_mfma_f32_16x16x32_bf16 v[20:23], v[160:163], v[200:203], v[20:23]
	v_mfma_f32_16x16x32_bf16 v[16:19], v[184:187], v[200:203], v[16:19]
	v_mfma_f32_16x16x32_bf16 v[12:15], v[160:163], v[208:211], v[12:15]
	v_mfma_f32_16x16x32_bf16 v[8:11], v[184:187], v[208:211], v[8:11]
	v_mfma_f32_16x16x32_bf16 v[4:7], v[160:163], v[216:219], v[4:7]
	v_mfma_f32_16x16x32_bf16 v[0:3], v[184:187], v[216:219], v[0:3]
	v_mfma_f32_16x16x32_bf16 v[28:31], v[164:167], v[196:199], v[28:31]
	v_mfma_f32_16x16x32_bf16 v[24:27], v[188:191], v[196:199], v[24:27]
	v_mfma_f32_16x16x32_bf16 v[20:23], v[164:167], v[204:207], v[20:23]
	v_mfma_f32_16x16x32_bf16 v[16:19], v[188:191], v[204:207], v[16:19]
	v_mfma_f32_16x16x32_bf16 v[12:15], v[164:167], v[212:215], v[12:15]
	v_mfma_f32_16x16x32_bf16 v[8:11], v[188:191], v[212:215], v[8:11]
	v_mfma_f32_16x16x32_bf16 v[4:7], v[164:167], v[228:231], v[4:7]
	v_mfma_f32_16x16x32_bf16 v[0:3], v[188:191], v[228:231], v[0:3]
	s_setprio 0
	s_barrier
	s_add_i32 s66, s66, 2
	s_add_u32 s64, s64, 0x100
	s_addc_u32 s65, s65, 0
	s_cmp_gt_u32 s66, 13
	s_mov_b64 s[46:47], s[48:49]
.LBB0_601:
	s_add_u32 s48, s46, 0x100
	s_addc_u32 s49, s47, 0
	s_add_i32 s0, 0, 0x10000
	s_cmp_eq_u32 s66, 12
	s_cselect_b32 s53, s37, s49
	s_cselect_b32 s52, s62, s48
	v_add_u32_e32 v146, s0, v149
	s_cselect_b32 s51, s35, s65
	s_cselect_b32 s50, s63, s64
	s_add_i32 s12, 0, 0x14000
	ds_read_b128 v[128:131], v146
	ds_read_b128 v[132:135], v146 offset:1024
	ds_read_b128 v[152:155], v146 offset:2048
	ds_read_b128 v[156:159], v146 offset:3072
	v_add_u32_e32 v146, s12, v149
	ds_read_b128 v[160:163], v146
	ds_read_b128 v[164:167], v146 offset:1024
	ds_read_b128 v[184:187], v146 offset:2048
	ds_read_b128 v[188:191], v146 offset:3072
	s_add_i32 m0, s45, 0xc000
	ds_read_b128 v[192:195], v151
	ds_read_b128 v[196:199], v151 offset:1024
	ds_read_b128 v[200:203], v151 offset:2048
	ds_read_b128 v[204:207], v151 offset:3072
	ds_read_b128 v[208:211], v151 offset:4096
	ds_read_b128 v[212:215], v151 offset:5120
	ds_read_b128 v[216:219], v151 offset:6144
	ds_read_b128 v[228:231], v151 offset:7168
	global_load_lds_dwordx4 v142, s[46:47]
	s_add_i32 m0, s45, 0xe000
	s_nop 0
	global_load_lds_dwordx4 v144, s[46:47]
	s_waitcnt vmcnt(8)
	s_waitcnt lgkmcnt(0)
	s_barrier
	s_setprio 1
	s_waitcnt lgkmcnt(0)
	v_mfma_f32_16x16x32_bf16 v[124:127], v[128:131], v[192:195], v[124:127]
	v_mfma_f32_16x16x32_bf16 v[120:123], v[152:155], v[192:195], v[120:123]
	v_mfma_f32_16x16x32_bf16 v[116:119], v[128:131], v[200:203], v[116:119]
	v_mfma_f32_16x16x32_bf16 v[112:115], v[152:155], v[200:203], v[112:115]
	v_mfma_f32_16x16x32_bf16 v[108:111], v[128:131], v[208:211], v[108:111]
	v_mfma_f32_16x16x32_bf16 v[104:107], v[152:155], v[208:211], v[104:107]
	v_mfma_f32_16x16x32_bf16 v[100:103], v[128:131], v[216:219], v[100:103]
	v_mfma_f32_16x16x32_bf16 v[96:99], v[152:155], v[216:219], v[96:99]
	v_mfma_f32_16x16x32_bf16 v[124:127], v[132:135], v[196:199], v[124:127]
	v_mfma_f32_16x16x32_bf16 v[120:123], v[156:159], v[196:199], v[120:123]
	v_mfma_f32_16x16x32_bf16 v[116:119], v[132:135], v[204:207], v[116:119]
	v_mfma_f32_16x16x32_bf16 v[112:115], v[156:159], v[204:207], v[112:115]
	v_mfma_f32_16x16x32_bf16 v[108:111], v[132:135], v[212:215], v[108:111]
	v_mfma_f32_16x16x32_bf16 v[104:107], v[156:159], v[212:215], v[104:107]
	v_mfma_f32_16x16x32_bf16 v[100:103], v[132:135], v[228:231], v[100:103]
	v_mfma_f32_16x16x32_bf16 v[96:99], v[156:159], v[228:231], v[96:99]
	s_setprio 0
	s_setprio 1
	v_mfma_f32_16x16x32_bf16 v[68:71], v[160:163], v[192:195], v[68:71]
	v_mfma_f32_16x16x32_bf16 v[60:63], v[184:187], v[192:195], v[60:63]
	v_mfma_f32_16x16x32_bf16 v[52:55], v[160:163], v[200:203], v[52:55]
	v_mfma_f32_16x16x32_bf16 v[48:51], v[184:187], v[200:203], v[48:51]
	v_mfma_f32_16x16x32_bf16 v[44:47], v[160:163], v[208:211], v[44:47]
	v_mfma_f32_16x16x32_bf16 v[40:43], v[184:187], v[208:211], v[40:43]
	v_mfma_f32_16x16x32_bf16 v[36:39], v[160:163], v[216:219], v[36:39]
	v_mfma_f32_16x16x32_bf16 v[32:35], v[184:187], v[216:219], v[32:35]
	v_mfma_f32_16x16x32_bf16 v[68:71], v[164:167], v[196:199], v[68:71]
	v_mfma_f32_16x16x32_bf16 v[60:63], v[188:191], v[196:199], v[60:63]
	v_mfma_f32_16x16x32_bf16 v[52:55], v[164:167], v[204:207], v[52:55]
	v_mfma_f32_16x16x32_bf16 v[48:51], v[188:191], v[204:207], v[48:51]
	v_mfma_f32_16x16x32_bf16 v[44:47], v[164:167], v[212:215], v[44:47]
	v_mfma_f32_16x16x32_bf16 v[40:43], v[188:191], v[212:215], v[40:43]
	v_mfma_f32_16x16x32_bf16 v[36:39], v[164:167], v[228:231], v[36:39]
	v_mfma_f32_16x16x32_bf16 v[32:35], v[188:191], v[228:231], v[32:35]
	s_setprio 0
	s_barrier
	s_add_i32 s0, s0, s55
	v_lshl_add_u64 v[146:147], s[50:51], 0, v[170:171]
	s_mov_b32 m0, s0
	ds_read_b128 v[192:195], v151 offset:16384
	ds_read_b128 v[196:199], v151 offset:17408
	ds_read_b128 v[200:203], v151 offset:18432
	ds_read_b128 v[204:207], v151 offset:19456
	ds_read_b128 v[208:211], v151 offset:20480
	ds_read_b128 v[212:215], v151 offset:21504
	ds_read_b128 v[216:219], v151 offset:22528
	ds_read_b128 v[228:231], v151 offset:23552
	global_load_lds_dwordx4 v[146:147], off
	s_add_i32 m0, s0, 0x2000
	s_add_u32 s0, s50, 0x40000
	v_lshl_add_u64 v[232:233], s[50:51], 0, v[140:141]
	s_addc_u32 s1, s51, 0
	s_add_i32 s12, s12, s55
	global_load_lds_dwordx4 v[232:233], off
	s_mov_b32 m0, s12
	v_lshl_add_u64 v[236:237], s[52:53], 0, v[138:139]
	global_load_lds_dwordx4 v170, s[0:1]
	s_add_i32 m0, s12, 0x2000
	s_nop 0
	global_load_lds_dwordx4 v140, s[0:1]
	v_lshl_add_u64 v[234:235], s[52:53], 0, v[136:137]
	s_waitcnt vmcnt(6)
	s_waitcnt lgkmcnt(0)
	s_barrier
	s_setprio 1
	s_waitcnt lgkmcnt(0)
	v_mfma_f32_16x16x32_bf16 v[92:95], v[128:131], v[192:195], v[92:95]
	v_mfma_f32_16x16x32_bf16 v[88:91], v[152:155], v[192:195], v[88:91]
	v_mfma_f32_16x16x32_bf16 v[84:87], v[128:131], v[200:203], v[84:87]
	v_mfma_f32_16x16x32_bf16 v[80:83], v[152:155], v[200:203], v[80:83]
	v_mfma_f32_16x16x32_bf16 v[76:79], v[128:131], v[208:211], v[76:79]
	v_mfma_f32_16x16x32_bf16 v[72:75], v[152:155], v[208:211], v[72:75]
	v_mfma_f32_16x16x32_bf16 v[64:67], v[128:131], v[216:219], v[64:67]
	v_mfma_f32_16x16x32_bf16 v[56:59], v[152:155], v[216:219], v[56:59]
	v_mfma_f32_16x16x32_bf16 v[92:95], v[132:135], v[196:199], v[92:95]
	v_mfma_f32_16x16x32_bf16 v[88:91], v[156:159], v[196:199], v[88:91]
	v_mfma_f32_16x16x32_bf16 v[84:87], v[132:135], v[204:207], v[84:87]
	v_mfma_f32_16x16x32_bf16 v[80:83], v[156:159], v[204:207], v[80:83]
	v_mfma_f32_16x16x32_bf16 v[76:79], v[132:135], v[212:215], v[76:79]
	v_mfma_f32_16x16x32_bf16 v[72:75], v[156:159], v[212:215], v[72:75]
	v_mfma_f32_16x16x32_bf16 v[64:67], v[132:135], v[228:231], v[64:67]
	v_mfma_f32_16x16x32_bf16 v[56:59], v[156:159], v[228:231], v[56:59]
	s_setprio 0
	s_setprio 1
	v_mfma_f32_16x16x32_bf16 v[28:31], v[160:163], v[192:195], v[28:31]
	v_mfma_f32_16x16x32_bf16 v[24:27], v[184:187], v[192:195], v[24:27]
	v_mfma_f32_16x16x32_bf16 v[20:23], v[160:163], v[200:203], v[20:23]
	v_mfma_f32_16x16x32_bf16 v[16:19], v[184:187], v[200:203], v[16:19]
	v_mfma_f32_16x16x32_bf16 v[12:15], v[160:163], v[208:211], v[12:15]
	v_mfma_f32_16x16x32_bf16 v[8:11], v[184:187], v[208:211], v[8:11]
	v_mfma_f32_16x16x32_bf16 v[4:7], v[160:163], v[216:219], v[4:7]
	v_mfma_f32_16x16x32_bf16 v[0:3], v[184:187], v[216:219], v[0:3]
	v_mfma_f32_16x16x32_bf16 v[28:31], v[164:167], v[196:199], v[28:31]
	v_mfma_f32_16x16x32_bf16 v[24:27], v[188:191], v[196:199], v[24:27]
	v_mfma_f32_16x16x32_bf16 v[20:23], v[164:167], v[204:207], v[20:23]
	v_mfma_f32_16x16x32_bf16 v[16:19], v[188:191], v[204:207], v[16:19]
	v_mfma_f32_16x16x32_bf16 v[12:15], v[164:167], v[212:215], v[12:15]
	v_mfma_f32_16x16x32_bf16 v[8:11], v[188:191], v[212:215], v[8:11]
	v_mfma_f32_16x16x32_bf16 v[4:7], v[164:167], v[228:231], v[4:7]
	v_mfma_f32_16x16x32_bf16 v[0:3], v[188:191], v[228:231], v[0:3]
	s_setprio 0
	s_barrier
	s_add_i32 s12, 0, 0x18000
	s_add_i32 s13, 0, 0x1c000
	v_add_u32_e32 v156, s12, v149
	v_add_u32_e32 v188, s13, v149
	ds_read_b128 v[128:131], v156
	ds_read_b128 v[132:135], v156 offset:1024
	ds_read_b128 v[152:155], v156 offset:2048
	ds_read_b128 v[156:159], v156 offset:3072
	ds_read_b128 v[160:163], v188
	ds_read_b128 v[164:167], v188 offset:1024
	ds_read_b128 v[184:187], v188 offset:2048
	ds_read_b128 v[188:191], v188 offset:3072
	s_add_u32 s0, s52, 0x40000
	s_addc_u32 s1, s53, 0
	s_mov_b32 m0, s57
	ds_read_b128 v[192:195], v151 offset:32768
	ds_read_b128 v[196:199], v151 offset:33792
	ds_read_b128 v[200:203], v151 offset:34816
	ds_read_b128 v[204:207], v151 offset:35840
	ds_read_b128 v[208:211], v151 offset:36864
	ds_read_b128 v[212:215], v151 offset:37888
	ds_read_b128 v[216:219], v151 offset:38912
	ds_read_b128 v[228:231], v151 offset:39936
	global_load_lds_dwordx4 v136, s[0:1]
	s_mov_b32 m0, s58
	s_nop 0
	global_load_lds_dwordx4 v138, s[0:1]
	s_mov_b32 m0, s45
	s_nop 0
	global_load_lds_dwordx4 v[234:235], off
	s_mov_b32 m0, s56
	s_nop 0
	global_load_lds_dwordx4 v[236:237], off
	s_waitcnt vmcnt(8)
	s_waitcnt lgkmcnt(0)
	s_barrier
	s_setprio 1
	s_waitcnt lgkmcnt(0)
	v_mfma_f32_16x16x32_bf16 v[124:127], v[128:131], v[192:195], v[124:127]
	v_mfma_f32_16x16x32_bf16 v[120:123], v[152:155], v[192:195], v[120:123]
	v_mfma_f32_16x16x32_bf16 v[116:119], v[128:131], v[200:203], v[116:119]
	v_mfma_f32_16x16x32_bf16 v[112:115], v[152:155], v[200:203], v[112:115]
	v_mfma_f32_16x16x32_bf16 v[108:111], v[128:131], v[208:211], v[108:111]
	v_mfma_f32_16x16x32_bf16 v[104:107], v[152:155], v[208:211], v[104:107]
	v_mfma_f32_16x16x32_bf16 v[100:103], v[128:131], v[216:219], v[100:103]
	v_mfma_f32_16x16x32_bf16 v[96:99], v[152:155], v[216:219], v[96:99]
	v_mfma_f32_16x16x32_bf16 v[124:127], v[132:135], v[196:199], v[124:127]
	v_mfma_f32_16x16x32_bf16 v[120:123], v[156:159], v[196:199], v[120:123]
	v_mfma_f32_16x16x32_bf16 v[116:119], v[132:135], v[204:207], v[116:119]
	v_mfma_f32_16x16x32_bf16 v[112:115], v[156:159], v[204:207], v[112:115]
	v_mfma_f32_16x16x32_bf16 v[108:111], v[132:135], v[212:215], v[108:111]
	v_mfma_f32_16x16x32_bf16 v[104:107], v[156:159], v[212:215], v[104:107]
	v_mfma_f32_16x16x32_bf16 v[100:103], v[132:135], v[228:231], v[100:103]
	v_mfma_f32_16x16x32_bf16 v[96:99], v[156:159], v[228:231], v[96:99]
	s_setprio 0
	s_setprio 1
	v_mfma_f32_16x16x32_bf16 v[68:71], v[160:163], v[192:195], v[68:71]
	v_mfma_f32_16x16x32_bf16 v[60:63], v[184:187], v[192:195], v[60:63]
	v_mfma_f32_16x16x32_bf16 v[52:55], v[160:163], v[200:203], v[52:55]
	v_mfma_f32_16x16x32_bf16 v[48:51], v[184:187], v[200:203], v[48:51]
	v_mfma_f32_16x16x32_bf16 v[44:47], v[160:163], v[208:211], v[44:47]
	v_mfma_f32_16x16x32_bf16 v[40:43], v[184:187], v[208:211], v[40:43]
	v_mfma_f32_16x16x32_bf16 v[36:39], v[160:163], v[216:219], v[36:39]
	v_mfma_f32_16x16x32_bf16 v[32:35], v[184:187], v[216:219], v[32:35]
	v_mfma_f32_16x16x32_bf16 v[68:71], v[164:167], v[196:199], v[68:71]
	v_mfma_f32_16x16x32_bf16 v[60:63], v[188:191], v[196:199], v[60:63]
	v_mfma_f32_16x16x32_bf16 v[52:55], v[164:167], v[204:207], v[52:55]
	v_mfma_f32_16x16x32_bf16 v[48:51], v[188:191], v[204:207], v[48:51]
	v_mfma_f32_16x16x32_bf16 v[44:47], v[164:167], v[212:215], v[44:47]
	v_mfma_f32_16x16x32_bf16 v[40:43], v[188:191], v[212:215], v[40:43]
	v_mfma_f32_16x16x32_bf16 v[36:39], v[164:167], v[228:231], v[36:39]
	v_mfma_f32_16x16x32_bf16 v[32:35], v[188:191], v[228:231], v[32:35]
	s_setprio 0
	s_barrier
	s_add_i32 s0, s12, s55
	v_lshl_add_u64 v[146:147], v[146:147], 0, s[16:17]
	s_mov_b32 m0, s0
	ds_read_b128 v[192:195], v151 offset:49152
	ds_read_b128 v[196:199], v151 offset:50176
	ds_read_b128 v[200:203], v151 offset:51200
	ds_read_b128 v[204:207], v151 offset:52224
	ds_read_b128 v[208:211], v151 offset:53248
	ds_read_b128 v[212:215], v151 offset:54272
	ds_read_b128 v[216:219], v151 offset:55296
	ds_read_b128 v[228:231], v151 offset:56320
	global_load_lds_dwordx4 v[146:147], off
	s_add_i32 m0, s0, 0x2000
	s_add_u32 s0, s50, 0x40080
	v_lshl_add_u64 v[146:147], v[232:233], 0, s[16:17]
	s_addc_u32 s1, s51, 0
	s_add_i32 s12, s13, s55
	global_load_lds_dwordx4 v[146:147], off
	s_mov_b32 m0, s12
	s_nop 0
	global_load_lds_dwordx4 v170, s[0:1]
	s_add_i32 m0, s12, 0x2000
	s_nop 0
	global_load_lds_dwordx4 v140, s[0:1]
	v_lshl_add_u64 v[146:147], v[234:235], 0, s[16:17]
	s_mov_b32 m0, s59
	s_nop 0
	global_load_lds_dwordx4 v[146:147], off
	v_lshl_add_u64 v[146:147], v[236:237], 0, s[16:17]
	s_mov_b32 m0, s60
	s_nop 0
	global_load_lds_dwordx4 v[146:147], off
	s_waitcnt vmcnt(6)
	s_waitcnt lgkmcnt(0)
	s_barrier
	s_setprio 1
	s_waitcnt lgkmcnt(0)
	v_mfma_f32_16x16x32_bf16 v[92:95], v[128:131], v[192:195], v[92:95]
	v_mfma_f32_16x16x32_bf16 v[88:91], v[152:155], v[192:195], v[88:91]
	v_mfma_f32_16x16x32_bf16 v[84:87], v[128:131], v[200:203], v[84:87]
	v_mfma_f32_16x16x32_bf16 v[80:83], v[152:155], v[200:203], v[80:83]
	v_mfma_f32_16x16x32_bf16 v[76:79], v[128:131], v[208:211], v[76:79]
	v_mfma_f32_16x16x32_bf16 v[72:75], v[152:155], v[208:211], v[72:75]
	v_mfma_f32_16x16x32_bf16 v[64:67], v[128:131], v[216:219], v[64:67]
	v_mfma_f32_16x16x32_bf16 v[56:59], v[152:155], v[216:219], v[56:59]
	v_mfma_f32_16x16x32_bf16 v[92:95], v[132:135], v[196:199], v[92:95]
	v_mfma_f32_16x16x32_bf16 v[88:91], v[156:159], v[196:199], v[88:91]
	v_mfma_f32_16x16x32_bf16 v[84:87], v[132:135], v[204:207], v[84:87]
	v_mfma_f32_16x16x32_bf16 v[80:83], v[156:159], v[204:207], v[80:83]
	v_mfma_f32_16x16x32_bf16 v[76:79], v[132:135], v[212:215], v[76:79]
	v_mfma_f32_16x16x32_bf16 v[72:75], v[156:159], v[212:215], v[72:75]
	v_mfma_f32_16x16x32_bf16 v[64:67], v[132:135], v[228:231], v[64:67]
	v_mfma_f32_16x16x32_bf16 v[56:59], v[156:159], v[228:231], v[56:59]
	s_setprio 0
	s_setprio 1
	v_mfma_f32_16x16x32_bf16 v[28:31], v[160:163], v[192:195], v[28:31]
	v_mfma_f32_16x16x32_bf16 v[24:27], v[184:187], v[192:195], v[24:27]
	v_mfma_f32_16x16x32_bf16 v[20:23], v[160:163], v[200:203], v[20:23]
	v_mfma_f32_16x16x32_bf16 v[16:19], v[184:187], v[200:203], v[16:19]
	v_mfma_f32_16x16x32_bf16 v[12:15], v[160:163], v[208:211], v[12:15]
	v_mfma_f32_16x16x32_bf16 v[8:11], v[184:187], v[208:211], v[8:11]
	v_mfma_f32_16x16x32_bf16 v[4:7], v[160:163], v[216:219], v[4:7]
	v_mfma_f32_16x16x32_bf16 v[0:3], v[184:187], v[216:219], v[0:3]
	v_mfma_f32_16x16x32_bf16 v[28:31], v[164:167], v[196:199], v[28:31]
	v_mfma_f32_16x16x32_bf16 v[24:27], v[188:191], v[196:199], v[24:27]
	v_mfma_f32_16x16x32_bf16 v[20:23], v[164:167], v[204:207], v[20:23]
	v_mfma_f32_16x16x32_bf16 v[16:19], v[188:191], v[204:207], v[16:19]
	v_mfma_f32_16x16x32_bf16 v[12:15], v[164:167], v[212:215], v[12:15]
	v_mfma_f32_16x16x32_bf16 v[8:11], v[188:191], v[212:215], v[8:11]
	v_mfma_f32_16x16x32_bf16 v[4:7], v[164:167], v[228:231], v[4:7]
	v_mfma_f32_16x16x32_bf16 v[0:3], v[188:191], v[228:231], v[0:3]
	s_setprio 0
	s_barrier
	s_add_i32 s66, s66, 2
	s_add_u32 s64, s64, 0x100
	s_addc_u32 s65, s65, 0
	s_cmp_gt_u32 s66, 13
	s_mov_b64 s[46:47], s[48:49]
	s_cbranch_scc0 .LBB0_601
	s_and_b64 vcc, exec, s[30:31]
	s_cbranch_vccz .LBB0_604
	s_barrier
.LBB0_604:
	v_lshl_or_b32 v160, s61, 8, v150
	v_or_b32_e32 v146, 0x80, v160
	v_ashrrev_i32_e32 v161, 31, v160
	v_ashrrev_i32_e32 v147, 31, v146
	v_lshl_add_u64 v[128:129], v[160:161], 2, s[8:9]
	v_lshl_add_u64 v[132:133], v[146:147], 2, s[8:9]
	global_load_dwordx4 v[152:155], v[128:129], off offset:16
	global_load_dwordx4 v[156:159], v[128:129], off
	s_nop 0
	global_load_dwordx4 v[128:131], v[132:133], off offset:16
	s_nop 0
	global_load_dwordx4 v[132:135], v[132:133], off
	s_waitcnt vmcnt(0)
	v_fmamk_f32 v156, v156, 0x3a800000, v220
	v_fmamk_f32 v152, v152, 0x3a800000, v220
	v_fmamk_f32 v157, v157, 0x3a800000, v220
	v_fmamk_f32 v153, v153, 0x3a800000, v220
	v_rsq_f32_e32 v156, v156
	v_rsq_f32_e32 v152, v152
	v_rsq_f32_e32 v157, v157
	v_rsq_f32_e32 v153, v153
	v_fmamk_f32 v158, v158, 0x3a800000, v220
	v_fmamk_f32 v154, v154, 0x3a800000, v220
	v_fmamk_f32 v159, v159, 0x3a800000, v220
	v_fmamk_f32 v155, v155, 0x3a800000, v220
	v_rsq_f32_e32 v158, v158
	v_rsq_f32_e32 v154, v154
	v_rsq_f32_e32 v159, v159
	v_rsq_f32_e32 v155, v155
	v_lshl_add_u32 v162, s44, 8, v148
	v_pk_mul_f32 v[124:125], v[124:125], v[156:157]
	v_pk_mul_f32 v[120:121], v[120:121], v[152:153]
	v_ashrrev_i32_e32 v163, 31, v162
	v_lshl_add_u64 v[160:161], v[160:161], 1, s[28:29]
	v_pk_mul_f32 v[126:127], v[126:127], v[158:159]
	v_pk_mul_f32 v[164:165], v[122:123], v[154:155]
	v_cvt_pk_bf16_f32 v122, v124, v125
	v_cvt_pk_bf16_f32 v123, v126, v127
	v_cvt_pk_bf16_f32 v124, v120, v121
	v_lshlrev_b64 v[120:121], 17, v[162:163]
	v_lshl_add_u64 v[126:127], v[160:161], 0, v[120:121]
	v_cvt_pk_bf16_f32 v125, v164, v165
	global_store_dwordx4 v[126:127], v[122:125], off
	v_pk_mul_f32 v[116:117], v[116:117], v[156:157]
	v_pk_mul_f32 v[112:113], v[112:113], v[152:153]
	v_or_b32_e32 v122, 16, v162
	v_ashrrev_i32_e32 v123, 31, v122
	v_pk_mul_f32 v[118:119], v[118:119], v[158:159]
	v_pk_mul_f32 v[124:125], v[114:115], v[154:155]
	v_cvt_pk_bf16_f32 v114, v116, v117
	v_cvt_pk_bf16_f32 v115, v118, v119
	v_cvt_pk_bf16_f32 v116, v112, v113
	v_lshlrev_b64 v[112:113], 17, v[122:123]
	v_lshl_add_u64 v[118:119], v[160:161], 0, v[112:113]
	v_cvt_pk_bf16_f32 v117, v124, v125
	global_store_dwordx4 v[118:119], v[114:117], off
	v_pk_mul_f32 v[108:109], v[108:109], v[156:157]
	v_pk_mul_f32 v[104:105], v[104:105], v[152:153]
	v_or_b32_e32 v114, 32, v162
	v_ashrrev_i32_e32 v115, 31, v114
	v_pk_mul_f32 v[110:111], v[110:111], v[158:159]
	v_pk_mul_f32 v[116:117], v[106:107], v[154:155]
	v_cvt_pk_bf16_f32 v106, v108, v109
	v_cvt_pk_bf16_f32 v107, v110, v111
	v_cvt_pk_bf16_f32 v108, v104, v105
	v_lshlrev_b64 v[104:105], 17, v[114:115]
	v_lshl_add_u64 v[110:111], v[160:161], 0, v[104:105]
	v_cvt_pk_bf16_f32 v109, v116, v117
	global_store_dwordx4 v[110:111], v[106:109], off
	v_pk_mul_f32 v[100:101], v[100:101], v[156:157]
	v_pk_mul_f32 v[96:97], v[96:97], v[152:153]
	v_or_b32_e32 v106, 48, v162
	v_ashrrev_i32_e32 v107, 31, v106
	v_pk_mul_f32 v[102:103], v[102:103], v[158:159]
	v_pk_mul_f32 v[108:109], v[98:99], v[154:155]
	v_cvt_pk_bf16_f32 v98, v100, v101
	v_cvt_pk_bf16_f32 v99, v102, v103
	v_cvt_pk_bf16_f32 v100, v96, v97
	v_lshlrev_b64 v[96:97], 17, v[106:107]
	v_lshl_add_u64 v[102:103], v[160:161], 0, v[96:97]
	v_cvt_pk_bf16_f32 v101, v108, v109
	global_store_dwordx4 v[102:103], v[98:101], off
	v_pk_mul_f32 v[92:93], v[92:93], v[156:157]
	v_pk_mul_f32 v[94:95], v[94:95], v[158:159]
	v_add_u32_e32 v98, 0x80, v162
	v_ashrrev_i32_e32 v99, 31, v98
	v_pk_mul_f32 v[100:101], v[90:91], v[154:155]
	v_pk_mul_f32 v[90:91], v[88:89], v[152:153]
	v_cvt_pk_bf16_f32 v88, v92, v93
	v_lshlrev_b64 v[92:93], 17, v[98:99]
	v_cvt_pk_bf16_f32 v89, v94, v95
	v_lshl_add_u64 v[94:95], v[160:161], 0, v[92:93]
	v_cvt_pk_bf16_f32 v90, v90, v91
	v_cvt_pk_bf16_f32 v91, v100, v101
	global_store_dwordx4 v[94:95], v[88:91], off
	v_pk_mul_f32 v[84:85], v[84:85], v[156:157]
	v_pk_mul_f32 v[86:87], v[86:87], v[158:159]
	v_add_u32_e32 v88, 0x90, v162
	v_ashrrev_i32_e32 v89, 31, v88
	v_pk_mul_f32 v[90:91], v[82:83], v[154:155]
	v_pk_mul_f32 v[82:83], v[80:81], v[152:153]
	v_cvt_pk_bf16_f32 v80, v84, v85
	v_lshlrev_b64 v[84:85], 17, v[88:89]
	v_cvt_pk_bf16_f32 v81, v86, v87
	v_lshl_add_u64 v[86:87], v[160:161], 0, v[84:85]
	v_cvt_pk_bf16_f32 v82, v82, v83
	v_cvt_pk_bf16_f32 v83, v90, v91
	global_store_dwordx4 v[86:87], v[80:83], off
	v_pk_mul_f32 v[76:77], v[76:77], v[156:157]
	v_pk_mul_f32 v[78:79], v[78:79], v[158:159]
	v_add_u32_e32 v80, 0xa0, v162
	v_ashrrev_i32_e32 v81, 31, v80
	v_pk_mul_f32 v[82:83], v[74:75], v[154:155]
	v_pk_mul_f32 v[74:75], v[72:73], v[152:153]
	v_cvt_pk_bf16_f32 v72, v76, v77
	v_lshlrev_b64 v[76:77], 17, v[80:81]
	v_cvt_pk_bf16_f32 v73, v78, v79
	v_lshl_add_u64 v[78:79], v[160:161], 0, v[76:77]
	v_cvt_pk_bf16_f32 v74, v74, v75
	v_cvt_pk_bf16_f32 v75, v82, v83
	global_store_dwordx4 v[78:79], v[72:75], off
	v_pk_mul_f32 v[64:65], v[64:65], v[156:157]
	v_pk_mul_f32 v[66:67], v[66:67], v[158:159]
	v_add_u32_e32 v72, 0xb0, v162
	v_ashrrev_i32_e32 v73, 31, v72
	v_pk_mul_f32 v[74:75], v[58:59], v[154:155]
	v_pk_mul_f32 v[58:59], v[56:57], v[152:153]
	v_cvt_pk_bf16_f32 v56, v64, v65
	v_lshlrev_b64 v[64:65], 17, v[72:73]
	v_cvt_pk_bf16_f32 v57, v66, v67
	v_lshl_add_u64 v[66:67], v[160:161], 0, v[64:65]
	v_cvt_pk_bf16_f32 v58, v58, v59
	v_cvt_pk_bf16_f32 v59, v74, v75
	global_store_dwordx4 v[66:67], v[56:59], off
	s_andn2_b64 vcc, exec, s[4:5]
	s_mov_b64 s[4:5], -1
	v_fmamk_f32 v56, v132, 0x3a800000, v220
	v_fmamk_f32 v57, v134, 0x3a800000, v220
	v_rsq_f32_e32 v66, v56
	v_fmamk_f32 v56, v128, 0x3a800000, v220
	v_rsq_f32_e32 v74, v57
	v_fmamk_f32 v57, v130, 0x3a800000, v220
	v_rsq_f32_e32 v72, v56
	v_fmamk_f32 v56, v133, 0x3a800000, v220
	v_rsq_f32_e32 v78, v57
	v_fmamk_f32 v57, v135, 0x3a800000, v220
	v_rsq_f32_e32 v67, v56
	v_fmamk_f32 v56, v129, 0x3a800000, v220
	v_rsq_f32_e32 v75, v57
	v_fmamk_f32 v57, v131, 0x3a800000, v220
	v_rsq_f32_e32 v79, v57
	v_rsq_f32_e32 v73, v56
	v_pk_mul_f32 v[58:59], v[70:71], v[74:75]
	v_pk_mul_f32 v[56:57], v[68:69], v[66:67]
	v_pk_mul_f32 v[62:63], v[62:63], v[78:79]
	v_pk_mul_f32 v[60:61], v[60:61], v[72:73]
	v_cvt_pk_bf16_f32 v56, v56, v57
	v_cvt_pk_bf16_f32 v57, v58, v59
	v_pk_mul_f32 v[52:53], v[52:53], v[66:67]
	v_cvt_pk_bf16_f32 v58, v60, v61
	v_cvt_pk_bf16_f32 v59, v62, v63
	v_lshl_add_u64 v[60:61], s[28:29], 0, v[120:121]
	v_lshlrev_b64 v[62:63], 1, v[146:147]
	v_lshl_add_u64 v[60:61], v[60:61], 0, v[62:63]
	global_store_dwordx4 v[60:61], v[56:59], off
	v_pk_mul_f32 v[54:55], v[54:55], v[74:75]
	v_pk_mul_f32 v[44:45], v[44:45], v[66:67]
	v_pk_mul_f32 v[56:57], v[50:51], v[78:79]
	v_pk_mul_f32 v[50:51], v[48:49], v[72:73]
	v_cvt_pk_bf16_f32 v48, v52, v53
	v_lshl_add_u64 v[52:53], s[28:29], 0, v[112:113]
	v_cvt_pk_bf16_f32 v49, v54, v55
	v_lshl_add_u64 v[52:53], v[52:53], 0, v[62:63]
	v_cvt_pk_bf16_f32 v50, v50, v51
	v_cvt_pk_bf16_f32 v51, v56, v57
	global_store_dwordx4 v[52:53], v[48:51], off
	v_pk_mul_f32 v[46:47], v[46:47], v[74:75]
	v_pk_mul_f32 v[36:37], v[36:37], v[66:67]
	v_pk_mul_f32 v[48:49], v[42:43], v[78:79]
	v_pk_mul_f32 v[42:43], v[40:41], v[72:73]
	v_cvt_pk_bf16_f32 v40, v44, v45
	v_lshl_add_u64 v[44:45], s[28:29], 0, v[104:105]
	v_cvt_pk_bf16_f32 v41, v46, v47
	v_lshl_add_u64 v[44:45], v[44:45], 0, v[62:63]
	v_cvt_pk_bf16_f32 v42, v42, v43
	v_cvt_pk_bf16_f32 v43, v48, v49
	global_store_dwordx4 v[44:45], v[40:43], off
	v_pk_mul_f32 v[38:39], v[38:39], v[74:75]
	v_pk_mul_f32 v[28:29], v[28:29], v[66:67]
	v_pk_mul_f32 v[40:41], v[34:35], v[78:79]
	v_pk_mul_f32 v[34:35], v[32:33], v[72:73]
	v_cvt_pk_bf16_f32 v32, v36, v37
	v_lshl_add_u64 v[36:37], s[28:29], 0, v[96:97]
	v_cvt_pk_bf16_f32 v33, v38, v39
	v_lshl_add_u64 v[36:37], v[36:37], 0, v[62:63]
	v_cvt_pk_bf16_f32 v34, v34, v35
	v_cvt_pk_bf16_f32 v35, v40, v41
	global_store_dwordx4 v[36:37], v[32:35], off
	v_pk_mul_f32 v[30:31], v[30:31], v[74:75]
	v_pk_mul_f32 v[20:21], v[20:21], v[66:67]
	v_pk_mul_f32 v[32:33], v[26:27], v[78:79]
	v_pk_mul_f32 v[26:27], v[24:25], v[72:73]
	v_cvt_pk_bf16_f32 v24, v28, v29
	v_lshl_add_u64 v[28:29], s[28:29], 0, v[92:93]
	v_cvt_pk_bf16_f32 v25, v30, v31
	v_lshl_add_u64 v[28:29], v[28:29], 0, v[62:63]
	v_cvt_pk_bf16_f32 v26, v26, v27
	v_cvt_pk_bf16_f32 v27, v32, v33
	global_store_dwordx4 v[28:29], v[24:27], off
	v_pk_mul_f32 v[22:23], v[22:23], v[74:75]
	v_pk_mul_f32 v[12:13], v[12:13], v[66:67]
	v_pk_mul_f32 v[24:25], v[18:19], v[78:79]
	v_pk_mul_f32 v[18:19], v[16:17], v[72:73]
	v_cvt_pk_bf16_f32 v16, v20, v21
	v_lshl_add_u64 v[20:21], s[28:29], 0, v[84:85]
	v_cvt_pk_bf16_f32 v17, v22, v23
	v_lshl_add_u64 v[20:21], v[20:21], 0, v[62:63]
	v_cvt_pk_bf16_f32 v18, v18, v19
	v_cvt_pk_bf16_f32 v19, v24, v25
	global_store_dwordx4 v[20:21], v[16:19], off
	v_pk_mul_f32 v[14:15], v[14:15], v[74:75]
	v_pk_mul_f32 v[4:5], v[4:5], v[66:67]
	v_pk_mul_f32 v[16:17], v[10:11], v[78:79]
	v_pk_mul_f32 v[10:11], v[8:9], v[72:73]
	v_cvt_pk_bf16_f32 v8, v12, v13
	v_lshl_add_u64 v[12:13], s[28:29], 0, v[76:77]
	v_cvt_pk_bf16_f32 v9, v14, v15
	v_lshl_add_u64 v[12:13], v[12:13], 0, v[62:63]
	v_cvt_pk_bf16_f32 v10, v10, v11
	v_cvt_pk_bf16_f32 v11, v16, v17
	global_store_dwordx4 v[12:13], v[8:11], off
	v_pk_mul_f32 v[6:7], v[6:7], v[74:75]
	s_nop 0
	v_pk_mul_f32 v[8:9], v[2:3], v[78:79]
	v_pk_mul_f32 v[2:3], v[0:1], v[72:73]
	v_cvt_pk_bf16_f32 v0, v4, v5
	v_lshl_add_u64 v[4:5], s[28:29], 0, v[64:65]
	v_lshl_add_u64 v[4:5], v[4:5], 0, v[62:63]
	v_cvt_pk_bf16_f32 v1, v6, v7
	v_cvt_pk_bf16_f32 v2, v2, v3
	v_cvt_pk_bf16_f32 v3, v8, v9
	global_store_dwordx4 v[4:5], v[0:3], off
	s_cbranch_vccnz .LBB0_593
	s_andn2_b64 vcc, exec, s[6:7]
	s_cbranch_vccnz .LBB0_592
	s_mov_b32 s98, 1
	s_branch .LBB0_592

.LBB0_775:
	s_ashr_i32 s37, s36, 31
	s_lshl_b64 s[0:1], s[36:37], 19
	s_add_u32 s40, s15, s0
	s_addc_u32 s41, s22, s1
	s_and_b64 s[0:1], s[6:7], exec
	s_cselect_b32 s37, s41, s49
	s_cselect_b32 s45, s40, s48
	s_ashr_i32 s35, s34, 31
	s_lshl_b64 s[0:1], s[34:35], 19
	s_add_u32 s42, s23, s0
	s_addc_u32 s43, s39, s1
	s_and_b64 s[0:1], s[6:7], exec
	s_cselect_b32 s35, s43, s51
	s_cselect_b32 s63, s42, s50
	s_add_u32 s64, s50, 0x100
	s_addc_u32 s65, s51, 0
	s_mov_b32 s66, -2
	s_waitcnt lgkmcnt(0)
	s_waitcnt vmcnt(0)
	s_cmp_eq_u32 s98, 1
	s_cbranch_scc0 .Lrestag_776
	s_barrier
	s_mov_b32 s98, 0
.Lrestag_776:
	s_add_u32 s50, s48, 0x100
	s_addc_u32 s51, s49, 0
	s_add_i32 s0, 0, 0x10000
	s_cmp_eq_u32 s66, 12
	s_cselect_b32 s55, s37, s51
	s_cselect_b32 s54, s45, s50
	s_cselect_b32 s53, s35, s65
	s_cselect_b32 s52, s63, s64
	s_add_i32 s12, 0, 0x14000
	v_add_u32_e32 v140, s0, v197
	v_add_u32_e32 v184, s12, v197
	ds_read_b128 v[128:131], v140
	ds_read_b128 v[132:135], v140 offset:1024
	ds_read_b128 v[136:139], v140 offset:2048
	ds_read_b128 v[140:143], v140 offset:3072
	ds_read_b128 v[144:147], v184
	ds_read_b128 v[148:151], v184 offset:1024
	ds_read_b128 v[164:167], v184 offset:2048
	ds_read_b128 v[184:187], v184 offset:3072
	s_add_i32 m0, s47, 0xc000
	ds_read_b128 v[188:191], v198
	ds_read_b128 v[192:195], v198 offset:1024
	ds_read_b128 v[200:203], v198 offset:2048
	ds_read_b128 v[204:207], v198 offset:3072
	ds_read_b128 v[208:211], v198 offset:4096
	ds_read_b128 v[212:215], v198 offset:5120
	ds_read_b128 v[216:219], v198 offset:6144
	ds_read_b128 v[228:231], v198 offset:7168
	global_load_lds_dwordx4 v160, s[48:49]
	s_add_i32 m0, s47, 0xe000
	s_nop 0
	global_load_lds_dwordx4 v162, s[48:49]
	s_nop 0
	s_waitcnt lgkmcnt(0)
	s_barrier
	s_setprio 1
	s_waitcnt lgkmcnt(0)
	v_mfma_f32_16x16x32_bf16 v[124:127], v[128:131], v[188:191], 0
	v_mfma_f32_16x16x32_bf16 v[120:123], v[136:139], v[188:191], 0
	v_mfma_f32_16x16x32_bf16 v[108:111], v[128:131], v[200:203], 0
	v_mfma_f32_16x16x32_bf16 v[104:107], v[136:139], v[200:203], 0
	v_mfma_f32_16x16x32_bf16 v[92:95], v[128:131], v[208:211], 0
	v_mfma_f32_16x16x32_bf16 v[88:91], v[136:139], v[208:211], 0
	v_mfma_f32_16x16x32_bf16 v[76:79], v[128:131], v[216:219], 0
	v_mfma_f32_16x16x32_bf16 v[72:75], v[136:139], v[216:219], 0
	v_mfma_f32_16x16x32_bf16 v[124:127], v[132:135], v[192:195], v[124:127]
	v_mfma_f32_16x16x32_bf16 v[120:123], v[140:143], v[192:195], v[120:123]
	v_mfma_f32_16x16x32_bf16 v[108:111], v[132:135], v[204:207], v[108:111]
	v_mfma_f32_16x16x32_bf16 v[104:107], v[140:143], v[204:207], v[104:107]
	v_mfma_f32_16x16x32_bf16 v[92:95], v[132:135], v[212:215], v[92:95]
	v_mfma_f32_16x16x32_bf16 v[88:91], v[140:143], v[212:215], v[88:91]
	v_mfma_f32_16x16x32_bf16 v[76:79], v[132:135], v[228:231], v[76:79]
	v_mfma_f32_16x16x32_bf16 v[72:75], v[140:143], v[228:231], v[72:75]
	s_setprio 0
	s_setprio 1
	v_mfma_f32_16x16x32_bf16 v[116:119], v[144:147], v[188:191], 0
	v_mfma_f32_16x16x32_bf16 v[112:115], v[164:167], v[188:191], 0
	v_mfma_f32_16x16x32_bf16 v[100:103], v[144:147], v[200:203], 0
	v_mfma_f32_16x16x32_bf16 v[96:99], v[164:167], v[200:203], 0
	v_mfma_f32_16x16x32_bf16 v[84:87], v[144:147], v[208:211], 0
	v_mfma_f32_16x16x32_bf16 v[80:83], v[164:167], v[208:211], 0
	v_mfma_f32_16x16x32_bf16 v[68:71], v[144:147], v[216:219], 0
	v_mfma_f32_16x16x32_bf16 v[64:67], v[164:167], v[216:219], 0
	v_mfma_f32_16x16x32_bf16 v[116:119], v[148:151], v[192:195], v[116:119]
	v_mfma_f32_16x16x32_bf16 v[112:115], v[184:187], v[192:195], v[112:115]
	v_mfma_f32_16x16x32_bf16 v[100:103], v[148:151], v[204:207], v[100:103]
	v_mfma_f32_16x16x32_bf16 v[96:99], v[184:187], v[204:207], v[96:99]
	v_mfma_f32_16x16x32_bf16 v[84:87], v[148:151], v[212:215], v[84:87]
	v_mfma_f32_16x16x32_bf16 v[80:83], v[184:187], v[212:215], v[80:83]
	v_mfma_f32_16x16x32_bf16 v[68:71], v[148:151], v[228:231], v[68:71]
	v_mfma_f32_16x16x32_bf16 v[64:67], v[184:187], v[228:231], v[64:67]
	s_setprio 0
	s_barrier
	s_add_i32 s0, s0, s56
	v_lshl_add_u64 v[232:233], s[52:53], 0, v[170:171]
	s_mov_b32 m0, s0
	ds_read_b128 v[188:191], v198 offset:16384
	ds_read_b128 v[192:195], v198 offset:17408
	ds_read_b128 v[200:203], v198 offset:18432
	ds_read_b128 v[204:207], v198 offset:19456
	ds_read_b128 v[208:211], v198 offset:20480
	ds_read_b128 v[212:215], v198 offset:21504
	ds_read_b128 v[216:219], v198 offset:22528
	ds_read_b128 v[228:231], v198 offset:23552
	global_load_lds_dwordx4 v[232:233], off
	s_add_i32 m0, s0, 0x2000
	s_add_u32 s0, s52, 0x40000
	v_lshl_add_u64 v[234:235], s[52:53], 0, v[156:157]
	s_addc_u32 s1, s53, 0
	s_add_i32 s12, s12, s56
	global_load_lds_dwordx4 v[234:235], off
	s_mov_b32 m0, s12
	v_lshl_add_u64 v[238:239], s[54:55], 0, v[154:155]
	global_load_lds_dwordx4 v170, s[0:1]
	s_add_i32 m0, s12, 0x2000
	s_nop 0
	global_load_lds_dwordx4 v156, s[0:1]
	v_lshl_add_u64 v[236:237], s[54:55], 0, v[152:153]
	s_nop 0
	s_waitcnt lgkmcnt(0)
	s_barrier
	s_setprio 1
	s_waitcnt lgkmcnt(0)
	v_mfma_f32_16x16x32_bf16 v[60:63], v[128:131], v[188:191], 0
	v_mfma_f32_16x16x32_bf16 v[56:59], v[136:139], v[188:191], 0
	v_mfma_f32_16x16x32_bf16 v[44:47], v[128:131], v[200:203], 0
	v_mfma_f32_16x16x32_bf16 v[40:43], v[136:139], v[200:203], 0
	v_mfma_f32_16x16x32_bf16 v[28:31], v[128:131], v[208:211], 0
	v_mfma_f32_16x16x32_bf16 v[24:27], v[136:139], v[208:211], 0
	v_mfma_f32_16x16x32_bf16 v[12:15], v[128:131], v[216:219], 0
	v_mfma_f32_16x16x32_bf16 v[8:11], v[136:139], v[216:219], 0
	v_mfma_f32_16x16x32_bf16 v[60:63], v[132:135], v[192:195], v[60:63]
	v_mfma_f32_16x16x32_bf16 v[56:59], v[140:143], v[192:195], v[56:59]
	v_mfma_f32_16x16x32_bf16 v[44:47], v[132:135], v[204:207], v[44:47]
	v_mfma_f32_16x16x32_bf16 v[40:43], v[140:143], v[204:207], v[40:43]
	v_mfma_f32_16x16x32_bf16 v[28:31], v[132:135], v[212:215], v[28:31]
	v_mfma_f32_16x16x32_bf16 v[24:27], v[140:143], v[212:215], v[24:27]
	v_mfma_f32_16x16x32_bf16 v[12:15], v[132:135], v[228:231], v[12:15]
	v_mfma_f32_16x16x32_bf16 v[8:11], v[140:143], v[228:231], v[8:11]
	s_setprio 0
	s_setprio 1
	v_mfma_f32_16x16x32_bf16 v[52:55], v[144:147], v[188:191], 0
	v_mfma_f32_16x16x32_bf16 v[48:51], v[164:167], v[188:191], 0
	v_mfma_f32_16x16x32_bf16 v[36:39], v[144:147], v[200:203], 0
	v_mfma_f32_16x16x32_bf16 v[32:35], v[164:167], v[200:203], 0
	v_mfma_f32_16x16x32_bf16 v[20:23], v[144:147], v[208:211], 0
	v_mfma_f32_16x16x32_bf16 v[16:19], v[164:167], v[208:211], 0
	v_mfma_f32_16x16x32_bf16 v[4:7], v[144:147], v[216:219], 0
	v_mfma_f32_16x16x32_bf16 v[0:3], v[164:167], v[216:219], 0
	v_mfma_f32_16x16x32_bf16 v[52:55], v[148:151], v[192:195], v[52:55]
	v_mfma_f32_16x16x32_bf16 v[48:51], v[184:187], v[192:195], v[48:51]
	v_mfma_f32_16x16x32_bf16 v[36:39], v[148:151], v[204:207], v[36:39]
	v_mfma_f32_16x16x32_bf16 v[32:35], v[184:187], v[204:207], v[32:35]
	v_mfma_f32_16x16x32_bf16 v[20:23], v[148:151], v[212:215], v[20:23]
	v_mfma_f32_16x16x32_bf16 v[16:19], v[184:187], v[212:215], v[16:19]
	v_mfma_f32_16x16x32_bf16 v[4:7], v[148:151], v[228:231], v[4:7]
	v_mfma_f32_16x16x32_bf16 v[0:3], v[184:187], v[228:231], v[0:3]
	s_setprio 0
	s_barrier
	s_add_i32 s12, 0, 0x18000
	s_add_i32 s13, 0, 0x1c000
	v_add_u32_e32 v140, s12, v197
	v_add_u32_e32 v184, s13, v197
	ds_read_b128 v[128:131], v140
	ds_read_b128 v[132:135], v140 offset:1024
	ds_read_b128 v[136:139], v140 offset:2048
	ds_read_b128 v[140:143], v140 offset:3072
	ds_read_b128 v[144:147], v184
	ds_read_b128 v[148:151], v184 offset:1024
	ds_read_b128 v[164:167], v184 offset:2048
	ds_read_b128 v[184:187], v184 offset:3072
	s_add_u32 s0, s54, 0x40000
	s_addc_u32 s1, s55, 0
	s_mov_b32 m0, s58
	ds_read_b128 v[188:191], v198 offset:32768
	ds_read_b128 v[192:195], v198 offset:33792
	ds_read_b128 v[200:203], v198 offset:34816
	ds_read_b128 v[204:207], v198 offset:35840
	ds_read_b128 v[208:211], v198 offset:36864
	ds_read_b128 v[212:215], v198 offset:37888
	ds_read_b128 v[216:219], v198 offset:38912
	ds_read_b128 v[228:231], v198 offset:39936
	global_load_lds_dwordx4 v152, s[0:1]
	s_mov_b32 m0, s59
	s_nop 0
	global_load_lds_dwordx4 v154, s[0:1]
	s_mov_b32 m0, s47
	s_nop 0
	global_load_lds_dwordx4 v[236:237], off
	s_mov_b32 m0, s57
	s_nop 0
	global_load_lds_dwordx4 v[238:239], off
	s_waitcnt vmcnt(8)
	s_waitcnt lgkmcnt(0)
	s_barrier
	s_setprio 1
	s_waitcnt lgkmcnt(0)
	v_mfma_f32_16x16x32_bf16 v[124:127], v[128:131], v[188:191], v[124:127]
	v_mfma_f32_16x16x32_bf16 v[120:123], v[136:139], v[188:191], v[120:123]
	v_mfma_f32_16x16x32_bf16 v[108:111], v[128:131], v[200:203], v[108:111]
	v_mfma_f32_16x16x32_bf16 v[104:107], v[136:139], v[200:203], v[104:107]
	v_mfma_f32_16x16x32_bf16 v[92:95], v[128:131], v[208:211], v[92:95]
	v_mfma_f32_16x16x32_bf16 v[88:91], v[136:139], v[208:211], v[88:91]
	v_mfma_f32_16x16x32_bf16 v[76:79], v[128:131], v[216:219], v[76:79]
	v_mfma_f32_16x16x32_bf16 v[72:75], v[136:139], v[216:219], v[72:75]
	v_mfma_f32_16x16x32_bf16 v[124:127], v[132:135], v[192:195], v[124:127]
	v_mfma_f32_16x16x32_bf16 v[120:123], v[140:143], v[192:195], v[120:123]
	v_mfma_f32_16x16x32_bf16 v[108:111], v[132:135], v[204:207], v[108:111]
	v_mfma_f32_16x16x32_bf16 v[104:107], v[140:143], v[204:207], v[104:107]
	v_mfma_f32_16x16x32_bf16 v[92:95], v[132:135], v[212:215], v[92:95]
	v_mfma_f32_16x16x32_bf16 v[88:91], v[140:143], v[212:215], v[88:91]
	v_mfma_f32_16x16x32_bf16 v[76:79], v[132:135], v[228:231], v[76:79]
	v_mfma_f32_16x16x32_bf16 v[72:75], v[140:143], v[228:231], v[72:75]
	s_setprio 0
	s_setprio 1
	v_mfma_f32_16x16x32_bf16 v[116:119], v[144:147], v[188:191], v[116:119]
	v_mfma_f32_16x16x32_bf16 v[112:115], v[164:167], v[188:191], v[112:115]
	v_mfma_f32_16x16x32_bf16 v[100:103], v[144:147], v[200:203], v[100:103]
	v_mfma_f32_16x16x32_bf16 v[96:99], v[164:167], v[200:203], v[96:99]
	v_mfma_f32_16x16x32_bf16 v[84:87], v[144:147], v[208:211], v[84:87]
	v_mfma_f32_16x16x32_bf16 v[80:83], v[164:167], v[208:211], v[80:83]
	v_mfma_f32_16x16x32_bf16 v[68:71], v[144:147], v[216:219], v[68:71]
	v_mfma_f32_16x16x32_bf16 v[64:67], v[164:167], v[216:219], v[64:67]
	v_mfma_f32_16x16x32_bf16 v[116:119], v[148:151], v[192:195], v[116:119]
	v_mfma_f32_16x16x32_bf16 v[112:115], v[184:187], v[192:195], v[112:115]
	v_mfma_f32_16x16x32_bf16 v[100:103], v[148:151], v[204:207], v[100:103]
	v_mfma_f32_16x16x32_bf16 v[96:99], v[184:187], v[204:207], v[96:99]
	v_mfma_f32_16x16x32_bf16 v[84:87], v[148:151], v[212:215], v[84:87]
	v_mfma_f32_16x16x32_bf16 v[80:83], v[184:187], v[212:215], v[80:83]
	v_mfma_f32_16x16x32_bf16 v[68:71], v[148:151], v[228:231], v[68:71]
	v_mfma_f32_16x16x32_bf16 v[64:67], v[184:187], v[228:231], v[64:67]
	s_setprio 0
	s_barrier
	s_add_i32 s0, s12, s56
	v_lshl_add_u64 v[232:233], v[232:233], 0, s[16:17]
	s_mov_b32 m0, s0
	ds_read_b128 v[188:191], v198 offset:49152
	ds_read_b128 v[192:195], v198 offset:50176
	ds_read_b128 v[200:203], v198 offset:51200
	ds_read_b128 v[204:207], v198 offset:52224
	ds_read_b128 v[208:211], v198 offset:53248
	ds_read_b128 v[212:215], v198 offset:54272
	ds_read_b128 v[216:219], v198 offset:55296
	ds_read_b128 v[228:231], v198 offset:56320
	global_load_lds_dwordx4 v[232:233], off
	s_add_i32 m0, s0, 0x2000
	s_add_u32 s0, s52, 0x40080
	v_lshl_add_u64 v[232:233], v[234:235], 0, s[16:17]
	s_addc_u32 s1, s53, 0
	s_add_i32 s12, s13, s56
	global_load_lds_dwordx4 v[232:233], off
	s_mov_b32 m0, s12
	s_nop 0
	global_load_lds_dwordx4 v170, s[0:1]
	s_add_i32 m0, s12, 0x2000
	s_nop 0
	global_load_lds_dwordx4 v156, s[0:1]
	v_lshl_add_u64 v[232:233], v[236:237], 0, s[16:17]
	s_mov_b32 m0, s60
	s_nop 0
	global_load_lds_dwordx4 v[232:233], off
	v_lshl_add_u64 v[232:233], v[238:239], 0, s[16:17]
	s_mov_b32 m0, s61
	s_nop 0
	global_load_lds_dwordx4 v[232:233], off
	s_waitcnt vmcnt(6)
	s_waitcnt lgkmcnt(0)
	s_barrier
	s_setprio 1
	s_waitcnt lgkmcnt(0)
	v_mfma_f32_16x16x32_bf16 v[60:63], v[128:131], v[188:191], v[60:63]
	v_mfma_f32_16x16x32_bf16 v[56:59], v[136:139], v[188:191], v[56:59]
	v_mfma_f32_16x16x32_bf16 v[44:47], v[128:131], v[200:203], v[44:47]
	v_mfma_f32_16x16x32_bf16 v[40:43], v[136:139], v[200:203], v[40:43]
	v_mfma_f32_16x16x32_bf16 v[28:31], v[128:131], v[208:211], v[28:31]
	v_mfma_f32_16x16x32_bf16 v[24:27], v[136:139], v[208:211], v[24:27]
	v_mfma_f32_16x16x32_bf16 v[12:15], v[128:131], v[216:219], v[12:15]
	v_mfma_f32_16x16x32_bf16 v[8:11], v[136:139], v[216:219], v[8:11]
	v_mfma_f32_16x16x32_bf16 v[60:63], v[132:135], v[192:195], v[60:63]
	v_mfma_f32_16x16x32_bf16 v[56:59], v[140:143], v[192:195], v[56:59]
	v_mfma_f32_16x16x32_bf16 v[44:47], v[132:135], v[204:207], v[44:47]
	v_mfma_f32_16x16x32_bf16 v[40:43], v[140:143], v[204:207], v[40:43]
	v_mfma_f32_16x16x32_bf16 v[28:31], v[132:135], v[212:215], v[28:31]
	v_mfma_f32_16x16x32_bf16 v[24:27], v[140:143], v[212:215], v[24:27]
	v_mfma_f32_16x16x32_bf16 v[12:15], v[132:135], v[228:231], v[12:15]
	v_mfma_f32_16x16x32_bf16 v[8:11], v[140:143], v[228:231], v[8:11]
	s_setprio 0
	s_setprio 1
	v_mfma_f32_16x16x32_bf16 v[52:55], v[144:147], v[188:191], v[52:55]
	v_mfma_f32_16x16x32_bf16 v[48:51], v[164:167], v[188:191], v[48:51]
	v_mfma_f32_16x16x32_bf16 v[36:39], v[144:147], v[200:203], v[36:39]
	v_mfma_f32_16x16x32_bf16 v[32:35], v[164:167], v[200:203], v[32:35]
	v_mfma_f32_16x16x32_bf16 v[20:23], v[144:147], v[208:211], v[20:23]
	v_mfma_f32_16x16x32_bf16 v[16:19], v[164:167], v[208:211], v[16:19]
	v_mfma_f32_16x16x32_bf16 v[4:7], v[144:147], v[216:219], v[4:7]
	v_mfma_f32_16x16x32_bf16 v[0:3], v[164:167], v[216:219], v[0:3]
	v_mfma_f32_16x16x32_bf16 v[52:55], v[148:151], v[192:195], v[52:55]
	v_mfma_f32_16x16x32_bf16 v[48:51], v[184:187], v[192:195], v[48:51]
	v_mfma_f32_16x16x32_bf16 v[36:39], v[148:151], v[204:207], v[36:39]
	v_mfma_f32_16x16x32_bf16 v[32:35], v[184:187], v[204:207], v[32:35]
	v_mfma_f32_16x16x32_bf16 v[20:23], v[148:151], v[212:215], v[20:23]
	v_mfma_f32_16x16x32_bf16 v[16:19], v[184:187], v[212:215], v[16:19]
	v_mfma_f32_16x16x32_bf16 v[4:7], v[148:151], v[228:231], v[4:7]
	v_mfma_f32_16x16x32_bf16 v[0:3], v[184:187], v[228:231], v[0:3]
	s_setprio 0
	s_barrier
	s_add_i32 s66, s66, 2
	s_add_u32 s64, s64, 0x100
	s_addc_u32 s65, s65, 0
	s_cmp_gt_u32 s66, 13
	s_mov_b64 s[48:49], s[50:51]
.LBB0_776:
	s_add_u32 s50, s48, 0x100
	s_addc_u32 s51, s49, 0
	s_add_i32 s0, 0, 0x10000
	s_cmp_eq_u32 s66, 12
	s_cselect_b32 s55, s37, s51
	s_cselect_b32 s54, s45, s50
	s_cselect_b32 s53, s35, s65
	s_cselect_b32 s52, s63, s64
	s_add_i32 s12, 0, 0x14000
	v_add_u32_e32 v140, s0, v197
	v_add_u32_e32 v184, s12, v197
	ds_read_b128 v[128:131], v140
	ds_read_b128 v[132:135], v140 offset:1024
	ds_read_b128 v[136:139], v140 offset:2048
	ds_read_b128 v[140:143], v140 offset:3072
	ds_read_b128 v[144:147], v184
	ds_read_b128 v[148:151], v184 offset:1024
	ds_read_b128 v[164:167], v184 offset:2048
	ds_read_b128 v[184:187], v184 offset:3072
	s_add_i32 m0, s47, 0xc000
	ds_read_b128 v[188:191], v198
	ds_read_b128 v[192:195], v198 offset:1024
	ds_read_b128 v[200:203], v198 offset:2048
	ds_read_b128 v[204:207], v198 offset:3072
	ds_read_b128 v[208:211], v198 offset:4096
	ds_read_b128 v[212:215], v198 offset:5120
	ds_read_b128 v[216:219], v198 offset:6144
	ds_read_b128 v[228:231], v198 offset:7168
	global_load_lds_dwordx4 v160, s[48:49]
	s_add_i32 m0, s47, 0xe000
	s_nop 0
	global_load_lds_dwordx4 v162, s[48:49]
	s_waitcnt vmcnt(8)
	s_waitcnt lgkmcnt(0)
	s_barrier
	s_setprio 1
	s_waitcnt lgkmcnt(0)
	v_mfma_f32_16x16x32_bf16 v[124:127], v[128:131], v[188:191], v[124:127]
	v_mfma_f32_16x16x32_bf16 v[120:123], v[136:139], v[188:191], v[120:123]
	v_mfma_f32_16x16x32_bf16 v[108:111], v[128:131], v[200:203], v[108:111]
	v_mfma_f32_16x16x32_bf16 v[104:107], v[136:139], v[200:203], v[104:107]
	v_mfma_f32_16x16x32_bf16 v[92:95], v[128:131], v[208:211], v[92:95]
	v_mfma_f32_16x16x32_bf16 v[88:91], v[136:139], v[208:211], v[88:91]
	v_mfma_f32_16x16x32_bf16 v[76:79], v[128:131], v[216:219], v[76:79]
	v_mfma_f32_16x16x32_bf16 v[72:75], v[136:139], v[216:219], v[72:75]
	v_mfma_f32_16x16x32_bf16 v[124:127], v[132:135], v[192:195], v[124:127]
	v_mfma_f32_16x16x32_bf16 v[120:123], v[140:143], v[192:195], v[120:123]
	v_mfma_f32_16x16x32_bf16 v[108:111], v[132:135], v[204:207], v[108:111]
	v_mfma_f32_16x16x32_bf16 v[104:107], v[140:143], v[204:207], v[104:107]
	v_mfma_f32_16x16x32_bf16 v[92:95], v[132:135], v[212:215], v[92:95]
	v_mfma_f32_16x16x32_bf16 v[88:91], v[140:143], v[212:215], v[88:91]
	v_mfma_f32_16x16x32_bf16 v[76:79], v[132:135], v[228:231], v[76:79]
	v_mfma_f32_16x16x32_bf16 v[72:75], v[140:143], v[228:231], v[72:75]
	s_setprio 0
	s_setprio 1
	v_mfma_f32_16x16x32_bf16 v[116:119], v[144:147], v[188:191], v[116:119]
	v_mfma_f32_16x16x32_bf16 v[112:115], v[164:167], v[188:191], v[112:115]
	v_mfma_f32_16x16x32_bf16 v[100:103], v[144:147], v[200:203], v[100:103]
	v_mfma_f32_16x16x32_bf16 v[96:99], v[164:167], v[200:203], v[96:99]
	v_mfma_f32_16x16x32_bf16 v[84:87], v[144:147], v[208:211], v[84:87]
	v_mfma_f32_16x16x32_bf16 v[80:83], v[164:167], v[208:211], v[80:83]
	v_mfma_f32_16x16x32_bf16 v[68:71], v[144:147], v[216:219], v[68:71]
	v_mfma_f32_16x16x32_bf16 v[64:67], v[164:167], v[216:219], v[64:67]
	v_mfma_f32_16x16x32_bf16 v[116:119], v[148:151], v[192:195], v[116:119]
	v_mfma_f32_16x16x32_bf16 v[112:115], v[184:187], v[192:195], v[112:115]
	v_mfma_f32_16x16x32_bf16 v[100:103], v[148:151], v[204:207], v[100:103]
	v_mfma_f32_16x16x32_bf16 v[96:99], v[184:187], v[204:207], v[96:99]
	v_mfma_f32_16x16x32_bf16 v[84:87], v[148:151], v[212:215], v[84:87]
	v_mfma_f32_16x16x32_bf16 v[80:83], v[184:187], v[212:215], v[80:83]
	v_mfma_f32_16x16x32_bf16 v[68:71], v[148:151], v[228:231], v[68:71]
	v_mfma_f32_16x16x32_bf16 v[64:67], v[184:187], v[228:231], v[64:67]
	s_setprio 0
	s_barrier
	s_add_i32 s0, s0, s56
	v_lshl_add_u64 v[232:233], s[52:53], 0, v[170:171]
	s_mov_b32 m0, s0
	ds_read_b128 v[188:191], v198 offset:16384
	ds_read_b128 v[192:195], v198 offset:17408
	ds_read_b128 v[200:203], v198 offset:18432
	ds_read_b128 v[204:207], v198 offset:19456
	ds_read_b128 v[208:211], v198 offset:20480
	ds_read_b128 v[212:215], v198 offset:21504
	ds_read_b128 v[216:219], v198 offset:22528
	ds_read_b128 v[228:231], v198 offset:23552
	global_load_lds_dwordx4 v[232:233], off
	s_add_i32 m0, s0, 0x2000
	s_add_u32 s0, s52, 0x40000
	v_lshl_add_u64 v[234:235], s[52:53], 0, v[156:157]
	s_addc_u32 s1, s53, 0
	s_add_i32 s12, s12, s56
	global_load_lds_dwordx4 v[234:235], off
	s_mov_b32 m0, s12
	v_lshl_add_u64 v[238:239], s[54:55], 0, v[154:155]
	global_load_lds_dwordx4 v170, s[0:1]
	s_add_i32 m0, s12, 0x2000
	s_nop 0
	global_load_lds_dwordx4 v156, s[0:1]
	v_lshl_add_u64 v[236:237], s[54:55], 0, v[152:153]
	s_waitcnt vmcnt(6)
	s_waitcnt lgkmcnt(0)
	s_barrier
	s_setprio 1
	s_waitcnt lgkmcnt(0)
	v_mfma_f32_16x16x32_bf16 v[60:63], v[128:131], v[188:191], v[60:63]
	v_mfma_f32_16x16x32_bf16 v[56:59], v[136:139], v[188:191], v[56:59]
	v_mfma_f32_16x16x32_bf16 v[44:47], v[128:131], v[200:203], v[44:47]
	v_mfma_f32_16x16x32_bf16 v[40:43], v[136:139], v[200:203], v[40:43]
	v_mfma_f32_16x16x32_bf16 v[28:31], v[128:131], v[208:211], v[28:31]
	v_mfma_f32_16x16x32_bf16 v[24:27], v[136:139], v[208:211], v[24:27]
	v_mfma_f32_16x16x32_bf16 v[12:15], v[128:131], v[216:219], v[12:15]
	v_mfma_f32_16x16x32_bf16 v[8:11], v[136:139], v[216:219], v[8:11]
	v_mfma_f32_16x16x32_bf16 v[60:63], v[132:135], v[192:195], v[60:63]
	v_mfma_f32_16x16x32_bf16 v[56:59], v[140:143], v[192:195], v[56:59]
	v_mfma_f32_16x16x32_bf16 v[44:47], v[132:135], v[204:207], v[44:47]
	v_mfma_f32_16x16x32_bf16 v[40:43], v[140:143], v[204:207], v[40:43]
	v_mfma_f32_16x16x32_bf16 v[28:31], v[132:135], v[212:215], v[28:31]
	v_mfma_f32_16x16x32_bf16 v[24:27], v[140:143], v[212:215], v[24:27]
	v_mfma_f32_16x16x32_bf16 v[12:15], v[132:135], v[228:231], v[12:15]
	v_mfma_f32_16x16x32_bf16 v[8:11], v[140:143], v[228:231], v[8:11]
	s_setprio 0
	s_setprio 1
	v_mfma_f32_16x16x32_bf16 v[52:55], v[144:147], v[188:191], v[52:55]
	v_mfma_f32_16x16x32_bf16 v[48:51], v[164:167], v[188:191], v[48:51]
	v_mfma_f32_16x16x32_bf16 v[36:39], v[144:147], v[200:203], v[36:39]
	v_mfma_f32_16x16x32_bf16 v[32:35], v[164:167], v[200:203], v[32:35]
	v_mfma_f32_16x16x32_bf16 v[20:23], v[144:147], v[208:211], v[20:23]
	v_mfma_f32_16x16x32_bf16 v[16:19], v[164:167], v[208:211], v[16:19]
	v_mfma_f32_16x16x32_bf16 v[4:7], v[144:147], v[216:219], v[4:7]
	v_mfma_f32_16x16x32_bf16 v[0:3], v[164:167], v[216:219], v[0:3]
	v_mfma_f32_16x16x32_bf16 v[52:55], v[148:151], v[192:195], v[52:55]
	v_mfma_f32_16x16x32_bf16 v[48:51], v[184:187], v[192:195], v[48:51]
	v_mfma_f32_16x16x32_bf16 v[36:39], v[148:151], v[204:207], v[36:39]
	v_mfma_f32_16x16x32_bf16 v[32:35], v[184:187], v[204:207], v[32:35]
	v_mfma_f32_16x16x32_bf16 v[20:23], v[148:151], v[212:215], v[20:23]
	v_mfma_f32_16x16x32_bf16 v[16:19], v[184:187], v[212:215], v[16:19]
	v_mfma_f32_16x16x32_bf16 v[4:7], v[148:151], v[228:231], v[4:7]
	v_mfma_f32_16x16x32_bf16 v[0:3], v[184:187], v[228:231], v[0:3]
	s_setprio 0
	s_barrier
	s_add_i32 s12, 0, 0x18000
	s_add_i32 s13, 0, 0x1c000
	v_add_u32_e32 v140, s12, v197
	v_add_u32_e32 v184, s13, v197
	ds_read_b128 v[128:131], v140
	ds_read_b128 v[132:135], v140 offset:1024
	ds_read_b128 v[136:139], v140 offset:2048
	ds_read_b128 v[140:143], v140 offset:3072
	ds_read_b128 v[144:147], v184
	ds_read_b128 v[148:151], v184 offset:1024
	ds_read_b128 v[164:167], v184 offset:2048
	ds_read_b128 v[184:187], v184 offset:3072
	s_add_u32 s0, s54, 0x40000
	s_addc_u32 s1, s55, 0
	s_mov_b32 m0, s58
	ds_read_b128 v[188:191], v198 offset:32768
	ds_read_b128 v[192:195], v198 offset:33792
	ds_read_b128 v[200:203], v198 offset:34816
	ds_read_b128 v[204:207], v198 offset:35840
	ds_read_b128 v[208:211], v198 offset:36864
	ds_read_b128 v[212:215], v198 offset:37888
	ds_read_b128 v[216:219], v198 offset:38912
	ds_read_b128 v[228:231], v198 offset:39936
	global_load_lds_dwordx4 v152, s[0:1]
	s_mov_b32 m0, s59
	s_nop 0
	global_load_lds_dwordx4 v154, s[0:1]
	s_mov_b32 m0, s47
	s_nop 0
	global_load_lds_dwordx4 v[236:237], off
	s_mov_b32 m0, s57
	s_nop 0
	global_load_lds_dwordx4 v[238:239], off
	s_waitcnt vmcnt(8)
	s_waitcnt lgkmcnt(0)
	s_barrier
	s_setprio 1
	s_waitcnt lgkmcnt(0)
	v_mfma_f32_16x16x32_bf16 v[124:127], v[128:131], v[188:191], v[124:127]
	v_mfma_f32_16x16x32_bf16 v[120:123], v[136:139], v[188:191], v[120:123]
	v_mfma_f32_16x16x32_bf16 v[108:111], v[128:131], v[200:203], v[108:111]
	v_mfma_f32_16x16x32_bf16 v[104:107], v[136:139], v[200:203], v[104:107]
	v_mfma_f32_16x16x32_bf16 v[92:95], v[128:131], v[208:211], v[92:95]
	v_mfma_f32_16x16x32_bf16 v[88:91], v[136:139], v[208:211], v[88:91]
	v_mfma_f32_16x16x32_bf16 v[76:79], v[128:131], v[216:219], v[76:79]
	v_mfma_f32_16x16x32_bf16 v[72:75], v[136:139], v[216:219], v[72:75]
	v_mfma_f32_16x16x32_bf16 v[124:127], v[132:135], v[192:195], v[124:127]
	v_mfma_f32_16x16x32_bf16 v[120:123], v[140:143], v[192:195], v[120:123]
	v_mfma_f32_16x16x32_bf16 v[108:111], v[132:135], v[204:207], v[108:111]
	v_mfma_f32_16x16x32_bf16 v[104:107], v[140:143], v[204:207], v[104:107]
	v_mfma_f32_16x16x32_bf16 v[92:95], v[132:135], v[212:215], v[92:95]
	v_mfma_f32_16x16x32_bf16 v[88:91], v[140:143], v[212:215], v[88:91]
	v_mfma_f32_16x16x32_bf16 v[76:79], v[132:135], v[228:231], v[76:79]
	v_mfma_f32_16x16x32_bf16 v[72:75], v[140:143], v[228:231], v[72:75]
	s_setprio 0
	s_setprio 1
	v_mfma_f32_16x16x32_bf16 v[116:119], v[144:147], v[188:191], v[116:119]
	v_mfma_f32_16x16x32_bf16 v[112:115], v[164:167], v[188:191], v[112:115]
	v_mfma_f32_16x16x32_bf16 v[100:103], v[144:147], v[200:203], v[100:103]
	v_mfma_f32_16x16x32_bf16 v[96:99], v[164:167], v[200:203], v[96:99]
	v_mfma_f32_16x16x32_bf16 v[84:87], v[144:147], v[208:211], v[84:87]
	v_mfma_f32_16x16x32_bf16 v[80:83], v[164:167], v[208:211], v[80:83]
	v_mfma_f32_16x16x32_bf16 v[68:71], v[144:147], v[216:219], v[68:71]
	v_mfma_f32_16x16x32_bf16 v[64:67], v[164:167], v[216:219], v[64:67]
	v_mfma_f32_16x16x32_bf16 v[116:119], v[148:151], v[192:195], v[116:119]
	v_mfma_f32_16x16x32_bf16 v[112:115], v[184:187], v[192:195], v[112:115]
	v_mfma_f32_16x16x32_bf16 v[100:103], v[148:151], v[204:207], v[100:103]
	v_mfma_f32_16x16x32_bf16 v[96:99], v[184:187], v[204:207], v[96:99]
	v_mfma_f32_16x16x32_bf16 v[84:87], v[148:151], v[212:215], v[84:87]
	v_mfma_f32_16x16x32_bf16 v[80:83], v[184:187], v[212:215], v[80:83]
	v_mfma_f32_16x16x32_bf16 v[68:71], v[148:151], v[228:231], v[68:71]
	v_mfma_f32_16x16x32_bf16 v[64:67], v[184:187], v[228:231], v[64:67]
	s_setprio 0
	s_barrier
	s_add_i32 s0, s12, s56
	v_lshl_add_u64 v[232:233], v[232:233], 0, s[16:17]
	s_mov_b32 m0, s0
	ds_read_b128 v[188:191], v198 offset:49152
	ds_read_b128 v[192:195], v198 offset:50176
	ds_read_b128 v[200:203], v198 offset:51200
	ds_read_b128 v[204:207], v198 offset:52224
	ds_read_b128 v[208:211], v198 offset:53248
	ds_read_b128 v[212:215], v198 offset:54272
	ds_read_b128 v[216:219], v198 offset:55296
	ds_read_b128 v[228:231], v198 offset:56320
	global_load_lds_dwordx4 v[232:233], off
	s_add_i32 m0, s0, 0x2000
	s_add_u32 s0, s52, 0x40080
	v_lshl_add_u64 v[232:233], v[234:235], 0, s[16:17]
	s_addc_u32 s1, s53, 0
	s_add_i32 s12, s13, s56
	global_load_lds_dwordx4 v[232:233], off
	s_mov_b32 m0, s12
	s_nop 0
	global_load_lds_dwordx4 v170, s[0:1]
	s_add_i32 m0, s12, 0x2000
	s_nop 0
	global_load_lds_dwordx4 v156, s[0:1]
	v_lshl_add_u64 v[232:233], v[236:237], 0, s[16:17]
	s_mov_b32 m0, s60
	s_nop 0
	global_load_lds_dwordx4 v[232:233], off
	v_lshl_add_u64 v[232:233], v[238:239], 0, s[16:17]
	s_mov_b32 m0, s61
	s_nop 0
	global_load_lds_dwordx4 v[232:233], off
	s_waitcnt vmcnt(6)
	s_waitcnt lgkmcnt(0)
	s_barrier
	s_setprio 1
	s_waitcnt lgkmcnt(0)
	v_mfma_f32_16x16x32_bf16 v[60:63], v[128:131], v[188:191], v[60:63]
	v_mfma_f32_16x16x32_bf16 v[56:59], v[136:139], v[188:191], v[56:59]
	v_mfma_f32_16x16x32_bf16 v[44:47], v[128:131], v[200:203], v[44:47]
	v_mfma_f32_16x16x32_bf16 v[40:43], v[136:139], v[200:203], v[40:43]
	v_mfma_f32_16x16x32_bf16 v[28:31], v[128:131], v[208:211], v[28:31]
	v_mfma_f32_16x16x32_bf16 v[24:27], v[136:139], v[208:211], v[24:27]
	v_mfma_f32_16x16x32_bf16 v[12:15], v[128:131], v[216:219], v[12:15]
	v_mfma_f32_16x16x32_bf16 v[8:11], v[136:139], v[216:219], v[8:11]
	v_mfma_f32_16x16x32_bf16 v[60:63], v[132:135], v[192:195], v[60:63]
	v_mfma_f32_16x16x32_bf16 v[56:59], v[140:143], v[192:195], v[56:59]
	v_mfma_f32_16x16x32_bf16 v[44:47], v[132:135], v[204:207], v[44:47]
	v_mfma_f32_16x16x32_bf16 v[40:43], v[140:143], v[204:207], v[40:43]
	v_mfma_f32_16x16x32_bf16 v[28:31], v[132:135], v[212:215], v[28:31]
	v_mfma_f32_16x16x32_bf16 v[24:27], v[140:143], v[212:215], v[24:27]
	v_mfma_f32_16x16x32_bf16 v[12:15], v[132:135], v[228:231], v[12:15]
	v_mfma_f32_16x16x32_bf16 v[8:11], v[140:143], v[228:231], v[8:11]
	s_setprio 0
	s_setprio 1
	v_mfma_f32_16x16x32_bf16 v[52:55], v[144:147], v[188:191], v[52:55]
	v_mfma_f32_16x16x32_bf16 v[48:51], v[164:167], v[188:191], v[48:51]
	v_mfma_f32_16x16x32_bf16 v[36:39], v[144:147], v[200:203], v[36:39]
	v_mfma_f32_16x16x32_bf16 v[32:35], v[164:167], v[200:203], v[32:35]
	v_mfma_f32_16x16x32_bf16 v[20:23], v[144:147], v[208:211], v[20:23]
	v_mfma_f32_16x16x32_bf16 v[16:19], v[164:167], v[208:211], v[16:19]
	v_mfma_f32_16x16x32_bf16 v[4:7], v[144:147], v[216:219], v[4:7]
	v_mfma_f32_16x16x32_bf16 v[0:3], v[164:167], v[216:219], v[0:3]
	v_mfma_f32_16x16x32_bf16 v[52:55], v[148:151], v[192:195], v[52:55]
	v_mfma_f32_16x16x32_bf16 v[48:51], v[184:187], v[192:195], v[48:51]
	v_mfma_f32_16x16x32_bf16 v[36:39], v[148:151], v[204:207], v[36:39]
	v_mfma_f32_16x16x32_bf16 v[32:35], v[184:187], v[204:207], v[32:35]
	v_mfma_f32_16x16x32_bf16 v[20:23], v[148:151], v[212:215], v[20:23]
	v_mfma_f32_16x16x32_bf16 v[16:19], v[184:187], v[212:215], v[16:19]
	v_mfma_f32_16x16x32_bf16 v[4:7], v[148:151], v[228:231], v[4:7]
	v_mfma_f32_16x16x32_bf16 v[0:3], v[184:187], v[228:231], v[0:3]
	s_setprio 0
	s_barrier
	s_add_i32 s66, s66, 2
	s_add_u32 s64, s64, 0x100
	s_addc_u32 s65, s65, 0
	s_cmp_gt_u32 s66, 13
	s_mov_b64 s[48:49], s[50:51]
	s_cbranch_scc0 .LBB0_776
	s_and_b64 vcc, exec, s[30:31]
	s_cbranch_vccz .LBB0_779
	s_barrier

.LBB0_795:
	s_or_b64 exec, exec, s[44:45]
	s_andn2_b64 vcc, exec, s[6:7]
	s_mov_b64 s[6:7], -1
	s_cbranch_vccnz .LBB0_768
	s_andn2_b64 vcc, exec, s[8:9]
	s_cbranch_vccnz .LBB0_767
	s_mov_b32 s98, 1
	s_branch .LBB0_767

.LBB0_862:
	s_ashr_i32 s51, s50, 31
	s_lshl_b64 s[0:1], s[50:51], 19
	s_add_u32 s52, s92, s0
	s_addc_u32 s53, s93, s1
	s_and_b64 s[0:1], s[8:9], exec
	s_cselect_b32 s23, s53, s61
	s_cselect_b32 s51, s52, s60
	s_ashr_i32 s49, s48, 31
	s_lshl_b64 s[0:1], s[48:49], 19
	s_add_u32 s54, s94, s0
	s_addc_u32 s55, s95, s1
	s_and_b64 s[0:1], s[8:9], exec
	s_cselect_b32 s49, s55, s63
	s_cselect_b32 s57, s54, s62
	s_add_u32 vcc_lo, s62, 0x100
	s_addc_u32 vcc_hi, s63, 0
	s_mov_b32 s12, -2
	s_waitcnt vmcnt(0)
	s_cmp_eq_u32 s98, 1
	s_cbranch_scc0 .Lrestag_863
	s_barrier
	s_mov_b32 s98, 0
.Lrestag_863:
	s_add_u32 s62, s60, 0x100
	s_addc_u32 s63, s61, 0
	s_add_i32 s0, 0, 0x10000
	s_cmp_eq_u32 s12, 12
	s_cselect_b32 s67, s23, s63
	s_cselect_b32 s66, s51, s62
	s_cselect_b32 s65, s49, vcc_hi
	s_cselect_b32 s64, s57, vcc_lo
	s_add_i32 s13, 0, 0x14000
	v_add_u32_e32 v64, s0, v228
	v_add_u32_e32 v92, s13, v228
	ds_read_b128 v[48:51], v64
	ds_read_b128 v[52:55], v64 offset:1024
	ds_read_b128 v[60:63], v64 offset:2048
	ds_read_b128 v[64:67], v64 offset:3072
	ds_read_b128 v[72:75], v92
	ds_read_b128 v[80:83], v92 offset:1024
	ds_read_b128 v[84:87], v92 offset:2048
	ds_read_b128 v[92:95], v92 offset:3072
	s_add_i32 m0, s59, 0xc000
	ds_read_b128 v[112:115], v230
	ds_read_b128 v[164:167], v230 offset:1024
	ds_read_b128 v[194:197], v230 offset:2048
	ds_read_b128 v[198:201], v230 offset:3072
	ds_read_b128 v[202:205], v230 offset:4096
	ds_read_b128 v[206:209], v230 offset:5120
	ds_read_b128 v[210:213], v230 offset:6144
	ds_read_b128 v[214:217], v230 offset:7168
	global_load_lds_dwordx4 v190, s[60:61]
	s_add_i32 m0, s59, 0xe000
	s_nop 0
	global_load_lds_dwordx4 v192, s[60:61]
	s_nop 0
	s_waitcnt lgkmcnt(0)
	s_barrier
	s_setprio 1
	s_waitcnt lgkmcnt(0)
	v_mfma_f32_16x16x32_bf16 v[160:163], v[48:51], v[112:115], 0
	v_mfma_f32_16x16x32_bf16 v[156:159], v[60:63], v[112:115], 0
	v_mfma_f32_16x16x32_bf16 v[128:131], v[48:51], v[194:197], 0
	v_mfma_f32_16x16x32_bf16 v[124:127], v[60:63], v[194:197], 0
	v_mfma_f32_16x16x32_bf16 v[108:111], v[48:51], v[202:205], 0
	v_mfma_f32_16x16x32_bf16 v[104:107], v[60:63], v[202:205], 0
	v_mfma_f32_16x16x32_bf16 v[100:103], v[48:51], v[210:213], 0
	v_mfma_f32_16x16x32_bf16 v[96:99], v[60:63], v[210:213], 0
	v_mfma_f32_16x16x32_bf16 v[160:163], v[52:55], v[164:167], v[160:163]
	v_mfma_f32_16x16x32_bf16 v[156:159], v[64:67], v[164:167], v[156:159]
	v_mfma_f32_16x16x32_bf16 v[128:131], v[52:55], v[198:201], v[128:131]
	v_mfma_f32_16x16x32_bf16 v[124:127], v[64:67], v[198:201], v[124:127]
	v_mfma_f32_16x16x32_bf16 v[108:111], v[52:55], v[206:209], v[108:111]
	v_mfma_f32_16x16x32_bf16 v[104:107], v[64:67], v[206:209], v[104:107]
	v_mfma_f32_16x16x32_bf16 v[100:103], v[52:55], v[214:217], v[100:103]
	v_mfma_f32_16x16x32_bf16 v[96:99], v[64:67], v[214:217], v[96:99]
	s_setprio 0
	s_setprio 1
	v_mfma_f32_16x16x32_bf16 v[152:155], v[72:75], v[112:115], 0
	v_mfma_f32_16x16x32_bf16 v[120:123], v[72:75], v[194:197], 0
	v_mfma_f32_16x16x32_bf16 v[116:119], v[84:87], v[194:197], 0
	v_mfma_f32_16x16x32_bf16 v[144:147], v[72:75], v[202:205], 0
	v_mfma_f32_16x16x32_bf16 v[140:143], v[84:87], v[202:205], 0
	v_mfma_f32_16x16x32_bf16 v[136:139], v[72:75], v[210:213], 0
	v_mfma_f32_16x16x32_bf16 v[132:135], v[84:87], v[210:213], 0
	v_mfma_f32_16x16x32_bf16 v[152:155], v[80:83], v[164:167], v[152:155]
	v_mfma_f32_16x16x32_bf16 v[112:115], v[84:87], v[112:115], 0
	v_mfma_f32_16x16x32_bf16 v[120:123], v[80:83], v[198:201], v[120:123]
	v_mfma_f32_16x16x32_bf16 v[116:119], v[92:95], v[198:201], v[116:119]
	v_mfma_f32_16x16x32_bf16 v[144:147], v[80:83], v[206:209], v[144:147]
	v_mfma_f32_16x16x32_bf16 v[140:143], v[92:95], v[206:209], v[140:143]
	v_mfma_f32_16x16x32_bf16 v[136:139], v[80:83], v[214:217], v[136:139]
	v_mfma_f32_16x16x32_bf16 v[132:135], v[92:95], v[214:217], v[132:135]
	v_mfma_f32_16x16x32_bf16 v[112:115], v[92:95], v[164:167], v[112:115]
	s_setprio 0
	s_barrier
	s_add_i32 s0, s0, s96
	v_lshl_add_u64 v[218:219], s[64:65], 0, v[170:171]
	s_mov_b32 m0, s0
	ds_read_b128 v[148:151], v230 offset:16384
	ds_read_b128 v[164:167], v230 offset:17408
	ds_read_b128 v[194:197], v230 offset:18432
	ds_read_b128 v[198:201], v230 offset:19456
	ds_read_b128 v[202:205], v230 offset:20480
	ds_read_b128 v[206:209], v230 offset:21504
	ds_read_b128 v[210:213], v230 offset:22528
	ds_read_b128 v[214:217], v230 offset:23552
	global_load_lds_dwordx4 v[218:219], off
	s_add_i32 m0, s0, 0x2000
	s_add_u32 s0, s64, 0x40000
	v_lshl_add_u64 v[232:233], s[64:65], 0, v[188:189]
	s_addc_u32 s1, s65, 0
	s_add_i32 s13, s13, s96
	global_load_lds_dwordx4 v[232:233], off
	s_mov_b32 m0, s13
	v_lshl_add_u64 v[236:237], s[66:67], 0, v[186:187]
	global_load_lds_dwordx4 v170, s[0:1]
	s_add_i32 m0, s13, 0x2000
	s_nop 0
	global_load_lds_dwordx4 v188, s[0:1]
	v_lshl_add_u64 v[234:235], s[66:67], 0, v[184:185]
	s_nop 0
	s_waitcnt lgkmcnt(0)
	s_barrier
	s_setprio 1
	s_waitcnt lgkmcnt(0)
	v_mfma_f32_16x16x32_bf16 v[88:91], v[48:51], v[148:151], 0
	v_mfma_f32_16x16x32_bf16 v[76:79], v[60:63], v[148:151], 0
	v_mfma_f32_16x16x32_bf16 v[28:31], v[48:51], v[194:197], 0
	v_mfma_f32_16x16x32_bf16 v[24:27], v[60:63], v[194:197], 0
	v_mfma_f32_16x16x32_bf16 v[12:15], v[48:51], v[202:205], 0
	v_mfma_f32_16x16x32_bf16 v[8:11], v[60:63], v[202:205], 0
	v_mfma_f32_16x16x32_bf16 v[4:7], v[48:51], v[210:213], 0
	v_mfma_f32_16x16x32_bf16 v[0:3], v[60:63], v[210:213], 0
	v_mfma_f32_16x16x32_bf16 v[88:91], v[52:55], v[164:167], v[88:91]
	v_mfma_f32_16x16x32_bf16 v[76:79], v[64:67], v[164:167], v[76:79]
	v_mfma_f32_16x16x32_bf16 v[28:31], v[52:55], v[198:201], v[28:31]
	v_mfma_f32_16x16x32_bf16 v[24:27], v[64:67], v[198:201], v[24:27]
	v_mfma_f32_16x16x32_bf16 v[12:15], v[52:55], v[206:209], v[12:15]
	v_mfma_f32_16x16x32_bf16 v[8:11], v[64:67], v[206:209], v[8:11]
	v_mfma_f32_16x16x32_bf16 v[4:7], v[52:55], v[214:217], v[4:7]
	v_mfma_f32_16x16x32_bf16 v[0:3], v[64:67], v[214:217], v[0:3]
	s_setprio 0
	s_setprio 1
	v_mfma_f32_16x16x32_bf16 v[20:23], v[72:75], v[194:197], 0
	v_mfma_f32_16x16x32_bf16 v[16:19], v[84:87], v[194:197], 0
	v_mfma_f32_16x16x32_bf16 v[44:47], v[72:75], v[202:205], 0
	v_mfma_f32_16x16x32_bf16 v[40:43], v[84:87], v[202:205], 0
	v_mfma_f32_16x16x32_bf16 v[36:39], v[72:75], v[210:213], 0
	v_mfma_f32_16x16x32_bf16 v[32:35], v[84:87], v[210:213], 0
	v_mfma_f32_16x16x32_bf16 v[48:51], v[72:75], v[148:151], 0
	v_mfma_f32_16x16x32_bf16 v[52:55], v[84:87], v[148:151], 0
	v_mfma_f32_16x16x32_bf16 v[20:23], v[80:83], v[198:201], v[20:23]
	v_mfma_f32_16x16x32_bf16 v[16:19], v[92:95], v[198:201], v[16:19]
	v_mfma_f32_16x16x32_bf16 v[44:47], v[80:83], v[206:209], v[44:47]
	v_mfma_f32_16x16x32_bf16 v[40:43], v[92:95], v[206:209], v[40:43]
	v_mfma_f32_16x16x32_bf16 v[36:39], v[80:83], v[214:217], v[36:39]
	v_mfma_f32_16x16x32_bf16 v[32:35], v[92:95], v[214:217], v[32:35]
	v_mfma_f32_16x16x32_bf16 v[48:51], v[80:83], v[164:167], v[48:51]
	v_mfma_f32_16x16x32_bf16 v[52:55], v[92:95], v[164:167], v[52:55]
	s_setprio 0
	s_barrier
	s_add_i32 s13, 0, 0x18000
	s_add_i32 s60, 0, 0x1c000
	v_add_u32_e32 v68, s13, v228
	v_add_u32_e32 v92, s60, v228
	ds_read_b128 v[56:59], v68
	ds_read_b128 v[60:63], v68 offset:1024
	ds_read_b128 v[64:67], v68 offset:2048
	ds_read_b128 v[68:71], v68 offset:3072
	ds_read_b128 v[72:75], v92
	ds_read_b128 v[80:83], v92 offset:1024
	ds_read_b128 v[84:87], v92 offset:2048
	ds_read_b128 v[92:95], v92 offset:3072
	s_add_u32 s0, s66, 0x40000
	s_addc_u32 s1, s67, 0
	s_mov_b32 m0, s39
	ds_read_b128 v[148:151], v230 offset:32768
	ds_read_b128 v[164:167], v230 offset:33792
	ds_read_b128 v[194:197], v230 offset:34816
	ds_read_b128 v[198:201], v230 offset:35840
	ds_read_b128 v[202:205], v230 offset:36864
	ds_read_b128 v[206:209], v230 offset:37888
	ds_read_b128 v[210:213], v230 offset:38912
	ds_read_b128 v[214:217], v230 offset:39936
	global_load_lds_dwordx4 v184, s[0:1]
	s_mov_b32 m0, s76
	s_nop 0
	global_load_lds_dwordx4 v186, s[0:1]
	s_mov_b32 m0, s59
	s_nop 0
	global_load_lds_dwordx4 v[234:235], off
	s_mov_b32 m0, s97
	s_nop 0
	global_load_lds_dwordx4 v[236:237], off
	s_waitcnt vmcnt(8)
	s_waitcnt lgkmcnt(0)
	s_barrier
	s_setprio 1
	s_waitcnt lgkmcnt(0)
	v_mfma_f32_16x16x32_bf16 v[160:163], v[56:59], v[148:151], v[160:163]
	v_mfma_f32_16x16x32_bf16 v[156:159], v[64:67], v[148:151], v[156:159]
	v_mfma_f32_16x16x32_bf16 v[128:131], v[56:59], v[194:197], v[128:131]
	v_mfma_f32_16x16x32_bf16 v[124:127], v[64:67], v[194:197], v[124:127]
	v_mfma_f32_16x16x32_bf16 v[108:111], v[56:59], v[202:205], v[108:111]
	v_mfma_f32_16x16x32_bf16 v[104:107], v[64:67], v[202:205], v[104:107]
	v_mfma_f32_16x16x32_bf16 v[100:103], v[56:59], v[210:213], v[100:103]
	v_mfma_f32_16x16x32_bf16 v[96:99], v[64:67], v[210:213], v[96:99]
	v_mfma_f32_16x16x32_bf16 v[160:163], v[60:63], v[164:167], v[160:163]
	v_mfma_f32_16x16x32_bf16 v[156:159], v[68:71], v[164:167], v[156:159]
	v_mfma_f32_16x16x32_bf16 v[128:131], v[60:63], v[198:201], v[128:131]
	v_mfma_f32_16x16x32_bf16 v[124:127], v[68:71], v[198:201], v[124:127]
	v_mfma_f32_16x16x32_bf16 v[108:111], v[60:63], v[206:209], v[108:111]
	v_mfma_f32_16x16x32_bf16 v[104:107], v[68:71], v[206:209], v[104:107]
	v_mfma_f32_16x16x32_bf16 v[100:103], v[60:63], v[214:217], v[100:103]
	v_mfma_f32_16x16x32_bf16 v[96:99], v[68:71], v[214:217], v[96:99]
	s_setprio 0
	s_setprio 1
	v_mfma_f32_16x16x32_bf16 v[112:115], v[84:87], v[148:151], v[112:115]
	v_mfma_f32_16x16x32_bf16 v[152:155], v[72:75], v[148:151], v[152:155]
	v_mfma_f32_16x16x32_bf16 v[148:151], v[92:95], v[164:167], v[112:115]
	v_mfma_f32_16x16x32_bf16 v[112:115], v[72:75], v[194:197], v[120:123]
	v_mfma_f32_16x16x32_bf16 v[120:123], v[80:83], v[198:201], v[112:115]
	v_mfma_f32_16x16x32_bf16 v[112:115], v[84:87], v[194:197], v[116:119]
	v_mfma_f32_16x16x32_bf16 v[116:119], v[92:95], v[198:201], v[112:115]
	v_mfma_f32_16x16x32_bf16 v[112:115], v[72:75], v[202:205], v[144:147]
	v_mfma_f32_16x16x32_bf16 v[144:147], v[80:83], v[206:209], v[112:115]
	v_mfma_f32_16x16x32_bf16 v[112:115], v[84:87], v[202:205], v[140:143]
	v_mfma_f32_16x16x32_bf16 v[140:143], v[92:95], v[206:209], v[112:115]
	v_mfma_f32_16x16x32_bf16 v[112:115], v[72:75], v[210:213], v[136:139]
	v_mfma_f32_16x16x32_bf16 v[136:139], v[80:83], v[214:217], v[112:115]
	v_mfma_f32_16x16x32_bf16 v[112:115], v[84:87], v[210:213], v[132:135]
	v_mfma_f32_16x16x32_bf16 v[152:155], v[80:83], v[164:167], v[152:155]
	v_mfma_f32_16x16x32_bf16 v[132:135], v[92:95], v[214:217], v[112:115]
	s_setprio 0
	s_barrier
	s_add_i32 s0, s13, s96
	v_lshl_add_u64 v[218:219], v[218:219], 0, s[16:17]
	s_mov_b32 m0, s0
	s_nop 0
	ds_read_b128 v[112:115], v230 offset:49152
	ds_read_b128 v[164:167], v230 offset:50176
	ds_read_b128 v[194:197], v230 offset:51200
	ds_read_b128 v[198:201], v230 offset:52224
	ds_read_b128 v[202:205], v230 offset:53248
	ds_read_b128 v[206:209], v230 offset:54272
	ds_read_b128 v[210:213], v230 offset:55296
	ds_read_b128 v[214:217], v230 offset:56320
	global_load_lds_dwordx4 v[218:219], off
	s_add_i32 m0, s0, 0x2000
	s_add_u32 s0, s64, 0x40080
	v_lshl_add_u64 v[218:219], v[232:233], 0, s[16:17]
	s_addc_u32 s1, s65, 0
	s_add_i32 s13, s60, s96
	global_load_lds_dwordx4 v[218:219], off
	s_mov_b32 m0, s13
	s_nop 0
	global_load_lds_dwordx4 v170, s[0:1]
	s_add_i32 m0, s13, 0x2000
	s_nop 0
	global_load_lds_dwordx4 v188, s[0:1]
	v_lshl_add_u64 v[218:219], v[234:235], 0, s[16:17]
	s_mov_b32 m0, s75
	s_nop 0
	global_load_lds_dwordx4 v[218:219], off
	v_lshl_add_u64 v[218:219], v[236:237], 0, s[16:17]
	s_mov_b32 m0, s91
	s_nop 0
	global_load_lds_dwordx4 v[218:219], off
	s_waitcnt vmcnt(6)
	s_waitcnt lgkmcnt(0)
	s_barrier
	s_setprio 1
	s_waitcnt lgkmcnt(0)
	v_mfma_f32_16x16x32_bf16 v[88:91], v[56:59], v[112:115], v[88:91]
	v_mfma_f32_16x16x32_bf16 v[76:79], v[64:67], v[112:115], v[76:79]
	v_mfma_f32_16x16x32_bf16 v[28:31], v[56:59], v[194:197], v[28:31]
	v_mfma_f32_16x16x32_bf16 v[24:27], v[64:67], v[194:197], v[24:27]
	v_mfma_f32_16x16x32_bf16 v[12:15], v[56:59], v[202:205], v[12:15]
	v_mfma_f32_16x16x32_bf16 v[8:11], v[64:67], v[202:205], v[8:11]
	v_mfma_f32_16x16x32_bf16 v[4:7], v[56:59], v[210:213], v[4:7]
	v_mfma_f32_16x16x32_bf16 v[0:3], v[64:67], v[210:213], v[0:3]
	v_mfma_f32_16x16x32_bf16 v[88:91], v[60:63], v[164:167], v[88:91]
	v_mfma_f32_16x16x32_bf16 v[76:79], v[68:71], v[164:167], v[76:79]
	v_mfma_f32_16x16x32_bf16 v[28:31], v[60:63], v[198:201], v[28:31]
	v_mfma_f32_16x16x32_bf16 v[24:27], v[68:71], v[198:201], v[24:27]
	v_mfma_f32_16x16x32_bf16 v[12:15], v[60:63], v[206:209], v[12:15]
	v_mfma_f32_16x16x32_bf16 v[8:11], v[68:71], v[206:209], v[8:11]
	v_mfma_f32_16x16x32_bf16 v[4:7], v[60:63], v[214:217], v[4:7]
	v_mfma_f32_16x16x32_bf16 v[0:3], v[68:71], v[214:217], v[0:3]
	s_setprio 0
	s_setprio 1
	v_mfma_f32_16x16x32_bf16 v[48:51], v[72:75], v[112:115], v[48:51]
	v_mfma_f32_16x16x32_bf16 v[68:71], v[80:83], v[164:167], v[48:51]
	v_mfma_f32_16x16x32_bf16 v[48:51], v[84:87], v[112:115], v[52:55]
	v_mfma_f32_16x16x32_bf16 v[20:23], v[72:75], v[194:197], v[20:23]
	v_mfma_f32_16x16x32_bf16 v[16:19], v[84:87], v[194:197], v[16:19]
	v_mfma_f32_16x16x32_bf16 v[44:47], v[72:75], v[202:205], v[44:47]
	v_mfma_f32_16x16x32_bf16 v[40:43], v[84:87], v[202:205], v[40:43]
	v_mfma_f32_16x16x32_bf16 v[36:39], v[72:75], v[210:213], v[36:39]
	v_mfma_f32_16x16x32_bf16 v[32:35], v[84:87], v[210:213], v[32:35]
	v_mfma_f32_16x16x32_bf16 v[56:59], v[92:95], v[164:167], v[48:51]
	v_mfma_f32_16x16x32_bf16 v[20:23], v[80:83], v[198:201], v[20:23]
	v_mfma_f32_16x16x32_bf16 v[16:19], v[92:95], v[198:201], v[16:19]
	v_mfma_f32_16x16x32_bf16 v[44:47], v[80:83], v[206:209], v[44:47]
	v_mfma_f32_16x16x32_bf16 v[40:43], v[92:95], v[206:209], v[40:43]
	v_mfma_f32_16x16x32_bf16 v[36:39], v[80:83], v[214:217], v[36:39]
	v_mfma_f32_16x16x32_bf16 v[32:35], v[92:95], v[214:217], v[32:35]
	s_setprio 0
	s_barrier
	s_add_i32 s12, s12, 2
	s_add_u32 vcc_lo, vcc_lo, 0x100
	s_addc_u32 vcc_hi, vcc_hi, 0
	s_cmp_gt_u32 s12, 13
	s_mov_b64 s[60:61], s[62:63]
.LBB0_863:
	s_add_u32 s62, s60, 0x100
	s_addc_u32 s63, s61, 0
	s_add_i32 s0, 0, 0x10000
	s_cmp_eq_u32 s12, 12
	s_cselect_b32 s67, s23, s63
	s_cselect_b32 s66, s51, s62
	s_cselect_b32 s65, s49, vcc_hi
	s_cselect_b32 s64, s57, vcc_lo
	s_add_i32 s13, 0, 0x14000
	v_add_u32_e32 v64, s0, v228
	v_add_u32_e32 v92, s13, v228
	ds_read_b128 v[48:51], v64
	ds_read_b128 v[52:55], v64 offset:1024
	ds_read_b128 v[60:63], v64 offset:2048
	ds_read_b128 v[64:67], v64 offset:3072
	ds_read_b128 v[72:75], v92
	ds_read_b128 v[80:83], v92 offset:1024
	ds_read_b128 v[84:87], v92 offset:2048
	ds_read_b128 v[92:95], v92 offset:3072
	s_add_i32 m0, s59, 0xc000
	ds_read_b128 v[112:115], v230
	ds_read_b128 v[164:167], v230 offset:1024
	ds_read_b128 v[194:197], v230 offset:2048
	ds_read_b128 v[198:201], v230 offset:3072
	ds_read_b128 v[202:205], v230 offset:4096
	ds_read_b128 v[206:209], v230 offset:5120
	ds_read_b128 v[210:213], v230 offset:6144
	ds_read_b128 v[214:217], v230 offset:7168
	global_load_lds_dwordx4 v190, s[60:61]
	s_add_i32 m0, s59, 0xe000
	s_nop 0
	global_load_lds_dwordx4 v192, s[60:61]
	s_waitcnt vmcnt(8)
	s_waitcnt lgkmcnt(0)
	s_barrier
	s_setprio 1
	s_waitcnt lgkmcnt(0)
	v_mfma_f32_16x16x32_bf16 v[160:163], v[48:51], v[112:115], v[160:163]
	v_mfma_f32_16x16x32_bf16 v[156:159], v[60:63], v[112:115], v[156:159]
	v_mfma_f32_16x16x32_bf16 v[128:131], v[48:51], v[194:197], v[128:131]
	v_mfma_f32_16x16x32_bf16 v[124:127], v[60:63], v[194:197], v[124:127]
	v_mfma_f32_16x16x32_bf16 v[108:111], v[48:51], v[202:205], v[108:111]
	v_mfma_f32_16x16x32_bf16 v[104:107], v[60:63], v[202:205], v[104:107]
	v_mfma_f32_16x16x32_bf16 v[100:103], v[48:51], v[210:213], v[100:103]
	v_mfma_f32_16x16x32_bf16 v[96:99], v[60:63], v[210:213], v[96:99]
	v_mfma_f32_16x16x32_bf16 v[160:163], v[52:55], v[164:167], v[160:163]
	v_mfma_f32_16x16x32_bf16 v[156:159], v[64:67], v[164:167], v[156:159]
	v_mfma_f32_16x16x32_bf16 v[128:131], v[52:55], v[198:201], v[128:131]
	v_mfma_f32_16x16x32_bf16 v[124:127], v[64:67], v[198:201], v[124:127]
	v_mfma_f32_16x16x32_bf16 v[108:111], v[52:55], v[206:209], v[108:111]
	v_mfma_f32_16x16x32_bf16 v[104:107], v[64:67], v[206:209], v[104:107]
	v_mfma_f32_16x16x32_bf16 v[100:103], v[52:55], v[214:217], v[100:103]
	v_mfma_f32_16x16x32_bf16 v[96:99], v[64:67], v[214:217], v[96:99]
	s_setprio 0
	s_setprio 1
	v_mfma_f32_16x16x32_bf16 v[152:155], v[72:75], v[112:115], v[152:155]
	v_mfma_f32_16x16x32_bf16 v[120:123], v[72:75], v[194:197], v[120:123]
	v_mfma_f32_16x16x32_bf16 v[116:119], v[84:87], v[194:197], v[116:119]
	v_mfma_f32_16x16x32_bf16 v[144:147], v[72:75], v[202:205], v[144:147]
	v_mfma_f32_16x16x32_bf16 v[140:143], v[84:87], v[202:205], v[140:143]
	v_mfma_f32_16x16x32_bf16 v[136:139], v[72:75], v[210:213], v[136:139]
	v_mfma_f32_16x16x32_bf16 v[132:135], v[84:87], v[210:213], v[132:135]
	v_mfma_f32_16x16x32_bf16 v[152:155], v[80:83], v[164:167], v[152:155]
	v_mfma_f32_16x16x32_bf16 v[112:115], v[84:87], v[112:115], v[148:151]
	v_mfma_f32_16x16x32_bf16 v[120:123], v[80:83], v[198:201], v[120:123]
	v_mfma_f32_16x16x32_bf16 v[116:119], v[92:95], v[198:201], v[116:119]
	v_mfma_f32_16x16x32_bf16 v[144:147], v[80:83], v[206:209], v[144:147]
	v_mfma_f32_16x16x32_bf16 v[140:143], v[92:95], v[206:209], v[140:143]
	v_mfma_f32_16x16x32_bf16 v[136:139], v[80:83], v[214:217], v[136:139]
	v_mfma_f32_16x16x32_bf16 v[132:135], v[92:95], v[214:217], v[132:135]
	v_mfma_f32_16x16x32_bf16 v[112:115], v[92:95], v[164:167], v[112:115]
	s_setprio 0
	s_barrier
	s_add_i32 s0, s0, s96
	v_lshl_add_u64 v[218:219], s[64:65], 0, v[170:171]
	s_mov_b32 m0, s0
	ds_read_b128 v[148:151], v230 offset:16384
	ds_read_b128 v[164:167], v230 offset:17408
	ds_read_b128 v[194:197], v230 offset:18432
	ds_read_b128 v[198:201], v230 offset:19456
	ds_read_b128 v[202:205], v230 offset:20480
	ds_read_b128 v[206:209], v230 offset:21504
	ds_read_b128 v[210:213], v230 offset:22528
	ds_read_b128 v[214:217], v230 offset:23552
	global_load_lds_dwordx4 v[218:219], off
	s_add_i32 m0, s0, 0x2000
	s_add_u32 s0, s64, 0x40000
	v_lshl_add_u64 v[232:233], s[64:65], 0, v[188:189]
	s_addc_u32 s1, s65, 0
	s_add_i32 s13, s13, s96
	global_load_lds_dwordx4 v[232:233], off
	s_mov_b32 m0, s13
	v_lshl_add_u64 v[236:237], s[66:67], 0, v[186:187]
	global_load_lds_dwordx4 v170, s[0:1]
	s_add_i32 m0, s13, 0x2000
	s_nop 0
	global_load_lds_dwordx4 v188, s[0:1]
	v_lshl_add_u64 v[234:235], s[66:67], 0, v[184:185]
	s_waitcnt vmcnt(6)
	s_waitcnt lgkmcnt(0)
	s_barrier
	s_setprio 1
	s_waitcnt lgkmcnt(0)
	v_mfma_f32_16x16x32_bf16 v[88:91], v[48:51], v[148:151], v[88:91]
	v_mfma_f32_16x16x32_bf16 v[76:79], v[60:63], v[148:151], v[76:79]
	v_mfma_f32_16x16x32_bf16 v[28:31], v[48:51], v[194:197], v[28:31]
	v_mfma_f32_16x16x32_bf16 v[24:27], v[60:63], v[194:197], v[24:27]
	v_mfma_f32_16x16x32_bf16 v[12:15], v[48:51], v[202:205], v[12:15]
	v_mfma_f32_16x16x32_bf16 v[8:11], v[60:63], v[202:205], v[8:11]
	v_mfma_f32_16x16x32_bf16 v[4:7], v[48:51], v[210:213], v[4:7]
	v_mfma_f32_16x16x32_bf16 v[0:3], v[60:63], v[210:213], v[0:3]
	v_mfma_f32_16x16x32_bf16 v[88:91], v[52:55], v[164:167], v[88:91]
	v_mfma_f32_16x16x32_bf16 v[76:79], v[64:67], v[164:167], v[76:79]
	v_mfma_f32_16x16x32_bf16 v[28:31], v[52:55], v[198:201], v[28:31]
	v_mfma_f32_16x16x32_bf16 v[24:27], v[64:67], v[198:201], v[24:27]
	v_mfma_f32_16x16x32_bf16 v[12:15], v[52:55], v[206:209], v[12:15]
	v_mfma_f32_16x16x32_bf16 v[8:11], v[64:67], v[206:209], v[8:11]
	v_mfma_f32_16x16x32_bf16 v[4:7], v[52:55], v[214:217], v[4:7]
	v_mfma_f32_16x16x32_bf16 v[0:3], v[64:67], v[214:217], v[0:3]
	s_setprio 0
	s_setprio 1
	v_mfma_f32_16x16x32_bf16 v[20:23], v[72:75], v[194:197], v[20:23]
	v_mfma_f32_16x16x32_bf16 v[16:19], v[84:87], v[194:197], v[16:19]
	v_mfma_f32_16x16x32_bf16 v[44:47], v[72:75], v[202:205], v[44:47]
	v_mfma_f32_16x16x32_bf16 v[40:43], v[84:87], v[202:205], v[40:43]
	v_mfma_f32_16x16x32_bf16 v[36:39], v[72:75], v[210:213], v[36:39]
	v_mfma_f32_16x16x32_bf16 v[32:35], v[84:87], v[210:213], v[32:35]
	v_mfma_f32_16x16x32_bf16 v[48:51], v[72:75], v[148:151], v[68:71]
	v_mfma_f32_16x16x32_bf16 v[52:55], v[84:87], v[148:151], v[56:59]
	v_mfma_f32_16x16x32_bf16 v[20:23], v[80:83], v[198:201], v[20:23]
	v_mfma_f32_16x16x32_bf16 v[16:19], v[92:95], v[198:201], v[16:19]
	v_mfma_f32_16x16x32_bf16 v[44:47], v[80:83], v[206:209], v[44:47]
	v_mfma_f32_16x16x32_bf16 v[40:43], v[92:95], v[206:209], v[40:43]
	v_mfma_f32_16x16x32_bf16 v[36:39], v[80:83], v[214:217], v[36:39]
	v_mfma_f32_16x16x32_bf16 v[32:35], v[92:95], v[214:217], v[32:35]
	v_mfma_f32_16x16x32_bf16 v[48:51], v[80:83], v[164:167], v[48:51]
	v_mfma_f32_16x16x32_bf16 v[52:55], v[92:95], v[164:167], v[52:55]
	s_setprio 0
	s_barrier
	s_add_i32 s13, 0, 0x18000
	s_add_i32 s60, 0, 0x1c000
	v_add_u32_e32 v68, s13, v228
	v_add_u32_e32 v92, s60, v228
	ds_read_b128 v[56:59], v68
	ds_read_b128 v[60:63], v68 offset:1024
	ds_read_b128 v[64:67], v68 offset:2048
	ds_read_b128 v[68:71], v68 offset:3072
	ds_read_b128 v[72:75], v92
	ds_read_b128 v[80:83], v92 offset:1024
	ds_read_b128 v[84:87], v92 offset:2048
	ds_read_b128 v[92:95], v92 offset:3072
	s_add_u32 s0, s66, 0x40000
	s_addc_u32 s1, s67, 0
	s_mov_b32 m0, s39
	ds_read_b128 v[148:151], v230 offset:32768
	ds_read_b128 v[164:167], v230 offset:33792
	ds_read_b128 v[194:197], v230 offset:34816
	ds_read_b128 v[198:201], v230 offset:35840
	ds_read_b128 v[202:205], v230 offset:36864
	ds_read_b128 v[206:209], v230 offset:37888
	ds_read_b128 v[210:213], v230 offset:38912
	ds_read_b128 v[214:217], v230 offset:39936
	global_load_lds_dwordx4 v184, s[0:1]
	s_mov_b32 m0, s76
	s_nop 0
	global_load_lds_dwordx4 v186, s[0:1]
	s_mov_b32 m0, s59
	s_nop 0
	global_load_lds_dwordx4 v[234:235], off
	s_mov_b32 m0, s97
	s_nop 0
	global_load_lds_dwordx4 v[236:237], off
	s_waitcnt vmcnt(8)
	s_waitcnt lgkmcnt(0)
	s_barrier
	s_setprio 1
	s_waitcnt lgkmcnt(0)
	v_mfma_f32_16x16x32_bf16 v[160:163], v[56:59], v[148:151], v[160:163]
	v_mfma_f32_16x16x32_bf16 v[156:159], v[64:67], v[148:151], v[156:159]
	v_mfma_f32_16x16x32_bf16 v[128:131], v[56:59], v[194:197], v[128:131]
	v_mfma_f32_16x16x32_bf16 v[124:127], v[64:67], v[194:197], v[124:127]
	v_mfma_f32_16x16x32_bf16 v[108:111], v[56:59], v[202:205], v[108:111]
	v_mfma_f32_16x16x32_bf16 v[104:107], v[64:67], v[202:205], v[104:107]
	v_mfma_f32_16x16x32_bf16 v[100:103], v[56:59], v[210:213], v[100:103]
	v_mfma_f32_16x16x32_bf16 v[96:99], v[64:67], v[210:213], v[96:99]
	v_mfma_f32_16x16x32_bf16 v[160:163], v[60:63], v[164:167], v[160:163]
	v_mfma_f32_16x16x32_bf16 v[156:159], v[68:71], v[164:167], v[156:159]
	v_mfma_f32_16x16x32_bf16 v[128:131], v[60:63], v[198:201], v[128:131]
	v_mfma_f32_16x16x32_bf16 v[124:127], v[68:71], v[198:201], v[124:127]
	v_mfma_f32_16x16x32_bf16 v[108:111], v[60:63], v[206:209], v[108:111]
	v_mfma_f32_16x16x32_bf16 v[104:107], v[68:71], v[206:209], v[104:107]
	v_mfma_f32_16x16x32_bf16 v[100:103], v[60:63], v[214:217], v[100:103]
	v_mfma_f32_16x16x32_bf16 v[96:99], v[68:71], v[214:217], v[96:99]
	s_setprio 0
	s_setprio 1
	v_mfma_f32_16x16x32_bf16 v[112:115], v[84:87], v[148:151], v[112:115]
	v_mfma_f32_16x16x32_bf16 v[152:155], v[72:75], v[148:151], v[152:155]
	v_mfma_f32_16x16x32_bf16 v[148:151], v[92:95], v[164:167], v[112:115]
	v_mfma_f32_16x16x32_bf16 v[112:115], v[72:75], v[194:197], v[120:123]
	v_mfma_f32_16x16x32_bf16 v[120:123], v[80:83], v[198:201], v[112:115]
	v_mfma_f32_16x16x32_bf16 v[112:115], v[84:87], v[194:197], v[116:119]
	v_mfma_f32_16x16x32_bf16 v[116:119], v[92:95], v[198:201], v[112:115]
	v_mfma_f32_16x16x32_bf16 v[112:115], v[72:75], v[202:205], v[144:147]
	v_mfma_f32_16x16x32_bf16 v[144:147], v[80:83], v[206:209], v[112:115]
	v_mfma_f32_16x16x32_bf16 v[112:115], v[84:87], v[202:205], v[140:143]
	v_mfma_f32_16x16x32_bf16 v[140:143], v[92:95], v[206:209], v[112:115]
	v_mfma_f32_16x16x32_bf16 v[112:115], v[72:75], v[210:213], v[136:139]
	v_mfma_f32_16x16x32_bf16 v[136:139], v[80:83], v[214:217], v[112:115]
	v_mfma_f32_16x16x32_bf16 v[112:115], v[84:87], v[210:213], v[132:135]
	v_mfma_f32_16x16x32_bf16 v[152:155], v[80:83], v[164:167], v[152:155]
	v_mfma_f32_16x16x32_bf16 v[132:135], v[92:95], v[214:217], v[112:115]
	s_setprio 0
	s_barrier
	s_add_i32 s0, s13, s96
	v_lshl_add_u64 v[218:219], v[218:219], 0, s[16:17]
	s_mov_b32 m0, s0
	s_nop 0
	ds_read_b128 v[112:115], v230 offset:49152
	ds_read_b128 v[164:167], v230 offset:50176
	ds_read_b128 v[194:197], v230 offset:51200
	ds_read_b128 v[198:201], v230 offset:52224
	ds_read_b128 v[202:205], v230 offset:53248
	ds_read_b128 v[206:209], v230 offset:54272
	ds_read_b128 v[210:213], v230 offset:55296
	ds_read_b128 v[214:217], v230 offset:56320
	global_load_lds_dwordx4 v[218:219], off
	s_add_i32 m0, s0, 0x2000
	s_add_u32 s0, s64, 0x40080
	v_lshl_add_u64 v[218:219], v[232:233], 0, s[16:17]
	s_addc_u32 s1, s65, 0
	s_add_i32 s13, s60, s96
	global_load_lds_dwordx4 v[218:219], off
	s_mov_b32 m0, s13
	s_nop 0
	global_load_lds_dwordx4 v170, s[0:1]
	s_add_i32 m0, s13, 0x2000
	s_nop 0
	global_load_lds_dwordx4 v188, s[0:1]
	v_lshl_add_u64 v[218:219], v[234:235], 0, s[16:17]
	s_mov_b32 m0, s75
	s_nop 0
	global_load_lds_dwordx4 v[218:219], off
	v_lshl_add_u64 v[218:219], v[236:237], 0, s[16:17]
	s_mov_b32 m0, s91
	s_nop 0
	global_load_lds_dwordx4 v[218:219], off
	s_waitcnt vmcnt(6)
	s_waitcnt lgkmcnt(0)
	s_barrier
	s_setprio 1
	s_waitcnt lgkmcnt(0)
	v_mfma_f32_16x16x32_bf16 v[88:91], v[56:59], v[112:115], v[88:91]
	v_mfma_f32_16x16x32_bf16 v[76:79], v[64:67], v[112:115], v[76:79]
	v_mfma_f32_16x16x32_bf16 v[28:31], v[56:59], v[194:197], v[28:31]
	v_mfma_f32_16x16x32_bf16 v[24:27], v[64:67], v[194:197], v[24:27]
	v_mfma_f32_16x16x32_bf16 v[12:15], v[56:59], v[202:205], v[12:15]
	v_mfma_f32_16x16x32_bf16 v[8:11], v[64:67], v[202:205], v[8:11]
	v_mfma_f32_16x16x32_bf16 v[4:7], v[56:59], v[210:213], v[4:7]
	v_mfma_f32_16x16x32_bf16 v[0:3], v[64:67], v[210:213], v[0:3]
	v_mfma_f32_16x16x32_bf16 v[88:91], v[60:63], v[164:167], v[88:91]
	v_mfma_f32_16x16x32_bf16 v[76:79], v[68:71], v[164:167], v[76:79]
	v_mfma_f32_16x16x32_bf16 v[28:31], v[60:63], v[198:201], v[28:31]
	v_mfma_f32_16x16x32_bf16 v[24:27], v[68:71], v[198:201], v[24:27]
	v_mfma_f32_16x16x32_bf16 v[12:15], v[60:63], v[206:209], v[12:15]
	v_mfma_f32_16x16x32_bf16 v[8:11], v[68:71], v[206:209], v[8:11]
	v_mfma_f32_16x16x32_bf16 v[4:7], v[60:63], v[214:217], v[4:7]
	v_mfma_f32_16x16x32_bf16 v[0:3], v[68:71], v[214:217], v[0:3]
	s_setprio 0
	s_setprio 1
	v_mfma_f32_16x16x32_bf16 v[48:51], v[72:75], v[112:115], v[48:51]
	v_mfma_f32_16x16x32_bf16 v[68:71], v[80:83], v[164:167], v[48:51]
	v_mfma_f32_16x16x32_bf16 v[48:51], v[84:87], v[112:115], v[52:55]
	v_mfma_f32_16x16x32_bf16 v[20:23], v[72:75], v[194:197], v[20:23]
	v_mfma_f32_16x16x32_bf16 v[16:19], v[84:87], v[194:197], v[16:19]
	v_mfma_f32_16x16x32_bf16 v[44:47], v[72:75], v[202:205], v[44:47]
	v_mfma_f32_16x16x32_bf16 v[40:43], v[84:87], v[202:205], v[40:43]
	v_mfma_f32_16x16x32_bf16 v[36:39], v[72:75], v[210:213], v[36:39]
	v_mfma_f32_16x16x32_bf16 v[32:35], v[84:87], v[210:213], v[32:35]
	v_mfma_f32_16x16x32_bf16 v[56:59], v[92:95], v[164:167], v[48:51]
	v_mfma_f32_16x16x32_bf16 v[20:23], v[80:83], v[198:201], v[20:23]
	v_mfma_f32_16x16x32_bf16 v[16:19], v[92:95], v[198:201], v[16:19]
	v_mfma_f32_16x16x32_bf16 v[44:47], v[80:83], v[206:209], v[44:47]
	v_mfma_f32_16x16x32_bf16 v[40:43], v[92:95], v[206:209], v[40:43]
	v_mfma_f32_16x16x32_bf16 v[36:39], v[80:83], v[214:217], v[36:39]
	v_mfma_f32_16x16x32_bf16 v[32:35], v[92:95], v[214:217], v[32:35]
	s_setprio 0
	s_barrier
	s_add_i32 s12, s12, 2
	s_add_u32 vcc_lo, vcc_lo, 0x100
	s_addc_u32 vcc_hi, vcc_hi, 0
	s_cmp_gt_u32 s12, 13
	s_mov_b64 s[60:61], s[62:63]
	s_cbranch_scc0 .LBB0_863
	s_and_b64 vcc, exec, s[42:43]
	s_cbranch_vccz .LBB0_866
	s_barrier

.LBB0_890:
	s_or_b64 exec, exec, s[56:57]
	s_andn2_b64 vcc, exec, s[8:9]
	s_mov_b64 s[8:9], -1
	s_cbranch_vccnz .LBB0_859
	s_andn2_b64 vcc, exec, s[28:29]
	s_cbranch_vccnz .LBB0_858
	s_mov_b32 s98, 1
	s_branch .LBB0_858

.LBB0_1028:
	s_add_u32 s54, s34, 0x100
	s_addc_u32 s55, s35, 0
	s_mov_b32 s12, -2
	s_waitcnt vmcnt(0)
	s_cmp_eq_u32 s98, 1
	s_cbranch_scc0 .Lrestag_1029
	s_barrier
	s_mov_b32 s98, 0
.Lrestag_1029:
	s_add_u32 s34, s30, 0x100
	s_addc_u32 s35, s31, 0
	s_add_i32 s0, 0, 0x10000
	s_cmp_eq_u32 s12, 40
	s_cselect_b32 s41, s7, s35
	s_cselect_b32 s40, s6, s34
	v_add_u32_e32 v150, s0, v153
	s_cselect_b32 s37, s27, s55
	s_cselect_b32 s36, s26, s54
	s_add_i32 s13, 0, 0x14000
	ds_read_b128 v[128:131], v150
	ds_read_b128 v[146:149], v150 offset:1024
	ds_read_b128 v[156:159], v150 offset:2048
	ds_read_b128 v[160:163], v150 offset:3072
	v_add_u32_e32 v150, s13, v153
	ds_read_b128 v[164:167], v150
	ds_read_b128 v[184:187], v150 offset:1024
	ds_read_b128 v[188:191], v150 offset:2048
	ds_read_b128 v[192:195], v150 offset:3072
	s_add_i32 m0, s43, 0xc000
	ds_read_b128 v[196:199], v154
	ds_read_b128 v[200:203], v154 offset:1024
	ds_read_b128 v[204:207], v154 offset:2048
	ds_read_b128 v[208:211], v154 offset:3072
	ds_read_b128 v[212:215], v154 offset:4096
	ds_read_b128 v[216:219], v154 offset:5120
	ds_read_b128 v[228:231], v154 offset:6144
	ds_read_b128 v[232:235], v154 offset:7168
	global_load_lds_dwordx4 v142, s[30:31]
	s_add_i32 m0, s43, 0xe000
	s_nop 0
	global_load_lds_dwordx4 v144, s[30:31]
	s_nop 0
	s_waitcnt lgkmcnt(0)
	s_barrier
	s_setprio 1
	s_waitcnt lgkmcnt(0)
	v_mfma_f32_16x16x32_bf16 v[124:127], v[128:131], v[196:199], 0
	v_mfma_f32_16x16x32_bf16 v[120:123], v[156:159], v[196:199], 0
	v_mfma_f32_16x16x32_bf16 v[112:115], v[128:131], v[204:207], 0
	v_mfma_f32_16x16x32_bf16 v[104:107], v[156:159], v[204:207], 0
	v_mfma_f32_16x16x32_bf16 v[96:99], v[128:131], v[212:215], 0
	v_mfma_f32_16x16x32_bf16 v[88:91], v[156:159], v[212:215], 0
	v_mfma_f32_16x16x32_bf16 v[80:83], v[128:131], v[228:231], 0
	v_mfma_f32_16x16x32_bf16 v[72:75], v[156:159], v[228:231], 0
	v_mfma_f32_16x16x32_bf16 v[124:127], v[146:149], v[200:203], v[124:127]
	v_mfma_f32_16x16x32_bf16 v[120:123], v[160:163], v[200:203], v[120:123]
	v_mfma_f32_16x16x32_bf16 v[112:115], v[146:149], v[208:211], v[112:115]
	v_mfma_f32_16x16x32_bf16 v[104:107], v[160:163], v[208:211], v[104:107]
	v_mfma_f32_16x16x32_bf16 v[96:99], v[146:149], v[216:219], v[96:99]
	v_mfma_f32_16x16x32_bf16 v[88:91], v[160:163], v[216:219], v[88:91]
	v_mfma_f32_16x16x32_bf16 v[80:83], v[146:149], v[232:235], v[80:83]
	v_mfma_f32_16x16x32_bf16 v[72:75], v[160:163], v[232:235], v[72:75]
	s_setprio 0
	s_setprio 1
	v_mfma_f32_16x16x32_bf16 v[116:119], v[164:167], v[196:199], 0
	v_mfma_f32_16x16x32_bf16 v[108:111], v[188:191], v[196:199], 0
	v_mfma_f32_16x16x32_bf16 v[100:103], v[164:167], v[204:207], 0
	v_mfma_f32_16x16x32_bf16 v[92:95], v[188:191], v[204:207], 0
	v_mfma_f32_16x16x32_bf16 v[84:87], v[164:167], v[212:215], 0
	v_mfma_f32_16x16x32_bf16 v[76:79], v[188:191], v[212:215], 0
	v_mfma_f32_16x16x32_bf16 v[68:71], v[164:167], v[228:231], 0
	v_mfma_f32_16x16x32_bf16 v[64:67], v[188:191], v[228:231], 0
	v_mfma_f32_16x16x32_bf16 v[116:119], v[184:187], v[200:203], v[116:119]
	v_mfma_f32_16x16x32_bf16 v[108:111], v[192:195], v[200:203], v[108:111]
	v_mfma_f32_16x16x32_bf16 v[100:103], v[184:187], v[208:211], v[100:103]
	v_mfma_f32_16x16x32_bf16 v[92:95], v[192:195], v[208:211], v[92:95]
	v_mfma_f32_16x16x32_bf16 v[84:87], v[184:187], v[216:219], v[84:87]
	v_mfma_f32_16x16x32_bf16 v[76:79], v[192:195], v[216:219], v[76:79]
	v_mfma_f32_16x16x32_bf16 v[68:71], v[184:187], v[232:235], v[68:71]
	v_mfma_f32_16x16x32_bf16 v[64:67], v[192:195], v[232:235], v[64:67]
	s_setprio 0
	s_barrier
	s_add_i32 s0, s0, s42
	v_lshl_add_u64 v[150:151], s[36:37], 0, v[170:171]
	s_mov_b32 m0, s0
	ds_read_b128 v[196:199], v154 offset:16384
	ds_read_b128 v[200:203], v154 offset:17408
	ds_read_b128 v[204:207], v154 offset:18432
	ds_read_b128 v[208:211], v154 offset:19456
	ds_read_b128 v[212:215], v154 offset:20480
	ds_read_b128 v[216:219], v154 offset:21504
	ds_read_b128 v[228:231], v154 offset:22528
	ds_read_b128 v[232:235], v154 offset:23552
	global_load_lds_dwordx4 v[150:151], off
	s_add_i32 m0, s0, 0x2000
	s_add_u32 s0, s36, 0xb0000
	v_lshl_add_u64 v[236:237], s[36:37], 0, v[136:137]
	s_addc_u32 s1, s37, 0
	s_add_i32 s13, s13, s42
	global_load_lds_dwordx4 v[236:237], off
	s_mov_b32 m0, s13
	v_lshl_add_u64 v[240:241], s[40:41], 0, v[134:135]
	global_load_lds_dwordx4 v170, s[0:1]
	s_add_i32 m0, s13, 0x2000
	s_nop 0
	global_load_lds_dwordx4 v136, s[0:1]
	v_lshl_add_u64 v[238:239], s[40:41], 0, v[132:133]
	s_nop 0
	s_waitcnt lgkmcnt(0)
	s_barrier
	s_setprio 1
	s_waitcnt lgkmcnt(0)
	v_mfma_f32_16x16x32_bf16 v[60:63], v[128:131], v[196:199], 0
	v_mfma_f32_16x16x32_bf16 v[56:59], v[156:159], v[196:199], 0
	v_mfma_f32_16x16x32_bf16 v[48:51], v[128:131], v[204:207], 0
	v_mfma_f32_16x16x32_bf16 v[40:43], v[156:159], v[204:207], 0
	v_mfma_f32_16x16x32_bf16 v[32:35], v[128:131], v[212:215], 0
	v_mfma_f32_16x16x32_bf16 v[24:27], v[156:159], v[212:215], 0
	v_mfma_f32_16x16x32_bf16 v[16:19], v[128:131], v[228:231], 0
	v_mfma_f32_16x16x32_bf16 v[8:11], v[156:159], v[228:231], 0
	v_mfma_f32_16x16x32_bf16 v[60:63], v[146:149], v[200:203], v[60:63]
	v_mfma_f32_16x16x32_bf16 v[56:59], v[160:163], v[200:203], v[56:59]
	v_mfma_f32_16x16x32_bf16 v[48:51], v[146:149], v[208:211], v[48:51]
	v_mfma_f32_16x16x32_bf16 v[40:43], v[160:163], v[208:211], v[40:43]
	v_mfma_f32_16x16x32_bf16 v[32:35], v[146:149], v[216:219], v[32:35]
	v_mfma_f32_16x16x32_bf16 v[24:27], v[160:163], v[216:219], v[24:27]
	v_mfma_f32_16x16x32_bf16 v[16:19], v[146:149], v[232:235], v[16:19]
	v_mfma_f32_16x16x32_bf16 v[8:11], v[160:163], v[232:235], v[8:11]
	s_setprio 0
	s_setprio 1
	v_mfma_f32_16x16x32_bf16 v[52:55], v[164:167], v[196:199], 0
	v_mfma_f32_16x16x32_bf16 v[44:47], v[188:191], v[196:199], 0
	v_mfma_f32_16x16x32_bf16 v[36:39], v[164:167], v[204:207], 0
	v_mfma_f32_16x16x32_bf16 v[28:31], v[188:191], v[204:207], 0
	v_mfma_f32_16x16x32_bf16 v[20:23], v[164:167], v[212:215], 0
	v_mfma_f32_16x16x32_bf16 v[12:15], v[188:191], v[212:215], 0
	v_mfma_f32_16x16x32_bf16 v[4:7], v[164:167], v[228:231], 0
	v_mfma_f32_16x16x32_bf16 v[0:3], v[188:191], v[228:231], 0
	v_mfma_f32_16x16x32_bf16 v[52:55], v[184:187], v[200:203], v[52:55]
	v_mfma_f32_16x16x32_bf16 v[44:47], v[192:195], v[200:203], v[44:47]
	v_mfma_f32_16x16x32_bf16 v[36:39], v[184:187], v[208:211], v[36:39]
	v_mfma_f32_16x16x32_bf16 v[28:31], v[192:195], v[208:211], v[28:31]
	v_mfma_f32_16x16x32_bf16 v[20:23], v[184:187], v[216:219], v[20:23]
	v_mfma_f32_16x16x32_bf16 v[12:15], v[192:195], v[216:219], v[12:15]
	v_mfma_f32_16x16x32_bf16 v[4:7], v[184:187], v[232:235], v[4:7]
	v_mfma_f32_16x16x32_bf16 v[0:3], v[192:195], v[232:235], v[0:3]
	s_setprio 0
	s_barrier
	s_add_i32 s13, 0, 0x18000
	v_add_u32_e32 v155, s13, v153
	s_add_i32 s30, 0, 0x1c000
	ds_read_b128 v[128:131], v155
	ds_read_b128 v[146:149], v155 offset:1024
	ds_read_b128 v[156:159], v155 offset:2048
	ds_read_b128 v[160:163], v155 offset:3072
	v_add_u32_e32 v155, s30, v153
	ds_read_b128 v[164:167], v155
	ds_read_b128 v[184:187], v155 offset:1024
	ds_read_b128 v[188:191], v155 offset:2048
	ds_read_b128 v[192:195], v155 offset:3072
	s_add_u32 s0, s40, 0xb0000
	s_addc_u32 s1, s41, 0
	s_mov_b32 m0, s45
	ds_read_b128 v[196:199], v154 offset:32768
	ds_read_b128 v[200:203], v154 offset:33792
	ds_read_b128 v[204:207], v154 offset:34816
	ds_read_b128 v[208:211], v154 offset:35840
	ds_read_b128 v[212:215], v154 offset:36864
	ds_read_b128 v[216:219], v154 offset:37888
	ds_read_b128 v[228:231], v154 offset:38912
	ds_read_b128 v[232:235], v154 offset:39936
	global_load_lds_dwordx4 v132, s[0:1]
	s_mov_b32 m0, s46
	s_nop 0
	global_load_lds_dwordx4 v134, s[0:1]
	s_mov_b32 m0, s43
	s_nop 0
	global_load_lds_dwordx4 v[238:239], off
	s_mov_b32 m0, s44
	s_nop 0
	global_load_lds_dwordx4 v[240:241], off
	s_waitcnt vmcnt(8)
	s_waitcnt lgkmcnt(0)
	s_barrier
	s_setprio 1
	s_waitcnt lgkmcnt(0)
	v_mfma_f32_16x16x32_bf16 v[124:127], v[128:131], v[196:199], v[124:127]
	v_mfma_f32_16x16x32_bf16 v[120:123], v[156:159], v[196:199], v[120:123]
	v_mfma_f32_16x16x32_bf16 v[112:115], v[128:131], v[204:207], v[112:115]
	v_mfma_f32_16x16x32_bf16 v[104:107], v[156:159], v[204:207], v[104:107]
	v_mfma_f32_16x16x32_bf16 v[96:99], v[128:131], v[212:215], v[96:99]
	v_mfma_f32_16x16x32_bf16 v[88:91], v[156:159], v[212:215], v[88:91]
	v_mfma_f32_16x16x32_bf16 v[80:83], v[128:131], v[228:231], v[80:83]
	v_mfma_f32_16x16x32_bf16 v[72:75], v[156:159], v[228:231], v[72:75]
	v_mfma_f32_16x16x32_bf16 v[124:127], v[146:149], v[200:203], v[124:127]
	v_mfma_f32_16x16x32_bf16 v[120:123], v[160:163], v[200:203], v[120:123]
	v_mfma_f32_16x16x32_bf16 v[112:115], v[146:149], v[208:211], v[112:115]
	v_mfma_f32_16x16x32_bf16 v[104:107], v[160:163], v[208:211], v[104:107]
	v_mfma_f32_16x16x32_bf16 v[96:99], v[146:149], v[216:219], v[96:99]
	v_mfma_f32_16x16x32_bf16 v[88:91], v[160:163], v[216:219], v[88:91]
	v_mfma_f32_16x16x32_bf16 v[80:83], v[146:149], v[232:235], v[80:83]
	v_mfma_f32_16x16x32_bf16 v[72:75], v[160:163], v[232:235], v[72:75]
	s_setprio 0
	s_setprio 1
	v_mfma_f32_16x16x32_bf16 v[116:119], v[164:167], v[196:199], v[116:119]
	v_mfma_f32_16x16x32_bf16 v[108:111], v[188:191], v[196:199], v[108:111]
	v_mfma_f32_16x16x32_bf16 v[100:103], v[164:167], v[204:207], v[100:103]
	v_mfma_f32_16x16x32_bf16 v[92:95], v[188:191], v[204:207], v[92:95]
	v_mfma_f32_16x16x32_bf16 v[84:87], v[164:167], v[212:215], v[84:87]
	v_mfma_f32_16x16x32_bf16 v[76:79], v[188:191], v[212:215], v[76:79]
	v_mfma_f32_16x16x32_bf16 v[68:71], v[164:167], v[228:231], v[68:71]
	v_mfma_f32_16x16x32_bf16 v[64:67], v[188:191], v[228:231], v[64:67]
	v_mfma_f32_16x16x32_bf16 v[116:119], v[184:187], v[200:203], v[116:119]
	v_mfma_f32_16x16x32_bf16 v[108:111], v[192:195], v[200:203], v[108:111]
	v_mfma_f32_16x16x32_bf16 v[100:103], v[184:187], v[208:211], v[100:103]
	v_mfma_f32_16x16x32_bf16 v[92:95], v[192:195], v[208:211], v[92:95]
	v_mfma_f32_16x16x32_bf16 v[84:87], v[184:187], v[216:219], v[84:87]
	v_mfma_f32_16x16x32_bf16 v[76:79], v[192:195], v[216:219], v[76:79]
	v_mfma_f32_16x16x32_bf16 v[68:71], v[184:187], v[232:235], v[68:71]
	v_mfma_f32_16x16x32_bf16 v[64:67], v[192:195], v[232:235], v[64:67]
	s_setprio 0
	s_barrier
	s_add_i32 s0, s13, s42
	v_lshl_add_u64 v[150:151], v[150:151], 0, s[16:17]
	s_mov_b32 m0, s0
	ds_read_b128 v[196:199], v154 offset:49152
	ds_read_b128 v[200:203], v154 offset:50176
	ds_read_b128 v[204:207], v154 offset:51200
	ds_read_b128 v[208:211], v154 offset:52224
	ds_read_b128 v[212:215], v154 offset:53248
	ds_read_b128 v[216:219], v154 offset:54272
	ds_read_b128 v[228:231], v154 offset:55296
	ds_read_b128 v[232:235], v154 offset:56320
	global_load_lds_dwordx4 v[150:151], off
	s_add_i32 m0, s0, 0x2000
	s_add_u32 s0, s36, 0xb0080
	v_lshl_add_u64 v[150:151], v[236:237], 0, s[16:17]
	s_addc_u32 s1, s37, 0
	s_add_i32 s13, s30, s42
	global_load_lds_dwordx4 v[150:151], off
	s_mov_b32 m0, s13
	s_nop 0
	global_load_lds_dwordx4 v170, s[0:1]
	s_add_i32 m0, s13, 0x2000
	s_nop 0
	global_load_lds_dwordx4 v136, s[0:1]
	v_lshl_add_u64 v[150:151], v[238:239], 0, s[16:17]
	s_mov_b32 m0, s47
	s_nop 0
	global_load_lds_dwordx4 v[150:151], off
	v_lshl_add_u64 v[150:151], v[240:241], 0, s[16:17]
	s_mov_b32 m0, s48
	s_nop 0
	global_load_lds_dwordx4 v[150:151], off
	s_waitcnt vmcnt(6)
	s_waitcnt lgkmcnt(0)
	s_barrier
	s_setprio 1
	s_waitcnt lgkmcnt(0)
	v_mfma_f32_16x16x32_bf16 v[60:63], v[128:131], v[196:199], v[60:63]
	v_mfma_f32_16x16x32_bf16 v[56:59], v[156:159], v[196:199], v[56:59]
	v_mfma_f32_16x16x32_bf16 v[48:51], v[128:131], v[204:207], v[48:51]
	v_mfma_f32_16x16x32_bf16 v[40:43], v[156:159], v[204:207], v[40:43]
	v_mfma_f32_16x16x32_bf16 v[32:35], v[128:131], v[212:215], v[32:35]
	v_mfma_f32_16x16x32_bf16 v[24:27], v[156:159], v[212:215], v[24:27]
	v_mfma_f32_16x16x32_bf16 v[16:19], v[128:131], v[228:231], v[16:19]
	v_mfma_f32_16x16x32_bf16 v[8:11], v[156:159], v[228:231], v[8:11]
	v_mfma_f32_16x16x32_bf16 v[60:63], v[146:149], v[200:203], v[60:63]
	v_mfma_f32_16x16x32_bf16 v[56:59], v[160:163], v[200:203], v[56:59]
	v_mfma_f32_16x16x32_bf16 v[48:51], v[146:149], v[208:211], v[48:51]
	v_mfma_f32_16x16x32_bf16 v[40:43], v[160:163], v[208:211], v[40:43]
	v_mfma_f32_16x16x32_bf16 v[32:35], v[146:149], v[216:219], v[32:35]
	v_mfma_f32_16x16x32_bf16 v[24:27], v[160:163], v[216:219], v[24:27]
	v_mfma_f32_16x16x32_bf16 v[16:19], v[146:149], v[232:235], v[16:19]
	v_mfma_f32_16x16x32_bf16 v[8:11], v[160:163], v[232:235], v[8:11]
	s_setprio 0
	s_setprio 1
	v_mfma_f32_16x16x32_bf16 v[52:55], v[164:167], v[196:199], v[52:55]
	v_mfma_f32_16x16x32_bf16 v[44:47], v[188:191], v[196:199], v[44:47]
	v_mfma_f32_16x16x32_bf16 v[36:39], v[164:167], v[204:207], v[36:39]
	v_mfma_f32_16x16x32_bf16 v[28:31], v[188:191], v[204:207], v[28:31]
	v_mfma_f32_16x16x32_bf16 v[20:23], v[164:167], v[212:215], v[20:23]
	v_mfma_f32_16x16x32_bf16 v[12:15], v[188:191], v[212:215], v[12:15]
	v_mfma_f32_16x16x32_bf16 v[4:7], v[164:167], v[228:231], v[4:7]
	v_mfma_f32_16x16x32_bf16 v[0:3], v[188:191], v[228:231], v[0:3]
	v_mfma_f32_16x16x32_bf16 v[52:55], v[184:187], v[200:203], v[52:55]
	v_mfma_f32_16x16x32_bf16 v[44:47], v[192:195], v[200:203], v[44:47]
	v_mfma_f32_16x16x32_bf16 v[36:39], v[184:187], v[208:211], v[36:39]
	v_mfma_f32_16x16x32_bf16 v[28:31], v[192:195], v[208:211], v[28:31]
	v_mfma_f32_16x16x32_bf16 v[20:23], v[184:187], v[216:219], v[20:23]
	v_mfma_f32_16x16x32_bf16 v[12:15], v[192:195], v[216:219], v[12:15]
	v_mfma_f32_16x16x32_bf16 v[4:7], v[184:187], v[232:235], v[4:7]
	v_mfma_f32_16x16x32_bf16 v[0:3], v[192:195], v[232:235], v[0:3]
	s_setprio 0
	s_barrier
	s_add_i32 s12, s12, 2
	s_add_u32 s54, s54, 0x100
	s_addc_u32 s55, s55, 0
	s_cmp_gt_u32 s12, 41
	s_mov_b64 s[30:31], s[34:35]
.LBB0_1029:
	s_add_u32 s34, s30, 0x100
	s_addc_u32 s35, s31, 0
	s_add_i32 s0, 0, 0x10000
	s_cmp_eq_u32 s12, 40
	s_cselect_b32 s41, s7, s35
	s_cselect_b32 s40, s6, s34
	v_add_u32_e32 v150, s0, v153
	s_cselect_b32 s37, s27, s55
	s_cselect_b32 s36, s26, s54
	s_add_i32 s13, 0, 0x14000
	ds_read_b128 v[128:131], v150
	ds_read_b128 v[146:149], v150 offset:1024
	ds_read_b128 v[156:159], v150 offset:2048
	ds_read_b128 v[160:163], v150 offset:3072
	v_add_u32_e32 v150, s13, v153
	ds_read_b128 v[164:167], v150
	ds_read_b128 v[184:187], v150 offset:1024
	ds_read_b128 v[188:191], v150 offset:2048
	ds_read_b128 v[192:195], v150 offset:3072
	s_add_i32 m0, s43, 0xc000
	ds_read_b128 v[196:199], v154
	ds_read_b128 v[200:203], v154 offset:1024
	ds_read_b128 v[204:207], v154 offset:2048
	ds_read_b128 v[208:211], v154 offset:3072
	ds_read_b128 v[212:215], v154 offset:4096
	ds_read_b128 v[216:219], v154 offset:5120
	ds_read_b128 v[228:231], v154 offset:6144
	ds_read_b128 v[232:235], v154 offset:7168
	global_load_lds_dwordx4 v142, s[30:31]
	s_add_i32 m0, s43, 0xe000
	s_nop 0
	global_load_lds_dwordx4 v144, s[30:31]
	s_waitcnt vmcnt(8)
	s_waitcnt lgkmcnt(0)
	s_barrier
	s_setprio 1
	s_waitcnt lgkmcnt(0)
	v_mfma_f32_16x16x32_bf16 v[124:127], v[128:131], v[196:199], v[124:127]
	v_mfma_f32_16x16x32_bf16 v[120:123], v[156:159], v[196:199], v[120:123]
	v_mfma_f32_16x16x32_bf16 v[112:115], v[128:131], v[204:207], v[112:115]
	v_mfma_f32_16x16x32_bf16 v[104:107], v[156:159], v[204:207], v[104:107]
	v_mfma_f32_16x16x32_bf16 v[96:99], v[128:131], v[212:215], v[96:99]
	v_mfma_f32_16x16x32_bf16 v[88:91], v[156:159], v[212:215], v[88:91]
	v_mfma_f32_16x16x32_bf16 v[80:83], v[128:131], v[228:231], v[80:83]
	v_mfma_f32_16x16x32_bf16 v[72:75], v[156:159], v[228:231], v[72:75]
	v_mfma_f32_16x16x32_bf16 v[124:127], v[146:149], v[200:203], v[124:127]
	v_mfma_f32_16x16x32_bf16 v[120:123], v[160:163], v[200:203], v[120:123]
	v_mfma_f32_16x16x32_bf16 v[112:115], v[146:149], v[208:211], v[112:115]
	v_mfma_f32_16x16x32_bf16 v[104:107], v[160:163], v[208:211], v[104:107]
	v_mfma_f32_16x16x32_bf16 v[96:99], v[146:149], v[216:219], v[96:99]
	v_mfma_f32_16x16x32_bf16 v[88:91], v[160:163], v[216:219], v[88:91]
	v_mfma_f32_16x16x32_bf16 v[80:83], v[146:149], v[232:235], v[80:83]
	v_mfma_f32_16x16x32_bf16 v[72:75], v[160:163], v[232:235], v[72:75]
	s_setprio 0
	s_setprio 1
	v_mfma_f32_16x16x32_bf16 v[116:119], v[164:167], v[196:199], v[116:119]
	v_mfma_f32_16x16x32_bf16 v[108:111], v[188:191], v[196:199], v[108:111]
	v_mfma_f32_16x16x32_bf16 v[100:103], v[164:167], v[204:207], v[100:103]
	v_mfma_f32_16x16x32_bf16 v[92:95], v[188:191], v[204:207], v[92:95]
	v_mfma_f32_16x16x32_bf16 v[84:87], v[164:167], v[212:215], v[84:87]
	v_mfma_f32_16x16x32_bf16 v[76:79], v[188:191], v[212:215], v[76:79]
	v_mfma_f32_16x16x32_bf16 v[68:71], v[164:167], v[228:231], v[68:71]
	v_mfma_f32_16x16x32_bf16 v[64:67], v[188:191], v[228:231], v[64:67]
	v_mfma_f32_16x16x32_bf16 v[116:119], v[184:187], v[200:203], v[116:119]
	v_mfma_f32_16x16x32_bf16 v[108:111], v[192:195], v[200:203], v[108:111]
	v_mfma_f32_16x16x32_bf16 v[100:103], v[184:187], v[208:211], v[100:103]
	v_mfma_f32_16x16x32_bf16 v[92:95], v[192:195], v[208:211], v[92:95]
	v_mfma_f32_16x16x32_bf16 v[84:87], v[184:187], v[216:219], v[84:87]
	v_mfma_f32_16x16x32_bf16 v[76:79], v[192:195], v[216:219], v[76:79]
	v_mfma_f32_16x16x32_bf16 v[68:71], v[184:187], v[232:235], v[68:71]
	v_mfma_f32_16x16x32_bf16 v[64:67], v[192:195], v[232:235], v[64:67]
	s_setprio 0
	s_barrier
	s_add_i32 s0, s0, s42
	v_lshl_add_u64 v[150:151], s[36:37], 0, v[170:171]
	s_mov_b32 m0, s0
	ds_read_b128 v[196:199], v154 offset:16384
	ds_read_b128 v[200:203], v154 offset:17408
	ds_read_b128 v[204:207], v154 offset:18432
	ds_read_b128 v[208:211], v154 offset:19456
	ds_read_b128 v[212:215], v154 offset:20480
	ds_read_b128 v[216:219], v154 offset:21504
	ds_read_b128 v[228:231], v154 offset:22528
	ds_read_b128 v[232:235], v154 offset:23552
	global_load_lds_dwordx4 v[150:151], off
	s_add_i32 m0, s0, 0x2000
	s_add_u32 s0, s36, 0xb0000
	v_lshl_add_u64 v[236:237], s[36:37], 0, v[136:137]
	s_addc_u32 s1, s37, 0
	s_add_i32 s13, s13, s42
	global_load_lds_dwordx4 v[236:237], off
	s_mov_b32 m0, s13
	v_lshl_add_u64 v[240:241], s[40:41], 0, v[134:135]
	global_load_lds_dwordx4 v170, s[0:1]
	s_add_i32 m0, s13, 0x2000
	s_nop 0
	global_load_lds_dwordx4 v136, s[0:1]
	v_lshl_add_u64 v[238:239], s[40:41], 0, v[132:133]
	s_waitcnt vmcnt(6)
	s_waitcnt lgkmcnt(0)
	s_barrier
	s_setprio 1
	s_waitcnt lgkmcnt(0)
	v_mfma_f32_16x16x32_bf16 v[60:63], v[128:131], v[196:199], v[60:63]
	v_mfma_f32_16x16x32_bf16 v[56:59], v[156:159], v[196:199], v[56:59]
	v_mfma_f32_16x16x32_bf16 v[48:51], v[128:131], v[204:207], v[48:51]
	v_mfma_f32_16x16x32_bf16 v[40:43], v[156:159], v[204:207], v[40:43]
	v_mfma_f32_16x16x32_bf16 v[32:35], v[128:131], v[212:215], v[32:35]
	v_mfma_f32_16x16x32_bf16 v[24:27], v[156:159], v[212:215], v[24:27]
	v_mfma_f32_16x16x32_bf16 v[16:19], v[128:131], v[228:231], v[16:19]
	v_mfma_f32_16x16x32_bf16 v[8:11], v[156:159], v[228:231], v[8:11]
	v_mfma_f32_16x16x32_bf16 v[60:63], v[146:149], v[200:203], v[60:63]
	v_mfma_f32_16x16x32_bf16 v[56:59], v[160:163], v[200:203], v[56:59]
	v_mfma_f32_16x16x32_bf16 v[48:51], v[146:149], v[208:211], v[48:51]
	v_mfma_f32_16x16x32_bf16 v[40:43], v[160:163], v[208:211], v[40:43]
	v_mfma_f32_16x16x32_bf16 v[32:35], v[146:149], v[216:219], v[32:35]
	v_mfma_f32_16x16x32_bf16 v[24:27], v[160:163], v[216:219], v[24:27]
	v_mfma_f32_16x16x32_bf16 v[16:19], v[146:149], v[232:235], v[16:19]
	v_mfma_f32_16x16x32_bf16 v[8:11], v[160:163], v[232:235], v[8:11]
	s_setprio 0
	s_setprio 1
	v_mfma_f32_16x16x32_bf16 v[52:55], v[164:167], v[196:199], v[52:55]
	v_mfma_f32_16x16x32_bf16 v[44:47], v[188:191], v[196:199], v[44:47]
	v_mfma_f32_16x16x32_bf16 v[36:39], v[164:167], v[204:207], v[36:39]
	v_mfma_f32_16x16x32_bf16 v[28:31], v[188:191], v[204:207], v[28:31]
	v_mfma_f32_16x16x32_bf16 v[20:23], v[164:167], v[212:215], v[20:23]
	v_mfma_f32_16x16x32_bf16 v[12:15], v[188:191], v[212:215], v[12:15]
	v_mfma_f32_16x16x32_bf16 v[4:7], v[164:167], v[228:231], v[4:7]
	v_mfma_f32_16x16x32_bf16 v[0:3], v[188:191], v[228:231], v[0:3]
	v_mfma_f32_16x16x32_bf16 v[52:55], v[184:187], v[200:203], v[52:55]
	v_mfma_f32_16x16x32_bf16 v[44:47], v[192:195], v[200:203], v[44:47]
	v_mfma_f32_16x16x32_bf16 v[36:39], v[184:187], v[208:211], v[36:39]
	v_mfma_f32_16x16x32_bf16 v[28:31], v[192:195], v[208:211], v[28:31]
	v_mfma_f32_16x16x32_bf16 v[20:23], v[184:187], v[216:219], v[20:23]
	v_mfma_f32_16x16x32_bf16 v[12:15], v[192:195], v[216:219], v[12:15]
	v_mfma_f32_16x16x32_bf16 v[4:7], v[184:187], v[232:235], v[4:7]
	v_mfma_f32_16x16x32_bf16 v[0:3], v[192:195], v[232:235], v[0:3]
	s_setprio 0
	s_barrier
	s_add_i32 s13, 0, 0x18000
	v_add_u32_e32 v155, s13, v153
	s_add_i32 s30, 0, 0x1c000
	ds_read_b128 v[128:131], v155
	ds_read_b128 v[146:149], v155 offset:1024
	ds_read_b128 v[156:159], v155 offset:2048
	ds_read_b128 v[160:163], v155 offset:3072
	v_add_u32_e32 v155, s30, v153
	ds_read_b128 v[164:167], v155
	ds_read_b128 v[184:187], v155 offset:1024
	ds_read_b128 v[188:191], v155 offset:2048
	ds_read_b128 v[192:195], v155 offset:3072
	s_add_u32 s0, s40, 0xb0000
	s_addc_u32 s1, s41, 0
	s_mov_b32 m0, s45
	ds_read_b128 v[196:199], v154 offset:32768
	ds_read_b128 v[200:203], v154 offset:33792
	ds_read_b128 v[204:207], v154 offset:34816
	ds_read_b128 v[208:211], v154 offset:35840
	ds_read_b128 v[212:215], v154 offset:36864
	ds_read_b128 v[216:219], v154 offset:37888
	ds_read_b128 v[228:231], v154 offset:38912
	ds_read_b128 v[232:235], v154 offset:39936
	global_load_lds_dwordx4 v132, s[0:1]
	s_mov_b32 m0, s46
	s_nop 0
	global_load_lds_dwordx4 v134, s[0:1]
	s_mov_b32 m0, s43
	s_nop 0
	global_load_lds_dwordx4 v[238:239], off
	s_mov_b32 m0, s44
	s_nop 0
	global_load_lds_dwordx4 v[240:241], off
	s_waitcnt vmcnt(8)
	s_waitcnt lgkmcnt(0)
	s_barrier
	s_setprio 1
	s_waitcnt lgkmcnt(0)
	v_mfma_f32_16x16x32_bf16 v[124:127], v[128:131], v[196:199], v[124:127]
	v_mfma_f32_16x16x32_bf16 v[120:123], v[156:159], v[196:199], v[120:123]
	v_mfma_f32_16x16x32_bf16 v[112:115], v[128:131], v[204:207], v[112:115]
	v_mfma_f32_16x16x32_bf16 v[104:107], v[156:159], v[204:207], v[104:107]
	v_mfma_f32_16x16x32_bf16 v[96:99], v[128:131], v[212:215], v[96:99]
	v_mfma_f32_16x16x32_bf16 v[88:91], v[156:159], v[212:215], v[88:91]
	v_mfma_f32_16x16x32_bf16 v[80:83], v[128:131], v[228:231], v[80:83]
	v_mfma_f32_16x16x32_bf16 v[72:75], v[156:159], v[228:231], v[72:75]
	v_mfma_f32_16x16x32_bf16 v[124:127], v[146:149], v[200:203], v[124:127]
	v_mfma_f32_16x16x32_bf16 v[120:123], v[160:163], v[200:203], v[120:123]
	v_mfma_f32_16x16x32_bf16 v[112:115], v[146:149], v[208:211], v[112:115]
	v_mfma_f32_16x16x32_bf16 v[104:107], v[160:163], v[208:211], v[104:107]
	v_mfma_f32_16x16x32_bf16 v[96:99], v[146:149], v[216:219], v[96:99]
	v_mfma_f32_16x16x32_bf16 v[88:91], v[160:163], v[216:219], v[88:91]
	v_mfma_f32_16x16x32_bf16 v[80:83], v[146:149], v[232:235], v[80:83]
	v_mfma_f32_16x16x32_bf16 v[72:75], v[160:163], v[232:235], v[72:75]
	s_setprio 0
	s_setprio 1
	v_mfma_f32_16x16x32_bf16 v[116:119], v[164:167], v[196:199], v[116:119]
	v_mfma_f32_16x16x32_bf16 v[108:111], v[188:191], v[196:199], v[108:111]
	v_mfma_f32_16x16x32_bf16 v[100:103], v[164:167], v[204:207], v[100:103]
	v_mfma_f32_16x16x32_bf16 v[92:95], v[188:191], v[204:207], v[92:95]
	v_mfma_f32_16x16x32_bf16 v[84:87], v[164:167], v[212:215], v[84:87]
	v_mfma_f32_16x16x32_bf16 v[76:79], v[188:191], v[212:215], v[76:79]
	v_mfma_f32_16x16x32_bf16 v[68:71], v[164:167], v[228:231], v[68:71]
	v_mfma_f32_16x16x32_bf16 v[64:67], v[188:191], v[228:231], v[64:67]
	v_mfma_f32_16x16x32_bf16 v[116:119], v[184:187], v[200:203], v[116:119]
	v_mfma_f32_16x16x32_bf16 v[108:111], v[192:195], v[200:203], v[108:111]
	v_mfma_f32_16x16x32_bf16 v[100:103], v[184:187], v[208:211], v[100:103]
	v_mfma_f32_16x16x32_bf16 v[92:95], v[192:195], v[208:211], v[92:95]
	v_mfma_f32_16x16x32_bf16 v[84:87], v[184:187], v[216:219], v[84:87]
	v_mfma_f32_16x16x32_bf16 v[76:79], v[192:195], v[216:219], v[76:79]
	v_mfma_f32_16x16x32_bf16 v[68:71], v[184:187], v[232:235], v[68:71]
	v_mfma_f32_16x16x32_bf16 v[64:67], v[192:195], v[232:235], v[64:67]
	s_setprio 0
	s_barrier
	s_add_i32 s0, s13, s42
	v_lshl_add_u64 v[150:151], v[150:151], 0, s[16:17]
	s_mov_b32 m0, s0
	ds_read_b128 v[196:199], v154 offset:49152
	ds_read_b128 v[200:203], v154 offset:50176
	ds_read_b128 v[204:207], v154 offset:51200
	ds_read_b128 v[208:211], v154 offset:52224
	ds_read_b128 v[212:215], v154 offset:53248
	ds_read_b128 v[216:219], v154 offset:54272
	ds_read_b128 v[228:231], v154 offset:55296
	ds_read_b128 v[232:235], v154 offset:56320
	global_load_lds_dwordx4 v[150:151], off
	s_add_i32 m0, s0, 0x2000
	s_add_u32 s0, s36, 0xb0080
	v_lshl_add_u64 v[150:151], v[236:237], 0, s[16:17]
	s_addc_u32 s1, s37, 0
	s_add_i32 s13, s30, s42
	global_load_lds_dwordx4 v[150:151], off
	s_mov_b32 m0, s13
	s_nop 0
	global_load_lds_dwordx4 v170, s[0:1]
	s_add_i32 m0, s13, 0x2000
	s_nop 0
	global_load_lds_dwordx4 v136, s[0:1]
	v_lshl_add_u64 v[150:151], v[238:239], 0, s[16:17]
	s_mov_b32 m0, s47
	s_nop 0
	global_load_lds_dwordx4 v[150:151], off
	v_lshl_add_u64 v[150:151], v[240:241], 0, s[16:17]
	s_mov_b32 m0, s48
	s_nop 0
	global_load_lds_dwordx4 v[150:151], off
	s_waitcnt vmcnt(6)
	s_waitcnt lgkmcnt(0)
	s_barrier
	s_setprio 1
	s_waitcnt lgkmcnt(0)
	v_mfma_f32_16x16x32_bf16 v[60:63], v[128:131], v[196:199], v[60:63]
	v_mfma_f32_16x16x32_bf16 v[56:59], v[156:159], v[196:199], v[56:59]
	v_mfma_f32_16x16x32_bf16 v[48:51], v[128:131], v[204:207], v[48:51]
	v_mfma_f32_16x16x32_bf16 v[40:43], v[156:159], v[204:207], v[40:43]
	v_mfma_f32_16x16x32_bf16 v[32:35], v[128:131], v[212:215], v[32:35]
	v_mfma_f32_16x16x32_bf16 v[24:27], v[156:159], v[212:215], v[24:27]
	v_mfma_f32_16x16x32_bf16 v[16:19], v[128:131], v[228:231], v[16:19]
	v_mfma_f32_16x16x32_bf16 v[8:11], v[156:159], v[228:231], v[8:11]
	v_mfma_f32_16x16x32_bf16 v[60:63], v[146:149], v[200:203], v[60:63]
	v_mfma_f32_16x16x32_bf16 v[56:59], v[160:163], v[200:203], v[56:59]
	v_mfma_f32_16x16x32_bf16 v[48:51], v[146:149], v[208:211], v[48:51]
	v_mfma_f32_16x16x32_bf16 v[40:43], v[160:163], v[208:211], v[40:43]
	v_mfma_f32_16x16x32_bf16 v[32:35], v[146:149], v[216:219], v[32:35]
	v_mfma_f32_16x16x32_bf16 v[24:27], v[160:163], v[216:219], v[24:27]
	v_mfma_f32_16x16x32_bf16 v[16:19], v[146:149], v[232:235], v[16:19]
	v_mfma_f32_16x16x32_bf16 v[8:11], v[160:163], v[232:235], v[8:11]
	s_setprio 0
	s_setprio 1
	v_mfma_f32_16x16x32_bf16 v[52:55], v[164:167], v[196:199], v[52:55]
	v_mfma_f32_16x16x32_bf16 v[44:47], v[188:191], v[196:199], v[44:47]
	v_mfma_f32_16x16x32_bf16 v[36:39], v[164:167], v[204:207], v[36:39]
	v_mfma_f32_16x16x32_bf16 v[28:31], v[188:191], v[204:207], v[28:31]
	v_mfma_f32_16x16x32_bf16 v[20:23], v[164:167], v[212:215], v[20:23]
	v_mfma_f32_16x16x32_bf16 v[12:15], v[188:191], v[212:215], v[12:15]
	v_mfma_f32_16x16x32_bf16 v[4:7], v[164:167], v[228:231], v[4:7]
	v_mfma_f32_16x16x32_bf16 v[0:3], v[188:191], v[228:231], v[0:3]
	v_mfma_f32_16x16x32_bf16 v[52:55], v[184:187], v[200:203], v[52:55]
	v_mfma_f32_16x16x32_bf16 v[44:47], v[192:195], v[200:203], v[44:47]
	v_mfma_f32_16x16x32_bf16 v[36:39], v[184:187], v[208:211], v[36:39]
	v_mfma_f32_16x16x32_bf16 v[28:31], v[192:195], v[208:211], v[28:31]
	v_mfma_f32_16x16x32_bf16 v[20:23], v[184:187], v[216:219], v[20:23]
	v_mfma_f32_16x16x32_bf16 v[12:15], v[192:195], v[216:219], v[12:15]
	v_mfma_f32_16x16x32_bf16 v[4:7], v[184:187], v[232:235], v[4:7]
	v_mfma_f32_16x16x32_bf16 v[0:3], v[192:195], v[232:235], v[0:3]
	s_setprio 0
	s_barrier
	s_add_i32 s12, s12, 2
	s_add_u32 s54, s54, 0x100
	s_addc_u32 s55, s55, 0
	s_cmp_gt_u32 s12, 41
	s_mov_b64 s[30:31], s[34:35]
	s_cbranch_scc0 .LBB0_1029
	s_and_b64 vcc, exec, s[24:25]
	s_cbranch_vccz .LBB0_1032
	s_barrier
.LBB0_1032:
	v_lshl_add_u32 v150, s52, 8, v152
	s_lshl_b32 s0, s53, 8
	s_ashr_i32 s1, s0, 31
	v_ashrrev_i32_e32 v151, 31, v150
	v_lshl_add_u64 v[148:149], s[0:1], 1, v[138:139]
	v_lshlrev_b64 v[128:129], 11, v[150:151]
	v_or_b32_e32 v200, 16, v150
	v_lshl_add_u64 v[128:129], v[148:149], 0, v[128:129]
	v_ashrrev_i32_e32 v201, 31, v200
	global_load_dwordx4 v[156:159], v[128:129], off
	global_load_dwordx4 v[160:163], v[128:129], off offset:256
	v_lshlrev_b64 v[128:129], 11, v[200:201]
	v_or_b32_e32 v202, 32, v150
	v_lshl_add_u64 v[128:129], v[148:149], 0, v[128:129]
	v_ashrrev_i32_e32 v203, 31, v202
	global_load_dwordx4 v[164:167], v[128:129], off
	global_load_dwordx4 v[184:187], v[128:129], off offset:256
	v_lshlrev_b64 v[128:129], 11, v[202:203]
	v_or_b32_e32 v204, 48, v150
	v_lshl_add_u64 v[128:129], v[148:149], 0, v[128:129]
	v_ashrrev_i32_e32 v205, 31, v204
	global_load_dwordx4 v[188:191], v[128:129], off
	global_load_dwordx4 v[192:195], v[128:129], off offset:256
	v_lshlrev_b64 v[128:129], 11, v[204:205]
	v_lshl_add_u64 v[128:129], v[148:149], 0, v[128:129]
	global_load_dwordx4 v[196:199], v[128:129], off
	s_nop 0
	global_load_dwordx4 v[128:131], v[128:129], off offset:256
	v_lshl_add_u64 v[146:147], s[0:1], 2, v[140:141]
	s_waitcnt vmcnt(0)
	v_lshlrev_b32_e32 v208, 16, v156
	v_and_b32_e32 v209, 0xffff0000, v156
	v_lshlrev_b32_e32 v156, 16, v157
	v_and_b32_e32 v157, 0xffff0000, v157
	v_lshlrev_b64 v[206:207], 12, v[150:151]
	v_pk_add_f32 v[126:127], v[126:127], v[156:157]
	v_lshlrev_b32_e32 v156, 16, v158
	v_and_b32_e32 v157, 0xffff0000, v158
	v_lshl_add_u64 v[206:207], v[146:147], 0, v[206:207]
	v_pk_add_f32 v[124:125], v[124:125], v[208:209]
	v_pk_add_f32 v[120:121], v[120:121], v[156:157]
	v_lshlrev_b32_e32 v156, 16, v159
	v_and_b32_e32 v157, 0xffff0000, v159
	v_pk_add_f32 v[122:123], v[122:123], v[156:157]
	global_store_dwordx4 v[206:207], v[124:127], off
	global_store_dwordx4 v[206:207], v[120:123], off offset:16
	s_nop 1
	v_lshlrev_b32_e32 v120, 16, v160
	v_and_b32_e32 v121, 0xffff0000, v160
	v_pk_add_f32 v[116:117], v[116:117], v[120:121]
	v_lshlrev_b32_e32 v120, 16, v161
	v_and_b32_e32 v121, 0xffff0000, v161
	v_pk_add_f32 v[118:119], v[118:119], v[120:121]
	v_lshlrev_b32_e32 v120, 16, v162
	v_and_b32_e32 v121, 0xffff0000, v162
	v_pk_add_f32 v[108:109], v[108:109], v[120:121]
	v_lshlrev_b32_e32 v120, 16, v163
	v_and_b32_e32 v121, 0xffff0000, v163
	v_pk_add_f32 v[110:111], v[110:111], v[120:121]
	global_store_dwordx4 v[206:207], v[116:119], off offset:512
	global_store_dwordx4 v[206:207], v[108:111], off offset:528
	s_nop 1
	v_lshlrev_b64 v[108:109], 12, v[200:201]
	v_lshl_add_u64 v[116:117], v[146:147], 0, v[108:109]
	v_lshlrev_b32_e32 v108, 16, v164
	v_and_b32_e32 v109, 0xffff0000, v164
	v_pk_add_f32 v[108:109], v[112:113], v[108:109]
	v_lshlrev_b32_e32 v110, 16, v165
	v_and_b32_e32 v111, 0xffff0000, v165
	v_lshlrev_b32_e32 v112, 16, v166
	v_and_b32_e32 v113, 0xffff0000, v166
	v_pk_add_f32 v[110:111], v[114:115], v[110:111]
	v_pk_add_f32 v[104:105], v[104:105], v[112:113]
	v_lshlrev_b32_e32 v112, 16, v167
	v_and_b32_e32 v113, 0xffff0000, v167
	v_pk_add_f32 v[106:107], v[106:107], v[112:113]
	global_store_dwordx4 v[116:117], v[108:111], off
	global_store_dwordx4 v[116:117], v[104:107], off offset:16
	s_nop 1
	v_lshlrev_b32_e32 v104, 16, v184
	v_and_b32_e32 v105, 0xffff0000, v184
	v_pk_add_f32 v[100:101], v[100:101], v[104:105]
	v_lshlrev_b32_e32 v104, 16, v185
	v_and_b32_e32 v105, 0xffff0000, v185
	v_pk_add_f32 v[102:103], v[102:103], v[104:105]
	v_lshlrev_b32_e32 v104, 16, v186
	v_and_b32_e32 v105, 0xffff0000, v186
	v_pk_add_f32 v[92:93], v[92:93], v[104:105]
	v_lshlrev_b32_e32 v104, 16, v187
	v_and_b32_e32 v105, 0xffff0000, v187
	v_pk_add_f32 v[94:95], v[94:95], v[104:105]
	global_store_dwordx4 v[116:117], v[100:103], off offset:512
	global_store_dwordx4 v[116:117], v[92:95], off offset:528
	s_nop 1
	v_lshlrev_b64 v[92:93], 12, v[202:203]
	v_lshl_add_u64 v[100:101], v[146:147], 0, v[92:93]
	v_lshlrev_b32_e32 v92, 16, v188
	v_and_b32_e32 v93, 0xffff0000, v188
	v_pk_add_f32 v[92:93], v[96:97], v[92:93]
	v_lshlrev_b32_e32 v94, 16, v189
	v_and_b32_e32 v95, 0xffff0000, v189
	v_lshlrev_b32_e32 v96, 16, v190
	v_and_b32_e32 v97, 0xffff0000, v190
	v_pk_add_f32 v[94:95], v[98:99], v[94:95]
	v_pk_add_f32 v[88:89], v[88:89], v[96:97]
	v_lshlrev_b32_e32 v96, 16, v191
	v_and_b32_e32 v97, 0xffff0000, v191
	v_pk_add_f32 v[90:91], v[90:91], v[96:97]
	global_store_dwordx4 v[100:101], v[92:95], off
	global_store_dwordx4 v[100:101], v[88:91], off offset:16
	s_nop 1
	v_lshlrev_b32_e32 v88, 16, v192
	v_and_b32_e32 v89, 0xffff0000, v192
	v_pk_add_f32 v[84:85], v[84:85], v[88:89]
	v_lshlrev_b32_e32 v88, 16, v193
	v_and_b32_e32 v89, 0xffff0000, v193
	v_pk_add_f32 v[86:87], v[86:87], v[88:89]
	v_lshlrev_b32_e32 v88, 16, v194
	v_and_b32_e32 v89, 0xffff0000, v194
	v_pk_add_f32 v[76:77], v[76:77], v[88:89]
	v_lshlrev_b32_e32 v88, 16, v195
	v_and_b32_e32 v89, 0xffff0000, v195
	v_pk_add_f32 v[78:79], v[78:79], v[88:89]
	global_store_dwordx4 v[100:101], v[84:87], off offset:512
	global_store_dwordx4 v[100:101], v[76:79], off offset:528
	s_nop 1
	v_lshlrev_b64 v[76:77], 12, v[204:205]
	v_lshl_add_u64 v[84:85], v[146:147], 0, v[76:77]
	v_lshlrev_b32_e32 v76, 16, v196
	v_and_b32_e32 v77, 0xffff0000, v196
	v_pk_add_f32 v[76:77], v[80:81], v[76:77]
	v_lshlrev_b32_e32 v78, 16, v197
	v_and_b32_e32 v79, 0xffff0000, v197
	v_lshlrev_b32_e32 v80, 16, v198
	v_and_b32_e32 v81, 0xffff0000, v198
	v_pk_add_f32 v[78:79], v[82:83], v[78:79]
	v_pk_add_f32 v[72:73], v[72:73], v[80:81]
	v_lshlrev_b32_e32 v80, 16, v199
	v_and_b32_e32 v81, 0xffff0000, v199
	v_pk_add_f32 v[74:75], v[74:75], v[80:81]
	global_store_dwordx4 v[84:85], v[76:79], off
	global_store_dwordx4 v[84:85], v[72:75], off offset:16
	s_nop 1
	v_lshlrev_b32_e32 v72, 16, v128
	v_and_b32_e32 v73, 0xffff0000, v128
	v_pk_add_f32 v[68:69], v[68:69], v[72:73]
	v_lshlrev_b32_e32 v72, 16, v129
	v_and_b32_e32 v73, 0xffff0000, v129
	v_pk_add_f32 v[70:71], v[70:71], v[72:73]
	v_lshlrev_b32_e32 v72, 16, v130
	v_and_b32_e32 v73, 0xffff0000, v130
	v_pk_add_f32 v[64:65], v[64:65], v[72:73]
	v_lshlrev_b32_e32 v72, 16, v131
	v_and_b32_e32 v73, 0xffff0000, v131
	v_pk_add_f32 v[66:67], v[66:67], v[72:73]
	global_store_dwordx4 v[84:85], v[68:71], off offset:512
	global_store_dwordx4 v[84:85], v[64:67], off offset:528
	v_add_u32_e32 v96, 0x80, v150
	v_ashrrev_i32_e32 v97, 31, v96
	v_lshlrev_b64 v[64:65], 11, v[96:97]
	v_add_u32_e32 v98, 0x90, v150
	v_lshl_add_u64 v[64:65], v[148:149], 0, v[64:65]
	v_ashrrev_i32_e32 v99, 31, v98
	global_load_dwordx4 v[68:71], v[64:65], off
	global_load_dwordx4 v[72:75], v[64:65], off offset:256
	v_lshlrev_b64 v[64:65], 11, v[98:99]
	v_add_u32_e32 v100, 0xa0, v150
	v_lshl_add_u64 v[64:65], v[148:149], 0, v[64:65]
	v_ashrrev_i32_e32 v101, 31, v100
	global_load_dwordx4 v[76:79], v[64:65], off
	global_load_dwordx4 v[80:83], v[64:65], off offset:256
	v_lshlrev_b64 v[64:65], 11, v[100:101]
	v_add_u32_e32 v102, 0xb0, v150
	v_lshl_add_u64 v[64:65], v[148:149], 0, v[64:65]
	v_ashrrev_i32_e32 v103, 31, v102
	global_load_dwordx4 v[84:87], v[64:65], off
	global_load_dwordx4 v[88:91], v[64:65], off offset:256
	v_lshlrev_b64 v[64:65], 11, v[102:103]
	v_lshl_add_u64 v[64:65], v[148:149], 0, v[64:65]
	global_load_dwordx4 v[92:95], v[64:65], off
	s_nop 0
	global_load_dwordx4 v[64:67], v[64:65], off offset:256
	s_waitcnt vmcnt(7)
	v_lshlrev_b32_e32 v104, 16, v68
	v_and_b32_e32 v105, 0xffff0000, v68
	v_lshlrev_b32_e32 v68, 16, v69
	v_and_b32_e32 v69, 0xffff0000, v69
	v_lshlrev_b64 v[96:97], 12, v[96:97]
	v_pk_add_f32 v[62:63], v[62:63], v[68:69]
	v_lshlrev_b32_e32 v68, 16, v70
	v_and_b32_e32 v69, 0xffff0000, v70
	v_lshl_add_u64 v[96:97], v[146:147], 0, v[96:97]
	v_pk_add_f32 v[60:61], v[60:61], v[104:105]
	v_pk_add_f32 v[56:57], v[56:57], v[68:69]
	v_lshlrev_b32_e32 v68, 16, v71
	v_and_b32_e32 v69, 0xffff0000, v71
	v_pk_add_f32 v[58:59], v[58:59], v[68:69]
	global_store_dwordx4 v[96:97], v[60:63], off
	global_store_dwordx4 v[96:97], v[56:59], off offset:16
	s_waitcnt vmcnt(8)
	s_nop 0
	v_lshlrev_b32_e32 v56, 16, v72
	v_and_b32_e32 v57, 0xffff0000, v72
	v_pk_add_f32 v[52:53], v[52:53], v[56:57]
	v_lshlrev_b32_e32 v56, 16, v73
	v_and_b32_e32 v57, 0xffff0000, v73
	v_pk_add_f32 v[54:55], v[54:55], v[56:57]
	v_lshlrev_b32_e32 v56, 16, v74
	v_and_b32_e32 v57, 0xffff0000, v74
	v_pk_add_f32 v[44:45], v[44:45], v[56:57]
	v_lshlrev_b32_e32 v56, 16, v75
	v_and_b32_e32 v57, 0xffff0000, v75
	v_pk_add_f32 v[46:47], v[46:47], v[56:57]
	global_store_dwordx4 v[96:97], v[52:55], off offset:512
	global_store_dwordx4 v[96:97], v[44:47], off offset:528
	s_nop 1
	v_lshlrev_b64 v[44:45], 12, v[98:99]
	v_lshl_add_u64 v[52:53], v[146:147], 0, v[44:45]
	s_waitcnt vmcnt(9)
	v_lshlrev_b32_e32 v44, 16, v76
	v_and_b32_e32 v45, 0xffff0000, v76
	v_pk_add_f32 v[44:45], v[48:49], v[44:45]
	v_lshlrev_b32_e32 v46, 16, v77
	v_and_b32_e32 v47, 0xffff0000, v77
	v_lshlrev_b32_e32 v48, 16, v78
	v_and_b32_e32 v49, 0xffff0000, v78
	v_pk_add_f32 v[46:47], v[50:51], v[46:47]
	v_pk_add_f32 v[40:41], v[40:41], v[48:49]
	v_lshlrev_b32_e32 v48, 16, v79
	v_and_b32_e32 v49, 0xffff0000, v79
	v_pk_add_f32 v[42:43], v[42:43], v[48:49]
	global_store_dwordx4 v[52:53], v[44:47], off
	global_store_dwordx4 v[52:53], v[40:43], off offset:16
	s_waitcnt vmcnt(10)
	s_nop 0
	v_lshlrev_b32_e32 v40, 16, v80
	v_and_b32_e32 v41, 0xffff0000, v80
	v_pk_add_f32 v[36:37], v[36:37], v[40:41]
	v_lshlrev_b32_e32 v40, 16, v81
	v_and_b32_e32 v41, 0xffff0000, v81
	v_pk_add_f32 v[38:39], v[38:39], v[40:41]
	v_lshlrev_b32_e32 v40, 16, v82
	v_and_b32_e32 v41, 0xffff0000, v82
	v_pk_add_f32 v[28:29], v[28:29], v[40:41]
	v_lshlrev_b32_e32 v40, 16, v83
	v_and_b32_e32 v41, 0xffff0000, v83
	v_pk_add_f32 v[30:31], v[30:31], v[40:41]
	global_store_dwordx4 v[52:53], v[36:39], off offset:512
	global_store_dwordx4 v[52:53], v[28:31], off offset:528
	s_nop 1
	v_lshlrev_b64 v[28:29], 12, v[100:101]
	v_lshl_add_u64 v[36:37], v[146:147], 0, v[28:29]
	s_waitcnt vmcnt(11)
	v_lshlrev_b32_e32 v28, 16, v84
	v_and_b32_e32 v29, 0xffff0000, v84
	v_pk_add_f32 v[28:29], v[32:33], v[28:29]
	v_lshlrev_b32_e32 v30, 16, v85
	v_and_b32_e32 v31, 0xffff0000, v85
	v_lshlrev_b32_e32 v32, 16, v86
	v_and_b32_e32 v33, 0xffff0000, v86
	v_pk_add_f32 v[30:31], v[34:35], v[30:31]
	v_pk_add_f32 v[24:25], v[24:25], v[32:33]
	v_lshlrev_b32_e32 v32, 16, v87
	v_and_b32_e32 v33, 0xffff0000, v87
	v_pk_add_f32 v[26:27], v[26:27], v[32:33]
	global_store_dwordx4 v[36:37], v[28:31], off
	global_store_dwordx4 v[36:37], v[24:27], off offset:16
	s_waitcnt vmcnt(12)
	s_nop 0
	v_lshlrev_b32_e32 v24, 16, v88
	v_and_b32_e32 v25, 0xffff0000, v88
	v_pk_add_f32 v[20:21], v[20:21], v[24:25]
	v_lshlrev_b32_e32 v24, 16, v89
	v_and_b32_e32 v25, 0xffff0000, v89
	v_pk_add_f32 v[22:23], v[22:23], v[24:25]
	v_lshlrev_b32_e32 v24, 16, v90
	v_and_b32_e32 v25, 0xffff0000, v90
	v_pk_add_f32 v[12:13], v[12:13], v[24:25]
	v_lshlrev_b32_e32 v24, 16, v91
	v_and_b32_e32 v25, 0xffff0000, v91
	v_pk_add_f32 v[14:15], v[14:15], v[24:25]
	global_store_dwordx4 v[36:37], v[20:23], off offset:512
	global_store_dwordx4 v[36:37], v[12:15], off offset:528
	s_nop 1
	v_lshlrev_b64 v[12:13], 12, v[102:103]
	v_lshl_add_u64 v[20:21], v[146:147], 0, v[12:13]
	s_waitcnt vmcnt(13)
	v_lshlrev_b32_e32 v12, 16, v92
	v_and_b32_e32 v13, 0xffff0000, v92
	v_pk_add_f32 v[12:13], v[16:17], v[12:13]
	v_lshlrev_b32_e32 v14, 16, v93
	v_and_b32_e32 v15, 0xffff0000, v93
	v_lshlrev_b32_e32 v16, 16, v94
	v_and_b32_e32 v17, 0xffff0000, v94
	v_pk_add_f32 v[14:15], v[18:19], v[14:15]
	v_pk_add_f32 v[8:9], v[8:9], v[16:17]
	v_lshlrev_b32_e32 v16, 16, v95
	v_and_b32_e32 v17, 0xffff0000, v95
	v_pk_add_f32 v[10:11], v[10:11], v[16:17]
	global_store_dwordx4 v[20:21], v[12:15], off
	global_store_dwordx4 v[20:21], v[8:11], off offset:16
	s_waitcnt vmcnt(14)
	s_nop 0
	v_lshlrev_b32_e32 v8, 16, v64
	v_and_b32_e32 v9, 0xffff0000, v64
	v_pk_add_f32 v[4:5], v[4:5], v[8:9]
	v_lshlrev_b32_e32 v8, 16, v65
	v_and_b32_e32 v9, 0xffff0000, v65
	v_pk_add_f32 v[6:7], v[6:7], v[8:9]
	v_lshlrev_b32_e32 v8, 16, v66
	v_and_b32_e32 v9, 0xffff0000, v66
	v_pk_add_f32 v[0:1], v[0:1], v[8:9]
	v_lshlrev_b32_e32 v8, 16, v67
	v_and_b32_e32 v9, 0xffff0000, v67
	v_pk_add_f32 v[2:3], v[2:3], v[8:9]
	global_store_dwordx4 v[20:21], v[4:7], off offset:512
	global_store_dwordx4 v[20:21], v[0:3], off offset:528
	s_and_b64 vcc, exec, s[4:5]
	s_mov_b64 s[4:5], -1
	s_cbranch_vccnz .LBB0_1017
	s_andn2_b64 vcc, exec, s[8:9]
	s_cbranch_vccnz .LBB0_1016
	s_mov_b32 s98, 1
	s_branch .LBB0_1016

.LBB0_1060:
	s_add_u32 s58, s40, 0x100
	s_addc_u32 s59, s41, 0
	s_mov_b32 s12, -2
	s_waitcnt lgkmcnt(0)
	s_waitcnt vmcnt(0)
	s_cmp_eq_u32 s98, 1
	s_cbranch_scc0 .Lrestag_1061
	s_barrier
	s_mov_b32 s98, 0
.Lrestag_1061:
	s_add_u32 s40, s36, 0x100
	s_addc_u32 s41, s37, 0
	s_add_i32 s0, 0, 0x10000
	s_cmp_eq_u32 s12, 40
	s_cselect_b32 s45, s9, s41
	s_cselect_b32 s44, s8, s40
	s_cselect_b32 s43, s35, s59
	s_cselect_b32 s42, s34, s58
	s_add_i32 s13, 0, 0x14000
	v_add_u32_e32 v140, s0, v197
	v_add_u32_e32 v184, s13, v197
	ds_read_b128 v[128:131], v140
	ds_read_b128 v[132:135], v140 offset:1024
	ds_read_b128 v[136:139], v140 offset:2048
	ds_read_b128 v[140:143], v140 offset:3072
	ds_read_b128 v[144:147], v184
	ds_read_b128 v[148:151], v184 offset:1024
	ds_read_b128 v[164:167], v184 offset:2048
	ds_read_b128 v[184:187], v184 offset:3072
	s_add_i32 m0, s47, 0xc000
	ds_read_b128 v[188:191], v198
	ds_read_b128 v[192:195], v198 offset:1024
	ds_read_b128 v[200:203], v198 offset:2048
	ds_read_b128 v[204:207], v198 offset:3072
	ds_read_b128 v[208:211], v198 offset:4096
	ds_read_b128 v[212:215], v198 offset:5120
	ds_read_b128 v[216:219], v198 offset:6144
	ds_read_b128 v[228:231], v198 offset:7168
	global_load_lds_dwordx4 v160, s[36:37]
	s_add_i32 m0, s47, 0xe000
	s_nop 0
	global_load_lds_dwordx4 v162, s[36:37]
	s_nop 0
	s_waitcnt lgkmcnt(0)
	s_barrier
	s_setprio 1
	s_waitcnt lgkmcnt(0)
	v_mfma_f32_16x16x32_bf16 v[124:127], v[128:131], v[188:191], 0
	v_mfma_f32_16x16x32_bf16 v[120:123], v[136:139], v[188:191], 0
	v_mfma_f32_16x16x32_bf16 v[108:111], v[128:131], v[200:203], 0
	v_mfma_f32_16x16x32_bf16 v[104:107], v[136:139], v[200:203], 0
	v_mfma_f32_16x16x32_bf16 v[92:95], v[128:131], v[208:211], 0
	v_mfma_f32_16x16x32_bf16 v[88:91], v[136:139], v[208:211], 0
	v_mfma_f32_16x16x32_bf16 v[76:79], v[128:131], v[216:219], 0
	v_mfma_f32_16x16x32_bf16 v[72:75], v[136:139], v[216:219], 0
	v_mfma_f32_16x16x32_bf16 v[124:127], v[132:135], v[192:195], v[124:127]
	v_mfma_f32_16x16x32_bf16 v[120:123], v[140:143], v[192:195], v[120:123]
	v_mfma_f32_16x16x32_bf16 v[108:111], v[132:135], v[204:207], v[108:111]
	v_mfma_f32_16x16x32_bf16 v[104:107], v[140:143], v[204:207], v[104:107]
	v_mfma_f32_16x16x32_bf16 v[92:95], v[132:135], v[212:215], v[92:95]
	v_mfma_f32_16x16x32_bf16 v[88:91], v[140:143], v[212:215], v[88:91]
	v_mfma_f32_16x16x32_bf16 v[76:79], v[132:135], v[228:231], v[76:79]
	v_mfma_f32_16x16x32_bf16 v[72:75], v[140:143], v[228:231], v[72:75]
	s_setprio 0
	s_setprio 1
	v_mfma_f32_16x16x32_bf16 v[116:119], v[144:147], v[188:191], 0
	v_mfma_f32_16x16x32_bf16 v[112:115], v[164:167], v[188:191], 0
	v_mfma_f32_16x16x32_bf16 v[100:103], v[144:147], v[200:203], 0
	v_mfma_f32_16x16x32_bf16 v[96:99], v[164:167], v[200:203], 0
	v_mfma_f32_16x16x32_bf16 v[84:87], v[144:147], v[208:211], 0
	v_mfma_f32_16x16x32_bf16 v[80:83], v[164:167], v[208:211], 0
	v_mfma_f32_16x16x32_bf16 v[68:71], v[144:147], v[216:219], 0
	v_mfma_f32_16x16x32_bf16 v[64:67], v[164:167], v[216:219], 0
	v_mfma_f32_16x16x32_bf16 v[116:119], v[148:151], v[192:195], v[116:119]
	v_mfma_f32_16x16x32_bf16 v[112:115], v[184:187], v[192:195], v[112:115]
	v_mfma_f32_16x16x32_bf16 v[100:103], v[148:151], v[204:207], v[100:103]
	v_mfma_f32_16x16x32_bf16 v[96:99], v[184:187], v[204:207], v[96:99]
	v_mfma_f32_16x16x32_bf16 v[84:87], v[148:151], v[212:215], v[84:87]
	v_mfma_f32_16x16x32_bf16 v[80:83], v[184:187], v[212:215], v[80:83]
	v_mfma_f32_16x16x32_bf16 v[68:71], v[148:151], v[228:231], v[68:71]
	v_mfma_f32_16x16x32_bf16 v[64:67], v[184:187], v[228:231], v[64:67]
	s_setprio 0
	s_barrier
	s_add_i32 s0, s0, s46
	v_lshl_add_u64 v[232:233], s[42:43], 0, v[170:171]
	s_mov_b32 m0, s0
	ds_read_b128 v[188:191], v198 offset:16384
	ds_read_b128 v[192:195], v198 offset:17408
	ds_read_b128 v[200:203], v198 offset:18432
	ds_read_b128 v[204:207], v198 offset:19456
	ds_read_b128 v[208:211], v198 offset:20480
	ds_read_b128 v[212:215], v198 offset:21504
	ds_read_b128 v[216:219], v198 offset:22528
	ds_read_b128 v[228:231], v198 offset:23552
	global_load_lds_dwordx4 v[232:233], off
	s_add_i32 m0, s0, 0x2000
	s_add_u32 s0, s42, 0xb0000
	v_lshl_add_u64 v[234:235], s[42:43], 0, v[156:157]
	s_addc_u32 s1, s43, 0
	s_add_i32 s13, s13, s46
	global_load_lds_dwordx4 v[234:235], off
	s_mov_b32 m0, s13
	v_lshl_add_u64 v[238:239], s[44:45], 0, v[154:155]
	global_load_lds_dwordx4 v170, s[0:1]
	s_add_i32 m0, s13, 0x2000
	s_nop 0
	global_load_lds_dwordx4 v156, s[0:1]
	v_lshl_add_u64 v[236:237], s[44:45], 0, v[152:153]
	s_nop 0
	s_waitcnt lgkmcnt(0)
	s_barrier
	s_setprio 1
	s_waitcnt lgkmcnt(0)
	v_mfma_f32_16x16x32_bf16 v[60:63], v[128:131], v[188:191], 0
	v_mfma_f32_16x16x32_bf16 v[56:59], v[136:139], v[188:191], 0
	v_mfma_f32_16x16x32_bf16 v[44:47], v[128:131], v[200:203], 0
	v_mfma_f32_16x16x32_bf16 v[40:43], v[136:139], v[200:203], 0
	v_mfma_f32_16x16x32_bf16 v[28:31], v[128:131], v[208:211], 0
	v_mfma_f32_16x16x32_bf16 v[24:27], v[136:139], v[208:211], 0
	v_mfma_f32_16x16x32_bf16 v[12:15], v[128:131], v[216:219], 0
	v_mfma_f32_16x16x32_bf16 v[8:11], v[136:139], v[216:219], 0
	v_mfma_f32_16x16x32_bf16 v[60:63], v[132:135], v[192:195], v[60:63]
	v_mfma_f32_16x16x32_bf16 v[56:59], v[140:143], v[192:195], v[56:59]
	v_mfma_f32_16x16x32_bf16 v[44:47], v[132:135], v[204:207], v[44:47]
	v_mfma_f32_16x16x32_bf16 v[40:43], v[140:143], v[204:207], v[40:43]
	v_mfma_f32_16x16x32_bf16 v[28:31], v[132:135], v[212:215], v[28:31]
	v_mfma_f32_16x16x32_bf16 v[24:27], v[140:143], v[212:215], v[24:27]
	v_mfma_f32_16x16x32_bf16 v[12:15], v[132:135], v[228:231], v[12:15]
	v_mfma_f32_16x16x32_bf16 v[8:11], v[140:143], v[228:231], v[8:11]
	s_setprio 0
	s_setprio 1
	v_mfma_f32_16x16x32_bf16 v[52:55], v[144:147], v[188:191], 0
	v_mfma_f32_16x16x32_bf16 v[48:51], v[164:167], v[188:191], 0
	v_mfma_f32_16x16x32_bf16 v[36:39], v[144:147], v[200:203], 0
	v_mfma_f32_16x16x32_bf16 v[32:35], v[164:167], v[200:203], 0
	v_mfma_f32_16x16x32_bf16 v[20:23], v[144:147], v[208:211], 0
	v_mfma_f32_16x16x32_bf16 v[16:19], v[164:167], v[208:211], 0
	v_mfma_f32_16x16x32_bf16 v[4:7], v[144:147], v[216:219], 0
	v_mfma_f32_16x16x32_bf16 v[0:3], v[164:167], v[216:219], 0
	v_mfma_f32_16x16x32_bf16 v[52:55], v[148:151], v[192:195], v[52:55]
	v_mfma_f32_16x16x32_bf16 v[48:51], v[184:187], v[192:195], v[48:51]
	v_mfma_f32_16x16x32_bf16 v[36:39], v[148:151], v[204:207], v[36:39]
	v_mfma_f32_16x16x32_bf16 v[32:35], v[184:187], v[204:207], v[32:35]
	v_mfma_f32_16x16x32_bf16 v[20:23], v[148:151], v[212:215], v[20:23]
	v_mfma_f32_16x16x32_bf16 v[16:19], v[184:187], v[212:215], v[16:19]
	v_mfma_f32_16x16x32_bf16 v[4:7], v[148:151], v[228:231], v[4:7]
	v_mfma_f32_16x16x32_bf16 v[0:3], v[184:187], v[228:231], v[0:3]
	s_setprio 0
	s_barrier
	s_add_i32 s13, 0, 0x18000
	s_add_i32 s36, 0, 0x1c000
	v_add_u32_e32 v140, s13, v197
	v_add_u32_e32 v184, s36, v197
	ds_read_b128 v[128:131], v140
	ds_read_b128 v[132:135], v140 offset:1024
	ds_read_b128 v[136:139], v140 offset:2048
	ds_read_b128 v[140:143], v140 offset:3072
	ds_read_b128 v[144:147], v184
	ds_read_b128 v[148:151], v184 offset:1024
	ds_read_b128 v[164:167], v184 offset:2048
	ds_read_b128 v[184:187], v184 offset:3072
	s_add_u32 s0, s44, 0xb0000
	s_addc_u32 s1, s45, 0
	s_mov_b32 m0, s49
	ds_read_b128 v[188:191], v198 offset:32768
	ds_read_b128 v[192:195], v198 offset:33792
	ds_read_b128 v[200:203], v198 offset:34816
	ds_read_b128 v[204:207], v198 offset:35840
	ds_read_b128 v[208:211], v198 offset:36864
	ds_read_b128 v[212:215], v198 offset:37888
	ds_read_b128 v[216:219], v198 offset:38912
	ds_read_b128 v[228:231], v198 offset:39936
	global_load_lds_dwordx4 v152, s[0:1]
	s_mov_b32 m0, s50
	s_nop 0
	global_load_lds_dwordx4 v154, s[0:1]
	s_mov_b32 m0, s47
	s_nop 0
	global_load_lds_dwordx4 v[236:237], off
	s_mov_b32 m0, s48
	s_nop 0
	global_load_lds_dwordx4 v[238:239], off
	s_waitcnt vmcnt(8)
	s_waitcnt lgkmcnt(0)
	s_barrier
	s_setprio 1
	s_waitcnt lgkmcnt(0)
	v_mfma_f32_16x16x32_bf16 v[124:127], v[128:131], v[188:191], v[124:127]
	v_mfma_f32_16x16x32_bf16 v[120:123], v[136:139], v[188:191], v[120:123]
	v_mfma_f32_16x16x32_bf16 v[108:111], v[128:131], v[200:203], v[108:111]
	v_mfma_f32_16x16x32_bf16 v[104:107], v[136:139], v[200:203], v[104:107]
	v_mfma_f32_16x16x32_bf16 v[92:95], v[128:131], v[208:211], v[92:95]
	v_mfma_f32_16x16x32_bf16 v[88:91], v[136:139], v[208:211], v[88:91]
	v_mfma_f32_16x16x32_bf16 v[76:79], v[128:131], v[216:219], v[76:79]
	v_mfma_f32_16x16x32_bf16 v[72:75], v[136:139], v[216:219], v[72:75]
	v_mfma_f32_16x16x32_bf16 v[124:127], v[132:135], v[192:195], v[124:127]
	v_mfma_f32_16x16x32_bf16 v[120:123], v[140:143], v[192:195], v[120:123]
	v_mfma_f32_16x16x32_bf16 v[108:111], v[132:135], v[204:207], v[108:111]
	v_mfma_f32_16x16x32_bf16 v[104:107], v[140:143], v[204:207], v[104:107]
	v_mfma_f32_16x16x32_bf16 v[92:95], v[132:135], v[212:215], v[92:95]
	v_mfma_f32_16x16x32_bf16 v[88:91], v[140:143], v[212:215], v[88:91]
	v_mfma_f32_16x16x32_bf16 v[76:79], v[132:135], v[228:231], v[76:79]
	v_mfma_f32_16x16x32_bf16 v[72:75], v[140:143], v[228:231], v[72:75]
	s_setprio 0
	s_setprio 1
	v_mfma_f32_16x16x32_bf16 v[116:119], v[144:147], v[188:191], v[116:119]
	v_mfma_f32_16x16x32_bf16 v[112:115], v[164:167], v[188:191], v[112:115]
	v_mfma_f32_16x16x32_bf16 v[100:103], v[144:147], v[200:203], v[100:103]
	v_mfma_f32_16x16x32_bf16 v[96:99], v[164:167], v[200:203], v[96:99]
	v_mfma_f32_16x16x32_bf16 v[84:87], v[144:147], v[208:211], v[84:87]
	v_mfma_f32_16x16x32_bf16 v[80:83], v[164:167], v[208:211], v[80:83]
	v_mfma_f32_16x16x32_bf16 v[68:71], v[144:147], v[216:219], v[68:71]
	v_mfma_f32_16x16x32_bf16 v[64:67], v[164:167], v[216:219], v[64:67]
	v_mfma_f32_16x16x32_bf16 v[116:119], v[148:151], v[192:195], v[116:119]
	v_mfma_f32_16x16x32_bf16 v[112:115], v[184:187], v[192:195], v[112:115]
	v_mfma_f32_16x16x32_bf16 v[100:103], v[148:151], v[204:207], v[100:103]
	v_mfma_f32_16x16x32_bf16 v[96:99], v[184:187], v[204:207], v[96:99]
	v_mfma_f32_16x16x32_bf16 v[84:87], v[148:151], v[212:215], v[84:87]
	v_mfma_f32_16x16x32_bf16 v[80:83], v[184:187], v[212:215], v[80:83]
	v_mfma_f32_16x16x32_bf16 v[68:71], v[148:151], v[228:231], v[68:71]
	v_mfma_f32_16x16x32_bf16 v[64:67], v[184:187], v[228:231], v[64:67]
	s_setprio 0
	s_barrier
	s_add_i32 s0, s13, s46
	v_lshl_add_u64 v[232:233], v[232:233], 0, s[16:17]
	s_mov_b32 m0, s0
	ds_read_b128 v[188:191], v198 offset:49152
	ds_read_b128 v[192:195], v198 offset:50176
	ds_read_b128 v[200:203], v198 offset:51200
	ds_read_b128 v[204:207], v198 offset:52224
	ds_read_b128 v[208:211], v198 offset:53248
	ds_read_b128 v[212:215], v198 offset:54272
	ds_read_b128 v[216:219], v198 offset:55296
	ds_read_b128 v[228:231], v198 offset:56320
	global_load_lds_dwordx4 v[232:233], off
	s_add_i32 m0, s0, 0x2000
	s_add_u32 s0, s42, 0xb0080
	v_lshl_add_u64 v[232:233], v[234:235], 0, s[16:17]
	s_addc_u32 s1, s43, 0
	s_add_i32 s13, s36, s46
	global_load_lds_dwordx4 v[232:233], off
	s_mov_b32 m0, s13
	s_nop 0
	global_load_lds_dwordx4 v170, s[0:1]
	s_add_i32 m0, s13, 0x2000
	s_nop 0
	global_load_lds_dwordx4 v156, s[0:1]
	v_lshl_add_u64 v[232:233], v[236:237], 0, s[16:17]
	s_mov_b32 m0, s51
	s_nop 0
	global_load_lds_dwordx4 v[232:233], off
	v_lshl_add_u64 v[232:233], v[238:239], 0, s[16:17]
	s_mov_b32 m0, s52
	s_nop 0
	global_load_lds_dwordx4 v[232:233], off
	s_waitcnt vmcnt(6)
	s_waitcnt lgkmcnt(0)
	s_barrier
	s_setprio 1
	s_waitcnt lgkmcnt(0)
	v_mfma_f32_16x16x32_bf16 v[60:63], v[128:131], v[188:191], v[60:63]
	v_mfma_f32_16x16x32_bf16 v[56:59], v[136:139], v[188:191], v[56:59]
	v_mfma_f32_16x16x32_bf16 v[44:47], v[128:131], v[200:203], v[44:47]
	v_mfma_f32_16x16x32_bf16 v[40:43], v[136:139], v[200:203], v[40:43]
	v_mfma_f32_16x16x32_bf16 v[28:31], v[128:131], v[208:211], v[28:31]
	v_mfma_f32_16x16x32_bf16 v[24:27], v[136:139], v[208:211], v[24:27]
	v_mfma_f32_16x16x32_bf16 v[12:15], v[128:131], v[216:219], v[12:15]
	v_mfma_f32_16x16x32_bf16 v[8:11], v[136:139], v[216:219], v[8:11]
	v_mfma_f32_16x16x32_bf16 v[60:63], v[132:135], v[192:195], v[60:63]
	v_mfma_f32_16x16x32_bf16 v[56:59], v[140:143], v[192:195], v[56:59]
	v_mfma_f32_16x16x32_bf16 v[44:47], v[132:135], v[204:207], v[44:47]
	v_mfma_f32_16x16x32_bf16 v[40:43], v[140:143], v[204:207], v[40:43]
	v_mfma_f32_16x16x32_bf16 v[28:31], v[132:135], v[212:215], v[28:31]
	v_mfma_f32_16x16x32_bf16 v[24:27], v[140:143], v[212:215], v[24:27]
	v_mfma_f32_16x16x32_bf16 v[12:15], v[132:135], v[228:231], v[12:15]
	v_mfma_f32_16x16x32_bf16 v[8:11], v[140:143], v[228:231], v[8:11]
	s_setprio 0
	s_setprio 1
	v_mfma_f32_16x16x32_bf16 v[52:55], v[144:147], v[188:191], v[52:55]
	v_mfma_f32_16x16x32_bf16 v[48:51], v[164:167], v[188:191], v[48:51]
	v_mfma_f32_16x16x32_bf16 v[36:39], v[144:147], v[200:203], v[36:39]
	v_mfma_f32_16x16x32_bf16 v[32:35], v[164:167], v[200:203], v[32:35]
	v_mfma_f32_16x16x32_bf16 v[20:23], v[144:147], v[208:211], v[20:23]
	v_mfma_f32_16x16x32_bf16 v[16:19], v[164:167], v[208:211], v[16:19]
	v_mfma_f32_16x16x32_bf16 v[4:7], v[144:147], v[216:219], v[4:7]
	v_mfma_f32_16x16x32_bf16 v[0:3], v[164:167], v[216:219], v[0:3]
	v_mfma_f32_16x16x32_bf16 v[52:55], v[148:151], v[192:195], v[52:55]
	v_mfma_f32_16x16x32_bf16 v[48:51], v[184:187], v[192:195], v[48:51]
	v_mfma_f32_16x16x32_bf16 v[36:39], v[148:151], v[204:207], v[36:39]
	v_mfma_f32_16x16x32_bf16 v[32:35], v[184:187], v[204:207], v[32:35]
	v_mfma_f32_16x16x32_bf16 v[20:23], v[148:151], v[212:215], v[20:23]
	v_mfma_f32_16x16x32_bf16 v[16:19], v[184:187], v[212:215], v[16:19]
	v_mfma_f32_16x16x32_bf16 v[4:7], v[148:151], v[228:231], v[4:7]
	v_mfma_f32_16x16x32_bf16 v[0:3], v[184:187], v[228:231], v[0:3]
	s_setprio 0
	s_barrier
	s_add_i32 s12, s12, 2
	s_add_u32 s58, s58, 0x100
	s_addc_u32 s59, s59, 0
	s_cmp_gt_u32 s12, 41
	s_mov_b64 s[36:37], s[40:41]
.LBB0_1061:
	s_add_u32 s40, s36, 0x100
	s_addc_u32 s41, s37, 0
	s_add_i32 s0, 0, 0x10000
	s_cmp_eq_u32 s12, 40
	s_cselect_b32 s45, s9, s41
	s_cselect_b32 s44, s8, s40
	s_cselect_b32 s43, s35, s59
	s_cselect_b32 s42, s34, s58
	s_add_i32 s13, 0, 0x14000
	v_add_u32_e32 v140, s0, v197
	v_add_u32_e32 v184, s13, v197
	ds_read_b128 v[128:131], v140
	ds_read_b128 v[132:135], v140 offset:1024
	ds_read_b128 v[136:139], v140 offset:2048
	ds_read_b128 v[140:143], v140 offset:3072
	ds_read_b128 v[144:147], v184
	ds_read_b128 v[148:151], v184 offset:1024
	ds_read_b128 v[164:167], v184 offset:2048
	ds_read_b128 v[184:187], v184 offset:3072
	s_add_i32 m0, s47, 0xc000
	ds_read_b128 v[188:191], v198
	ds_read_b128 v[192:195], v198 offset:1024
	ds_read_b128 v[200:203], v198 offset:2048
	ds_read_b128 v[204:207], v198 offset:3072
	ds_read_b128 v[208:211], v198 offset:4096
	ds_read_b128 v[212:215], v198 offset:5120
	ds_read_b128 v[216:219], v198 offset:6144
	ds_read_b128 v[228:231], v198 offset:7168
	global_load_lds_dwordx4 v160, s[36:37]
	s_add_i32 m0, s47, 0xe000
	s_nop 0
	global_load_lds_dwordx4 v162, s[36:37]
	s_waitcnt vmcnt(8)
	s_waitcnt lgkmcnt(0)
	s_barrier
	s_setprio 1
	s_waitcnt lgkmcnt(0)
	v_mfma_f32_16x16x32_bf16 v[124:127], v[128:131], v[188:191], v[124:127]
	v_mfma_f32_16x16x32_bf16 v[120:123], v[136:139], v[188:191], v[120:123]
	v_mfma_f32_16x16x32_bf16 v[108:111], v[128:131], v[200:203], v[108:111]
	v_mfma_f32_16x16x32_bf16 v[104:107], v[136:139], v[200:203], v[104:107]
	v_mfma_f32_16x16x32_bf16 v[92:95], v[128:131], v[208:211], v[92:95]
	v_mfma_f32_16x16x32_bf16 v[88:91], v[136:139], v[208:211], v[88:91]
	v_mfma_f32_16x16x32_bf16 v[76:79], v[128:131], v[216:219], v[76:79]
	v_mfma_f32_16x16x32_bf16 v[72:75], v[136:139], v[216:219], v[72:75]
	v_mfma_f32_16x16x32_bf16 v[124:127], v[132:135], v[192:195], v[124:127]
	v_mfma_f32_16x16x32_bf16 v[120:123], v[140:143], v[192:195], v[120:123]
	v_mfma_f32_16x16x32_bf16 v[108:111], v[132:135], v[204:207], v[108:111]
	v_mfma_f32_16x16x32_bf16 v[104:107], v[140:143], v[204:207], v[104:107]
	v_mfma_f32_16x16x32_bf16 v[92:95], v[132:135], v[212:215], v[92:95]
	v_mfma_f32_16x16x32_bf16 v[88:91], v[140:143], v[212:215], v[88:91]
	v_mfma_f32_16x16x32_bf16 v[76:79], v[132:135], v[228:231], v[76:79]
	v_mfma_f32_16x16x32_bf16 v[72:75], v[140:143], v[228:231], v[72:75]
	s_setprio 0
	s_setprio 1
	v_mfma_f32_16x16x32_bf16 v[116:119], v[144:147], v[188:191], v[116:119]
	v_mfma_f32_16x16x32_bf16 v[112:115], v[164:167], v[188:191], v[112:115]
	v_mfma_f32_16x16x32_bf16 v[100:103], v[144:147], v[200:203], v[100:103]
	v_mfma_f32_16x16x32_bf16 v[96:99], v[164:167], v[200:203], v[96:99]
	v_mfma_f32_16x16x32_bf16 v[84:87], v[144:147], v[208:211], v[84:87]
	v_mfma_f32_16x16x32_bf16 v[80:83], v[164:167], v[208:211], v[80:83]
	v_mfma_f32_16x16x32_bf16 v[68:71], v[144:147], v[216:219], v[68:71]
	v_mfma_f32_16x16x32_bf16 v[64:67], v[164:167], v[216:219], v[64:67]
	v_mfma_f32_16x16x32_bf16 v[116:119], v[148:151], v[192:195], v[116:119]
	v_mfma_f32_16x16x32_bf16 v[112:115], v[184:187], v[192:195], v[112:115]
	v_mfma_f32_16x16x32_bf16 v[100:103], v[148:151], v[204:207], v[100:103]
	v_mfma_f32_16x16x32_bf16 v[96:99], v[184:187], v[204:207], v[96:99]
	v_mfma_f32_16x16x32_bf16 v[84:87], v[148:151], v[212:215], v[84:87]
	v_mfma_f32_16x16x32_bf16 v[80:83], v[184:187], v[212:215], v[80:83]
	v_mfma_f32_16x16x32_bf16 v[68:71], v[148:151], v[228:231], v[68:71]
	v_mfma_f32_16x16x32_bf16 v[64:67], v[184:187], v[228:231], v[64:67]
	s_setprio 0
	s_barrier
	s_add_i32 s0, s0, s46
	v_lshl_add_u64 v[232:233], s[42:43], 0, v[170:171]
	s_mov_b32 m0, s0
	ds_read_b128 v[188:191], v198 offset:16384
	ds_read_b128 v[192:195], v198 offset:17408
	ds_read_b128 v[200:203], v198 offset:18432
	ds_read_b128 v[204:207], v198 offset:19456
	ds_read_b128 v[208:211], v198 offset:20480
	ds_read_b128 v[212:215], v198 offset:21504
	ds_read_b128 v[216:219], v198 offset:22528
	ds_read_b128 v[228:231], v198 offset:23552
	global_load_lds_dwordx4 v[232:233], off
	s_add_i32 m0, s0, 0x2000
	s_add_u32 s0, s42, 0xb0000
	v_lshl_add_u64 v[234:235], s[42:43], 0, v[156:157]
	s_addc_u32 s1, s43, 0
	s_add_i32 s13, s13, s46
	global_load_lds_dwordx4 v[234:235], off
	s_mov_b32 m0, s13
	v_lshl_add_u64 v[238:239], s[44:45], 0, v[154:155]
	global_load_lds_dwordx4 v170, s[0:1]
	s_add_i32 m0, s13, 0x2000
	s_nop 0
	global_load_lds_dwordx4 v156, s[0:1]
	v_lshl_add_u64 v[236:237], s[44:45], 0, v[152:153]
	s_waitcnt vmcnt(6)
	s_waitcnt lgkmcnt(0)
	s_barrier
	s_setprio 1
	s_waitcnt lgkmcnt(0)
	v_mfma_f32_16x16x32_bf16 v[60:63], v[128:131], v[188:191], v[60:63]
	v_mfma_f32_16x16x32_bf16 v[56:59], v[136:139], v[188:191], v[56:59]
	v_mfma_f32_16x16x32_bf16 v[44:47], v[128:131], v[200:203], v[44:47]
	v_mfma_f32_16x16x32_bf16 v[40:43], v[136:139], v[200:203], v[40:43]
	v_mfma_f32_16x16x32_bf16 v[28:31], v[128:131], v[208:211], v[28:31]
	v_mfma_f32_16x16x32_bf16 v[24:27], v[136:139], v[208:211], v[24:27]
	v_mfma_f32_16x16x32_bf16 v[12:15], v[128:131], v[216:219], v[12:15]
	v_mfma_f32_16x16x32_bf16 v[8:11], v[136:139], v[216:219], v[8:11]
	v_mfma_f32_16x16x32_bf16 v[60:63], v[132:135], v[192:195], v[60:63]
	v_mfma_f32_16x16x32_bf16 v[56:59], v[140:143], v[192:195], v[56:59]
	v_mfma_f32_16x16x32_bf16 v[44:47], v[132:135], v[204:207], v[44:47]
	v_mfma_f32_16x16x32_bf16 v[40:43], v[140:143], v[204:207], v[40:43]
	v_mfma_f32_16x16x32_bf16 v[28:31], v[132:135], v[212:215], v[28:31]
	v_mfma_f32_16x16x32_bf16 v[24:27], v[140:143], v[212:215], v[24:27]
	v_mfma_f32_16x16x32_bf16 v[12:15], v[132:135], v[228:231], v[12:15]
	v_mfma_f32_16x16x32_bf16 v[8:11], v[140:143], v[228:231], v[8:11]
	s_setprio 0
	s_setprio 1
	v_mfma_f32_16x16x32_bf16 v[52:55], v[144:147], v[188:191], v[52:55]
	v_mfma_f32_16x16x32_bf16 v[48:51], v[164:167], v[188:191], v[48:51]
	v_mfma_f32_16x16x32_bf16 v[36:39], v[144:147], v[200:203], v[36:39]
	v_mfma_f32_16x16x32_bf16 v[32:35], v[164:167], v[200:203], v[32:35]
	v_mfma_f32_16x16x32_bf16 v[20:23], v[144:147], v[208:211], v[20:23]
	v_mfma_f32_16x16x32_bf16 v[16:19], v[164:167], v[208:211], v[16:19]
	v_mfma_f32_16x16x32_bf16 v[4:7], v[144:147], v[216:219], v[4:7]
	v_mfma_f32_16x16x32_bf16 v[0:3], v[164:167], v[216:219], v[0:3]
	v_mfma_f32_16x16x32_bf16 v[52:55], v[148:151], v[192:195], v[52:55]
	v_mfma_f32_16x16x32_bf16 v[48:51], v[184:187], v[192:195], v[48:51]
	v_mfma_f32_16x16x32_bf16 v[36:39], v[148:151], v[204:207], v[36:39]
	v_mfma_f32_16x16x32_bf16 v[32:35], v[184:187], v[204:207], v[32:35]
	v_mfma_f32_16x16x32_bf16 v[20:23], v[148:151], v[212:215], v[20:23]
	v_mfma_f32_16x16x32_bf16 v[16:19], v[184:187], v[212:215], v[16:19]
	v_mfma_f32_16x16x32_bf16 v[4:7], v[148:151], v[228:231], v[4:7]
	v_mfma_f32_16x16x32_bf16 v[0:3], v[184:187], v[228:231], v[0:3]
	s_setprio 0
	s_barrier
	s_add_i32 s13, 0, 0x18000
	s_add_i32 s36, 0, 0x1c000
	v_add_u32_e32 v140, s13, v197
	v_add_u32_e32 v184, s36, v197
	ds_read_b128 v[128:131], v140
	ds_read_b128 v[132:135], v140 offset:1024
	ds_read_b128 v[136:139], v140 offset:2048
	ds_read_b128 v[140:143], v140 offset:3072
	ds_read_b128 v[144:147], v184
	ds_read_b128 v[148:151], v184 offset:1024
	ds_read_b128 v[164:167], v184 offset:2048
	ds_read_b128 v[184:187], v184 offset:3072
	s_add_u32 s0, s44, 0xb0000
	s_addc_u32 s1, s45, 0
	s_mov_b32 m0, s49
	ds_read_b128 v[188:191], v198 offset:32768
	ds_read_b128 v[192:195], v198 offset:33792
	ds_read_b128 v[200:203], v198 offset:34816
	ds_read_b128 v[204:207], v198 offset:35840
	ds_read_b128 v[208:211], v198 offset:36864
	ds_read_b128 v[212:215], v198 offset:37888
	ds_read_b128 v[216:219], v198 offset:38912
	ds_read_b128 v[228:231], v198 offset:39936
	global_load_lds_dwordx4 v152, s[0:1]
	s_mov_b32 m0, s50
	s_nop 0
	global_load_lds_dwordx4 v154, s[0:1]
	s_mov_b32 m0, s47
	s_nop 0
	global_load_lds_dwordx4 v[236:237], off
	s_mov_b32 m0, s48
	s_nop 0
	global_load_lds_dwordx4 v[238:239], off
	s_waitcnt vmcnt(8)
	s_waitcnt lgkmcnt(0)
	s_barrier
	s_setprio 1
	s_waitcnt lgkmcnt(0)
	v_mfma_f32_16x16x32_bf16 v[124:127], v[128:131], v[188:191], v[124:127]
	v_mfma_f32_16x16x32_bf16 v[120:123], v[136:139], v[188:191], v[120:123]
	v_mfma_f32_16x16x32_bf16 v[108:111], v[128:131], v[200:203], v[108:111]
	v_mfma_f32_16x16x32_bf16 v[104:107], v[136:139], v[200:203], v[104:107]
	v_mfma_f32_16x16x32_bf16 v[92:95], v[128:131], v[208:211], v[92:95]
	v_mfma_f32_16x16x32_bf16 v[88:91], v[136:139], v[208:211], v[88:91]
	v_mfma_f32_16x16x32_bf16 v[76:79], v[128:131], v[216:219], v[76:79]
	v_mfma_f32_16x16x32_bf16 v[72:75], v[136:139], v[216:219], v[72:75]
	v_mfma_f32_16x16x32_bf16 v[124:127], v[132:135], v[192:195], v[124:127]
	v_mfma_f32_16x16x32_bf16 v[120:123], v[140:143], v[192:195], v[120:123]
	v_mfma_f32_16x16x32_bf16 v[108:111], v[132:135], v[204:207], v[108:111]
	v_mfma_f32_16x16x32_bf16 v[104:107], v[140:143], v[204:207], v[104:107]
	v_mfma_f32_16x16x32_bf16 v[92:95], v[132:135], v[212:215], v[92:95]
	v_mfma_f32_16x16x32_bf16 v[88:91], v[140:143], v[212:215], v[88:91]
	v_mfma_f32_16x16x32_bf16 v[76:79], v[132:135], v[228:231], v[76:79]
	v_mfma_f32_16x16x32_bf16 v[72:75], v[140:143], v[228:231], v[72:75]
	s_setprio 0
	s_setprio 1
	v_mfma_f32_16x16x32_bf16 v[116:119], v[144:147], v[188:191], v[116:119]
	v_mfma_f32_16x16x32_bf16 v[112:115], v[164:167], v[188:191], v[112:115]
	v_mfma_f32_16x16x32_bf16 v[100:103], v[144:147], v[200:203], v[100:103]
	v_mfma_f32_16x16x32_bf16 v[96:99], v[164:167], v[200:203], v[96:99]
	v_mfma_f32_16x16x32_bf16 v[84:87], v[144:147], v[208:211], v[84:87]
	v_mfma_f32_16x16x32_bf16 v[80:83], v[164:167], v[208:211], v[80:83]
	v_mfma_f32_16x16x32_bf16 v[68:71], v[144:147], v[216:219], v[68:71]
	v_mfma_f32_16x16x32_bf16 v[64:67], v[164:167], v[216:219], v[64:67]
	v_mfma_f32_16x16x32_bf16 v[116:119], v[148:151], v[192:195], v[116:119]
	v_mfma_f32_16x16x32_bf16 v[112:115], v[184:187], v[192:195], v[112:115]
	v_mfma_f32_16x16x32_bf16 v[100:103], v[148:151], v[204:207], v[100:103]
	v_mfma_f32_16x16x32_bf16 v[96:99], v[184:187], v[204:207], v[96:99]
	v_mfma_f32_16x16x32_bf16 v[84:87], v[148:151], v[212:215], v[84:87]
	v_mfma_f32_16x16x32_bf16 v[80:83], v[184:187], v[212:215], v[80:83]
	v_mfma_f32_16x16x32_bf16 v[68:71], v[148:151], v[228:231], v[68:71]
	v_mfma_f32_16x16x32_bf16 v[64:67], v[184:187], v[228:231], v[64:67]
	s_setprio 0
	s_barrier
	s_add_i32 s0, s13, s46
	v_lshl_add_u64 v[232:233], v[232:233], 0, s[16:17]
	s_mov_b32 m0, s0
	ds_read_b128 v[188:191], v198 offset:49152
	ds_read_b128 v[192:195], v198 offset:50176
	ds_read_b128 v[200:203], v198 offset:51200
	ds_read_b128 v[204:207], v198 offset:52224
	ds_read_b128 v[208:211], v198 offset:53248
	ds_read_b128 v[212:215], v198 offset:54272
	ds_read_b128 v[216:219], v198 offset:55296
	ds_read_b128 v[228:231], v198 offset:56320
	global_load_lds_dwordx4 v[232:233], off
	s_add_i32 m0, s0, 0x2000
	s_add_u32 s0, s42, 0xb0080
	v_lshl_add_u64 v[232:233], v[234:235], 0, s[16:17]
	s_addc_u32 s1, s43, 0
	s_add_i32 s13, s36, s46
	global_load_lds_dwordx4 v[232:233], off
	s_mov_b32 m0, s13
	s_nop 0
	global_load_lds_dwordx4 v170, s[0:1]
	s_add_i32 m0, s13, 0x2000
	s_nop 0
	global_load_lds_dwordx4 v156, s[0:1]
	v_lshl_add_u64 v[232:233], v[236:237], 0, s[16:17]
	s_mov_b32 m0, s51
	s_nop 0
	global_load_lds_dwordx4 v[232:233], off
	v_lshl_add_u64 v[232:233], v[238:239], 0, s[16:17]
	s_mov_b32 m0, s52
	s_nop 0
	global_load_lds_dwordx4 v[232:233], off
	s_waitcnt vmcnt(6)
	s_waitcnt lgkmcnt(0)
	s_barrier
	s_setprio 1
	s_waitcnt lgkmcnt(0)
	v_mfma_f32_16x16x32_bf16 v[60:63], v[128:131], v[188:191], v[60:63]
	v_mfma_f32_16x16x32_bf16 v[56:59], v[136:139], v[188:191], v[56:59]
	v_mfma_f32_16x16x32_bf16 v[44:47], v[128:131], v[200:203], v[44:47]
	v_mfma_f32_16x16x32_bf16 v[40:43], v[136:139], v[200:203], v[40:43]
	v_mfma_f32_16x16x32_bf16 v[28:31], v[128:131], v[208:211], v[28:31]
	v_mfma_f32_16x16x32_bf16 v[24:27], v[136:139], v[208:211], v[24:27]
	v_mfma_f32_16x16x32_bf16 v[12:15], v[128:131], v[216:219], v[12:15]
	v_mfma_f32_16x16x32_bf16 v[8:11], v[136:139], v[216:219], v[8:11]
	v_mfma_f32_16x16x32_bf16 v[60:63], v[132:135], v[192:195], v[60:63]
	v_mfma_f32_16x16x32_bf16 v[56:59], v[140:143], v[192:195], v[56:59]
	v_mfma_f32_16x16x32_bf16 v[44:47], v[132:135], v[204:207], v[44:47]
	v_mfma_f32_16x16x32_bf16 v[40:43], v[140:143], v[204:207], v[40:43]
	v_mfma_f32_16x16x32_bf16 v[28:31], v[132:135], v[212:215], v[28:31]
	v_mfma_f32_16x16x32_bf16 v[24:27], v[140:143], v[212:215], v[24:27]
	v_mfma_f32_16x16x32_bf16 v[12:15], v[132:135], v[228:231], v[12:15]
	v_mfma_f32_16x16x32_bf16 v[8:11], v[140:143], v[228:231], v[8:11]
	s_setprio 0
	s_setprio 1
	v_mfma_f32_16x16x32_bf16 v[52:55], v[144:147], v[188:191], v[52:55]
	v_mfma_f32_16x16x32_bf16 v[48:51], v[164:167], v[188:191], v[48:51]
	v_mfma_f32_16x16x32_bf16 v[36:39], v[144:147], v[200:203], v[36:39]
	v_mfma_f32_16x16x32_bf16 v[32:35], v[164:167], v[200:203], v[32:35]
	v_mfma_f32_16x16x32_bf16 v[20:23], v[144:147], v[208:211], v[20:23]
	v_mfma_f32_16x16x32_bf16 v[16:19], v[164:167], v[208:211], v[16:19]
	v_mfma_f32_16x16x32_bf16 v[4:7], v[144:147], v[216:219], v[4:7]
	v_mfma_f32_16x16x32_bf16 v[0:3], v[164:167], v[216:219], v[0:3]
	v_mfma_f32_16x16x32_bf16 v[52:55], v[148:151], v[192:195], v[52:55]
	v_mfma_f32_16x16x32_bf16 v[48:51], v[184:187], v[192:195], v[48:51]
	v_mfma_f32_16x16x32_bf16 v[36:39], v[148:151], v[204:207], v[36:39]
	v_mfma_f32_16x16x32_bf16 v[32:35], v[184:187], v[204:207], v[32:35]
	v_mfma_f32_16x16x32_bf16 v[20:23], v[148:151], v[212:215], v[20:23]
	v_mfma_f32_16x16x32_bf16 v[16:19], v[184:187], v[212:215], v[16:19]
	v_mfma_f32_16x16x32_bf16 v[4:7], v[148:151], v[228:231], v[4:7]
	v_mfma_f32_16x16x32_bf16 v[0:3], v[184:187], v[228:231], v[0:3]
	s_setprio 0
	s_barrier
	s_add_i32 s12, s12, 2
	s_add_u32 s58, s58, 0x100
	s_addc_u32 s59, s59, 0
	s_cmp_gt_u32 s12, 41
	s_mov_b64 s[36:37], s[40:41]
	s_cbranch_scc0 .LBB0_1061
	s_and_b64 vcc, exec, s[30:31]
	s_cbranch_vccz .LBB0_1064
	s_barrier

.LBB0_1080:
	s_or_b64 exec, exec, s[36:37]
	s_and_b64 vcc, exec, s[6:7]
	s_mov_b64 s[6:7], -1
	s_cbranch_vccnz .LBB0_1049
	s_andn2_b64 vcc, exec, s[24:25]
	s_cbranch_vccnz .LBB0_1048
	s_mov_b32 s98, 1
	s_branch .LBB0_1048

	.amdhsa_kernel _Z8yoco_fwd4Args
		.amdhsa_group_segment_fixed_size 0
		.amdhsa_private_segment_fixed_size 0
		.amdhsa_kernarg_size 464
		.amdhsa_user_sgpr_count 2
		.amdhsa_user_sgpr_dispatch_ptr 0
		.amdhsa_user_sgpr_queue_ptr 0
		.amdhsa_user_sgpr_kernarg_segment_ptr 1
		.amdhsa_user_sgpr_dispatch_id 0
		.amdhsa_user_sgpr_kernarg_preload_length 0
		.amdhsa_user_sgpr_kernarg_preload_offset 0
		.amdhsa_user_sgpr_private_segment_size 0
		.amdhsa_uses_dynamic_stack 0
		.amdhsa_enable_private_segment 0
		.amdhsa_system_sgpr_workgroup_id_x 1
		.amdhsa_system_sgpr_workgroup_id_y 0
		.amdhsa_system_sgpr_workgroup_id_z 0
		.amdhsa_system_sgpr_workgroup_info 0
		.amdhsa_system_vgpr_workitem_id 2
		.amdhsa_next_free_vgpr 245
		.amdhsa_next_free_sgpr 102
		.amdhsa_accum_offset 248
		.amdhsa_reserve_vcc 1
		.amdhsa_float_round_mode_32 0
		.amdhsa_float_round_mode_16_64 0
		.amdhsa_float_denorm_mode_32 3
		.amdhsa_float_denorm_mode_16_64 3
		.amdhsa_dx10_clamp 1
		.amdhsa_ieee_mode 1
		.amdhsa_fp16_overflow 0
		.amdhsa_tg_split 0
		.amdhsa_exception_fp_ieee_invalid_op 0
		.amdhsa_exception_fp_denorm_src 0
		.amdhsa_exception_fp_ieee_div_zero 0
		.amdhsa_exception_fp_ieee_overflow 0
		.amdhsa_exception_fp_ieee_underflow 0
		.amdhsa_exception_fp_ieee_inexact 0
		.amdhsa_exception_int_div_zero 0
	.end_amdhsa_kernel

amdhsa.kernels:
  - .agpr_count:     0
    .args:
      - .offset:         0
        .size:           208
        .value_kind:     by_value
      - .offset:         208
        .size:           4
        .value_kind:     hidden_block_count_x
      - .offset:         212
        .size:           4
        .value_kind:     hidden_block_count_y
      - .offset:         216
        .size:           4
        .value_kind:     hidden_block_count_z
      - .offset:         220
        .size:           2
        .value_kind:     hidden_group_size_x
      - .offset:         222
        .size:           2
        .value_kind:     hidden_group_size_y
      - .offset:         224
        .size:           2
        .value_kind:     hidden_group_size_z
      - .offset:         226
        .size:           2
        .value_kind:     hidden_remainder_x
      - .offset:         228
        .size:           2
        .value_kind:     hidden_remainder_y
      - .offset:         230
        .size:           2
        .value_kind:     hidden_remainder_z
      - .offset:         248
        .size:           8
        .value_kind:     hidden_global_offset_x
      - .offset:         256
        .size:           8
        .value_kind:     hidden_global_offset_y
      - .offset:         264
        .size:           8
        .value_kind:     hidden_global_offset_z
      - .offset:         272
        .size:           2
        .value_kind:     hidden_grid_dims
      - .offset:         296
        .size:           8
        .value_kind:     hidden_multigrid_sync_arg
      - .offset:         328
        .size:           4
        .value_kind:     hidden_dynamic_lds_size
    .group_segment_fixed_size: 0
    .kernarg_segment_align: 8
    .kernarg_segment_size: 464
    .language:       OpenCL C
    .language_version:
      - 2
      - 0
    .max_flat_workgroup_size: 512
    .name:           _Z8yoco_fwd4Args
    .private_segment_fixed_size: 0
    .sgpr_count:     108
    .sgpr_spill_count: 47
    .symbol:         _Z8yoco_fwd4Args.kd
    .uniform_work_group_size: 1
    .uses_dynamic_stack: false
    .vgpr_count:     245
    .vgpr_spill_count: 0
    .wavefront_size: 64
